# fused pairwise DPP/permlane reduction steps (fewer wait-state nops)
# baseline (speedup 1.0000x reference)
; DI float wave_sum(float v) { for (int o = 32; o; o >>= 1) v += __shfl_xor(v, o); return v; }
; DI void rmsnorm_phase(const float* x, const float* g, bf16_t* h, int ntok, const int tid) {
;     ...
;     for (int t0 = (blockIdx.x * 8 + wv) * 2; t0 < ntok; t0 += gridDim.x * 16) {
;         f32x4 v[2][4];
; #pragma unroll
;         for (int u = 0; u < 2; ++u)
; #pragma unroll
;             for (int c = 0; c < 4; ++c) v[u][c] = ((const f32x4*)(x + (size_t)(t0 + u) * 1024))[lane + 64 * c];
; #pragma unroll
;         for (int u = 0; u < 2; ++u) { float ss = 0.f;
; #pragma unroll
;             for (int c = 0; c < 4; ++c) ss += v[u][c][0] * v[u][c][0] + v[u][c][1] * v[u][c][1] + v[u][c][2] * v[u][c][2] + v[u][c][3] * v[u][c][3];
;             ss = wave_sum(ss);
.LBB0_127:
	v_ashrrev_i32_e32 v51, 31, v50
	v_lshlrev_b64 v[18:19], 12, v[50:51]
	v_add_u32_e32 v56, 1, v50
	v_lshl_add_u64 v[18:19], v[52:53], 0, v[18:19]
	v_ashrrev_i32_e32 v57, 31, v56
	global_load_dwordx4 v[46:49], v[18:19], off
	global_load_dwordx4 v[42:45], v[18:19], off offset:1024
	global_load_dwordx4 v[38:41], v[18:19], off offset:2048
	global_load_dwordx4 v[34:37], v[18:19], off offset:3072
	v_lshlrev_b64 v[18:19], 12, v[56:57]
	v_lshl_add_u64 v[18:19], v[52:53], 0, v[18:19]
	global_load_dwordx4 v[30:33], v[18:19], off
	global_load_dwordx4 v[26:29], v[18:19], off offset:1024
	global_load_dwordx4 v[22:25], v[18:19], off offset:2048
	s_nop 0
	global_load_dwordx4 v[18:21], v[18:19], off offset:3072
	s_waitcnt vmcnt(0)
	v_mov_b32_e32 v66, v47
	v_mov_b32_e32 v67, v43
	v_mov_b32_e32 v58, v46
	v_mov_b32_e32 v72, v31
	v_mov_b32_e32 v73, v27
	v_mov_b32_e32 v59, v42
	v_pk_mul_f32 v[66:67], v[66:67], v[66:67]
	v_mov_b32_e32 v70, v30
	v_mov_b32_e32 v71, v26
	v_pk_mul_f32 v[72:73], v[72:73], v[72:73]
	v_pk_fma_f32 v[58:59], v[58:59], v[58:59], v[66:67]
	v_mov_b32_e32 v66, v48
	v_mov_b32_e32 v67, v44
	v_pk_fma_f32 v[70:71], v[70:71], v[70:71], v[72:73]
	v_mov_b32_e32 v72, v32
	v_mov_b32_e32 v73, v28
	v_pk_fma_f32 v[58:59], v[66:67], v[66:67], v[58:59]
	v_mov_b32_e32 v66, v49
	v_mov_b32_e32 v67, v45
	v_mov_b32_e32 v68, v39
	v_mov_b32_e32 v69, v35
	v_pk_fma_f32 v[70:71], v[72:73], v[72:73], v[70:71]
	v_mov_b32_e32 v72, v33
	v_mov_b32_e32 v73, v29
	v_mov_b32_e32 v74, v23
	v_mov_b32_e32 v75, v19
	v_pk_fma_f32 v[66:67], v[66:67], v[66:67], v[58:59]
	v_mov_b32_e32 v58, v38
	v_mov_b32_e32 v59, v34
	v_pk_mul_f32 v[68:69], v[68:69], v[68:69]
	v_pk_fma_f32 v[70:71], v[72:73], v[72:73], v[70:71]
	v_mov_b32_e32 v72, v22
	v_mov_b32_e32 v73, v18
	v_pk_mul_f32 v[74:75], v[74:75], v[74:75]
	v_pk_fma_f32 v[58:59], v[58:59], v[58:59], v[68:69]
	v_mov_b32_e32 v68, v40
	v_mov_b32_e32 v69, v36
	v_pk_fma_f32 v[72:73], v[72:73], v[72:73], v[74:75]
	v_mov_b32_e32 v74, v24
	v_mov_b32_e32 v75, v20
	v_pk_fma_f32 v[58:59], v[68:69], v[68:69], v[58:59]
	v_mov_b32_e32 v68, v41
	v_mov_b32_e32 v69, v37
	v_pk_fma_f32 v[72:73], v[74:75], v[74:75], v[72:73]
	v_mov_b32_e32 v74, v25
	v_mov_b32_e32 v75, v21
	v_pk_fma_f32 v[68:69], v[68:69], v[68:69], v[58:59]
	v_pk_fma_f32 v[72:73], v[74:75], v[74:75], v[72:73]
	v_mov_b32_e32 v74, v70
	v_mov_b32_e32 v75, v66
	v_mov_b32_e32 v66, v71
	v_pk_add_f32 v[66:67], v[74:75], v[66:67]
	v_mov_b32_e32 v70, v72
	v_mov_b32_e32 v71, v68
	v_pk_add_f32 v[66:67], v[66:67], v[70:71]
	v_mov_b32_e32 v68, v73
	v_pk_add_f32 v[66:67], v[66:67], v[68:69]
	v_mov_b32_e32 v69, v67
	v_mov_b32_e32 v68, v66
	s_nop 0
	v_permlane32_swap_b32_e32 v69, v67
	v_permlane32_swap_b32_e32 v68, v66
	v_lshlrev_b64 v[58:59], 11, v[50:51]
	v_lshl_add_u64 v[58:59], v[54:55], 0, v[58:59]
	v_add_u32_e32 v50, s17, v50
	s_waitcnt lgkmcnt(0)
	v_pk_add_f32 v[66:67], v[66:67], v[68:69]
	v_mov_b32_e32 v69, v67
	v_mov_b32_e32 v68, v66
	s_nop 0
	v_permlane16_swap_b32_e32 v69, v67
	v_permlane16_swap_b32_e32 v68, v66
	s_waitcnt lgkmcnt(0)
	v_pk_add_f32 v[66:67], v[66:67], v[68:69]
	s_nop 1
	v_mov_b32_dpp v69, v67 row_ror:8 row_mask:0xf bank_mask:0xf
	v_mov_b32_dpp v68, v66 row_ror:8 row_mask:0xf bank_mask:0xf
	s_waitcnt lgkmcnt(0)
	v_pk_add_f32 v[66:67], v[66:67], v[68:69]
	s_nop 1
	v_mov_b32_dpp v69, v67 row_shl:4 row_mask:0xf bank_mask:0x5
	v_mov_b32_dpp v69, v67 row_shr:4 row_mask:0xf bank_mask:0xa
	v_mov_b32_dpp v68, v66 row_shl:4 row_mask:0xf bank_mask:0x5
	v_mov_b32_dpp v68, v66 row_shr:4 row_mask:0xf bank_mask:0xa
	s_waitcnt lgkmcnt(0)
; DI unsigned pk2(float lo, float hi) { const f32x2 v = {lo, hi}; return __builtin_bit_cast(unsigned, __builtin_convertvector(v, bf16v2_t)); }
; DI float wave_sum(float v) { for (int o = 32; o; o >>= 1) v += __shfl_xor(v, o); return v; }
; DI void rmsnorm_phase(const float* x, const float* g, bf16_t* h, int ntok, const int tid) {
;     ...
;             ss = wave_sum(ss);
;             const float rs = rsqrtf(ss * (1.f / 1024.f) + NEPS);
; #pragma unroll
;             for (int c = 0; c < 4; ++c) { u32x2 o; o[0] = pk2(v[u][c][0] * rs * gg[c][0], v[u][c][1] * rs * gg[c][1]); o[1] = pk2(v[u][c][2] * rs * gg[c][2], v[u][c][3] * rs * gg[c][3]);
;                 *(u32x2*)(h + (size_t)(t0 + u) * 1024 + (lane + 64 * c) * 4) = o; } }
;     }
	v_pk_add_f32 v[66:67], v[66:67], v[68:69]
	s_nop 1
	v_mov_b32_dpp v69, v67 quad_perm:[2,3,0,1] row_mask:0xf bank_mask:0xf
	v_mov_b32_dpp v68, v66 quad_perm:[2,3,0,1] row_mask:0xf bank_mask:0xf
	s_waitcnt lgkmcnt(0)
	v_pk_add_f32 v[66:67], v[66:67], v[68:69]
	s_nop 1
	v_mov_b32_dpp v69, v67 quad_perm:[1,0,3,2] row_mask:0xf bank_mask:0xf
	v_mov_b32_dpp v68, v66 quad_perm:[1,0,3,2] row_mask:0xf bank_mask:0xf
	s_waitcnt lgkmcnt(0)
	v_pk_add_f32 v[66:67], v[66:67], v[68:69]
	s_nop 0
	v_pk_fma_f32 v[66:67], v[66:67], s[12:13], v[190:191] op_sel_hi:[1,0,0]
	s_nop 0
	v_mul_f32_e32 v0, 0x4b800000, v67
	v_cmp_gt_f32_e64 s[0:1], s77, v67
	v_cmp_gt_f32_e32 vcc, s77, v66
	s_nop 0
	v_cndmask_b32_e64 v0, v67, v0, s[0:1]
	v_rsq_f32_e32 v0, v0
	s_nop 0
	v_mul_f32_e32 v51, 0x45800000, v0
	v_cndmask_b32_e64 v0, v0, v51, s[0:1]
	v_pk_mul_f32 v[46:47], v[46:47], v[0:1] op_sel_hi:[1,0]
	v_pk_mul_f32 v[48:49], v[48:49], v[0:1] op_sel_hi:[1,0]
	v_pk_mul_f32 v[42:43], v[42:43], v[0:1] op_sel_hi:[1,0]
	v_pk_mul_f32 v[44:45], v[44:45], v[0:1] op_sel_hi:[1,0]
	v_pk_mul_f32 v[38:39], v[38:39], v[0:1] op_sel_hi:[1,0]
	v_pk_mul_f32 v[40:41], v[40:41], v[0:1] op_sel_hi:[1,0]
	v_pk_mul_f32 v[34:35], v[34:35], v[0:1] op_sel_hi:[1,0]
	v_pk_mul_f32 v[36:37], v[36:37], v[0:1] op_sel_hi:[1,0]
	v_mul_f32_e32 v0, 0x4b800000, v66
	v_cndmask_b32_e32 v0, v66, v0, vcc
	v_rsq_f32_e32 v0, v0
	v_pk_mul_f32 v[34:35], v[2:3], v[34:35]
	v_pk_mul_f32 v[36:37], v[4:5], v[36:37]
	v_cvt_pk_bf16_f32 v34, v34, v35
	v_cvt_pk_bf16_f32 v35, v36, v37
	global_store_dwordx2 v[58:59], v[34:35], off offset:1536
	v_mul_f32_e32 v34, 0x45800000, v0
	v_cndmask_b32_e32 v0, v0, v34, vcc
	v_pk_mul_f32 v[30:31], v[30:31], v[0:1] op_sel_hi:[1,0]
	v_pk_mul_f32 v[32:33], v[32:33], v[0:1] op_sel_hi:[1,0]
	v_pk_mul_f32 v[26:27], v[26:27], v[0:1] op_sel_hi:[1,0]
	v_pk_mul_f32 v[28:29], v[28:29], v[0:1] op_sel_hi:[1,0]
	v_pk_mul_f32 v[22:23], v[22:23], v[0:1] op_sel_hi:[1,0]
	v_pk_mul_f32 v[24:25], v[24:25], v[0:1] op_sel_hi:[1,0]
	v_pk_mul_f32 v[18:19], v[18:19], v[0:1] op_sel_hi:[1,0]
	v_pk_mul_f32 v[20:21], v[20:21], v[0:1] op_sel_hi:[1,0]
	v_pk_mul_f32 v[46:47], v[14:15], v[46:47]
	v_pk_mul_f32 v[48:49], v[16:17], v[48:49]
	v_pk_mul_f32 v[42:43], v[10:11], v[42:43]
	v_pk_mul_f32 v[44:45], v[12:13], v[44:45]
	v_pk_mul_f32 v[38:39], v[6:7], v[38:39]
	v_pk_mul_f32 v[40:41], v[8:9], v[40:41]
	v_lshlrev_b64 v[34:35], 11, v[56:57]
	v_pk_mul_f32 v[30:31], v[14:15], v[30:31]
	v_pk_mul_f32 v[32:33], v[16:17], v[32:33]
	v_pk_mul_f32 v[26:27], v[10:11], v[26:27]
	v_pk_mul_f32 v[28:29], v[12:13], v[28:29]
	v_pk_mul_f32 v[22:23], v[6:7], v[22:23]
	v_pk_mul_f32 v[24:25], v[8:9], v[24:25]
	v_pk_mul_f32 v[18:19], v[2:3], v[18:19]
	v_pk_mul_f32 v[20:21], v[4:5], v[20:21]
	v_cmp_lt_i32_e32 vcc, s16, v50
	v_cvt_pk_bf16_f32 v46, v46, v47
	v_cvt_pk_bf16_f32 v47, v48, v49
	v_cvt_pk_bf16_f32 v42, v42, v43
	v_cvt_pk_bf16_f32 v43, v44, v45
	v_cvt_pk_bf16_f32 v38, v38, v39
	v_cvt_pk_bf16_f32 v39, v40, v41
	v_cvt_pk_bf16_f32 v30, v30, v31
	v_cvt_pk_bf16_f32 v31, v32, v33
	v_lshl_add_u64 v[32:33], v[54:55], 0, v[34:35]
	v_cvt_pk_bf16_f32 v26, v26, v27
	v_cvt_pk_bf16_f32 v27, v28, v29
	v_cvt_pk_bf16_f32 v22, v22, v23
	v_cvt_pk_bf16_f32 v23, v24, v25
	v_cvt_pk_bf16_f32 v18, v18, v19
	v_cvt_pk_bf16_f32 v19, v20, v21
	s_or_b64 s[34:35], vcc, s[34:35]
	global_store_dwordx2 v[58:59], v[46:47], off
	global_store_dwordx2 v[58:59], v[42:43], off offset:512
	global_store_dwordx2 v[58:59], v[38:39], off offset:1024
	global_store_dwordx2 v[32:33], v[30:31], off
	global_store_dwordx2 v[32:33], v[26:27], off offset:512
	global_store_dwordx2 v[32:33], v[22:23], off offset:1024
	global_store_dwordx2 v[32:33], v[18:19], off offset:1536
	s_andn2_b64 exec, exec, s[34:35]
	s_cbranch_execnz .LBB0_127

; DI void run_phase(const Params& p, int ph, unsigned char* smem, const int tid, const int rep) {
;     ...
;         { const float* g1 = PIN(12) + l * 192; const float* g2 = PIN(13) + l * 192; const float* g3 = PIN(17) + l * 128; const float* g4 = PIN(18) + l * 128;
;           float a1 = fmaxf(fmaxf(fabsf(g1[lane]), fabsf(g1[lane + 64])), fabsf(g1[lane + 128])), a2 = fmaxf(fmaxf(fabsf(g2[lane]), fabsf(g2[lane + 64])), fabsf(g2[lane + 128]));
;           float a3 = fmaxf(fabsf(g3[lane]), fabsf(g3[lane + 64])), a4 = fmaxf(fabsf(g4[lane]), fabsf(g4[lane + 64]));
;           for (int o = 32; o; o >>= 1) { a1 = fmaxf(a1, __shfl_xor(a1, o)); a2 = fmaxf(a2, __shfl_xor(a2, o)); a3 = fmaxf(a3, __shfl_xor(a3, o)); a4 = fmaxf(a4, __shfl_xor(a4, o)); }
;           if (tid == 0) { float* mp = (float*)(smem + LDS_BYTES - 48); mp[0] = a1 * a2 * 13.856406460551018f * LOG2E; mp[1] = a3 * a4 * 11.313708498984761f * LOG2E; } }
.LBB0_203:
	s_andn2_b64 vcc, exec, s[0:1]
	s_cbranch_vccnz .LBB0_325
	v_readlane_b32 s0, v255, 3
	s_mov_b32 s4, s0
	s_mul_i32 s14, s4, 0xc0
	v_readlane_b32 s1, v255, 4
	s_lshl_b32 s0, s0, 7
	s_ashr_i32 s15, s14, 31
	v_readlane_b32 s40, v254, 35
	s_ashr_i32 s1, s0, 31
	s_lshl_b64 s[14:15], s[14:15], 2
	v_readlane_b32 s48, v254, 43
	v_readlane_b32 s49, v254, 44
	s_add_u32 s24, s48, s14
	v_readlane_b32 s50, v254, 45
	s_addc_u32 s25, s49, s15
	v_readlane_b32 s41, v254, 36
	v_readlane_b32 s42, v254, 37
	v_readlane_b32 s43, v254, 38
	v_readlane_b32 s44, v254, 39
	v_readlane_b32 s45, v254, 40
	v_readlane_b32 s46, v254, 41
	v_readlane_b32 s47, v254, 42
	v_readlane_b32 s51, v254, 46
	v_readlane_b32 s52, v254, 47
	v_readlane_b32 s53, v254, 48
	v_readlane_b32 s54, v254, 49
	v_readlane_b32 s55, v254, 50
	s_add_u32 s14, s50, s14
	s_addc_u32 s15, s51, s15
	v_readlane_b32 s40, v254, 51
	s_lshl_b64 s[0:1], s[0:1], 2
	v_readlane_b32 s42, v254, 53
	v_readlane_b32 s43, v254, 54
	s_add_u32 s34, s42, s0
	v_readlane_b32 s44, v254, 55
	s_addc_u32 s35, s43, s1
	v_lshlrev_b32_e32 v0, 2, v194
	v_readlane_b32 s45, v254, 56
	global_load_dword v2, v0, s[24:25]
	global_load_dword v3, v0, s[24:25] offset:256
	global_load_dword v4, v0, s[24:25] offset:512
	global_load_dword v5, v0, s[14:15]
	global_load_dword v6, v0, s[14:15] offset:256
	global_load_dword v7, v0, s[14:15] offset:512
	global_load_dword v8, v0, s[34:35]
	global_load_dword v9, v0, s[34:35] offset:256
	s_add_u32 s14, s44, s0
	s_addc_u32 s15, s45, s1
	global_load_dword v10, v0, s[14:15] offset:256
	s_nop 0
	global_load_dword v0, v0, s[14:15]
	v_and_b32_e32 v11, 64, v218
	v_xor_b32_e32 v12, 32, v218
	v_add_u32_e32 v11, 64, v11
	v_cmp_lt_i32_e32 vcc, v12, v11
	v_xor_b32_e32 v13, 16, v218
	v_xor_b32_e32 v14, 8, v218
	v_cndmask_b32_e32 v12, v218, v12, vcc
	v_lshlrev_b32_e32 v191, 2, v12
	v_cmp_lt_i32_e32 vcc, v13, v11
	v_xor_b32_e32 v15, 4, v218
	v_xor_b32_e32 v16, 2, v218
	v_cndmask_b32_e32 v13, v218, v13, vcc
	v_lshlrev_b32_e32 v227, 2, v13
	v_cmp_lt_i32_e32 vcc, v14, v11
	v_xor_b32_e32 v17, 1, v218
	v_cmp_eq_u32_e64 s[38:39], 0, v225
	v_cndmask_b32_e32 v14, v218, v14, vcc
	v_lshlrev_b32_e32 v228, 2, v14
	v_cmp_lt_i32_e32 vcc, v15, v11
	v_readlane_b32 s41, v254, 52
	v_readlane_b32 s46, v254, 57
	v_cndmask_b32_e32 v15, v218, v15, vcc
	v_lshlrev_b32_e32 v229, 2, v15
	v_cmp_lt_i32_e32 vcc, v16, v11
	v_readlane_b32 s47, v254, 58
	v_readlane_b32 s48, v254, 59
	v_cndmask_b32_e32 v16, v218, v16, vcc
	v_lshlrev_b32_e32 v230, 2, v16
	v_cmp_lt_i32_e32 vcc, v17, v11
	v_readlane_b32 s49, v254, 60
	v_readlane_b32 s50, v254, 61
	v_cndmask_b32_e32 v11, v218, v17, vcc
	v_lshlrev_b32_e32 v231, 2, v11
	v_readlane_b32 s51, v254, 62
	v_readlane_b32 s52, v254, 63
	v_readlane_b32 s53, v255, 0
	v_readlane_b32 s54, v255, 1
	v_readlane_b32 s55, v255, 2
	s_waitcnt vmcnt(0)
	v_max3_f32 v2, |v2|, |v3|, |v4|
	v_mov_b32_e32 v3, v2
	s_nop 1
	v_permlane32_swap_b32_e32 v3, v2
	v_max3_f32 v4, |v5|, |v6|, |v7|
	ds_bpermute_b32 v5, v191, v4
	v_max_f32_e64 v6, |v9|, |v9|
	v_max_f32_e64 v7, |v8|, |v8|
	v_max_f32_e32 v6, v7, v6
	v_max_f32_e64 v7, |v10|, |v10|
	v_max_f32_e64 v0, |v0|, |v0|
	s_waitcnt lgkmcnt(1)
	v_max_f32_e32 v3, v3, v3
	v_mov_b32_e32 v8, v6
	s_nop 1
	v_permlane32_swap_b32_e32 v8, v6
	v_max_f32_e32 v0, v0, v7
	v_max_f32_e32 v2, v2, v3
	s_waitcnt lgkmcnt(1)
	v_max_f32_e32 v3, v5, v5
	v_mov_b32_e32 v5, v0
	s_nop 1
	v_permlane32_swap_b32_e32 v5, v0
	v_mov_b32_e32 v7, v2
	s_nop 1
	v_permlane16_swap_b32_e32 v7, v2
	s_waitcnt lgkmcnt(2)
	v_max_f32_e32 v8, v8, v8
	v_max_f32_e32 v6, v6, v8
	v_max_f32_e32 v3, v4, v3
	s_waitcnt lgkmcnt(1)
	v_max_f32_e32 v5, v5, v5
	s_waitcnt lgkmcnt(0)
	v_max_f32_e32 v7, v7, v7
	v_mov_b32_e32 v8, v6
	s_nop 1
	v_permlane16_swap_b32_e32 v8, v6
	v_max_f32_e32 v0, v0, v5
	v_mov_b32_e32 v4, v3
	s_nop 1
	v_permlane16_swap_b32_e32 v4, v3
	v_max_f32_e32 v2, v2, v7
	v_mov_b32_e32 v5, v0
	s_nop 1
	v_permlane16_swap_b32_e32 v5, v0
	s_nop 1
	v_mov_b32_dpp v7, v2 row_ror:8 row_mask:0xf bank_mask:0xf
	s_waitcnt lgkmcnt(3)
	v_max_f32_e32 v8, v8, v8
	s_waitcnt lgkmcnt(2)
	v_max_f32_e32 v4, v4, v4
	v_max_f32_e32 v6, v6, v8
	s_waitcnt lgkmcnt(1)
	v_max_f32_e32 v5, v5, v5
	v_max_f32_e32 v3, v3, v4
	s_waitcnt lgkmcnt(0)
	v_max_f32_e32 v7, v7, v7
	s_nop 1
	v_mov_b32_dpp v8, v6 row_ror:8 row_mask:0xf bank_mask:0xf
	v_max_f32_e32 v0, v0, v5
	s_nop 1
	v_mov_b32_dpp v4, v3 row_ror:8 row_mask:0xf bank_mask:0xf
	v_max_f32_e32 v2, v2, v7
	s_nop 1
	v_mov_b32_dpp v5, v0 row_ror:8 row_mask:0xf bank_mask:0xf
	s_nop 1
	v_mov_b32_dpp v7, v2 row_shl:4 row_mask:0xf bank_mask:0x5
	v_mov_b32_dpp v7, v2 row_shr:4 row_mask:0xf bank_mask:0xa
	s_waitcnt lgkmcnt(3)
	v_max_f32_e32 v8, v8, v8
	s_waitcnt lgkmcnt(2)
	v_max_f32_e32 v4, v4, v4
	v_max_f32_e32 v6, v6, v8
	s_waitcnt lgkmcnt(1)
	v_max_f32_e32 v5, v5, v5
	v_max_f32_e32 v3, v3, v4
	s_waitcnt lgkmcnt(0)
	v_max_f32_e32 v7, v7, v7
	s_nop 1
	v_mov_b32_dpp v8, v6 row_shl:4 row_mask:0xf bank_mask:0x5
	v_mov_b32_dpp v8, v6 row_shr:4 row_mask:0xf bank_mask:0xa
	v_max_f32_e32 v0, v0, v5
	s_nop 1
	v_mov_b32_dpp v4, v3 row_shl:4 row_mask:0xf bank_mask:0x5
	v_mov_b32_dpp v4, v3 row_shr:4 row_mask:0xf bank_mask:0xa
	v_max_f32_e32 v2, v2, v7
	s_nop 1
	v_mov_b32_dpp v5, v0 row_shl:4 row_mask:0xf bank_mask:0x5
	v_mov_b32_dpp v5, v0 row_shr:4 row_mask:0xf bank_mask:0xa
	s_nop 1
	v_mov_b32_dpp v7, v2 quad_perm:[2,3,0,1] row_mask:0xf bank_mask:0xf
	s_waitcnt lgkmcnt(3)
	v_max_f32_e32 v8, v8, v8
	s_waitcnt lgkmcnt(2)
	v_max_f32_e32 v4, v4, v4
	v_max_f32_e32 v6, v6, v8
	s_waitcnt lgkmcnt(1)
	v_max_f32_e32 v5, v5, v5
	v_max_f32_e32 v3, v3, v4
	s_waitcnt lgkmcnt(0)
	v_max_f32_e32 v7, v7, v7
	s_nop 1
	v_mov_b32_dpp v8, v6 quad_perm:[2,3,0,1] row_mask:0xf bank_mask:0xf
	v_max_f32_e32 v9, v0, v5
	s_nop 1
	v_mov_b32_dpp v4, v3 quad_perm:[2,3,0,1] row_mask:0xf bank_mask:0xf
	v_max_f32_e32 v0, v2, v7
	s_nop 1
	v_mov_b32_dpp v7, v9 quad_perm:[2,3,0,1] row_mask:0xf bank_mask:0xf
	s_waitcnt lgkmcnt(2)
	v_max_f32_e32 v5, v8, v8
	v_max_f32_e32 v5, v6, v5
	s_waitcnt lgkmcnt(1)
	v_max_f32_e32 v4, v4, v4
	v_max_f32_e32 v3, v3, v4
	s_waitcnt lgkmcnt(0)
	v_max_f32_e32 v6, v7, v7
	v_max_f32_e32 v7, v9, v6
	s_nop 1
	v_mov_b32_dpp v2, v0 quad_perm:[1,0,3,2] row_mask:0xf bank_mask:0xf
	v_mov_b32_dpp v4, v3 quad_perm:[1,0,3,2] row_mask:0xf bank_mask:0xf
	s_nop 1
	v_mov_b32_dpp v6, v5 quad_perm:[1,0,3,2] row_mask:0xf bank_mask:0xf
	v_mov_b32_dpp v8, v7 quad_perm:[1,0,3,2] row_mask:0xf bank_mask:0xf
	s_and_saveexec_b64 s[14:15], s[38:39]
	s_cbranch_execz .LBB0_206
; DI void run_phase(const Params& p, int ph, unsigned char* smem, const int tid, const int rep) {
;     ...
;           for (int o = 32; o; o >>= 1) { a1 = fmaxf(a1, __shfl_xor(a1, o)); a2 = fmaxf(a2, __shfl_xor(a2, o)); a3 = fmaxf(a3, __shfl_xor(a3, o)); a4 = fmaxf(a4, __shfl_xor(a4, o)); }
;           if (tid == 0) { float* mp = (float*)(smem + LDS_BYTES - 48); mp[0] = a1 * a2 * 13.856406460551018f * LOG2E; mp[1] = a3 * a4 * 11.313708498984761f * LOG2E; } }
;         if (tid == 0) s_item[1] = 0;
	s_waitcnt lgkmcnt(0)
	v_max_f32_e32 v8, v8, v8
	v_max_f32_e32 v7, v7, v7
	v_max_f32_e32 v6, v6, v6
	v_max_f32_e32 v5, v5, v5
	v_max_f32_e32 v4, v4, v4
	v_max_f32_e32 v3, v3, v3
	v_max_f32_e32 v2, v2, v2
	v_max_f32_e32 v0, v0, v0
	v_max_f32_e32 v7, v7, v8
	v_max_f32_e32 v5, v5, v6
	v_max_f32_e32 v6, v3, v4
	v_max_f32_e32 v4, v0, v2
	s_mov_b32 s24, 0x415db3d7
	v_pk_mul_f32 v[2:3], v[4:5], v[6:7]
	s_mov_b32 s25, 0x413504f3
	v_pk_mul_f32 v[2:3], v[2:3], s[24:25]
	s_mov_b32 s4, 0x3fb8aa3b
	v_pk_mul_f32 v[2:3], v[2:3], s[4:5] op_sel_hi:[1,0]
	v_readlane_b32 s4, v254, 4
	s_nop 1
	v_mov_b32_e32 v0, s4
	v_readlane_b32 s4, v254, 5
	ds_write_b64 v0, v[2:3]
	s_nop 0
	v_mov_b32_e32 v0, s4
	ds_write_b32 v0, v1

.LBB0_207:
	v_add_u32_e32 v0, 0xfc0, v8
	v_mov_b64_e32 v[10:11], s[30:31]
	v_mad_u64_u32 v[10:11], s[0:1], v0, s3, v[10:11]
	s_lshl_b32 s4, s34, 1
	v_lshlrev_b64 v[38:39], 12, v[0:1]
	v_lshl_add_u64 v[10:11], v[10:11], 0, s[4:5]
	v_lshlrev_b32_e32 v0, 1, v6
	v_lshl_add_u64 v[6:7], v[10:11], 0, v[0:1]
	v_or_b32_e32 v10, 0x1000, v38
	v_mov_b32_e32 v11, v39
	v_lshl_add_u64 v[8:9], v[4:5], 0, v[38:39]
	v_lshl_add_u64 v[10:11], v[4:5], 0, v[10:11]
	global_load_dword v37, v[8:9], off
	global_load_dword v43, v[10:11], off
	global_load_dword v42, v[6:7], off offset:3072
	s_movk_i32 s0, 0x3000
	v_add_co_u32_e32 v10, vcc, s0, v6
	s_movk_i32 s0, 0x5000
	s_nop 0
	v_addc_co_u32_e32 v11, vcc, 0, v7, vcc
	global_load_dword v45, v[10:11], off offset:896
	v_or_b32_e32 v10, 0x2000, v38
	v_mov_b32_e32 v11, v39
	v_lshl_add_u64 v[10:11], v[4:5], 0, v[10:11]
	global_load_dword v35, v[10:11], off
	v_add_co_u32_e32 v10, vcc, s0, v6
	s_mov_b32 s4, 0x8000
	s_nop 0
	v_addc_co_u32_e32 v11, vcc, 0, v7, vcc
	global_load_dword v36, v[10:11], off offset:2816
	v_or_b32_e32 v10, 0x3000, v38
	v_mov_b32_e32 v11, v39
	v_lshl_add_u64 v[10:11], v[4:5], 0, v[10:11]
	global_load_dword v33, v[10:11], off
	v_add_co_u32_e32 v10, vcc, s4, v6
	s_mov_b32 s12, 0xa000
	s_nop 0
	v_addc_co_u32_e32 v11, vcc, 0, v7, vcc
	global_load_dword v34, v[10:11], off offset:640
	v_or_b32_e32 v10, 0x4000, v38
	v_mov_b32_e32 v11, v39
	v_lshl_add_u64 v[10:11], v[4:5], 0, v[10:11]
	global_load_dword v31, v[10:11], off
	v_add_co_u32_e32 v10, vcc, s12, v6
	s_mov_b32 s0, 0xd000
	s_nop 0
	v_addc_co_u32_e32 v11, vcc, 0, v7, vcc
	global_load_dword v32, v[10:11], off offset:2560
	v_or_b32_e32 v10, 0x5000, v38
	v_mov_b32_e32 v11, v39
	v_lshl_add_u64 v[10:11], v[4:5], 0, v[10:11]
	global_load_dword v29, v[10:11], off
	v_add_co_u32_e32 v10, vcc, s0, v6
	s_mov_b32 s0, 0xf000
	s_nop 0
	v_addc_co_u32_e32 v11, vcc, 0, v7, vcc
	global_load_dword v30, v[10:11], off offset:384
	v_or_b32_e32 v10, 0x6000, v38
	v_mov_b32_e32 v11, v39
	v_lshl_add_u64 v[10:11], v[4:5], 0, v[10:11]
	global_load_dword v27, v[10:11], off
	v_add_co_u32_e32 v10, vcc, s0, v6
	s_mov_b32 s0, 0x12000
	s_nop 0
	v_addc_co_u32_e32 v11, vcc, 0, v7, vcc
	global_load_dword v28, v[10:11], off offset:2304
	v_or_b32_e32 v10, 0x7000, v38
	v_mov_b32_e32 v11, v39
	v_lshl_add_u64 v[10:11], v[4:5], 0, v[10:11]
	global_load_dword v25, v[10:11], off
	v_add_co_u32_e32 v10, vcc, s0, v6
	s_mov_b32 s0, 0x14000
	s_nop 0
	v_addc_co_u32_e32 v11, vcc, 0, v7, vcc
	global_load_dword v26, v[10:11], off offset:128
	v_or_b32_e32 v10, 0x8000, v38
	v_mov_b32_e32 v11, v39
	v_lshl_add_u64 v[10:11], v[4:5], 0, v[10:11]
	global_load_dword v23, v[10:11], off
	v_add_co_u32_e32 v10, vcc, s0, v6
	s_mov_b32 s0, 0x16000
	s_nop 0
	v_addc_co_u32_e32 v11, vcc, 0, v7, vcc
	global_load_dword v24, v[10:11], off offset:2048
	v_or_b32_e32 v10, 0x9000, v38
	v_mov_b32_e32 v11, v39
	v_lshl_add_u64 v[10:11], v[4:5], 0, v[10:11]
	global_load_dword v21, v[10:11], off
	v_add_co_u32_e32 v10, vcc, s0, v6
	s_mov_b32 s0, 0x19000
	s_nop 0
	v_addc_co_u32_e32 v11, vcc, 0, v7, vcc
	global_load_dword v22, v[10:11], off offset:3968
	v_or_b32_e32 v10, 0xa000, v38
	v_mov_b32_e32 v11, v39
	v_lshl_add_u64 v[10:11], v[4:5], 0, v[10:11]
	global_load_dword v19, v[10:11], off
	v_add_co_u32_e32 v10, vcc, s0, v6
	s_mov_b32 s0, 0x1b000
	s_nop 0
	v_addc_co_u32_e32 v11, vcc, 0, v7, vcc
	global_load_dword v20, v[10:11], off offset:1792
	v_or_b32_e32 v10, 0xb000, v38
	v_mov_b32_e32 v11, v39
	v_lshl_add_u64 v[10:11], v[4:5], 0, v[10:11]
	global_load_dword v17, v[10:11], off
	v_add_co_u32_e32 v10, vcc, s0, v6
	s_mov_b32 s0, 0x1e000
	s_nop 0
	v_addc_co_u32_e32 v11, vcc, 0, v7, vcc
	global_load_dword v18, v[10:11], off offset:3712
	v_or_b32_e32 v10, 0xc000, v38
	v_mov_b32_e32 v11, v39
	v_lshl_add_u64 v[10:11], v[4:5], 0, v[10:11]
	global_load_dword v15, v[10:11], off
	v_add_co_u32_e32 v10, vcc, s0, v6
	s_mov_b32 s0, 0x20000
	s_nop 0
	v_addc_co_u32_e32 v11, vcc, 0, v7, vcc
	global_load_dword v16, v[10:11], off offset:1536
	v_or_b32_e32 v10, 0xd000, v38
	v_mov_b32_e32 v11, v39
	v_lshl_add_u64 v[10:11], v[4:5], 0, v[10:11]
	global_load_dword v13, v[10:11], off
	v_add_co_u32_e32 v10, vcc, s0, v6
	s_mov_b32 s0, 0x23000
	s_nop 0
	v_addc_co_u32_e32 v11, vcc, 0, v7, vcc
	global_load_dword v14, v[10:11], off offset:3456
	v_or_b32_e32 v10, 0xe000, v38
	v_mov_b32_e32 v11, v39
	v_add_co_u32_e32 v40, vcc, s0, v6
	v_or_b32_e32 v38, 0xf000, v38
	v_lshl_add_u64 v[10:11], v[4:5], 0, v[10:11]
	v_addc_co_u32_e32 v41, vcc, 0, v7, vcc
	v_lshl_add_u64 v[4:5], v[4:5], 0, v[38:39]
	s_mov_b32 s0, 0x25000
	global_load_dword v0, v[4:5], off
	v_add_co_u32_e32 v4, vcc, s0, v6
	global_load_dword v11, v[10:11], off
	s_nop 0
	v_addc_co_u32_e32 v5, vcc, 0, v7, vcc
	global_load_dword v10, v[4:5], off offset:3200
	s_waitcnt vmcnt(28)
	v_lshlrev_b32_e32 v4, 16, v42
	v_lshlrev_b32_e32 v6, 16, v37
	v_and_b32_e32 v7, 0xffff0000, v37
	v_mul_f32_e32 v37, 0xbfb8aa3b, v4
	v_exp_f32_e32 v37, v37
	v_and_b32_e32 v5, 0xffff0000, v42
	global_load_dword v12, v[40:41], off offset:1280
	v_lshlrev_b32_e32 v42, 16, v43
	v_add_f32_e32 v37, 1.0, v37
	v_rcp_f32_e32 v40, v37
	v_mul_f32_e32 v37, 0xbfb8aa3b, v5
	v_exp_f32_e32 v37, v37
	v_and_b32_e32 v43, 0xffff0000, v43
	v_pk_mul_f32 v[38:39], v[6:7], v[6:7]
	s_waitcnt vmcnt(28)
	v_lshlrev_b32_e32 v44, 16, v45
	v_add_f32_e32 v37, 1.0, v37
	v_rcp_f32_e32 v41, v37
	v_mov_b32_e32 v47, v38
	v_and_b32_e32 v45, 0xffff0000, v45
	v_pk_mul_f32 v[40:41], v[40:41], v[4:5]
	v_pk_mul_f32 v[4:5], v[42:43], v[42:43]
	s_nop 0
	v_mov_b32_e32 v46, v4
	v_mov_b32_e32 v38, v5
	v_pk_add_f32 v[4:5], v[46:47], v[38:39]
	v_mov_b32_e32 v39, v5
	v_mov_b32_e32 v38, v4
	s_nop 0
	v_permlane32_swap_b32_e32 v39, v5
	v_permlane32_swap_b32_e32 v38, v4
	s_waitcnt lgkmcnt(0)
	v_pk_add_f32 v[4:5], v[4:5], v[38:39]
	v_mov_b32_e32 v39, v5
	v_mov_b32_e32 v38, v4
	s_nop 0
	v_permlane16_swap_b32_e32 v39, v5
	v_permlane16_swap_b32_e32 v38, v4
	s_waitcnt lgkmcnt(0)
	v_pk_add_f32 v[4:5], v[4:5], v[38:39]
	s_nop 1
	v_mov_b32_dpp v39, v5 row_ror:8 row_mask:0xf bank_mask:0xf
	v_mov_b32_dpp v38, v4 row_ror:8 row_mask:0xf bank_mask:0xf
	s_waitcnt lgkmcnt(0)
	v_pk_add_f32 v[4:5], v[4:5], v[38:39]
	s_nop 1
	v_mov_b32_dpp v39, v5 row_shl:4 row_mask:0xf bank_mask:0x5
	v_mov_b32_dpp v39, v5 row_shr:4 row_mask:0xf bank_mask:0xa
	v_mov_b32_dpp v38, v4 row_shl:4 row_mask:0xf bank_mask:0x5
	v_mov_b32_dpp v38, v4 row_shr:4 row_mask:0xf bank_mask:0xa
	s_waitcnt lgkmcnt(0)
	v_pk_add_f32 v[4:5], v[4:5], v[38:39]
	s_nop 1
	v_mov_b32_dpp v39, v5 quad_perm:[2,3,0,1] row_mask:0xf bank_mask:0xf
	v_mov_b32_dpp v38, v4 quad_perm:[2,3,0,1] row_mask:0xf bank_mask:0xf
	s_waitcnt lgkmcnt(0)
	v_pk_add_f32 v[4:5], v[4:5], v[38:39]
	s_nop 1
	v_mov_b32_dpp v39, v5 quad_perm:[1,0,3,2] row_mask:0xf bank_mask:0xf
	v_mov_b32_dpp v38, v4 quad_perm:[1,0,3,2] row_mask:0xf bank_mask:0xf
	s_waitcnt lgkmcnt(0)
	v_pk_add_f32 v[38:39], v[4:5], v[38:39]
	v_mov_b64_e32 v[4:5], s[72:73]
	v_pk_fma_f32 v[38:39], v[38:39], s[96:97], v[4:5] op_sel_hi:[1,0,0]
	s_nop 0
	v_mul_f32_e32 v37, 0x4b800000, v39
	v_cmp_gt_f32_e64 s[0:1], s77, v39
	v_cmp_gt_f32_e32 vcc, s77, v38
	s_nop 0
	v_cndmask_b32_e64 v37, v39, v37, s[0:1]
	v_rsq_f32_e32 v37, v37
	s_nop 0
	v_mul_f32_e32 v39, 0x45800000, v37
	v_cndmask_b32_e64 v46, v37, v39, s[0:1]
	v_pk_mul_f32 v[6:7], v[46:47], v[6:7] op_sel_hi:[0,1]
	v_pk_mul_f32 v[6:7], v[2:3], v[6:7]
	v_mul_f32_e32 v37, 0xbfb8aa3b, v45
	v_pk_mul_f32 v[6:7], v[40:41], v[6:7]
	v_exp_f32_e32 v37, v37
	v_cvt_pk_bf16_f32 v6, v6, v7
	global_store_dword v[8:9], v6, off
	v_mul_f32_e32 v6, 0x4b800000, v38
	v_cndmask_b32_e32 v6, v38, v6, vcc
	v_rsq_f32_e32 v6, v6
	v_add_f32_e32 v37, 1.0, v37
	v_rcp_f32_e32 v39, v37
	s_waitcnt vmcnt(27)
	v_lshlrev_b32_e32 v40, 16, v36
	v_mul_f32_e32 v7, 0x45800000, v6
	v_cndmask_b32_e32 v6, v6, v7, vcc
	v_mul_f32_e32 v7, 0xbfb8aa3b, v44
	v_exp_f32_e32 v7, v7
	v_and_b32_e32 v41, 0xffff0000, v36
	s_movk_i32 s0, 0x2000
	v_add_f32_e32 v7, 1.0, v7
	v_rcp_f32_e32 v38, v7
	v_pk_mul_f32 v[6:7], v[6:7], v[42:43] op_sel_hi:[0,1]
	v_pk_mul_f32 v[6:7], v[2:3], v[6:7]
	v_pk_mul_f32 v[38:39], v[38:39], v[44:45]
	s_nop 0
	v_pk_mul_f32 v[6:7], v[38:39], v[6:7]
	v_lshlrev_b32_e32 v38, 16, v35
	v_and_b32_e32 v39, 0xffff0000, v35
	v_mul_f32_e32 v35, 0xbfb8aa3b, v40
	v_exp_f32_e32 v35, v35
	v_cvt_pk_bf16_f32 v37, v6, v7
	v_add_co_u32_e32 v6, vcc, s0, v8
	v_add_f32_e32 v35, 1.0, v35
	v_rcp_f32_e32 v42, v35
	v_mul_f32_e32 v35, 0xbfb8aa3b, v41
	v_exp_f32_e32 v35, v35
	v_addc_co_u32_e32 v7, vcc, 0, v9, vcc
	global_store_dword v[6:7], v37, off offset:-4096
	v_add_f32_e32 v35, 1.0, v35
	v_rcp_f32_e32 v43, v35
	v_pk_mul_f32 v[36:37], v[38:39], v[38:39]
	s_waitcnt vmcnt(26)
	v_lshlrev_b32_e32 v44, 16, v34
	v_and_b32_e32 v45, 0xffff0000, v34
	v_pk_mul_f32 v[40:41], v[42:43], v[40:41]
	v_lshlrev_b32_e32 v42, 16, v33
	v_and_b32_e32 v43, 0xffff0000, v33
	v_pk_mul_f32 v[34:35], v[42:43], v[42:43]
	v_mov_b32_e32 v47, v36
	v_mov_b32_e32 v46, v34
	v_mov_b32_e32 v36, v35
	v_pk_add_f32 v[34:35], v[46:47], v[36:37]
	v_mov_b32_e32 v37, v35
	v_mov_b32_e32 v36, v34
	s_nop 0
	v_permlane32_swap_b32_e32 v37, v35
	v_permlane32_swap_b32_e32 v36, v34
	s_waitcnt lgkmcnt(0)
	v_pk_add_f32 v[34:35], v[34:35], v[36:37]
	v_mov_b32_e32 v37, v35
	v_mov_b32_e32 v36, v34
	s_nop 0
	v_permlane16_swap_b32_e32 v37, v35
	v_permlane16_swap_b32_e32 v36, v34
	s_waitcnt lgkmcnt(0)
	v_pk_add_f32 v[34:35], v[34:35], v[36:37]
	s_nop 1
	v_mov_b32_dpp v37, v35 row_ror:8 row_mask:0xf bank_mask:0xf
	v_mov_b32_dpp v36, v34 row_ror:8 row_mask:0xf bank_mask:0xf
	s_waitcnt lgkmcnt(0)
	v_pk_add_f32 v[34:35], v[34:35], v[36:37]
	s_nop 1
	v_mov_b32_dpp v37, v35 row_shl:4 row_mask:0xf bank_mask:0x5
	v_mov_b32_dpp v37, v35 row_shr:4 row_mask:0xf bank_mask:0xa
	v_mov_b32_dpp v36, v34 row_shl:4 row_mask:0xf bank_mask:0x5
	v_mov_b32_dpp v36, v34 row_shr:4 row_mask:0xf bank_mask:0xa
	s_waitcnt lgkmcnt(0)
	v_pk_add_f32 v[34:35], v[34:35], v[36:37]
	s_nop 1
	v_mov_b32_dpp v37, v35 quad_perm:[2,3,0,1] row_mask:0xf bank_mask:0xf
	v_mov_b32_dpp v36, v34 quad_perm:[2,3,0,1] row_mask:0xf bank_mask:0xf
	s_waitcnt lgkmcnt(0)
	v_pk_add_f32 v[34:35], v[34:35], v[36:37]
	s_nop 1
	v_mov_b32_dpp v37, v35 quad_perm:[1,0,3,2] row_mask:0xf bank_mask:0xf
	v_mov_b32_dpp v36, v34 quad_perm:[1,0,3,2] row_mask:0xf bank_mask:0xf
	s_waitcnt lgkmcnt(0)
	v_pk_add_f32 v[34:35], v[34:35], v[36:37]
	s_nop 0
	v_pk_fma_f32 v[34:35], v[34:35], s[96:97], v[4:5] op_sel_hi:[1,0,0]
	s_nop 0
	v_mul_f32_e32 v33, 0x4b800000, v35
	v_cmp_gt_f32_e64 s[0:1], s77, v35
	v_cmp_gt_f32_e32 vcc, s77, v34
	s_nop 0
	v_cndmask_b32_e64 v33, v35, v33, s[0:1]
	v_rsq_f32_e32 v33, v33
	s_nop 0
	v_mul_f32_e32 v35, 0x45800000, v33
	v_cndmask_b32_e64 v36, v33, v35, s[0:1]
	v_pk_mul_f32 v[36:37], v[36:37], v[38:39] op_sel_hi:[0,1]
	v_pk_mul_f32 v[36:37], v[2:3], v[36:37]
	s_nop 0
	v_pk_mul_f32 v[36:37], v[40:41], v[36:37]
	s_waitcnt vmcnt(22)
	v_lshlrev_b32_e32 v40, 16, v30
	v_cvt_pk_bf16_f32 v33, v36, v37
	global_store_dword v[6:7], v33, off
	v_mul_f32_e32 v6, 0x4b800000, v34
	v_cndmask_b32_e32 v6, v34, v6, vcc
	v_rsq_f32_e32 v6, v6
	v_mul_f32_e32 v33, 0xbfb8aa3b, v45
	v_exp_f32_e32 v33, v33
	v_lshlrev_b32_e32 v36, 16, v32
	v_mul_f32_e32 v7, 0x45800000, v6
	v_cndmask_b32_e32 v6, v6, v7, vcc
	v_mul_f32_e32 v7, 0xbfb8aa3b, v44
	v_exp_f32_e32 v7, v7
	v_add_f32_e32 v33, 1.0, v33
	v_rcp_f32_e32 v35, v33
	v_and_b32_e32 v37, 0xffff0000, v32
	v_add_f32_e32 v7, 1.0, v7
	v_rcp_f32_e32 v34, v7
	v_pk_mul_f32 v[6:7], v[6:7], v[42:43] op_sel_hi:[0,1]
	v_pk_mul_f32 v[6:7], v[2:3], v[6:7]
	v_and_b32_e32 v41, 0xffff0000, v30
	v_pk_mul_f32 v[34:35], v[34:35], v[44:45]
	s_nop 0
	v_pk_mul_f32 v[6:7], v[34:35], v[6:7]
	v_lshlrev_b32_e32 v34, 16, v31
	v_and_b32_e32 v35, 0xffff0000, v31
	v_mul_f32_e32 v31, 0xbfb8aa3b, v36
	v_exp_f32_e32 v31, v31
	v_cvt_pk_bf16_f32 v33, v6, v7
	v_add_co_u32_e32 v6, vcc, s76, v8
	v_add_f32_e32 v31, 1.0, v31
	v_rcp_f32_e32 v38, v31
	v_mul_f32_e32 v31, 0xbfb8aa3b, v37
	v_exp_f32_e32 v31, v31
	v_addc_co_u32_e32 v7, vcc, 0, v9, vcc
	global_store_dword v[6:7], v33, off offset:-4096
	v_add_f32_e32 v31, 1.0, v31
	v_rcp_f32_e32 v39, v31
	v_pk_mul_f32 v[32:33], v[34:35], v[34:35]
	v_pk_mul_f32 v[36:37], v[38:39], v[36:37]
	v_lshlrev_b32_e32 v38, 16, v29
	v_and_b32_e32 v39, 0xffff0000, v29
	v_pk_mul_f32 v[30:31], v[38:39], v[38:39]
	v_mov_b32_e32 v43, v32
	v_mov_b32_e32 v42, v30
	v_mov_b32_e32 v32, v31
	v_pk_add_f32 v[30:31], v[42:43], v[32:33]
	v_mov_b32_e32 v33, v31
	v_mov_b32_e32 v32, v30
	s_nop 0
	v_permlane32_swap_b32_e32 v33, v31
	v_permlane32_swap_b32_e32 v32, v30
	s_waitcnt lgkmcnt(0)
	v_pk_add_f32 v[30:31], v[30:31], v[32:33]
	v_mov_b32_e32 v33, v31
	v_mov_b32_e32 v32, v30
	s_nop 0
	v_permlane16_swap_b32_e32 v33, v31
	v_permlane16_swap_b32_e32 v32, v30
	s_waitcnt lgkmcnt(0)
	v_pk_add_f32 v[30:31], v[30:31], v[32:33]
	s_nop 1
	v_mov_b32_dpp v33, v31 row_ror:8 row_mask:0xf bank_mask:0xf
	v_mov_b32_dpp v32, v30 row_ror:8 row_mask:0xf bank_mask:0xf
	s_waitcnt lgkmcnt(0)
	v_pk_add_f32 v[30:31], v[30:31], v[32:33]
	s_nop 1
	v_mov_b32_dpp v33, v31 row_shl:4 row_mask:0xf bank_mask:0x5
	v_mov_b32_dpp v33, v31 row_shr:4 row_mask:0xf bank_mask:0xa
	v_mov_b32_dpp v32, v30 row_shl:4 row_mask:0xf bank_mask:0x5
	v_mov_b32_dpp v32, v30 row_shr:4 row_mask:0xf bank_mask:0xa
	s_waitcnt lgkmcnt(0)
	v_pk_add_f32 v[30:31], v[30:31], v[32:33]
	s_nop 1
	v_mov_b32_dpp v33, v31 quad_perm:[2,3,0,1] row_mask:0xf bank_mask:0xf
	v_mov_b32_dpp v32, v30 quad_perm:[2,3,0,1] row_mask:0xf bank_mask:0xf
	s_waitcnt lgkmcnt(0)
	v_pk_add_f32 v[30:31], v[30:31], v[32:33]
	s_nop 1
	v_mov_b32_dpp v33, v31 quad_perm:[1,0,3,2] row_mask:0xf bank_mask:0xf
	v_mov_b32_dpp v32, v30 quad_perm:[1,0,3,2] row_mask:0xf bank_mask:0xf
	s_waitcnt lgkmcnt(0)
	v_pk_add_f32 v[30:31], v[30:31], v[32:33]
	s_nop 0
	v_pk_fma_f32 v[30:31], v[30:31], s[96:97], v[4:5] op_sel_hi:[1,0,0]
	s_nop 0
	v_mul_f32_e32 v29, 0x4b800000, v31
	v_cmp_gt_f32_e64 s[0:1], s77, v31
	v_cmp_gt_f32_e32 vcc, s77, v30
	s_nop 0
	v_cndmask_b32_e64 v29, v31, v29, s[0:1]
	v_rsq_f32_e32 v29, v29
	s_nop 0
	v_mul_f32_e32 v31, 0x45800000, v29
	v_cndmask_b32_e64 v32, v29, v31, s[0:1]
	v_pk_mul_f32 v[32:33], v[32:33], v[34:35] op_sel_hi:[0,1]
	v_pk_mul_f32 v[32:33], v[2:3], v[32:33]
	s_movk_i32 s0, 0x6000
	v_pk_mul_f32 v[32:33], v[36:37], v[32:33]
	s_waitcnt vmcnt(20)
	v_lshlrev_b32_e32 v36, 16, v26
	v_cvt_pk_bf16_f32 v29, v32, v33
	global_store_dword v[6:7], v29, off
	v_mul_f32_e32 v6, 0x4b800000, v30
	v_cndmask_b32_e32 v6, v30, v6, vcc
	v_rsq_f32_e32 v6, v6
	v_mul_f32_e32 v29, 0xbfb8aa3b, v41
	v_exp_f32_e32 v29, v29
	v_lshlrev_b32_e32 v32, 16, v28
	v_mul_f32_e32 v7, 0x45800000, v6
	v_cndmask_b32_e32 v6, v6, v7, vcc
	v_mul_f32_e32 v7, 0xbfb8aa3b, v40
	v_exp_f32_e32 v7, v7
	v_add_f32_e32 v29, 1.0, v29
	v_rcp_f32_e32 v31, v29
	v_and_b32_e32 v33, 0xffff0000, v28
	v_add_f32_e32 v7, 1.0, v7
	v_rcp_f32_e32 v30, v7
	v_pk_mul_f32 v[6:7], v[6:7], v[38:39] op_sel_hi:[0,1]
	v_pk_mul_f32 v[6:7], v[2:3], v[6:7]
	v_and_b32_e32 v37, 0xffff0000, v26
	v_pk_mul_f32 v[30:31], v[30:31], v[40:41]
	s_nop 0
	v_pk_mul_f32 v[6:7], v[30:31], v[6:7]
	v_lshlrev_b32_e32 v30, 16, v27
	v_and_b32_e32 v31, 0xffff0000, v27
	v_mul_f32_e32 v27, 0xbfb8aa3b, v32
	v_exp_f32_e32 v27, v27
	v_cvt_pk_bf16_f32 v29, v6, v7
	v_add_co_u32_e32 v6, vcc, s0, v8
	v_add_f32_e32 v27, 1.0, v27
	v_rcp_f32_e32 v34, v27
	v_mul_f32_e32 v27, 0xbfb8aa3b, v33
	v_exp_f32_e32 v27, v27
	v_addc_co_u32_e32 v7, vcc, 0, v9, vcc
	global_store_dword v[6:7], v29, off offset:-4096
	v_add_f32_e32 v27, 1.0, v27
	v_rcp_f32_e32 v35, v27
	v_pk_mul_f32 v[28:29], v[30:31], v[30:31]
	v_pk_mul_f32 v[32:33], v[34:35], v[32:33]
	v_lshlrev_b32_e32 v34, 16, v25
	v_and_b32_e32 v35, 0xffff0000, v25
	v_pk_mul_f32 v[26:27], v[34:35], v[34:35]
	v_mov_b32_e32 v39, v28
	v_mov_b32_e32 v38, v26
	v_mov_b32_e32 v28, v27
	v_pk_add_f32 v[26:27], v[38:39], v[28:29]
	v_mov_b32_e32 v29, v27
	v_mov_b32_e32 v28, v26
	s_nop 0
	v_permlane32_swap_b32_e32 v29, v27
	v_permlane32_swap_b32_e32 v28, v26
	s_waitcnt lgkmcnt(0)
	v_pk_add_f32 v[26:27], v[26:27], v[28:29]
	v_mov_b32_e32 v29, v27
	v_mov_b32_e32 v28, v26
	s_nop 0
	v_permlane16_swap_b32_e32 v29, v27
	v_permlane16_swap_b32_e32 v28, v26
	s_waitcnt lgkmcnt(0)
	v_pk_add_f32 v[26:27], v[26:27], v[28:29]
	s_nop 1
	v_mov_b32_dpp v29, v27 row_ror:8 row_mask:0xf bank_mask:0xf
	v_mov_b32_dpp v28, v26 row_ror:8 row_mask:0xf bank_mask:0xf
	s_waitcnt lgkmcnt(0)
	v_pk_add_f32 v[26:27], v[26:27], v[28:29]
	s_nop 1
	v_mov_b32_dpp v29, v27 row_shl:4 row_mask:0xf bank_mask:0x5
	v_mov_b32_dpp v29, v27 row_shr:4 row_mask:0xf bank_mask:0xa
	v_mov_b32_dpp v28, v26 row_shl:4 row_mask:0xf bank_mask:0x5
	v_mov_b32_dpp v28, v26 row_shr:4 row_mask:0xf bank_mask:0xa
	s_waitcnt lgkmcnt(0)
	v_pk_add_f32 v[26:27], v[26:27], v[28:29]
	s_nop 1
	v_mov_b32_dpp v29, v27 quad_perm:[2,3,0,1] row_mask:0xf bank_mask:0xf
	v_mov_b32_dpp v28, v26 quad_perm:[2,3,0,1] row_mask:0xf bank_mask:0xf
	s_waitcnt lgkmcnt(0)
	v_pk_add_f32 v[26:27], v[26:27], v[28:29]
	s_nop 1
	v_mov_b32_dpp v29, v27 quad_perm:[1,0,3,2] row_mask:0xf bank_mask:0xf
	v_mov_b32_dpp v28, v26 quad_perm:[1,0,3,2] row_mask:0xf bank_mask:0xf
	s_waitcnt lgkmcnt(0)
	v_pk_add_f32 v[26:27], v[26:27], v[28:29]
	s_nop 0
	v_pk_fma_f32 v[26:27], v[26:27], s[96:97], v[4:5] op_sel_hi:[1,0,0]
	s_nop 0
	v_mul_f32_e32 v25, 0x4b800000, v27
	v_cmp_gt_f32_e64 s[0:1], s77, v27
	v_cmp_gt_f32_e32 vcc, s77, v26
	s_nop 0
	v_cndmask_b32_e64 v25, v27, v25, s[0:1]
	v_rsq_f32_e32 v25, v25
	s_nop 0
	v_mul_f32_e32 v27, 0x45800000, v25
	v_cndmask_b32_e64 v28, v25, v27, s[0:1]
	v_pk_mul_f32 v[28:29], v[28:29], v[30:31] op_sel_hi:[0,1]
	v_pk_mul_f32 v[28:29], v[2:3], v[28:29]
	s_nop 0
	v_pk_mul_f32 v[28:29], v[32:33], v[28:29]
	s_waitcnt vmcnt(18)
	v_lshlrev_b32_e32 v32, 16, v22
	v_cvt_pk_bf16_f32 v25, v28, v29
	global_store_dword v[6:7], v25, off
	v_mul_f32_e32 v6, 0x4b800000, v26
	v_cndmask_b32_e32 v6, v26, v6, vcc
	v_rsq_f32_e32 v6, v6
	v_mul_f32_e32 v25, 0xbfb8aa3b, v37
	v_exp_f32_e32 v25, v25
	v_lshlrev_b32_e32 v28, 16, v24
	v_mul_f32_e32 v7, 0x45800000, v6
	v_cndmask_b32_e32 v6, v6, v7, vcc
	v_mul_f32_e32 v7, 0xbfb8aa3b, v36
	v_exp_f32_e32 v7, v7
	v_add_f32_e32 v25, 1.0, v25
	v_rcp_f32_e32 v27, v25
	v_and_b32_e32 v29, 0xffff0000, v24
	v_add_f32_e32 v7, 1.0, v7
	v_rcp_f32_e32 v26, v7
	v_pk_mul_f32 v[6:7], v[6:7], v[34:35] op_sel_hi:[0,1]
	v_pk_mul_f32 v[6:7], v[2:3], v[6:7]
	v_and_b32_e32 v33, 0xffff0000, v22
	v_pk_mul_f32 v[26:27], v[26:27], v[36:37]
	s_nop 0
	v_pk_mul_f32 v[6:7], v[26:27], v[6:7]
	v_lshlrev_b32_e32 v26, 16, v23
	v_and_b32_e32 v27, 0xffff0000, v23
	v_mul_f32_e32 v23, 0xbfb8aa3b, v28
	v_exp_f32_e32 v23, v23
	v_cvt_pk_bf16_f32 v25, v6, v7
	v_add_co_u32_e32 v6, vcc, s4, v8
	v_add_f32_e32 v23, 1.0, v23
	v_rcp_f32_e32 v30, v23
	v_mul_f32_e32 v23, 0xbfb8aa3b, v29
	v_exp_f32_e32 v23, v23
	v_addc_co_u32_e32 v7, vcc, 0, v9, vcc
	global_store_dword v[6:7], v25, off offset:-4096
	v_add_f32_e32 v23, 1.0, v23
	v_rcp_f32_e32 v31, v23
	v_pk_mul_f32 v[24:25], v[26:27], v[26:27]
	v_pk_mul_f32 v[28:29], v[30:31], v[28:29]
	v_lshlrev_b32_e32 v30, 16, v21
	v_and_b32_e32 v31, 0xffff0000, v21
	v_pk_mul_f32 v[22:23], v[30:31], v[30:31]
	v_mov_b32_e32 v35, v24
	v_mov_b32_e32 v34, v22
	v_mov_b32_e32 v24, v23
	v_pk_add_f32 v[22:23], v[34:35], v[24:25]
	v_mov_b32_e32 v25, v23
	v_mov_b32_e32 v24, v22
	s_nop 0
	v_permlane32_swap_b32_e32 v25, v23
	v_permlane32_swap_b32_e32 v24, v22
	s_waitcnt lgkmcnt(0)
	v_pk_add_f32 v[22:23], v[22:23], v[24:25]
	v_mov_b32_e32 v25, v23
	v_mov_b32_e32 v24, v22
	s_nop 0
	v_permlane16_swap_b32_e32 v25, v23
	v_permlane16_swap_b32_e32 v24, v22
	s_waitcnt lgkmcnt(0)
	v_pk_add_f32 v[22:23], v[22:23], v[24:25]
	s_nop 1
	v_mov_b32_dpp v25, v23 row_ror:8 row_mask:0xf bank_mask:0xf
	v_mov_b32_dpp v24, v22 row_ror:8 row_mask:0xf bank_mask:0xf
	s_waitcnt lgkmcnt(0)
	v_pk_add_f32 v[22:23], v[22:23], v[24:25]
	s_nop 1
	v_mov_b32_dpp v25, v23 row_shl:4 row_mask:0xf bank_mask:0x5
	v_mov_b32_dpp v25, v23 row_shr:4 row_mask:0xf bank_mask:0xa
	v_mov_b32_dpp v24, v22 row_shl:4 row_mask:0xf bank_mask:0x5
	v_mov_b32_dpp v24, v22 row_shr:4 row_mask:0xf bank_mask:0xa
	s_waitcnt lgkmcnt(0)
	v_pk_add_f32 v[22:23], v[22:23], v[24:25]
	s_nop 1
	v_mov_b32_dpp v25, v23 quad_perm:[2,3,0,1] row_mask:0xf bank_mask:0xf
	v_mov_b32_dpp v24, v22 quad_perm:[2,3,0,1] row_mask:0xf bank_mask:0xf
	s_waitcnt lgkmcnt(0)
	v_pk_add_f32 v[22:23], v[22:23], v[24:25]
	s_nop 1
	v_mov_b32_dpp v25, v23 quad_perm:[1,0,3,2] row_mask:0xf bank_mask:0xf
	v_mov_b32_dpp v24, v22 quad_perm:[1,0,3,2] row_mask:0xf bank_mask:0xf
	s_waitcnt lgkmcnt(0)
	v_pk_add_f32 v[22:23], v[22:23], v[24:25]
	s_nop 0
	v_pk_fma_f32 v[22:23], v[22:23], s[96:97], v[4:5] op_sel_hi:[1,0,0]
	s_nop 0
	v_mul_f32_e32 v21, 0x4b800000, v23
	v_cmp_gt_f32_e64 s[0:1], s77, v23
	v_cmp_gt_f32_e32 vcc, s77, v22
	s_nop 0
	v_cndmask_b32_e64 v21, v23, v21, s[0:1]
	v_rsq_f32_e32 v21, v21
	s_nop 0
	v_mul_f32_e32 v23, 0x45800000, v21
	v_cndmask_b32_e64 v24, v21, v23, s[0:1]
	v_pk_mul_f32 v[24:25], v[24:25], v[26:27] op_sel_hi:[0,1]
	v_pk_mul_f32 v[24:25], v[2:3], v[24:25]
	s_nop 0
	v_pk_mul_f32 v[24:25], v[28:29], v[24:25]
	s_waitcnt vmcnt(16)
	v_lshlrev_b32_e32 v28, 16, v18
	v_cvt_pk_bf16_f32 v21, v24, v25
	global_store_dword v[6:7], v21, off
	v_mul_f32_e32 v6, 0x4b800000, v22
	v_cndmask_b32_e32 v6, v22, v6, vcc
	v_rsq_f32_e32 v6, v6
	v_mul_f32_e32 v21, 0xbfb8aa3b, v33
	v_exp_f32_e32 v21, v21
	v_lshlrev_b32_e32 v24, 16, v20
	v_mul_f32_e32 v7, 0x45800000, v6
	v_cndmask_b32_e32 v6, v6, v7, vcc
	v_mul_f32_e32 v7, 0xbfb8aa3b, v32
	v_exp_f32_e32 v7, v7
	v_add_f32_e32 v21, 1.0, v21
	v_rcp_f32_e32 v23, v21
	v_and_b32_e32 v25, 0xffff0000, v20
	v_add_f32_e32 v7, 1.0, v7
	v_rcp_f32_e32 v22, v7
	v_pk_mul_f32 v[6:7], v[6:7], v[30:31] op_sel_hi:[0,1]
	v_pk_mul_f32 v[6:7], v[2:3], v[6:7]
	v_and_b32_e32 v29, 0xffff0000, v18
	v_pk_mul_f32 v[22:23], v[22:23], v[32:33]
	s_nop 0
	v_pk_mul_f32 v[6:7], v[22:23], v[6:7]
	v_lshlrev_b32_e32 v22, 16, v19
	v_and_b32_e32 v23, 0xffff0000, v19
	v_mul_f32_e32 v19, 0xbfb8aa3b, v24
	v_exp_f32_e32 v19, v19
	v_cvt_pk_bf16_f32 v21, v6, v7
	v_add_co_u32_e32 v6, vcc, s12, v8
	v_add_f32_e32 v19, 1.0, v19
	v_rcp_f32_e32 v26, v19
	v_mul_f32_e32 v19, 0xbfb8aa3b, v25
	v_exp_f32_e32 v19, v19
	v_addc_co_u32_e32 v7, vcc, 0, v9, vcc
	global_store_dword v[6:7], v21, off offset:-4096
	v_add_f32_e32 v19, 1.0, v19
	v_rcp_f32_e32 v27, v19
	v_pk_mul_f32 v[20:21], v[22:23], v[22:23]
	v_pk_mul_f32 v[24:25], v[26:27], v[24:25]
	v_lshlrev_b32_e32 v26, 16, v17
	v_and_b32_e32 v27, 0xffff0000, v17
	v_pk_mul_f32 v[18:19], v[26:27], v[26:27]
	v_mov_b32_e32 v31, v20
	v_mov_b32_e32 v30, v18
	v_mov_b32_e32 v20, v19
	v_pk_add_f32 v[18:19], v[30:31], v[20:21]
	v_mov_b32_e32 v21, v19
	v_mov_b32_e32 v20, v18
	s_nop 0
	v_permlane32_swap_b32_e32 v21, v19
	v_permlane32_swap_b32_e32 v20, v18
	s_waitcnt lgkmcnt(0)
	v_pk_add_f32 v[18:19], v[18:19], v[20:21]
	v_mov_b32_e32 v21, v19
	v_mov_b32_e32 v20, v18
	s_nop 0
	v_permlane16_swap_b32_e32 v21, v19
	v_permlane16_swap_b32_e32 v20, v18
	s_waitcnt lgkmcnt(0)
	v_pk_add_f32 v[18:19], v[18:19], v[20:21]
	s_nop 1
	v_mov_b32_dpp v21, v19 row_ror:8 row_mask:0xf bank_mask:0xf
	v_mov_b32_dpp v20, v18 row_ror:8 row_mask:0xf bank_mask:0xf
	s_waitcnt lgkmcnt(0)
	v_pk_add_f32 v[18:19], v[18:19], v[20:21]
	s_nop 1
	v_mov_b32_dpp v21, v19 row_shl:4 row_mask:0xf bank_mask:0x5
	v_mov_b32_dpp v21, v19 row_shr:4 row_mask:0xf bank_mask:0xa
	v_mov_b32_dpp v20, v18 row_shl:4 row_mask:0xf bank_mask:0x5
	v_mov_b32_dpp v20, v18 row_shr:4 row_mask:0xf bank_mask:0xa
	s_waitcnt lgkmcnt(0)
	v_pk_add_f32 v[18:19], v[18:19], v[20:21]
	s_nop 1
	v_mov_b32_dpp v21, v19 quad_perm:[2,3,0,1] row_mask:0xf bank_mask:0xf
	v_mov_b32_dpp v20, v18 quad_perm:[2,3,0,1] row_mask:0xf bank_mask:0xf
	s_waitcnt lgkmcnt(0)
	v_pk_add_f32 v[18:19], v[18:19], v[20:21]
	s_nop 1
	v_mov_b32_dpp v21, v19 quad_perm:[1,0,3,2] row_mask:0xf bank_mask:0xf
	v_mov_b32_dpp v20, v18 quad_perm:[1,0,3,2] row_mask:0xf bank_mask:0xf
	s_waitcnt lgkmcnt(0)
	v_pk_add_f32 v[18:19], v[18:19], v[20:21]
	s_nop 0
	v_pk_fma_f32 v[18:19], v[18:19], s[96:97], v[4:5] op_sel_hi:[1,0,0]
	s_nop 0
	v_mul_f32_e32 v17, 0x4b800000, v19
	v_cmp_gt_f32_e64 s[0:1], s77, v19
	v_cmp_gt_f32_e32 vcc, s77, v18
	s_nop 0
	v_cndmask_b32_e64 v17, v19, v17, s[0:1]
	v_rsq_f32_e32 v17, v17
	s_nop 0
	v_mul_f32_e32 v19, 0x45800000, v17
	v_cndmask_b32_e64 v20, v17, v19, s[0:1]
	v_pk_mul_f32 v[20:21], v[20:21], v[22:23] op_sel_hi:[0,1]
	v_pk_mul_f32 v[20:21], v[2:3], v[20:21]
	s_mov_b32 s0, 0xc000
	v_pk_mul_f32 v[20:21], v[24:25], v[20:21]
	s_waitcnt vmcnt(14)
	v_lshlrev_b32_e32 v24, 16, v14
	v_cvt_pk_bf16_f32 v17, v20, v21
	global_store_dword v[6:7], v17, off
	v_mul_f32_e32 v6, 0x4b800000, v18
	v_cndmask_b32_e32 v6, v18, v6, vcc
	v_rsq_f32_e32 v6, v6
	v_mul_f32_e32 v17, 0xbfb8aa3b, v29
	v_exp_f32_e32 v17, v17
	v_lshlrev_b32_e32 v20, 16, v16
	v_mul_f32_e32 v7, 0x45800000, v6
	v_cndmask_b32_e32 v6, v6, v7, vcc
	v_mul_f32_e32 v7, 0xbfb8aa3b, v28
	v_exp_f32_e32 v7, v7
	v_add_f32_e32 v17, 1.0, v17
	v_rcp_f32_e32 v19, v17
	v_and_b32_e32 v21, 0xffff0000, v16
	v_add_f32_e32 v7, 1.0, v7
	v_rcp_f32_e32 v18, v7
	v_pk_mul_f32 v[6:7], v[6:7], v[26:27] op_sel_hi:[0,1]
	v_pk_mul_f32 v[6:7], v[2:3], v[6:7]
	v_and_b32_e32 v25, 0xffff0000, v14
	v_pk_mul_f32 v[18:19], v[18:19], v[28:29]
	s_nop 0
	v_pk_mul_f32 v[6:7], v[18:19], v[6:7]
	v_lshlrev_b32_e32 v18, 16, v15
	v_and_b32_e32 v19, 0xffff0000, v15
	v_mul_f32_e32 v15, 0xbfb8aa3b, v20
	v_exp_f32_e32 v15, v15
	v_cvt_pk_bf16_f32 v17, v6, v7
	v_add_co_u32_e32 v6, vcc, s0, v8
	v_add_f32_e32 v15, 1.0, v15
	v_rcp_f32_e32 v22, v15
	v_mul_f32_e32 v15, 0xbfb8aa3b, v21
	v_exp_f32_e32 v15, v15
	v_addc_co_u32_e32 v7, vcc, 0, v9, vcc
	global_store_dword v[6:7], v17, off offset:-4096
	v_add_f32_e32 v15, 1.0, v15
	v_rcp_f32_e32 v23, v15
	v_pk_mul_f32 v[16:17], v[18:19], v[18:19]
	v_pk_mul_f32 v[20:21], v[22:23], v[20:21]
	v_lshlrev_b32_e32 v22, 16, v13
	v_and_b32_e32 v23, 0xffff0000, v13
	v_pk_mul_f32 v[14:15], v[22:23], v[22:23]
	v_mov_b32_e32 v27, v16
	v_mov_b32_e32 v26, v14
	v_mov_b32_e32 v16, v15
	v_pk_add_f32 v[14:15], v[26:27], v[16:17]
	v_mov_b32_e32 v17, v15
	v_mov_b32_e32 v16, v14
	s_nop 0
	v_permlane32_swap_b32_e32 v17, v15
	v_permlane32_swap_b32_e32 v16, v14
	s_waitcnt lgkmcnt(0)
	v_pk_add_f32 v[14:15], v[14:15], v[16:17]
	v_mov_b32_e32 v17, v15
	v_mov_b32_e32 v16, v14
	s_nop 0
	v_permlane16_swap_b32_e32 v17, v15
	v_permlane16_swap_b32_e32 v16, v14
	s_waitcnt lgkmcnt(0)
	v_pk_add_f32 v[14:15], v[14:15], v[16:17]
	s_nop 1
	v_mov_b32_dpp v17, v15 row_ror:8 row_mask:0xf bank_mask:0xf
	v_mov_b32_dpp v16, v14 row_ror:8 row_mask:0xf bank_mask:0xf
	s_waitcnt lgkmcnt(0)
	v_pk_add_f32 v[14:15], v[14:15], v[16:17]
	s_nop 1
	v_mov_b32_dpp v17, v15 row_shl:4 row_mask:0xf bank_mask:0x5
	v_mov_b32_dpp v17, v15 row_shr:4 row_mask:0xf bank_mask:0xa
	v_mov_b32_dpp v16, v14 row_shl:4 row_mask:0xf bank_mask:0x5
	v_mov_b32_dpp v16, v14 row_shr:4 row_mask:0xf bank_mask:0xa
	s_waitcnt lgkmcnt(0)
	v_pk_add_f32 v[14:15], v[14:15], v[16:17]
	s_nop 1
	v_mov_b32_dpp v17, v15 quad_perm:[2,3,0,1] row_mask:0xf bank_mask:0xf
	v_mov_b32_dpp v16, v14 quad_perm:[2,3,0,1] row_mask:0xf bank_mask:0xf
	s_waitcnt lgkmcnt(0)
	v_pk_add_f32 v[14:15], v[14:15], v[16:17]
	s_nop 1
	v_mov_b32_dpp v17, v15 quad_perm:[1,0,3,2] row_mask:0xf bank_mask:0xf
	v_mov_b32_dpp v16, v14 quad_perm:[1,0,3,2] row_mask:0xf bank_mask:0xf
	s_waitcnt lgkmcnt(0)
	v_pk_add_f32 v[14:15], v[14:15], v[16:17]
	s_nop 0
	v_pk_fma_f32 v[14:15], v[14:15], s[96:97], v[4:5] op_sel_hi:[1,0,0]
	s_nop 0
	v_mul_f32_e32 v13, 0x4b800000, v15
	v_cmp_gt_f32_e64 s[0:1], s77, v15
	v_cmp_gt_f32_e32 vcc, s77, v14
	s_nop 0
	v_cndmask_b32_e64 v13, v15, v13, s[0:1]
	v_rsq_f32_e32 v13, v13
	s_nop 0
	v_mul_f32_e32 v15, 0x45800000, v13
	v_cndmask_b32_e64 v16, v13, v15, s[0:1]
	v_pk_mul_f32 v[16:17], v[16:17], v[18:19] op_sel_hi:[0,1]
	v_pk_mul_f32 v[16:17], v[2:3], v[16:17]
	s_mov_b32 s0, 0xe000
	v_pk_mul_f32 v[16:17], v[20:21], v[16:17]
	s_waitcnt vmcnt(13)
	v_lshlrev_b32_e32 v20, 16, v10
	v_cvt_pk_bf16_f32 v13, v16, v17
	global_store_dword v[6:7], v13, off
	v_mul_f32_e32 v6, 0x4b800000, v14
	v_cndmask_b32_e32 v6, v14, v6, vcc
	v_rsq_f32_e32 v6, v6
	v_mul_f32_e32 v13, 0xbfb8aa3b, v25
	v_exp_f32_e32 v13, v13
	s_waitcnt vmcnt(13)
	v_lshlrev_b32_e32 v16, 16, v12
	v_mul_f32_e32 v7, 0x45800000, v6
	v_cndmask_b32_e32 v6, v6, v7, vcc
	v_mul_f32_e32 v7, 0xbfb8aa3b, v24
	v_exp_f32_e32 v7, v7
	v_add_f32_e32 v13, 1.0, v13
	v_rcp_f32_e32 v15, v13
	v_and_b32_e32 v17, 0xffff0000, v12
	v_add_f32_e32 v7, 1.0, v7
	v_rcp_f32_e32 v14, v7
	v_pk_mul_f32 v[6:7], v[6:7], v[22:23] op_sel_hi:[0,1]
	v_pk_mul_f32 v[6:7], v[2:3], v[6:7]
	v_and_b32_e32 v21, 0xffff0000, v10
	v_pk_mul_f32 v[14:15], v[14:15], v[24:25]
	s_nop 0
	v_pk_mul_f32 v[6:7], v[14:15], v[6:7]
	v_lshlrev_b32_e32 v14, 16, v11
	v_and_b32_e32 v15, 0xffff0000, v11
	v_mul_f32_e32 v11, 0xbfb8aa3b, v16
	v_exp_f32_e32 v11, v11
	v_cvt_pk_bf16_f32 v13, v6, v7
	v_add_co_u32_e32 v6, vcc, s0, v8
	v_add_f32_e32 v11, 1.0, v11
	v_rcp_f32_e32 v18, v11
	v_mul_f32_e32 v11, 0xbfb8aa3b, v17
	v_exp_f32_e32 v11, v11
	v_addc_co_u32_e32 v7, vcc, 0, v9, vcc
	global_store_dword v[6:7], v13, off offset:-4096
	v_add_f32_e32 v11, 1.0, v11
	v_rcp_f32_e32 v19, v11
	v_pk_mul_f32 v[12:13], v[14:15], v[14:15]
	v_pk_mul_f32 v[16:17], v[18:19], v[16:17]
	v_lshlrev_b32_e32 v18, 16, v0
	v_and_b32_e32 v19, 0xffff0000, v0
	v_pk_mul_f32 v[10:11], v[18:19], v[18:19]
	v_mov_b32_e32 v23, v12
	v_mov_b32_e32 v22, v10
	v_mov_b32_e32 v12, v11
	v_pk_add_f32 v[10:11], v[22:23], v[12:13]
	v_mov_b32_e32 v13, v11
	v_mov_b32_e32 v12, v10
	s_nop 0
	v_permlane32_swap_b32_e32 v13, v11
	v_permlane32_swap_b32_e32 v12, v10
	s_waitcnt lgkmcnt(0)
	v_pk_add_f32 v[10:11], v[10:11], v[12:13]
	v_mov_b32_e32 v13, v11
	v_mov_b32_e32 v12, v10
	s_nop 0
	v_permlane16_swap_b32_e32 v13, v11
	v_permlane16_swap_b32_e32 v12, v10
	s_waitcnt lgkmcnt(0)
	v_pk_add_f32 v[10:11], v[10:11], v[12:13]
	s_nop 1
	v_mov_b32_dpp v13, v11 row_ror:8 row_mask:0xf bank_mask:0xf
	v_mov_b32_dpp v12, v10 row_ror:8 row_mask:0xf bank_mask:0xf
	s_waitcnt lgkmcnt(0)
	v_pk_add_f32 v[10:11], v[10:11], v[12:13]
	s_nop 1
	v_mov_b32_dpp v13, v11 row_shl:4 row_mask:0xf bank_mask:0x5
	v_mov_b32_dpp v13, v11 row_shr:4 row_mask:0xf bank_mask:0xa
	v_mov_b32_dpp v12, v10 row_shl:4 row_mask:0xf bank_mask:0x5
	v_mov_b32_dpp v12, v10 row_shr:4 row_mask:0xf bank_mask:0xa
	s_waitcnt lgkmcnt(0)
	v_pk_add_f32 v[10:11], v[10:11], v[12:13]
	s_nop 1
	v_mov_b32_dpp v13, v11 quad_perm:[2,3,0,1] row_mask:0xf bank_mask:0xf
	v_mov_b32_dpp v12, v10 quad_perm:[2,3,0,1] row_mask:0xf bank_mask:0xf
	s_waitcnt lgkmcnt(0)
	v_pk_add_f32 v[10:11], v[10:11], v[12:13]
	s_nop 1
	v_mov_b32_dpp v13, v11 quad_perm:[1,0,3,2] row_mask:0xf bank_mask:0xf
	v_mov_b32_dpp v12, v10 quad_perm:[1,0,3,2] row_mask:0xf bank_mask:0xf
	s_waitcnt lgkmcnt(0)
	v_pk_add_f32 v[10:11], v[10:11], v[12:13]
	s_nop 0
	v_pk_fma_f32 v[4:5], v[10:11], s[96:97], v[4:5] op_sel_hi:[1,0,0]
	s_nop 0
	v_mul_f32_e32 v0, 0x4b800000, v5
	v_cmp_gt_f32_e64 s[0:1], s77, v5
	v_cmp_gt_f32_e32 vcc, s77, v4
	s_nop 0
	v_cndmask_b32_e64 v0, v5, v0, s[0:1]
	v_rsq_f32_e32 v0, v0
	s_nop 0
	v_mul_f32_e32 v5, 0x45800000, v0
	v_cndmask_b32_e64 v0, v0, v5, s[0:1]
	v_pk_mul_f32 v[10:11], v[0:1], v[14:15] op_sel_hi:[0,1]
	v_pk_mul_f32 v[10:11], v[2:3], v[10:11]
	s_nop 0
	v_pk_mul_f32 v[10:11], v[16:17], v[10:11]
	s_nop 0
	v_cvt_pk_bf16_f32 v0, v10, v11
	global_store_dword v[6:7], v0, off
	v_mul_f32_e32 v0, 0x4b800000, v4
	v_cndmask_b32_e32 v0, v4, v0, vcc
	v_rsq_f32_e32 v0, v0
	s_nop 0
	v_mul_f32_e32 v4, 0x45800000, v0
	v_cndmask_b32_e32 v0, v0, v4, vcc
	v_mul_f32_e32 v4, 0xbfb8aa3b, v20
	v_pk_mul_f32 v[6:7], v[0:1], v[18:19] op_sel_hi:[0,1]
	v_mul_f32_e32 v0, 0xbfb8aa3b, v21
	v_exp_f32_e32 v4, v4
	v_exp_f32_e32 v0, v0
	v_pk_mul_f32 v[2:3], v[2:3], v[6:7]
	v_add_f32_e32 v4, 1.0, v4
	v_add_f32_e32 v0, 1.0, v0
	v_rcp_f32_e32 v4, v4
	v_rcp_f32_e32 v5, v0
	s_nop 0
	v_pk_mul_f32 v[4:5], v[4:5], v[20:21]
	s_nop 0
	v_pk_mul_f32 v[2:3], v[4:5], v[2:3]
	s_nop 0
	v_cvt_pk_bf16_f32 v0, v2, v3
	v_add_co_u32_e32 v2, vcc, 0xf000, v8
	s_nop 1
	v_addc_co_u32_e32 v3, vcc, 0, v9, vcc
	global_store_dword v[2:3], v0, off

; DI float bf2f(bf16_t b) { return __uint_as_float(((unsigned)b) << 16); }
; DI void sg_item(int item, const bf16_t* proj, const bf16_t* sgw, const float* vng, const float* bs, bf16_t* obuf, unsigned char* smem, const int tid) {
;     const int lane = tid & 63, wv = tid >> 6, r = lane & 31, h2 = lane >> 5;
;     const int g = item & 3, n = (item >> 2) & 31, b = item >> 7;
;     const int t0 = b * SEQ + n * 128;
;     bf16_t* vT = (bf16_t*)smem;
;     const int tb = wv >> 1;
;     const bf16_t* W = sgw + (size_t)g * 16384;
;     bf16x8 wf[8];
; #pragma unroll
;     for (int ks = 0; ks < 8; ++ks) wf[ks] = *(const bf16x8*)(W + (32 * tb + r) * 128 + 16 * ks + 8 * h2);
;     float va[16][2];
; #pragma unroll
;     for (int e = 0; e < 16; ++e) { const bf16_t* vr = proj + (size_t)(t0 + wv * 16 + e) * PLD + 3008 + g * 128; va[e][0] = bf2f(vr[lane]); va[e][1] = bf2f(vr[lane + 64]); }
;     const float g0 = vng[g * 128 + lane], g1 = vng[g * 128 + lane + 64];
; DI void run_phase(const Params& p, int ph, unsigned char* smem, const int tid, const int rep) {
;     ...
;             const int v = *s_item;
;             if (v < 0) break;
;             const int xq = v >> 16, li = v & 0xffff;
;             int tq = tid; asm volatile("" : "+v"(tq));
;             if (li < 4) dn_scan_item(xq * 4 + li, da, smem, tq);
;             else if (li < 4 + 128) { const int idx = li - 4, qt = 15 - (idx >> 3), rr = xq * 8 + (idx & 7), type = rr & 1, bh = rr >> 1, b = bh >> 2, h = bh & 3;
;                 if (type == 0) attn_item<192, false>(mlaq + (size_t)b * SEQ * 768 + h * 192, 768, mlak + (size_t)b * SEQ * 768 + h * 192, 768, mlavt + (size_t)bh * 128 * SEQ, nullptr,
;                                                      obuf + (size_t)b * SEQ * 2048 + 512 + h * 128, 2048, qt, ((const float*)(smem + LDS_BYTES - 48))[0], smem, tq, rep);
;                 else attn_item<128, true>(proj + (size_t)b * SEQ * PLD + 3520 + h * 128, PLD, proj + (size_t)b * SEQ * PLD + 3520 + 512 + h * 128, PLD, foxvt + (size_t)bh * 128 * SEQ, foxcum + (size_t)bh * SEQ,
;                                           obuf + (size_t)b * SEQ * 2048 + 1536 + h * 128, 2048, qt, ((const float*)(smem + LDS_BYTES - 48))[1], smem, tq, rep); }
;             else sg_item(xq * 128 + (li - 132), proj, sgw, PIN(14) + l * 512, PIN(16) + l * 512, obuf, smem, tq);
.LBB0_222:
	s_or_b64 exec, exec, s[0:1]
	v_readlane_b32 s0, v254, 6
	s_waitcnt lgkmcnt(0)
	s_barrier
	v_mov_b32_e32 v0, s0
	ds_read_b32 v0, v0
	s_waitcnt lgkmcnt(0)
	v_cmp_gt_i32_e32 vcc, 0, v0
	v_readfirstlane_b32 s24, v0
	s_cbranch_vccnz .LBB0_265
	s_lshr_b32 s52, s24, 16
	s_and_b32 s54, s24, 0xffff
	v_mov_b32_e32 v196, v225
	s_cmp_gt_u32 s54, 3
	s_mov_b64 s[0:1], -1
	s_cbranch_scc0 .LBB0_304
	v_bfe_u32 v180, v196, 5, 1
	s_cmpk_gt_u32 s54, 0x83
	v_lshlrev_b32_e32 v198, 4, v180
	s_cbranch_scc0 .LBB0_244
	s_lshl_b32 s0, s52, 7
	s_add_i32 s14, s54, s0
	s_addk_i32 s14, 0xff7c
	s_and_b32 s4, s24, 3
	v_lshlrev_b32_e32 v0, 7, v196
	s_lshl_b32 s12, s14, 5
	v_ashrrev_i32_e32 v62, 7, v196
	s_lshl_b32 s0, s4, 15
	v_and_b32_e32 v0, 0xf80, v0
	s_add_u32 s0, s26, s0
	v_lshl_or_b32 v2, v62, 12, v0
	s_addc_u32 s1, s27, 0
	v_ashrrev_i32_e32 v3, 31, v2
	v_lshl_add_u64 v[2:3], v[2:3], 1, s[0:1]
	v_mov_b32_e32 v199, v1
	v_ashrrev_i32_e32 v5, 2, v196
	v_lshl_add_u64 v[2:3], v[2:3], 0, v[198:199]
	s_and_b32 s25, s12, 0xfffff80
	v_and_b32_e32 v96, -16, v5
	global_load_dwordx4 v[46:49], v[2:3], off
	global_load_dwordx4 v[42:45], v[2:3], off offset:32
	global_load_dwordx4 v[38:41], v[2:3], off offset:64
	global_load_dwordx4 v[34:37], v[2:3], off offset:96
	global_load_dwordx4 v[30:33], v[2:3], off offset:128
	global_load_dwordx4 v[26:29], v[2:3], off offset:160
	global_load_dwordx4 v[22:25], v[2:3], off offset:192
	global_load_dwordx4 v[18:21], v[2:3], off offset:224
	v_add_u32_e32 v4, s25, v96
	v_mov_b64_e32 v[2:3], s[30:31]
	v_and_b32_e32 v63, 63, v196
	s_lshl_b32 s34, s4, 7
	v_mad_i64_i32 v[6:7], s[0:1], v4, s3, v[2:3]
	s_lshl_b32 s4, s4, 8
	v_lshl_add_u64 v[6:7], v[6:7], 0, s[4:5]
	v_lshlrev_b32_e32 v0, 1, v63
	v_lshl_add_u64 v[12:13], v[6:7], 0, v[0:1]
	v_or_b32_e32 v6, 1, v4
	v_mad_i64_i32 v[6:7], s[0:1], v6, s3, v[2:3]
	v_lshl_add_u64 v[6:7], v[6:7], 0, s[4:5]
	v_lshl_add_u64 v[14:15], v[6:7], 0, v[0:1]
	v_or_b32_e32 v6, 2, v4
	v_mad_i64_i32 v[6:7], s[0:1], v6, s3, v[2:3]
	v_lshl_add_u64 v[6:7], v[6:7], 0, s[4:5]
	v_lshl_add_u64 v[16:17], v[6:7], 0, v[0:1]
	v_or_b32_e32 v6, 3, v4
	v_mad_i64_i32 v[6:7], s[0:1], v6, s3, v[2:3]
	v_lshl_add_u64 v[6:7], v[6:7], 0, s[4:5]
	v_lshl_add_u64 v[50:51], v[6:7], 0, v[0:1]
	v_or_b32_e32 v6, 4, v4
	v_mad_i64_i32 v[6:7], s[0:1], v6, s3, v[2:3]
	v_lshl_add_u64 v[6:7], v[6:7], 0, s[4:5]
	v_lshl_add_u64 v[66:67], v[6:7], 0, v[0:1]
	v_or_b32_e32 v6, 5, v4
	s_mov_b64 s[40:41], 0x1780
	v_mad_i64_i32 v[6:7], s[0:1], v6, s3, v[2:3]
	v_lshl_add_u64 v[56:57], v[12:13], 0, s[40:41]
	v_lshl_add_u64 v[6:7], v[6:7], 0, s[4:5]
	v_add_co_u32_e32 v12, vcc, s87, v12
	v_lshl_add_u64 v[70:71], v[6:7], 0, v[0:1]
	v_or_b32_e32 v6, 6, v4
	v_addc_co_u32_e32 v13, vcc, 0, v13, vcc
	v_lshl_add_u64 v[58:59], v[14:15], 0, s[40:41]
	v_mad_i64_i32 v[6:7], s[0:1], v6, s3, v[2:3]
	v_add_co_u32_e32 v14, vcc, s87, v14
	v_lshl_add_u64 v[6:7], v[6:7], 0, s[4:5]
	s_nop 0
	v_addc_co_u32_e32 v15, vcc, 0, v15, vcc
	v_lshl_add_u64 v[60:61], v[16:17], 0, s[40:41]
	v_lshl_add_u64 v[74:75], v[6:7], 0, v[0:1]
	v_or_b32_e32 v6, 7, v4
	v_add_co_u32_e32 v16, vcc, s87, v16
	v_mad_i64_i32 v[6:7], s[0:1], v6, s3, v[2:3]
	s_nop 0
	v_addc_co_u32_e32 v17, vcc, 0, v17, vcc
	v_lshl_add_u64 v[64:65], v[50:51], 0, s[40:41]
	v_lshl_add_u64 v[6:7], v[6:7], 0, s[4:5]
	v_or_b32_e32 v52, 11, v4
	v_add_co_u32_e32 v50, vcc, s87, v50
	v_lshl_add_u64 v[78:79], v[6:7], 0, v[0:1]
	v_or_b32_e32 v6, 8, v4
	v_or_b32_e32 v8, 9, v4
	v_or_b32_e32 v10, 10, v4
	v_mad_i64_i32 v[52:53], s[0:1], v52, s3, v[2:3]
	v_addc_co_u32_e32 v51, vcc, 0, v51, vcc
	global_load_ushort v97, v[12:13], off offset:1920
	global_load_ushort v98, v[14:15], off offset:1920
	global_load_ushort v99, v[16:17], off offset:1920
	global_load_ushort v100, v[50:51], off offset:1920
	v_or_b32_e32 v14, 12, v4
	v_or_b32_e32 v16, 13, v4
	v_or_b32_e32 v50, 14, v4
	v_or_b32_e32 v4, 15, v4
	v_mad_i64_i32 v[6:7], s[0:1], v6, s3, v[2:3]
	v_mad_i64_i32 v[8:9], s[0:1], v8, s3, v[2:3]
	v_mad_i64_i32 v[10:11], s[0:1], v10, s3, v[2:3]
	v_lshl_add_u64 v[12:13], v[52:53], 0, s[4:5]
	v_mad_i64_i32 v[14:15], s[0:1], v14, s3, v[2:3]
	v_mad_i64_i32 v[16:17], s[0:1], v16, s3, v[2:3]
	v_mad_i64_i32 v[50:51], s[0:1], v50, s3, v[2:3]
	v_mad_i64_i32 v[52:53], s[0:1], v4, s3, v[2:3]
	v_lshl_add_u64 v[6:7], v[6:7], 0, s[4:5]
	v_lshl_add_u64 v[8:9], v[8:9], 0, s[4:5]
	v_lshl_add_u64 v[10:11], v[10:11], 0, s[4:5]
	v_lshl_add_u64 v[14:15], v[14:15], 0, s[4:5]
	v_lshl_add_u64 v[16:17], v[16:17], 0, s[4:5]
	v_lshl_add_u64 v[50:51], v[50:51], 0, s[4:5]
	v_lshl_add_u64 v[52:53], v[52:53], 0, s[4:5]
	v_lshl_add_u64 v[82:83], v[6:7], 0, v[0:1]
	v_lshl_add_u64 v[84:85], v[8:9], 0, v[0:1]
	v_lshl_add_u64 v[86:87], v[10:11], 0, v[0:1]
	v_lshl_add_u64 v[88:89], v[12:13], 0, v[0:1]
	v_lshl_add_u64 v[90:91], v[14:15], 0, v[0:1]
	v_lshl_add_u64 v[92:93], v[16:17], 0, v[0:1]
	v_lshl_add_u64 v[94:95], v[50:51], 0, v[0:1]
	v_lshl_add_u64 v[54:55], v[52:53], 0, v[0:1]
	v_or_b32_e32 v0, s34, v63
	v_lshlrev_b32_e32 v0, 2, v0
	global_load_dword v4, v0, s[48:49]
	s_nop 0
	global_load_dword v0, v0, s[48:49] offset:256
	s_nop 0
	global_load_ushort v101, v[56:57], off offset:128
	global_load_ushort v102, v[58:59], off offset:128
	global_load_ushort v103, v[60:61], off offset:128
	global_load_ushort v104, v[64:65], off offset:128
	v_add_co_u32_e32 v56, vcc, s87, v66
	v_lshl_add_u64 v[68:69], v[66:67], 0, s[40:41]
	s_nop 0
	v_addc_co_u32_e32 v57, vcc, 0, v67, vcc
	v_add_co_u32_e32 v58, vcc, s87, v70
	v_lshl_add_u64 v[72:73], v[70:71], 0, s[40:41]
	s_nop 0
	v_addc_co_u32_e32 v59, vcc, 0, v71, vcc
	v_add_co_u32_e32 v60, vcc, s87, v74
	v_lshl_add_u64 v[76:77], v[74:75], 0, s[40:41]
	s_nop 0
	v_addc_co_u32_e32 v61, vcc, 0, v75, vcc
	v_add_co_u32_e32 v64, vcc, s87, v78
	v_lshl_add_u64 v[80:81], v[78:79], 0, s[40:41]
	s_nop 0
	v_addc_co_u32_e32 v65, vcc, 0, v79, vcc
	global_load_ushort v105, v[56:57], off offset:1920
	global_load_ushort v106, v[58:59], off offset:1920
	global_load_ushort v107, v[60:61], off offset:1920
	global_load_ushort v108, v[64:65], off offset:1920
	global_load_ushort v109, v[68:69], off offset:128
	global_load_ushort v110, v[72:73], off offset:128
	global_load_ushort v111, v[76:77], off offset:128
	global_load_ushort v112, v[80:81], off offset:128
	v_add_co_u32_e32 v56, vcc, s87, v82
	v_lshl_add_u64 v[6:7], v[82:83], 0, s[40:41]
	s_nop 0
	v_addc_co_u32_e32 v57, vcc, 0, v83, vcc
	v_add_co_u32_e32 v58, vcc, s87, v84
	v_lshl_add_u64 v[8:9], v[84:85], 0, s[40:41]
	s_nop 0
	v_addc_co_u32_e32 v59, vcc, 0, v85, vcc
	v_add_co_u32_e32 v60, vcc, s87, v86
	v_lshl_add_u64 v[10:11], v[86:87], 0, s[40:41]
	s_nop 0
	v_addc_co_u32_e32 v61, vcc, 0, v87, vcc
	v_add_co_u32_e32 v64, vcc, s87, v88
	v_lshl_add_u64 v[12:13], v[88:89], 0, s[40:41]
	s_waitcnt vmcnt(17)
; DI bf16_t f2bf(float f) { unsigned u = __float_as_uint(f); u += 0x7fffu + ((u >> 16) & 1u); return (bf16_t)(u >> 16); }
; DI float wave_sum(float v) { for (int o = 32; o; o >>= 1) v += __shfl_xor(v, o); return v; }
; DI float geluf_(float x) { const float u = 0.7978845608028654f * (x + 0.044715f * x * x * x); return x * __builtin_amdgcn_rcpf(1.f + __builtin_amdgcn_exp2f(-2.f * LOG2E * u)); }
; DI void sg_item(int item, const bf16_t* proj, const bf16_t* sgw, const float* vng, const float* bs, bf16_t* obuf, unsigned char* smem, const int tid) {
;     ...
; #pragma unroll
;     for (int e = 0; e < 16; ++e) { const int tt = wv * 16 + e;
;         const float a0 = geluf_(va[e][0]), a1 = geluf_(va[e][1]);
;         const float ss = wave_sum(a0 * a0 + a1 * a1); const float rs = rsqrtf(ss * (1.f / 128.f) + NEPS);
;         vT[lane * 136 + tt] = f2bf(a0 * rs * g0); vT[(lane + 64) * 136 + tt] = f2bf(a1 * rs * g1); }
	v_lshlrev_b32_e32 v70, 16, v97
	v_mul_f32_e32 v68, 0x3d372713, v70
	v_mul_f32_e32 v68, v68, v70
	v_fma_f32 v68, v68, v70, v70
	v_mul_f32_e32 v68, 0x3f4c422a, v68
	s_waitcnt vmcnt(16)
	v_lshlrev_b32_e32 v71, 16, v98
	v_mul_f32_e32 v68, 0xc038aa3b, v68
	v_exp_f32_e32 v72, v68
	v_mul_f32_e32 v68, 0x3d372713, v71
	v_mul_f32_e32 v68, v68, v71
	v_fma_f32 v68, v68, v71, v71
	v_mul_f32_e32 v68, 0x3f4c422a, v68
	v_mul_f32_e32 v68, 0xc038aa3b, v68
	s_waitcnt vmcnt(14)
	v_lshlrev_b32_e32 v69, 16, v100
	v_exp_f32_e32 v73, v68
	v_lshlrev_b32_e32 v68, 16, v99
	v_mul_f32_e32 v74, 0x3d372713, v68
	v_mul_f32_e32 v75, 0x3d372713, v69
	v_mul_f32_e32 v74, v74, v68
	v_mul_f32_e32 v75, v75, v69
	v_fma_f32 v74, v74, v68, v68
	v_fma_f32 v75, v75, v69, v69
	v_mul_f32_e32 v74, 0x3f4c422a, v74
	v_mul_f32_e32 v75, 0x3f4c422a, v75
	v_mul_f32_e32 v74, 0xc038aa3b, v74
	v_mul_f32_e32 v75, 0xc038aa3b, v75
	v_exp_f32_e32 v74, v74
	v_exp_f32_e32 v75, v75
	v_add_f32_e32 v72, 1.0, v72
	v_add_f32_e32 v73, 1.0, v73
	v_add_f32_e32 v74, 1.0, v74
	v_add_f32_e32 v75, 1.0, v75
	v_rcp_f32_e32 v74, v74
	v_rcp_f32_e32 v75, v75
	v_rcp_f32_e32 v72, v72
	v_rcp_f32_e32 v73, v73
	v_addc_co_u32_e32 v65, vcc, 0, v89, vcc
	s_waitcnt vmcnt(11)
	v_lshlrev_b32_e32 v76, 16, v101
	v_mul_f32_e32 v77, 0x3d372713, v76
	v_mul_f32_e32 v77, v77, v76
	v_fma_f32 v77, v77, v76, v76
	v_mul_f32_e32 v77, 0x3f4c422a, v77
	v_mul_f32_e32 v77, 0xc038aa3b, v77
	v_exp_f32_e32 v80, v77
	s_waitcnt vmcnt(10)
	v_lshlrev_b32_e32 v77, 16, v102
	v_mul_f32_e32 v81, 0x3d372713, v77
	s_waitcnt vmcnt(8)
	v_lshlrev_b32_e32 v79, 16, v104
	v_lshlrev_b32_e32 v78, 16, v103
	v_mul_f32_e32 v81, v81, v77
	v_fma_f32 v81, v81, v77, v77
	v_mul_f32_e32 v82, 0x3d372713, v78
	v_mul_f32_e32 v83, 0x3d372713, v79
	v_mul_f32_e32 v81, 0x3f4c422a, v81
	v_mul_f32_e32 v82, v82, v78
	v_mul_f32_e32 v83, v83, v79
	v_mul_f32_e32 v81, 0xc038aa3b, v81
	v_fma_f32 v82, v82, v78, v78
	v_fma_f32 v83, v83, v79, v79
	v_exp_f32_e32 v81, v81
	v_mul_f32_e32 v82, 0x3f4c422a, v82
	v_mul_f32_e32 v83, 0x3f4c422a, v83
	v_mul_f32_e32 v82, 0xc038aa3b, v82
	v_mul_f32_e32 v83, 0xc038aa3b, v83
	v_exp_f32_e32 v82, v82
	v_exp_f32_e32 v83, v83
	v_add_f32_e32 v80, 1.0, v80
	v_add_f32_e32 v81, 1.0, v81
	v_rcp_f32_e32 v80, v80
	v_rcp_f32_e32 v81, v81
	v_add_f32_e32 v82, 1.0, v82
	v_add_f32_e32 v83, 1.0, v83
	v_rcp_f32_e32 v82, v82
	v_rcp_f32_e32 v83, v83
	v_pk_mul_f32 v[68:69], v[74:75], v[68:69]
	v_pk_mul_f32 v[74:75], v[80:81], v[76:77]
	v_pk_mul_f32 v[70:71], v[72:73], v[70:71]
	v_pk_mul_f32 v[76:77], v[74:75], v[74:75]
	v_pk_mul_f32 v[72:73], v[82:83], v[78:79]
	v_pk_fma_f32 v[76:77], v[70:71], v[70:71], v[76:77]
	v_pk_mul_f32 v[78:79], v[72:73], v[72:73]
	v_mov_b32_e32 v80, v76
	v_mov_b32_e32 v81, v77
	s_nop 0
	v_permlane32_swap_b32_e32 v80, v76
	v_permlane32_swap_b32_e32 v81, v77
	v_pk_fma_f32 v[78:79], v[68:69], v[68:69], v[78:79]
	v_mov_b32_e32 v82, v78
	v_mov_b32_e32 v83, v79
	s_nop 0
	v_permlane32_swap_b32_e32 v82, v78
	v_permlane32_swap_b32_e32 v83, v79
	v_add_co_u32_e32 v66, vcc, s87, v90
	s_waitcnt lgkmcnt(2)
	v_pk_add_f32 v[76:77], v[76:77], v[80:81]
	v_mov_b32_e32 v80, v76
	v_mov_b32_e32 v81, v77
	s_nop 0
	v_permlane16_swap_b32_e32 v80, v76
	v_permlane16_swap_b32_e32 v81, v77
	s_waitcnt lgkmcnt(2)
	v_pk_add_f32 v[78:79], v[78:79], v[82:83]
	v_mov_b32_e32 v82, v78
	v_mov_b32_e32 v83, v79
	s_nop 0
	v_permlane16_swap_b32_e32 v82, v78
	v_permlane16_swap_b32_e32 v83, v79
	v_addc_co_u32_e32 v67, vcc, 0, v91, vcc
	s_waitcnt lgkmcnt(2)
	v_pk_add_f32 v[76:77], v[76:77], v[80:81]
	s_nop 1
	v_mov_b32_dpp v80, v76 row_ror:8 row_mask:0xf bank_mask:0xf
	v_mov_b32_dpp v81, v77 row_ror:8 row_mask:0xf bank_mask:0xf
	s_waitcnt lgkmcnt(2)
	v_pk_add_f32 v[78:79], v[78:79], v[82:83]
	s_nop 1
	v_mov_b32_dpp v82, v78 row_ror:8 row_mask:0xf bank_mask:0xf
	v_mov_b32_dpp v83, v79 row_ror:8 row_mask:0xf bank_mask:0xf
	v_add_co_u32_e32 v84, vcc, s87, v92
	s_waitcnt lgkmcnt(2)
	v_pk_add_f32 v[76:77], v[76:77], v[80:81]
	s_nop 1
	v_mov_b32_dpp v80, v76 row_shl:4 row_mask:0xf bank_mask:0x5
	v_mov_b32_dpp v80, v76 row_shr:4 row_mask:0xf bank_mask:0xa
	v_mov_b32_dpp v81, v77 row_shl:4 row_mask:0xf bank_mask:0x5
	v_mov_b32_dpp v81, v77 row_shr:4 row_mask:0xf bank_mask:0xa
	v_addc_co_u32_e32 v85, vcc, 0, v93, vcc
	s_waitcnt lgkmcnt(2)
	v_pk_add_f32 v[78:79], v[78:79], v[82:83]
	v_add_co_u32_e32 v86, vcc, s87, v94
	s_nop 1
	v_mov_b32_dpp v82, v78 row_shl:4 row_mask:0xf bank_mask:0x5
	v_mov_b32_dpp v82, v78 row_shr:4 row_mask:0xf bank_mask:0xa
	v_mov_b32_dpp v83, v79 row_shl:4 row_mask:0xf bank_mask:0x5
	v_mov_b32_dpp v83, v79 row_shr:4 row_mask:0xf bank_mask:0xa
	v_addc_co_u32_e32 v87, vcc, 0, v95, vcc
	v_add_co_u32_e32 v88, vcc, s87, v54
	v_lshl_add_u64 v[14:15], v[90:91], 0, s[40:41]
	v_lshl_add_u64 v[16:17], v[92:93], 0, s[40:41]
	v_lshl_add_u64 v[52:53], v[54:55], 0, s[40:41]
	v_addc_co_u32_e32 v89, vcc, 0, v55, vcc
	global_load_ushort v90, v[56:57], off offset:1920
	global_load_ushort v91, v[58:59], off offset:1920
	global_load_ushort v92, v[60:61], off offset:1920
	global_load_ushort v93, v[64:65], off offset:1920
	s_nop 0
	global_load_ushort v56, v[66:67], off offset:1920
	global_load_ushort v57, v[84:85], off offset:1920
	global_load_ushort v55, v[86:87], off offset:1920
	global_load_ushort v54, v[88:89], off offset:1920
	s_waitcnt lgkmcnt(2)
	v_pk_add_f32 v[58:59], v[76:77], v[80:81]
	s_nop 1
	v_mov_b32_dpp v60, v58 quad_perm:[2,3,0,1] row_mask:0xf bank_mask:0xf
	v_mov_b32_dpp v61, v59 quad_perm:[2,3,0,1] row_mask:0xf bank_mask:0xf
	s_waitcnt lgkmcnt(2)
; DI bf16_t f2bf(float f) { unsigned u = __float_as_uint(f); u += 0x7fffu + ((u >> 16) & 1u); return (bf16_t)(u >> 16); }
; DI float wave_sum(float v) { for (int o = 32; o; o >>= 1) v += __shfl_xor(v, o); return v; }
; DI float geluf_(float x) { const float u = 0.7978845608028654f * (x + 0.044715f * x * x * x); return x * __builtin_amdgcn_rcpf(1.f + __builtin_amdgcn_exp2f(-2.f * LOG2E * u)); }
; DI void sg_item(int item, const bf16_t* proj, const bf16_t* sgw, const float* vng, const float* bs, bf16_t* obuf, unsigned char* smem, const int tid) {
;     ...
; #pragma unroll
;     for (int e = 0; e < 16; ++e) { const int tt = wv * 16 + e;
;         const float a0 = geluf_(va[e][0]), a1 = geluf_(va[e][1]);
;         const float ss = wave_sum(a0 * a0 + a1 * a1); const float rs = rsqrtf(ss * (1.f / 128.f) + NEPS);
;         vT[lane * 136 + tt] = f2bf(a0 * rs * g0); vT[(lane + 64) * 136 + tt] = f2bf(a1 * rs * g1); }
	v_pk_add_f32 v[64:65], v[78:79], v[82:83]
	s_nop 1
	v_mov_b32_dpp v66, v64 quad_perm:[2,3,0,1] row_mask:0xf bank_mask:0xf
	v_mov_b32_dpp v67, v65 quad_perm:[2,3,0,1] row_mask:0xf bank_mask:0xf
	v_lshl_add_u64 v[50:51], v[94:95], 0, s[40:41]
	global_load_ushort v76, v[6:7], off offset:128
	global_load_ushort v77, v[8:9], off offset:128
	global_load_ushort v78, v[10:11], off offset:128
	global_load_ushort v79, v[12:13], off offset:128
	s_nop 0
	global_load_ushort v12, v[14:15], off offset:128
	global_load_ushort v13, v[16:17], off offset:128
	global_load_ushort v11, v[50:51], off offset:128
	global_load_ushort v10, v[52:53], off offset:128
	s_waitcnt lgkmcnt(2)
	v_pk_add_f32 v[6:7], v[58:59], v[60:61]
	s_nop 1
	v_mov_b32_dpp v8, v6 quad_perm:[1,0,3,2] row_mask:0xf bank_mask:0xf
	v_mov_b32_dpp v9, v7 quad_perm:[1,0,3,2] row_mask:0xf bank_mask:0xf
	s_waitcnt lgkmcnt(2)
	v_pk_add_f32 v[14:15], v[64:65], v[66:67]
	s_nop 1
	v_mov_b32_dpp v16, v14 quad_perm:[1,0,3,2] row_mask:0xf bank_mask:0xf
	v_mov_b32_dpp v17, v15 quad_perm:[1,0,3,2] row_mask:0xf bank_mask:0xf
	s_mov_b32 s56, 0x45800000
	s_waitcnt lgkmcnt(2)
	v_pk_add_f32 v[8:9], v[6:7], v[8:9]
	v_mov_b64_e32 v[6:7], s[72:73]
	v_pk_fma_f32 v[8:9], v[8:9], s[96:97], v[6:7] op_sel_hi:[1,0,0]
	s_waitcnt lgkmcnt(0)
	v_pk_add_f32 v[14:15], v[14:15], v[16:17]
	v_mul_f32_e32 v16, 0x4b800000, v8
	v_cmp_gt_f32_e32 vcc, s77, v8
	v_pk_fma_f32 v[14:15], v[14:15], s[96:97], v[6:7] op_sel_hi:[1,0,0]
	v_cmp_gt_f32_e64 s[0:1], s77, v9
	v_cndmask_b32_e32 v8, v8, v16, vcc
	v_rsq_f32_e32 v16, v8
	v_mul_f32_e32 v8, 0x4b800000, v9
	v_cndmask_b32_e64 v8, v9, v8, s[0:1]
	v_mul_f32_e32 v9, 0x4b800000, v14
	v_cmp_gt_f32_e64 s[40:41], s77, v14
	v_cmp_gt_f32_e64 s[42:43], s77, v15
	v_rsq_f32_e32 v17, v8
	v_cndmask_b32_e64 v9, v14, v9, s[40:41]
	v_rsq_f32_e32 v14, v9
	v_mul_f32_e32 v9, 0x4b800000, v15
	v_cndmask_b32_e64 v9, v15, v9, s[42:43]
	v_rsq_f32_e32 v15, v9
	v_pk_mul_f32 v[52:53], v[16:17], s[56:57] op_sel_hi:[1,0]
	v_mad_u32_u24 v8, v63, s10, 0
	v_cndmask_b32_e64 v17, v17, v53, s[0:1]
	v_pk_mul_f32 v[50:51], v[14:15], s[56:57] op_sel_hi:[1,0]
	v_cndmask_b32_e32 v16, v16, v52, vcc
	v_cndmask_b32_e64 v15, v15, v51, s[42:43]
	v_cndmask_b32_e64 v14, v14, v50, s[40:41]
	v_pk_mul_f32 v[52:53], v[70:71], v[16:17]
	v_pk_mul_f32 v[50:51], v[68:69], v[14:15]
	v_pk_mul_f32 v[52:53], v[4:5], v[52:53] op_sel_hi:[0,1]
	v_pk_mul_f32 v[50:51], v[4:5], v[50:51] op_sel_hi:[0,1]
	v_bfe_u32 v61, v52, 16, 1
	v_bfe_u32 v59, v50, 16, 1
	v_add3_u32 v63, v52, v61, s11
	s_waitcnt vmcnt(23)
	v_lshlrev_b32_e32 v52, 16, v105
	v_add3_u32 v81, v50, v59, s11
	v_mul_f32_e32 v50, 0x3d372713, v52
	v_mul_f32_e32 v50, v50, v52
	v_fma_f32 v50, v50, v52, v52
	v_bfe_u32 v60, v53, 16, 1
	v_mul_f32_e32 v50, 0x3f4c422a, v50
	v_bfe_u32 v58, v51, 16, 1
	v_add3_u32 v80, v53, v60, s11
	s_waitcnt vmcnt(22)
	v_lshlrev_b32_e32 v53, 16, v106
	v_mul_f32_e32 v50, 0xc038aa3b, v50
	s_waitcnt vmcnt(19)
	v_lshlrev_b32_e32 v64, 16, v109
	v_add3_u32 v82, v51, v58, s11
	v_exp_f32_e32 v58, v50
	v_mul_f32_e32 v50, 0x3d372713, v53
	v_mul_f32_e32 v65, 0x3d372713, v64
	v_mul_f32_e32 v50, v50, v53
	v_mul_f32_e32 v65, v65, v64
	v_fma_f32 v50, v50, v53, v53
	v_fma_f32 v65, v65, v64, v64
	v_mul_f32_e32 v50, 0x3f4c422a, v50
	v_mul_f32_e32 v65, 0x3f4c422a, v65
	v_mul_f32_e32 v50, 0xc038aa3b, v50
	v_mul_f32_e32 v65, 0xc038aa3b, v65
	v_lshlrev_b32_e32 v51, 16, v108
	v_exp_f32_e32 v59, v50
	v_lshlrev_b32_e32 v50, 16, v107
	v_exp_f32_e32 v68, v65
	s_waitcnt vmcnt(18)
	v_lshlrev_b32_e32 v65, 16, v110
	v_mul_f32_e32 v60, 0x3d372713, v50
	v_mul_f32_e32 v61, 0x3d372713, v51
	v_mul_f32_e32 v69, 0x3d372713, v65
	v_mul_f32_e32 v60, v60, v50
	v_mul_f32_e32 v61, v61, v51
	s_waitcnt vmcnt(16)
	v_lshlrev_b32_e32 v67, 16, v112
	v_lshlrev_b32_e32 v66, 16, v111
	v_mul_f32_e32 v69, v69, v65
	v_fma_f32 v60, v60, v50, v50
	v_fma_f32 v61, v61, v51, v51
	v_fma_f32 v69, v69, v65, v65
	v_mul_f32_e32 v70, 0x3d372713, v66
	v_mul_f32_e32 v71, 0x3d372713, v67
	v_mul_f32_e32 v60, 0x3f4c422a, v60
	v_mul_f32_e32 v61, 0x3f4c422a, v61
	v_mul_f32_e32 v69, 0x3f4c422a, v69
	v_mul_f32_e32 v70, v70, v66
	v_mul_f32_e32 v71, v71, v67
	v_mul_f32_e32 v60, 0xc038aa3b, v60
	v_mul_f32_e32 v61, 0xc038aa3b, v61
	v_mul_f32_e32 v69, 0xc038aa3b, v69
	v_fma_f32 v70, v70, v66, v66
	v_fma_f32 v71, v71, v67, v67
	v_exp_f32_e32 v60, v60
	v_exp_f32_e32 v61, v61
	v_exp_f32_e32 v69, v69
	v_mul_f32_e32 v70, 0x3f4c422a, v70
	v_mul_f32_e32 v71, 0x3f4c422a, v71
	v_mul_f32_e32 v70, 0xc038aa3b, v70
	v_mul_f32_e32 v71, 0xc038aa3b, v71
	v_exp_f32_e32 v70, v70
	v_exp_f32_e32 v71, v71
	v_add_f32_e32 v60, 1.0, v60
	v_add_f32_e32 v61, 1.0, v61
	v_add_f32_e32 v68, 1.0, v68
	v_add_f32_e32 v69, 1.0, v69
	v_add_f32_e32 v58, 1.0, v58
	v_add_f32_e32 v59, 1.0, v59
	v_rcp_f32_e32 v60, v60
	v_rcp_f32_e32 v61, v61
	v_rcp_f32_e32 v68, v68
	v_rcp_f32_e32 v69, v69
	v_rcp_f32_e32 v58, v58
	v_rcp_f32_e32 v59, v59
	v_add_f32_e32 v70, 1.0, v70
	v_add_f32_e32 v71, 1.0, v71
	v_rcp_f32_e32 v70, v70
	v_rcp_f32_e32 v71, v71
	v_pk_mul_f32 v[50:51], v[60:61], v[50:51]
	v_pk_mul_f32 v[60:61], v[68:69], v[64:65]
	v_pk_mul_f32 v[52:53], v[58:59], v[52:53]
	v_pk_mul_f32 v[64:65], v[60:61], v[60:61]
	v_pk_mul_f32 v[58:59], v[70:71], v[66:67]
	v_pk_fma_f32 v[64:65], v[52:53], v[52:53], v[64:65]
	v_pk_mul_f32 v[66:67], v[58:59], v[58:59]
	v_mov_b32_e32 v68, v64
	v_mov_b32_e32 v69, v65
	s_nop 0
	v_permlane32_swap_b32_e32 v68, v64
	v_permlane32_swap_b32_e32 v69, v65
	v_pk_fma_f32 v[66:67], v[50:51], v[50:51], v[66:67]
	v_mov_b32_e32 v70, v66
	v_mov_b32_e32 v71, v67
	s_nop 0
	v_permlane32_swap_b32_e32 v70, v66
	v_permlane32_swap_b32_e32 v71, v67
	v_pk_mul_f32 v[16:17], v[74:75], v[16:17]
	s_waitcnt lgkmcnt(2)
; DI bf16_t f2bf(float f) { unsigned u = __float_as_uint(f); u += 0x7fffu + ((u >> 16) & 1u); return (bf16_t)(u >> 16); }
; DI float wave_sum(float v) { for (int o = 32; o; o >>= 1) v += __shfl_xor(v, o); return v; }
; DI float geluf_(float x) { const float u = 0.7978845608028654f * (x + 0.044715f * x * x * x); return x * __builtin_amdgcn_rcpf(1.f + __builtin_amdgcn_exp2f(-2.f * LOG2E * u)); }
; DI void sg_item(int item, const bf16_t* proj, const bf16_t* sgw, const float* vng, const float* bs, bf16_t* obuf, unsigned char* smem, const int tid) {
;     ...
;     for (int e = 0; e < 16; ++e) { const int tt = wv * 16 + e;
;         const float a0 = geluf_(va[e][0]), a1 = geluf_(va[e][1]);
;         const float ss = wave_sum(a0 * a0 + a1 * a1); const float rs = rsqrtf(ss * (1.f / 128.f) + NEPS);
;         vT[lane * 136 + tt] = f2bf(a0 * rs * g0); vT[(lane + 64) * 136 + tt] = f2bf(a1 * rs * g1); }
	v_pk_add_f32 v[64:65], v[64:65], v[68:69]
	v_mov_b32_e32 v68, v64
	v_mov_b32_e32 v69, v65
	s_nop 0
	v_permlane16_swap_b32_e32 v68, v64
	v_permlane16_swap_b32_e32 v69, v65
	s_waitcnt lgkmcnt(2)
	v_pk_add_f32 v[66:67], v[66:67], v[70:71]
	v_mov_b32_e32 v70, v66
	v_mov_b32_e32 v71, v67
	s_nop 0
	v_permlane16_swap_b32_e32 v70, v66
	v_permlane16_swap_b32_e32 v71, v67
	v_pk_mul_f32 v[16:17], v[0:1], v[16:17] op_sel_hi:[0,1]
	s_waitcnt lgkmcnt(2)
	v_pk_add_f32 v[64:65], v[64:65], v[68:69]
	s_nop 1
	v_mov_b32_dpp v68, v64 row_ror:8 row_mask:0xf bank_mask:0xf
	v_mov_b32_dpp v69, v65 row_ror:8 row_mask:0xf bank_mask:0xf
	s_waitcnt lgkmcnt(2)
	v_pk_add_f32 v[66:67], v[66:67], v[70:71]
	s_nop 1
	v_mov_b32_dpp v70, v66 row_ror:8 row_mask:0xf bank_mask:0xf
	v_mov_b32_dpp v71, v67 row_ror:8 row_mask:0xf bank_mask:0xf
	v_bfe_u32 v74, v17, 16, 1
	s_waitcnt lgkmcnt(2)
	v_pk_add_f32 v[64:65], v[64:65], v[68:69]
	s_nop 1
	v_mov_b32_dpp v68, v64 row_shl:4 row_mask:0xf bank_mask:0x5
	v_mov_b32_dpp v68, v64 row_shr:4 row_mask:0xf bank_mask:0xa
	v_mov_b32_dpp v69, v65 row_shl:4 row_mask:0xf bank_mask:0x5
	v_mov_b32_dpp v69, v65 row_shr:4 row_mask:0xf bank_mask:0xa
	s_waitcnt lgkmcnt(2)
	v_pk_add_f32 v[66:67], v[66:67], v[70:71]
	s_nop 1
	v_mov_b32_dpp v70, v66 row_shl:4 row_mask:0xf bank_mask:0x5
	v_mov_b32_dpp v70, v66 row_shr:4 row_mask:0xf bank_mask:0xa
	v_mov_b32_dpp v71, v67 row_shl:4 row_mask:0xf bank_mask:0x5
	v_mov_b32_dpp v71, v67 row_shr:4 row_mask:0xf bank_mask:0xa
	v_bfe_u32 v75, v16, 16, 1
	s_waitcnt lgkmcnt(2)
	v_pk_add_f32 v[64:65], v[64:65], v[68:69]
	s_nop 1
	v_mov_b32_dpp v68, v64 quad_perm:[2,3,0,1] row_mask:0xf bank_mask:0xf
	v_mov_b32_dpp v69, v65 quad_perm:[2,3,0,1] row_mask:0xf bank_mask:0xf
	s_waitcnt lgkmcnt(2)
	v_pk_add_f32 v[66:67], v[66:67], v[70:71]
	s_nop 1
	v_mov_b32_dpp v70, v66 quad_perm:[2,3,0,1] row_mask:0xf bank_mask:0xf
	v_mov_b32_dpp v71, v67 quad_perm:[2,3,0,1] row_mask:0xf bank_mask:0xf
	v_add3_u32 v75, v16, v75, s11
	s_waitcnt lgkmcnt(2)
	v_pk_add_f32 v[64:65], v[64:65], v[68:69]
	s_nop 1
	v_mov_b32_dpp v68, v64 quad_perm:[1,0,3,2] row_mask:0xf bank_mask:0xf
	v_mov_b32_dpp v69, v65 quad_perm:[1,0,3,2] row_mask:0xf bank_mask:0xf
	s_waitcnt lgkmcnt(2)
	v_pk_add_f32 v[66:67], v[66:67], v[70:71]
	s_nop 1
	v_mov_b32_dpp v70, v66 quad_perm:[1,0,3,2] row_mask:0xf bank_mask:0xf
	v_mov_b32_dpp v71, v67 quad_perm:[1,0,3,2] row_mask:0xf bank_mask:0xf
	v_add3_u32 v74, v17, v74, s11
	s_waitcnt lgkmcnt(2)
	v_pk_add_f32 v[16:17], v[64:65], v[68:69]
	v_pk_mul_f32 v[14:15], v[72:73], v[14:15]
	v_pk_fma_f32 v[16:17], v[16:17], s[96:97], v[6:7] op_sel_hi:[1,0,0]
	s_waitcnt lgkmcnt(0)
	v_pk_add_f32 v[64:65], v[66:67], v[70:71]
	v_mul_f32_e32 v66, 0x4b800000, v16
	v_cmp_gt_f32_e32 vcc, s77, v16
	v_pk_fma_f32 v[64:65], v[64:65], s[96:97], v[6:7] op_sel_hi:[1,0,0]
	v_cmp_gt_f32_e64 s[0:1], s77, v17
	v_cndmask_b32_e32 v16, v16, v66, vcc
	v_mul_f32_e32 v66, 0x4b800000, v17
	v_cndmask_b32_e64 v17, v17, v66, s[0:1]
	v_mul_f32_e32 v66, 0x4b800000, v64
	v_cmp_gt_f32_e64 s[40:41], s77, v64
	v_rsq_f32_e32 v16, v16
	v_cmp_gt_f32_e64 s[42:43], s77, v65
	v_cndmask_b32_e64 v64, v64, v66, s[40:41]
	v_mul_f32_e32 v66, 0x4b800000, v65
	v_rsq_f32_e32 v17, v17
	v_cndmask_b32_e64 v65, v65, v66, s[42:43]
	v_rsq_f32_e32 v64, v64
	v_rsq_f32_e32 v65, v65
	v_pk_mul_f32 v[14:15], v[0:1], v[14:15] op_sel_hi:[0,1]
	v_pk_mul_f32 v[66:67], v[16:17], s[56:57] op_sel_hi:[1,0]
	v_bfe_u32 v72, v15, 16, 1
	v_bfe_u32 v73, v14, 16, 1
	v_cndmask_b32_e64 v67, v17, v67, s[0:1]
	v_cndmask_b32_e32 v66, v16, v66, vcc
	v_add3_u32 v73, v14, v73, s11
	v_add3_u32 v72, v15, v72, s11
	v_pk_mul_f32 v[14:15], v[64:65], s[56:57] op_sel_hi:[1,0]
	v_pk_mul_f32 v[16:17], v[52:53], v[66:67]
	v_cndmask_b32_e64 v65, v65, v15, s[42:43]
	v_cndmask_b32_e64 v64, v64, v14, s[40:41]
	v_pk_mul_f32 v[16:17], v[4:5], v[16:17] op_sel_hi:[0,1]
	v_pk_mul_f32 v[14:15], v[50:51], v[64:65]
	v_bfe_u32 v52, v17, 16, 1
	v_bfe_u32 v53, v16, 16, 1
	v_pk_mul_f32 v[14:15], v[4:5], v[14:15] op_sel_hi:[0,1]
	v_add3_u32 v16, v16, v53, s11
	v_add3_u32 v52, v17, v52, s11
	s_mov_b32 s12, 0x7060302
	v_bfe_u32 v50, v15, 16, 1
	v_perm_b32 v16, v52, v16, s12
	s_waitcnt vmcnt(15)
	v_lshlrev_b32_e32 v52, 16, v90
	v_add3_u32 v15, v15, v50, s11
	v_mul_f32_e32 v50, 0x3d372713, v52
	v_bfe_u32 v51, v14, 16, 1
	v_mul_f32_e32 v50, v50, v52
	v_add3_u32 v14, v14, v51, s11
	v_fma_f32 v50, v50, v52, v52
	v_lshl_add_u32 v9, v96, 1, v8
	v_perm_b32 v17, v15, v14, s12
	v_perm_b32 v15, v82, v81, s12
	v_perm_b32 v14, v80, v63, s12
	v_mul_f32_e32 v50, 0x3f4c422a, v50
	s_barrier
; DI bf16_t f2bf(float f) { unsigned u = __float_as_uint(f); u += 0x7fffu + ((u >> 16) & 1u); return (bf16_t)(u >> 16); }
; DI float wave_sum(float v) { for (int o = 32; o; o >>= 1) v += __shfl_xor(v, o); return v; }
; DI float geluf_(float x) { const float u = 0.7978845608028654f * (x + 0.044715f * x * x * x); return x * __builtin_amdgcn_rcpf(1.f + __builtin_amdgcn_exp2f(-2.f * LOG2E * u)); }
; DI void sg_item(int item, const bf16_t* proj, const bf16_t* sgw, const float* vng, const float* bs, bf16_t* obuf, unsigned char* smem, const int tid) {
;     ...
;     for (int e = 0; e < 16; ++e) { const int tt = wv * 16 + e;
;         const float a0 = geluf_(va[e][0]), a1 = geluf_(va[e][1]);
;         const float ss = wave_sum(a0 * a0 + a1 * a1); const float rs = rsqrtf(ss * (1.f / 128.f) + NEPS);
;         vT[lane * 136 + tt] = f2bf(a0 * rs * g0); vT[(lane + 64) * 136 + tt] = f2bf(a1 * rs * g1); }
	ds_write_b128 v9, v[14:17]
	v_pk_mul_f32 v[14:15], v[58:59], v[64:65]
	s_waitcnt vmcnt(14)
	v_lshlrev_b32_e32 v53, 16, v91
	v_mul_f32_e32 v50, 0xc038aa3b, v50
	s_waitcnt vmcnt(7)
	v_lshlrev_b32_e32 v64, 16, v76
	v_exp_f32_e32 v58, v50
	v_mul_f32_e32 v50, 0x3d372713, v53
	v_mul_f32_e32 v65, 0x3d372713, v64
	v_mul_f32_e32 v50, v50, v53
	v_mul_f32_e32 v65, v65, v64
	v_fma_f32 v50, v50, v53, v53
	v_fma_f32 v65, v65, v64, v64
	v_mul_f32_e32 v50, 0x3f4c422a, v50
	v_mul_f32_e32 v65, 0x3f4c422a, v65
	v_mul_f32_e32 v50, 0xc038aa3b, v50
	v_mul_f32_e32 v65, 0xc038aa3b, v65
	v_lshlrev_b32_e32 v51, 16, v93
	v_exp_f32_e32 v59, v50
	v_lshlrev_b32_e32 v50, 16, v92
	v_exp_f32_e32 v68, v65
	s_waitcnt vmcnt(6)
	v_lshlrev_b32_e32 v65, 16, v77
	v_pk_mul_f32 v[16:17], v[60:61], v[66:67]
	v_mul_f32_e32 v60, 0x3d372713, v50
	v_mul_f32_e32 v61, 0x3d372713, v51
	v_mul_f32_e32 v69, 0x3d372713, v65
	v_mul_f32_e32 v60, v60, v50
	v_mul_f32_e32 v61, v61, v51
	v_mul_f32_e32 v69, v69, v65
	v_fma_f32 v60, v60, v50, v50
	v_fma_f32 v61, v61, v51, v51
	v_fma_f32 v69, v69, v65, v65
	v_mul_f32_e32 v60, 0x3f4c422a, v60
	v_mul_f32_e32 v61, 0x3f4c422a, v61
	s_waitcnt vmcnt(4)
	v_lshlrev_b32_e32 v67, 16, v79
	v_lshlrev_b32_e32 v66, 16, v78
	v_mul_f32_e32 v69, 0x3f4c422a, v69
	v_mul_f32_e32 v60, 0xc038aa3b, v60
	v_mul_f32_e32 v61, 0xc038aa3b, v61
	v_mul_f32_e32 v69, 0xc038aa3b, v69
	v_mul_f32_e32 v70, 0x3d372713, v66
	v_mul_f32_e32 v71, 0x3d372713, v67
	v_exp_f32_e32 v60, v60
	v_exp_f32_e32 v61, v61
	v_exp_f32_e32 v69, v69
	v_mul_f32_e32 v70, v70, v66
	v_mul_f32_e32 v71, v71, v67
	v_fma_f32 v70, v70, v66, v66
	v_fma_f32 v71, v71, v67, v67
	v_mul_f32_e32 v70, 0x3f4c422a, v70
	v_mul_f32_e32 v71, 0x3f4c422a, v71
	v_mul_f32_e32 v70, 0xc038aa3b, v70
	v_mul_f32_e32 v71, 0xc038aa3b, v71
	v_add_f32_e32 v60, 1.0, v60
	v_add_f32_e32 v61, 1.0, v61
	v_add_f32_e32 v68, 1.0, v68
	v_exp_f32_e32 v70, v70
	v_exp_f32_e32 v71, v71
	v_add_f32_e32 v69, 1.0, v69
	v_add_f32_e32 v58, 1.0, v58
	v_add_f32_e32 v59, 1.0, v59
	v_rcp_f32_e32 v60, v60
	v_rcp_f32_e32 v61, v61
	v_rcp_f32_e32 v68, v68
	v_rcp_f32_e32 v69, v69
	v_rcp_f32_e32 v58, v58
	v_rcp_f32_e32 v59, v59
	v_add_f32_e32 v70, 1.0, v70
	v_add_f32_e32 v71, 1.0, v71
	v_rcp_f32_e32 v70, v70
	v_rcp_f32_e32 v71, v71
	v_pk_mul_f32 v[50:51], v[60:61], v[50:51]
	v_pk_mul_f32 v[60:61], v[68:69], v[64:65]
	v_pk_mul_f32 v[52:53], v[58:59], v[52:53]
	v_pk_mul_f32 v[64:65], v[60:61], v[60:61]
	v_pk_mul_f32 v[58:59], v[70:71], v[66:67]
	v_pk_fma_f32 v[64:65], v[52:53], v[52:53], v[64:65]
	v_mov_b32_e32 v68, v64
	v_mov_b32_e32 v69, v65
	s_nop 0
	v_permlane32_swap_b32_e32 v68, v64
	v_permlane32_swap_b32_e32 v69, v65
	v_pk_mul_f32 v[66:67], v[58:59], v[58:59]
	v_pk_mul_f32 v[16:17], v[0:1], v[16:17] op_sel_hi:[0,1]
	v_pk_fma_f32 v[66:67], v[50:51], v[50:51], v[66:67]
	v_mov_b32_e32 v70, v66
	v_mov_b32_e32 v71, v67
	s_nop 0
	v_permlane32_swap_b32_e32 v70, v66
	v_permlane32_swap_b32_e32 v71, v67
	s_waitcnt lgkmcnt(2)
	v_pk_add_f32 v[64:65], v[64:65], v[68:69]
	v_mov_b32_e32 v68, v64
	v_mov_b32_e32 v69, v65
	s_nop 0
	v_permlane16_swap_b32_e32 v68, v64
	v_permlane16_swap_b32_e32 v69, v65
	v_bfe_u32 v81, v17, 16, 1
	s_waitcnt lgkmcnt(2)
	v_pk_add_f32 v[66:67], v[66:67], v[70:71]
	v_mov_b32_e32 v70, v66
	v_mov_b32_e32 v71, v67
	s_nop 0
	v_permlane16_swap_b32_e32 v70, v66
	v_permlane16_swap_b32_e32 v71, v67
	s_waitcnt lgkmcnt(2)
	v_pk_add_f32 v[64:65], v[64:65], v[68:69]
	s_nop 1
	v_mov_b32_dpp v68, v64 row_ror:8 row_mask:0xf bank_mask:0xf
	v_mov_b32_dpp v69, v65 row_ror:8 row_mask:0xf bank_mask:0xf
	v_bfe_u32 v76, v16, 16, 1
	s_waitcnt lgkmcnt(2)
	v_pk_add_f32 v[66:67], v[66:67], v[70:71]
	s_nop 1
	v_mov_b32_dpp v70, v66 row_ror:8 row_mask:0xf bank_mask:0xf
	v_mov_b32_dpp v71, v67 row_ror:8 row_mask:0xf bank_mask:0xf
	v_add3_u32 v76, v16, v76, s11
	v_add3_u32 v77, v17, v81, s11
	s_waitcnt lgkmcnt(2)
	v_pk_add_f32 v[16:17], v[64:65], v[68:69]
	s_nop 1
	v_mov_b32_dpp v64, v16 row_shl:4 row_mask:0xf bank_mask:0x5
	v_mov_b32_dpp v64, v16 row_shr:4 row_mask:0xf bank_mask:0xa
	v_mov_b32_dpp v65, v17 row_shl:4 row_mask:0xf bank_mask:0x5
	v_mov_b32_dpp v65, v17 row_shr:4 row_mask:0xf bank_mask:0xa
	s_waitcnt lgkmcnt(2)
	v_pk_add_f32 v[66:67], v[66:67], v[70:71]
	s_nop 1
	v_mov_b32_dpp v68, v66 row_shl:4 row_mask:0xf bank_mask:0x5
	v_mov_b32_dpp v68, v66 row_shr:4 row_mask:0xf bank_mask:0xa
	v_mov_b32_dpp v69, v67 row_shl:4 row_mask:0xf bank_mask:0x5
	v_mov_b32_dpp v69, v67 row_shr:4 row_mask:0xf bank_mask:0xa
	v_pk_mul_f32 v[14:15], v[0:1], v[14:15] op_sel_hi:[0,1]
	s_waitcnt lgkmcnt(2)
	v_pk_add_f32 v[16:17], v[16:17], v[64:65]
	s_nop 1
	v_mov_b32_dpp v64, v16 quad_perm:[2,3,0,1] row_mask:0xf bank_mask:0xf
	v_mov_b32_dpp v65, v17 quad_perm:[2,3,0,1] row_mask:0xf bank_mask:0xf
	s_waitcnt lgkmcnt(2)
	v_pk_add_f32 v[66:67], v[66:67], v[68:69]
	s_nop 1
	v_mov_b32_dpp v68, v66 quad_perm:[2,3,0,1] row_mask:0xf bank_mask:0xf
	v_mov_b32_dpp v69, v67 quad_perm:[2,3,0,1] row_mask:0xf bank_mask:0xf
	v_bfe_u32 v63, v15, 16, 1
	s_waitcnt lgkmcnt(2)
	v_pk_add_f32 v[64:65], v[16:17], v[64:65]
	s_nop 1
	v_mov_b32_dpp v70, v64 quad_perm:[1,0,3,2] row_mask:0xf bank_mask:0xf
	v_mov_b32_dpp v71, v65 quad_perm:[1,0,3,2] row_mask:0xf bank_mask:0xf
	s_waitcnt lgkmcnt(2)
	v_pk_add_f32 v[66:67], v[66:67], v[68:69]
	s_nop 1
	v_mov_b32_dpp v68, v66 quad_perm:[1,0,3,2] row_mask:0xf bank_mask:0xf
	v_mov_b32_dpp v69, v67 quad_perm:[1,0,3,2] row_mask:0xf bank_mask:0xf
	v_bfe_u32 v80, v14, 16, 1
	s_waitcnt lgkmcnt(2)
	v_pk_add_f32 v[64:65], v[64:65], v[70:71]
	v_add3_u32 v14, v14, v80, s11
	v_add3_u32 v15, v15, v63, s11
	v_pk_fma_f32 v[64:65], v[64:65], s[96:97], v[6:7] op_sel_hi:[1,0,0]
	v_perm_b32 v17, v15, v14, s12
	v_mul_f32_e32 v14, 0x4b800000, v64
	v_cmp_gt_f32_e64 s[0:1], s77, v64
	s_waitcnt lgkmcnt(0)
; DI bf16_t f2bf(float f) { unsigned u = __float_as_uint(f); u += 0x7fffu + ((u >> 16) & 1u); return (bf16_t)(u >> 16); }
; DI float wave_sum(float v) { for (int o = 32; o; o >>= 1) v += __shfl_xor(v, o); return v; }
; DI float geluf_(float x) { const float u = 0.7978845608028654f * (x + 0.044715f * x * x * x); return x * __builtin_amdgcn_rcpf(1.f + __builtin_amdgcn_exp2f(-2.f * LOG2E * u)); }
; DI void sg_item(int item, const bf16_t* proj, const bf16_t* sgw, const float* vng, const float* bs, bf16_t* obuf, unsigned char* smem, const int tid) {
;     ...
;     for (int e = 0; e < 16; ++e) { const int tt = wv * 16 + e;
;         const float a0 = geluf_(va[e][0]), a1 = geluf_(va[e][1]);
;         const float ss = wave_sum(a0 * a0 + a1 * a1); const float rs = rsqrtf(ss * (1.f / 128.f) + NEPS);
;         vT[lane * 136 + tt] = f2bf(a0 * rs * g0); vT[(lane + 64) * 136 + tt] = f2bf(a1 * rs * g1); }
	v_pk_add_f32 v[66:67], v[66:67], v[68:69]
	v_cmp_gt_f32_e64 s[40:41], s77, v65
	v_cndmask_b32_e64 v14, v64, v14, s[0:1]
	v_rsq_f32_e32 v64, v14
	v_mul_f32_e32 v14, 0x4b800000, v65
	v_pk_fma_f32 v[66:67], v[66:67], s[96:97], v[6:7] op_sel_hi:[1,0,0]
	v_cndmask_b32_e64 v14, v65, v14, s[40:41]
	v_mul_f32_e32 v63, 0x4b800000, v66
	v_cmp_gt_f32_e32 vcc, s77, v66
	v_rsq_f32_e32 v65, v14
	v_cmp_gt_f32_e64 s[42:43], s77, v67
	v_cndmask_b32_e32 v63, v66, v63, vcc
	v_rsq_f32_e32 v66, v63
	v_mul_f32_e32 v63, 0x4b800000, v67
	v_perm_b32 v16, v77, v76, s12
	v_perm_b32 v15, v72, v73, s12
	v_cndmask_b32_e64 v63, v67, v63, s[42:43]
	v_perm_b32 v14, v74, v75, s12
	v_lshlrev_b32_e32 v56, 16, v56
	v_rsq_f32_e32 v67, v63
	ds_write_b128 v9, v[14:17] offset:17408
	v_pk_mul_f32 v[16:17], v[64:65], s[56:57] op_sel_hi:[1,0]
	v_mul_f32_e32 v63, 0x3d372713, v56
	v_cndmask_b32_e64 v17, v65, v17, s[40:41]
	v_mul_f32_e32 v63, v63, v56
	v_mov_b32_e32 v65, v56
	v_lshlrev_b32_e32 v57, 16, v57
	v_fmac_f32_e32 v65, v63, v65
	v_mul_f32_e32 v63, 0x3f4c422a, v65
	v_mul_f32_e32 v65, 0x3d372713, v57
	v_mul_f32_e32 v65, v65, v57
	v_mov_b32_e32 v68, v57
	v_fmac_f32_e32 v68, v65, v68
	v_mul_f32_e32 v63, 0xc038aa3b, v63
	v_mul_f32_e32 v65, 0x3f4c422a, v68
	v_exp_f32_e32 v63, v63
	v_mul_f32_e32 v65, 0xc038aa3b, v65
	v_exp_f32_e32 v65, v65
	s_waitcnt vmcnt(3)
	v_lshlrev_b32_e32 v12, 16, v12
	v_add_f32_e32 v63, 1.0, v63
	v_cndmask_b32_e64 v16, v64, v16, s[0:1]
	v_rcp_f32_e32 v64, v63
	v_add_f32_e32 v63, 1.0, v65
	v_mul_f32_e32 v65, 0x3d372713, v12
	v_mul_f32_e32 v65, v65, v12
	v_mov_b32_e32 v68, v12
	v_fmac_f32_e32 v68, v65, v68
	v_mul_f32_e32 v65, 0x3f4c422a, v68
	s_waitcnt vmcnt(2)
	v_lshlrev_b32_e32 v13, 16, v13
	v_mul_f32_e32 v65, 0xc038aa3b, v65
	v_exp_f32_e32 v68, v65
	v_mul_f32_e32 v65, 0x3d372713, v13
	v_mul_f32_e32 v65, v65, v13
	v_mov_b32_e32 v69, v13
	v_fmac_f32_e32 v69, v65, v69
	v_mul_f32_e32 v65, 0x3f4c422a, v69
	v_mul_f32_e32 v65, 0xc038aa3b, v65
	v_exp_f32_e32 v69, v65
	v_rcp_f32_e32 v65, v63
	v_add_f32_e32 v63, 1.0, v68
	v_rcp_f32_e32 v68, v63
	v_add_f32_e32 v63, 1.0, v69
	v_rcp_f32_e32 v69, v63
	v_pk_mul_f32 v[56:57], v[64:65], v[56:57]
	v_pk_mul_f32 v[14:15], v[66:67], s[56:57] op_sel_hi:[1,0]
	v_pk_mul_f32 v[52:53], v[52:53], v[16:17]
	v_pk_mul_f32 v[64:65], v[68:69], v[12:13]
	v_cndmask_b32_e64 v15, v67, v15, s[42:43]
	v_pk_mul_f32 v[12:13], v[64:65], v[64:65]
	v_cndmask_b32_e32 v14, v66, v14, vcc
	v_pk_fma_f32 v[12:13], v[56:57], v[56:57], v[12:13]
	v_mov_b32_e32 v66, v12
	v_mov_b32_e32 v67, v13
	s_nop 0
	v_permlane32_swap_b32_e32 v66, v12
	v_permlane32_swap_b32_e32 v67, v13
	v_pk_mul_f32 v[50:51], v[50:51], v[14:15]
	v_pk_mul_f32 v[52:53], v[4:5], v[52:53] op_sel_hi:[0,1]
	v_pk_mul_f32 v[50:51], v[4:5], v[50:51] op_sel_hi:[0,1]
	v_bfe_u32 v63, v51, 16, 1
	s_waitcnt lgkmcnt(0)
	v_pk_add_f32 v[12:13], v[12:13], v[66:67]
	v_mov_b32_e32 v66, v12
	v_mov_b32_e32 v67, v13
	s_nop 0
	v_permlane16_swap_b32_e32 v66, v12
	v_permlane16_swap_b32_e32 v67, v13
	v_bfe_u32 v68, v50, 16, 1
	v_add3_u32 v68, v50, v68, s11
	v_add3_u32 v63, v51, v63, s11
	v_pk_mul_f32 v[14:15], v[58:59], v[14:15]
	s_waitcnt lgkmcnt(0)
	v_pk_add_f32 v[12:13], v[12:13], v[66:67]
	s_nop 1
	v_mov_b32_dpp v66, v12 row_ror:8 row_mask:0xf bank_mask:0xf
	v_mov_b32_dpp v67, v13 row_ror:8 row_mask:0xf bank_mask:0xf
	v_bfe_u32 v69, v53, 16, 1
	v_pk_mul_f32 v[14:15], v[0:1], v[14:15] op_sel_hi:[0,1]
	v_bfe_u32 v70, v52, 16, 1
	v_add3_u32 v69, v53, v69, s11
	s_waitcnt lgkmcnt(0)
	v_pk_add_f32 v[12:13], v[12:13], v[66:67]
	s_nop 1
	v_mov_b32_dpp v50, v12 row_shl:4 row_mask:0xf bank_mask:0x5
	v_mov_b32_dpp v50, v12 row_shr:4 row_mask:0xf bank_mask:0xa
	v_mov_b32_dpp v51, v13 row_shl:4 row_mask:0xf bank_mask:0x5
	v_mov_b32_dpp v51, v13 row_shr:4 row_mask:0xf bank_mask:0xa
	v_pk_mul_f32 v[16:17], v[60:61], v[16:17]
	v_bfe_u32 v53, v14, 16, 1
	v_add3_u32 v70, v52, v70, s11
	v_pk_mul_f32 v[16:17], v[0:1], v[16:17] op_sel_hi:[0,1]
	s_waitcnt lgkmcnt(0)
	v_pk_add_f32 v[12:13], v[12:13], v[50:51]
	s_nop 1
	v_mov_b32_dpp v50, v12 quad_perm:[2,3,0,1] row_mask:0xf bank_mask:0xf
	v_mov_b32_dpp v51, v13 quad_perm:[2,3,0,1] row_mask:0xf bank_mask:0xf
	v_bfe_u32 v52, v15, 16, 1
	v_add3_u32 v60, v14, v53, s11
	v_lshlrev_b32_e32 v14, 16, v55
	v_bfe_u32 v58, v17, 16, 1
	s_waitcnt lgkmcnt(0)
	v_pk_add_f32 v[12:13], v[12:13], v[50:51]
	s_nop 1
	v_mov_b32_dpp v50, v12 quad_perm:[1,0,3,2] row_mask:0xf bank_mask:0xf
	v_mov_b32_dpp v51, v13 quad_perm:[1,0,3,2] row_mask:0xf bank_mask:0xf
	v_add3_u32 v61, v15, v52, s11
	s_waitcnt vmcnt(1)
	v_lshlrev_b32_e32 v15, 16, v11
	v_mul_f32_e32 v11, 0x3d372713, v14
	v_add3_u32 v58, v17, v58, s11
	v_mul_f32_e32 v11, v11, v14
	v_mov_b32_e32 v17, v14
	v_fmac_f32_e32 v17, v11, v17
	v_mul_f32_e32 v11, 0x3f4c422a, v17
	v_mul_f32_e32 v17, 0x3d372713, v15
	s_waitcnt lgkmcnt(0)
	v_pk_add_f32 v[12:13], v[12:13], v[50:51]
	v_mul_f32_e32 v17, v17, v15
	v_mov_b32_e32 v50, v15
	v_fmac_f32_e32 v50, v17, v50
	v_mul_f32_e32 v11, 0xc038aa3b, v11
	v_mul_f32_e32 v17, 0x3f4c422a, v50
	v_exp_f32_e32 v11, v11
	v_mul_f32_e32 v17, 0xc038aa3b, v17
	v_exp_f32_e32 v17, v17
	v_bfe_u32 v59, v16, 16, 1
	v_pk_fma_f32 v[12:13], v[12:13], s[96:97], v[6:7] op_sel_hi:[1,0,0]
	v_lshlrev_b32_e32 v50, 16, v54
	v_add3_u32 v59, v16, v59, s11
	v_mul_f32_e32 v16, 0x4b800000, v12
	v_cmp_gt_f32_e32 vcc, s77, v12
	v_add_f32_e32 v11, 1.0, v11
	s_waitcnt vmcnt(0)
; DI float bf2f(bf16_t b) { return __uint_as_float(((unsigned)b) << 16); }
; DI bf16_t f2bf(float f) { unsigned u = __float_as_uint(f); u += 0x7fffu + ((u >> 16) & 1u); return (bf16_t)(u >> 16); }
; DI float wave_sum(float v) { for (int o = 32; o; o >>= 1) v += __shfl_xor(v, o); return v; }
; DI float geluf_(float x) { const float u = 0.7978845608028654f * (x + 0.044715f * x * x * x); return x * __builtin_amdgcn_rcpf(1.f + __builtin_amdgcn_exp2f(-2.f * LOG2E * u)); }
; DI int crow(int i, int h) { return (i & 3) + 8 * (i >> 2) + 4 * h; }
; DI void sg_item(int item, const bf16_t* proj, const bf16_t* sgw, const float* vng, const float* bs, bf16_t* obuf, unsigned char* smem, const int tid) {
;     ...
;     for (int e = 0; e < 16; ++e) { const int tt = wv * 16 + e;
;         const float a0 = geluf_(va[e][0]), a1 = geluf_(va[e][1]);
;         const float ss = wave_sum(a0 * a0 + a1 * a1); const float rs = rsqrtf(ss * (1.f / 128.f) + NEPS);
;         vT[lane * 136 + tt] = f2bf(a0 * rs * g0); vT[(lane + 64) * 136 + tt] = f2bf(a1 * rs * g1); }
;     __syncthreads();
; #pragma unroll
;     for (int ci = 0; ci < 2; ++ci) { const int cb = 2 * (wv & 1) + ci; const int c = 32 * cb + r;
;         float uv[16];
; #pragma unroll
;         for (int i = 0; i < 16; ++i) uv[i] = bf2f(proj[(size_t)(t0 + 32 * tb + crow(i, h2)) * PLD + 2496 + g * 128 + c]);
	v_lshlrev_b32_e32 v51, 16, v10
	v_mul_f32_e32 v10, 0x3d372713, v50
	v_cndmask_b32_e32 v12, v12, v16, vcc
	v_rcp_f32_e32 v16, v11
	v_add_f32_e32 v11, 1.0, v17
	v_mul_f32_e32 v10, v10, v50
	v_mov_b32_e32 v17, v50
	v_fmac_f32_e32 v17, v10, v17
	v_mul_f32_e32 v10, 0x3f4c422a, v17
	v_mul_f32_e32 v17, 0x3d372713, v51
	v_mul_f32_e32 v17, v17, v51
	v_mov_b32_e32 v52, v51
	v_fmac_f32_e32 v52, v17, v52
	v_mul_f32_e32 v17, 0x3f4c422a, v52
	v_mul_f32_e32 v10, 0xc038aa3b, v10
	v_mul_f32_e32 v17, 0xc038aa3b, v17
	v_exp_f32_e32 v10, v10
	v_exp_f32_e32 v52, v17
	v_rcp_f32_e32 v17, v11
	v_cmp_gt_f32_e64 s[0:1], s77, v13
	v_add_f32_e32 v10, 1.0, v10
	v_add_f32_e32 v11, 1.0, v52
	v_rcp_f32_e32 v10, v10
	v_rcp_f32_e32 v11, v11
	v_pk_mul_f32 v[14:15], v[16:17], v[14:15]
	v_rsq_f32_e32 v12, v12
	v_pk_mul_f32 v[16:17], v[14:15], v[14:15]
	v_pk_mul_f32 v[50:51], v[10:11], v[50:51]
	v_mov_b32_e32 v53, v16
	v_pk_mul_f32 v[10:11], v[50:51], v[50:51]
	v_and_b32_e32 v126, 0x5f, v196
	v_mov_b32_e32 v52, v10
	v_mov_b32_e32 v16, v11
	v_pk_add_f32 v[10:11], v[52:53], v[16:17]
	v_mov_b32_e32 v17, v11
	v_mov_b32_e32 v16, v10
	s_nop 0
	v_permlane32_swap_b32_e32 v17, v11
	v_permlane32_swap_b32_e32 v16, v10
	v_mul_f32_e32 v52, 0x4b800000, v13
	v_cndmask_b32_e64 v13, v13, v52, s[0:1]
	v_rsq_f32_e32 v13, v13
	v_add_u32_e32 v127, 0, v198
	s_waitcnt lgkmcnt(0)
	v_pk_add_f32 v[10:11], v[10:11], v[16:17]
	v_mov_b32_e32 v17, v11
	v_mov_b32_e32 v16, v10
	s_nop 0
	v_permlane16_swap_b32_e32 v17, v11
	v_permlane16_swap_b32_e32 v16, v10
	v_pk_mul_f32 v[52:53], v[12:13], s[56:57] op_sel_hi:[1,0]
	s_waitcnt lgkmcnt(0)
	v_pk_add_f32 v[10:11], v[10:11], v[16:17]
	s_nop 1
	v_mov_b32_dpp v17, v11 row_ror:8 row_mask:0xf bank_mask:0xf
	v_mov_b32_dpp v16, v10 row_ror:8 row_mask:0xf bank_mask:0xf
	v_cndmask_b32_e64 v53, v13, v53, s[0:1]
	v_cndmask_b32_e32 v52, v12, v52, vcc
	v_pk_mul_f32 v[12:13], v[56:57], v[52:53]
	s_and_b32 s0, s14, 0x7ffffc
	v_pk_mul_f32 v[12:13], v[4:5], v[12:13] op_sel_hi:[0,1]
	v_and_b32_sdwa v54, v12, v241 dst_sel:DWORD dst_unused:UNUSED_PAD src0_sel:WORD_1 src1_sel:DWORD
	s_waitcnt lgkmcnt(0)
	v_pk_add_f32 v[16:17], v[10:11], v[16:17]
	v_add3_u32 v12, v12, v54, s11
	s_nop 1
	v_mov_b32_dpp v55, v17 row_shl:4 row_mask:0xf bank_mask:0x5
	v_mov_b32_dpp v55, v17 row_shr:4 row_mask:0xf bank_mask:0xa
	v_mov_b32_dpp v54, v16 row_shl:4 row_mask:0xf bank_mask:0x5
	v_mov_b32_dpp v54, v16 row_shr:4 row_mask:0xf bank_mask:0xa
	v_and_b32_sdwa v56, v13, v241 dst_sel:DWORD dst_unused:UNUSED_PAD src0_sel:WORD_1 src1_sel:DWORD
	v_add3_u32 v10, v13, v56, s11
	v_perm_b32 v12, v10, v12, s12
	v_perm_b32 v11, v63, v68, s12
	s_waitcnt lgkmcnt(0)
	v_pk_add_f32 v[16:17], v[16:17], v[54:55]
	s_nop 1
	v_mov_b32_dpp v55, v17 quad_perm:[2,3,0,1] row_mask:0xf bank_mask:0xf
	v_mov_b32_dpp v54, v16 quad_perm:[2,3,0,1] row_mask:0xf bank_mask:0xf
	v_perm_b32 v10, v69, v70, s12
	ds_write_b96 v9, v[10:12] offset:16
	v_pk_mul_f32 v[10:11], v[64:65], v[52:53]
	v_lshl_or_b32 v5, v5, 1, 30
	s_waitcnt lgkmcnt(1)
	v_pk_add_f32 v[16:17], v[16:17], v[54:55]
	s_nop 1
	v_mov_b32_dpp v53, v17 quad_perm:[1,0,3,2] row_mask:0xf bank_mask:0xf
	v_mov_b32_dpp v52, v16 quad_perm:[1,0,3,2] row_mask:0xf bank_mask:0xf
	v_pk_mul_f32 v[10:11], v[0:1], v[10:11] op_sel_hi:[0,1]
	v_and_b32_sdwa v12, v11, v241 dst_sel:DWORD dst_unused:UNUSED_PAD src0_sel:WORD_1 src1_sel:DWORD
	v_and_b32_sdwa v13, v10, v241 dst_sel:DWORD dst_unused:UNUSED_PAD src0_sel:WORD_1 src1_sel:DWORD
	v_add3_u32 v10, v10, v13, s11
	v_add3_u32 v11, v11, v12, s11
	v_perm_b32 v12, v11, v10, s12
	s_waitcnt lgkmcnt(0)
	v_pk_add_f32 v[10:11], v[16:17], v[52:53]
	v_add_u32_e32 v5, v8, v5
	v_pk_fma_f32 v[6:7], v[10:11], s[96:97], v[6:7] op_sel_hi:[1,0,0]
	v_perm_b32 v11, v61, v60, s12
	v_mul_f32_e32 v10, 0x4b800000, v7
	v_cmp_gt_f32_e32 vcc, s77, v7
	s_nop 1
	v_cndmask_b32_e32 v7, v7, v10, vcc
	v_rsq_f32_e32 v7, v7
	v_perm_b32 v10, v58, v59, s12
	ds_write_b96 v9, v[10:12] offset:17424
	v_mul_f32_e32 v10, 0x45800000, v7
	v_cndmask_b32_e32 v7, v7, v10, vcc
	v_mul_f32_e32 v10, v14, v7
	v_mul_f32_e32 v10, v4, v10
	v_bfe_u32 v11, v10, 16, 1
	v_add3_u32 v10, v10, v11, s11
	ds_write_b16_d16_hi v9, v10 offset:28
	v_mul_f32_e32 v10, 0x4b800000, v6
	v_cmp_gt_f32_e32 vcc, s77, v6
	v_mul_f32_e32 v7, v15, v7
	v_mul_f32_e32 v7, v0, v7
	v_cndmask_b32_e32 v6, v6, v10, vcc
	v_rsq_f32_e32 v6, v6
	v_bfe_u32 v10, v7, 16, 1
	v_add3_u32 v7, v7, v10, s11
	ds_write_b16_d16_hi v9, v7 offset:17436
	v_mul_f32_e32 v7, 0x45800000, v6
	v_cndmask_b32_e32 v6, v6, v7, vcc
	v_mul_f32_e32 v7, v50, v6
	v_mul_f32_e32 v4, v4, v7
	v_bfe_u32 v7, v4, 16, 1
	v_add3_u32 v4, v4, v7, s11
	ds_write_b16_d16_hi v5, v4
	v_mul_f32_e32 v4, v51, v6
	v_mul_f32_e32 v0, v0, v4
	v_bfe_u32 v4, v0, 16, 1
	v_add3_u32 v0, v0, v4, s11
	ds_write_b16_d16_hi v5, v0 offset:17408
	v_add_u32_e32 v0, s0, v62
	v_lshlrev_b32_e32 v50, 2, v180
	v_lshl_or_b32 v51, v0, 5, v50
	v_mad_i64_i32 v[4:5], s[0:1], v51, s3, v[2:3]
	v_lshl_add_u64 v[4:5], v[4:5], 0, s[4:5]
	v_lshlrev_b32_e32 v0, 1, v126
	v_or_b32_e32 v6, 1, v51
	v_lshl_add_u64 v[52:53], v[4:5], 0, v[0:1]
	v_mad_i64_i32 v[6:7], s[0:1], v6, s3, v[2:3]
	v_add_co_u32_e32 v4, vcc, s87, v52
	v_lshl_add_u64 v[6:7], v[6:7], 0, s[4:5]
	v_or_b32_e32 v8, 2, v51
	v_addc_co_u32_e32 v5, vcc, 0, v53, vcc
	v_lshl_add_u64 v[54:55], v[6:7], 0, v[0:1]
	v_mad_i64_i32 v[8:9], s[0:1], v8, s3, v[2:3]
	v_add_co_u32_e32 v6, vcc, s87, v54
	v_lshl_add_u64 v[8:9], v[8:9], 0, s[4:5]
	v_or_b32_e32 v10, 3, v51
	v_addc_co_u32_e32 v7, vcc, 0, v55, vcc
	v_lshl_add_u64 v[56:57], v[8:9], 0, v[0:1]
	v_mad_i64_i32 v[10:11], s[0:1], v10, s3, v[2:3]
	v_add_co_u32_e32 v8, vcc, s87, v56
	v_lshl_add_u64 v[10:11], v[10:11], 0, s[4:5]
	v_or_b32_e32 v12, 8, v51
	v_addc_co_u32_e32 v9, vcc, 0, v57, vcc
	v_lshl_add_u64 v[58:59], v[10:11], 0, v[0:1]
	v_mad_i64_i32 v[12:13], s[0:1], v12, s3, v[2:3]
	v_add_co_u32_e32 v10, vcc, s87, v58
	v_lshl_add_u64 v[12:13], v[12:13], 0, s[4:5]
	v_or_b32_e32 v14, 9, v51
	v_addc_co_u32_e32 v11, vcc, 0, v59, vcc
	v_lshl_add_u64 v[60:61], v[12:13], 0, v[0:1]
	v_mad_i64_i32 v[14:15], s[0:1], v14, s3, v[2:3]
	v_add_co_u32_e32 v12, vcc, s87, v60
	v_lshl_add_u64 v[14:15], v[14:15], 0, s[4:5]
	v_or_b32_e32 v16, 10, v51
	v_addc_co_u32_e32 v13, vcc, 0, v61, vcc
	v_lshl_add_u64 v[66:67], v[14:15], 0, v[0:1]
	v_mad_i64_i32 v[16:17], s[0:1], v16, s3, v[2:3]
	v_add_co_u32_e32 v14, vcc, s87, v66
	v_lshl_add_u64 v[16:17], v[16:17], 0, s[4:5]
	v_or_b32_e32 v63, 11, v51
	v_addc_co_u32_e32 v15, vcc, 0, v67, vcc
	v_lshl_add_u64 v[68:69], v[16:17], 0, v[0:1]
	v_mad_i64_i32 v[64:65], s[0:1], v63, s3, v[2:3]
	v_add_co_u32_e32 v16, vcc, s87, v68
	v_lshl_add_u64 v[64:65], v[64:65], 0, s[4:5]
	s_nop 0
	v_addc_co_u32_e32 v17, vcc, 0, v69, vcc
	v_lshl_add_u64 v[74:75], v[64:65], 0, v[0:1]
	v_add_co_u32_e32 v64, vcc, s87, v74
	s_waitcnt lgkmcnt(0)
	s_barrier
; DI float bf2f(bf16_t b) { return __uint_as_float(((unsigned)b) << 16); }
; DI int crow(int i, int h) { return (i & 3) + 8 * (i >> 2) + 4 * h; }
; DI void sg_item(int item, const bf16_t* proj, const bf16_t* sgw, const float* vng, const float* bs, bf16_t* obuf, unsigned char* smem, const int tid) {
;     ...
;     for (int ci = 0; ci < 2; ++ci) { const int cb = 2 * (wv & 1) + ci; const int c = 32 * cb + r;
;         float uv[16];
; #pragma unroll
;         for (int i = 0; i < 16; ++i) uv[i] = bf2f(proj[(size_t)(t0 + 32 * tb + crow(i, h2)) * PLD + 2496 + g * 128 + c]);
;         f32x16 acc; for (int i = 0; i < 16; ++i) acc[i] = 0.f;
	v_addc_co_u32_e32 v65, vcc, 0, v75, vcc
	global_load_ushort v94, v[4:5], off offset:896
	global_load_ushort v95, v[6:7], off offset:896
	global_load_ushort v96, v[8:9], off offset:896
	global_load_ushort v97, v[10:11], off offset:896
	global_load_ushort v124, v[12:13], off offset:896
	global_load_ushort v125, v[14:15], off offset:896
	global_load_ushort v128, v[16:17], off offset:896
	global_load_ushort v129, v[64:65], off offset:896
	v_or_b32_e32 v4, 16, v51
	v_mad_i64_i32 v[4:5], s[0:1], v4, s3, v[2:3]
	v_lshl_add_u64 v[4:5], v[4:5], 0, s[4:5]
	v_or_b32_e32 v6, 17, v51
	v_lshl_add_u64 v[76:77], v[4:5], 0, v[0:1]
	v_mad_i64_i32 v[6:7], s[0:1], v6, s3, v[2:3]
	v_add_co_u32_e32 v4, vcc, s87, v76
	v_lshl_add_u64 v[6:7], v[6:7], 0, s[4:5]
	v_or_b32_e32 v8, 18, v51
	v_addc_co_u32_e32 v5, vcc, 0, v77, vcc
	v_lshl_add_u64 v[80:81], v[6:7], 0, v[0:1]
	v_mad_i64_i32 v[8:9], s[0:1], v8, s3, v[2:3]
	v_add_co_u32_e32 v6, vcc, s87, v80
	v_lshl_add_u64 v[8:9], v[8:9], 0, s[4:5]
	v_or_b32_e32 v10, 19, v51
	v_addc_co_u32_e32 v7, vcc, 0, v81, vcc
	v_lshl_add_u64 v[82:83], v[8:9], 0, v[0:1]
	v_mad_i64_i32 v[10:11], s[0:1], v10, s3, v[2:3]
	v_add_co_u32_e32 v8, vcc, s87, v82
	v_lshl_add_u64 v[10:11], v[10:11], 0, s[4:5]
	v_or_b32_e32 v12, 24, v51
	v_addc_co_u32_e32 v9, vcc, 0, v83, vcc
	v_lshl_add_u64 v[84:85], v[10:11], 0, v[0:1]
	v_mad_i64_i32 v[12:13], s[0:1], v12, s3, v[2:3]
	v_add_co_u32_e32 v10, vcc, s87, v84
	v_lshl_add_u64 v[12:13], v[12:13], 0, s[4:5]
	v_or_b32_e32 v14, 25, v51
	v_addc_co_u32_e32 v11, vcc, 0, v85, vcc
	v_lshl_add_u64 v[86:87], v[12:13], 0, v[0:1]
	v_mad_i64_i32 v[14:15], s[0:1], v14, s3, v[2:3]
	v_add_co_u32_e32 v12, vcc, s87, v86
	v_lshl_add_u64 v[14:15], v[14:15], 0, s[4:5]
	v_or_b32_e32 v16, 26, v51
	v_addc_co_u32_e32 v13, vcc, 0, v87, vcc
	v_lshl_add_u64 v[88:89], v[14:15], 0, v[0:1]
	v_mad_i64_i32 v[16:17], s[0:1], v16, s3, v[2:3]
	v_add_co_u32_e32 v14, vcc, s87, v88
	v_lshl_add_u64 v[16:17], v[16:17], 0, s[4:5]
	v_or_b32_e32 v51, 27, v51
	v_addc_co_u32_e32 v15, vcc, 0, v89, vcc
	v_lshl_add_u64 v[90:91], v[16:17], 0, v[0:1]
	v_mad_i64_i32 v[2:3], s[0:1], v51, s3, v[2:3]
	v_add_co_u32_e32 v16, vcc, s87, v90
	v_lshl_add_u64 v[2:3], v[2:3], 0, s[4:5]
	s_nop 0
	v_addc_co_u32_e32 v17, vcc, 0, v91, vcc
	v_lshl_add_u64 v[92:93], v[2:3], 0, v[0:1]
	v_add_co_u32_e32 v2, vcc, 0x1000, v92
	v_mul_u32_u24_e32 v51, 0x110, v126
	s_nop 0
	v_addc_co_u32_e32 v3, vcc, 0, v93, vcc
	global_load_ushort v130, v[4:5], off offset:896
	global_load_ushort v131, v[6:7], off offset:896
	global_load_ushort v132, v[8:9], off offset:896
	global_load_ushort v133, v[10:11], off offset:896
	global_load_ushort v134, v[12:13], off offset:896
	global_load_ushort v135, v[14:15], off offset:896
	global_load_ushort v136, v[16:17], off offset:896
	global_load_ushort v137, v[2:3], off offset:896
	v_cmp_lt_i32_e32 vcc, -1, v62
	v_mov_b32_e32 v2, v1
	v_mov_b32_e32 v3, v1
	v_mov_b32_e32 v4, v1
	v_mov_b32_e32 v5, v1
	v_mov_b32_e32 v6, v1
	v_mov_b32_e32 v7, v1
	v_mov_b32_e32 v8, v1
	v_mov_b32_e32 v9, v1
	v_mov_b32_e32 v10, v1
	v_mov_b32_e32 v11, v1
	v_mov_b32_e32 v12, v1
	v_mov_b32_e32 v13, v1
	v_mov_b32_e32 v14, v1
	v_mov_b32_e32 v15, v1
	v_mov_b32_e32 v16, v1
	v_mov_b32_e32 v17, v1
	v_add_u32_e32 v51, v127, v51
	s_and_saveexec_b64 s[0:1], vcc
	s_cbranch_execnz .LBB0_266
	s_or_b64 exec, exec, s[0:1]
	s_and_saveexec_b64 s[0:1], vcc
	s_cbranch_execnz .LBB0_267

.LBB0_316:
	s_andn2_b64 vcc, exec, s[0:1]
	s_cbranch_vccnz .LBB0_313
	s_lshl_b64 s[0:1], s[4:5], 6
	v_lshl_add_u64 v[38:39], v[8:9], 0, s[0:1]
	v_mov_b64_e32 v[40:41], s[30:31]
	v_mad_u64_u32 v[40:41], s[0:1], v38, s3, v[40:41]
	v_mad_u32_u24 v41, v39, s3, v41
	s_lshl_b32 s0, s34, 1
	s_mov_b32 s1, s5
	v_lshlrev_b64 v[44:45], 12, v[38:39]
	v_lshl_add_u64 v[38:39], v[40:41], 0, s[0:1]
	v_lshlrev_b32_e32 v0, 1, v6
	v_lshl_add_u64 v[100:101], v[38:39], 0, v[0:1]
	v_lshl_add_u64 v[70:71], v[4:5], 0, v[44:45]
	global_load_dword v102, v[100:101], off offset:3072
	global_load_dword v99, v[70:71], off
	v_or_b32_e32 v38, 0x1000, v44
	v_mov_b32_e32 v39, v45
	v_lshl_add_u64 v[68:69], v[4:5], 0, v[38:39]
	global_load_dword v107, v[68:69], off
	s_movk_i32 s0, 0x3000
	v_add_co_u32_e32 v38, vcc, s0, v100
	s_movk_i32 s0, 0x5000
	s_nop 0
	v_addc_co_u32_e32 v39, vcc, 0, v101, vcc
	global_load_dword v109, v[38:39], off offset:896
	v_or_b32_e32 v38, 0x2000, v44
	v_mov_b32_e32 v39, v45
	v_lshl_add_u64 v[66:67], v[4:5], 0, v[38:39]
	v_add_co_u32_e32 v38, vcc, s0, v100
	global_load_dword v97, v[66:67], off
	s_nop 0
	v_addc_co_u32_e32 v39, vcc, 0, v101, vcc
	global_load_dword v98, v[38:39], off offset:2816
	v_or_b32_e32 v38, 0x3000, v44
	v_mov_b32_e32 v39, v45
	s_mov_b32 s0, 0x8000
	v_lshl_add_u64 v[64:65], v[4:5], 0, v[38:39]
	v_add_co_u32_e32 v38, vcc, s0, v100
	global_load_dword v95, v[64:65], off
	s_nop 0
	v_addc_co_u32_e32 v39, vcc, 0, v101, vcc
	global_load_dword v96, v[38:39], off offset:640
	v_or_b32_e32 v38, 0x4000, v44
	v_mov_b32_e32 v39, v45
	s_mov_b32 s0, 0xa000
	v_lshl_add_u64 v[62:63], v[4:5], 0, v[38:39]
	v_add_co_u32_e32 v38, vcc, s0, v100
	global_load_dword v93, v[62:63], off
	s_nop 0
	v_addc_co_u32_e32 v39, vcc, 0, v101, vcc
	global_load_dword v94, v[38:39], off offset:2560
	v_or_b32_e32 v38, 0x5000, v44
	v_mov_b32_e32 v39, v45
	s_mov_b32 s0, 0xd000
	v_lshl_add_u64 v[60:61], v[4:5], 0, v[38:39]
	v_add_co_u32_e32 v38, vcc, s0, v100
	s_mov_b32 s0, 0xf000
	s_nop 0
	v_addc_co_u32_e32 v39, vcc, 0, v101, vcc
	global_load_dword v92, v[38:39], off offset:384
	v_or_b32_e32 v38, 0x6000, v44
	v_mov_b32_e32 v39, v45
	v_lshl_add_u64 v[58:59], v[4:5], 0, v[38:39]
	v_add_co_u32_e32 v38, vcc, s0, v100
	s_mov_b32 s0, 0x12000
	s_nop 0
	v_addc_co_u32_e32 v39, vcc, 0, v101, vcc
	global_load_dword v90, v[38:39], off offset:2304
	v_or_b32_e32 v38, 0x7000, v44
	v_mov_b32_e32 v39, v45
	v_lshl_add_u64 v[56:57], v[4:5], 0, v[38:39]
	v_add_co_u32_e32 v38, vcc, s0, v100
	s_mov_b32 s0, 0x14000
	s_nop 0
	v_addc_co_u32_e32 v39, vcc, 0, v101, vcc
	global_load_dword v88, v[38:39], off offset:128
	v_or_b32_e32 v38, 0x8000, v44
	v_mov_b32_e32 v39, v45
	v_lshl_add_u64 v[54:55], v[4:5], 0, v[38:39]
	v_add_co_u32_e32 v38, vcc, s0, v100
	s_mov_b32 s0, 0x16000
	s_nop 0
	v_addc_co_u32_e32 v39, vcc, 0, v101, vcc
	global_load_dword v86, v[38:39], off offset:2048
	v_or_b32_e32 v38, 0x9000, v44
	v_mov_b32_e32 v39, v45
	v_lshl_add_u64 v[52:53], v[4:5], 0, v[38:39]
	v_add_co_u32_e32 v38, vcc, s0, v100
	s_mov_b32 s0, 0x19000
	s_nop 0
	v_addc_co_u32_e32 v39, vcc, 0, v101, vcc
	global_load_dword v84, v[38:39], off offset:3968
	v_or_b32_e32 v38, 0xa000, v44
	v_mov_b32_e32 v39, v45
	v_lshl_add_u64 v[50:51], v[4:5], 0, v[38:39]
	v_add_co_u32_e32 v38, vcc, s0, v100
	s_mov_b32 s0, 0x1b000
	s_nop 0
	v_addc_co_u32_e32 v39, vcc, 0, v101, vcc
	global_load_dword v82, v[38:39], off offset:1792
	v_or_b32_e32 v38, 0xb000, v44
	v_mov_b32_e32 v39, v45
	v_lshl_add_u64 v[48:49], v[4:5], 0, v[38:39]
	v_add_co_u32_e32 v38, vcc, s0, v100
	s_mov_b32 s0, 0x1e000
	s_nop 0
	v_addc_co_u32_e32 v39, vcc, 0, v101, vcc
	global_load_dword v80, v[38:39], off offset:3712
	v_or_b32_e32 v38, 0xc000, v44
	v_mov_b32_e32 v39, v45
	v_lshl_add_u64 v[46:47], v[4:5], 0, v[38:39]
	v_add_co_u32_e32 v38, vcc, s0, v100
	s_mov_b32 s0, 0x20000
	s_nop 0
	v_addc_co_u32_e32 v39, vcc, 0, v101, vcc
	global_load_dword v78, v[38:39], off offset:1536
	v_or_b32_e32 v38, 0xd000, v44
	v_mov_b32_e32 v39, v45
	v_lshl_add_u64 v[42:43], v[4:5], 0, v[38:39]
	v_add_co_u32_e32 v38, vcc, s0, v100
	s_mov_b32 s0, 0x23000
	s_nop 0
	v_addc_co_u32_e32 v39, vcc, 0, v101, vcc
	global_load_dword v76, v[38:39], off offset:3456
	v_or_b32_e32 v38, 0xe000, v44
	v_mov_b32_e32 v39, v45
	v_lshl_add_u64 v[40:41], v[4:5], 0, v[38:39]
	v_add_co_u32_e32 v38, vcc, s0, v100
	v_or_b32_e32 v44, 0xf000, v44
	s_nop 0
	v_addc_co_u32_e32 v39, vcc, 0, v101, vcc
	s_mov_b32 s0, 0x25000
	global_load_dword v74, v[38:39], off offset:1280
	v_lshl_add_u64 v[38:39], v[4:5], 0, v[44:45]
	v_add_co_u32_e32 v44, vcc, s0, v100
	s_waitcnt vmcnt(18)
	v_lshlrev_b32_e32 v100, 16, v99
	v_addc_co_u32_e32 v45, vcc, 0, v101, vcc
	global_load_dword v72, v[44:45], off offset:3200
	v_lshlrev_b32_e32 v44, 16, v102
	v_and_b32_e32 v101, 0xffff0000, v99
	v_mul_f32_e32 v99, 0xbfb8aa3b, v44
	v_exp_f32_e32 v99, v99
	v_and_b32_e32 v45, 0xffff0000, v102
	s_waitcnt vmcnt(18)
	v_lshlrev_b32_e32 v106, 16, v107
	v_and_b32_e32 v107, 0xffff0000, v107
	v_add_f32_e32 v99, 1.0, v99
	v_rcp_f32_e32 v104, v99
	v_mul_f32_e32 v99, 0xbfb8aa3b, v45
	v_exp_f32_e32 v99, v99
	v_pk_mul_f32 v[102:103], v[100:101], v[100:101]
	s_waitcnt vmcnt(17)
	v_lshlrev_b32_e32 v108, 16, v109
	v_mov_b32_e32 v111, v102
	v_add_f32_e32 v99, 1.0, v99
	v_rcp_f32_e32 v105, v99
	v_and_b32_e32 v109, 0xffff0000, v109
	global_load_dword v91, v[60:61], off
	global_load_dword v89, v[58:59], off
	global_load_dword v87, v[56:57], off
	global_load_dword v85, v[54:55], off
	global_load_dword v83, v[52:53], off
	global_load_dword v81, v[50:51], off
	global_load_dword v79, v[48:49], off
	global_load_dword v77, v[46:47], off
	v_pk_mul_f32 v[104:105], v[104:105], v[44:45]
	v_pk_mul_f32 v[44:45], v[106:107], v[106:107]
	global_load_dword v75, v[42:43], off
	global_load_dword v73, v[40:41], off
	global_load_dword v0, v[38:39], off
	v_mov_b32_e32 v110, v44
	v_mov_b32_e32 v102, v45
	v_pk_add_f32 v[44:45], v[110:111], v[102:103]
	v_mov_b32_e32 v103, v45
	v_mov_b32_e32 v102, v44
	s_nop 0
	v_permlane32_swap_b32_e32 v103, v45
	v_permlane32_swap_b32_e32 v102, v44
	s_waitcnt lgkmcnt(0)
	v_pk_add_f32 v[44:45], v[44:45], v[102:103]
	v_mov_b32_e32 v103, v45
	v_mov_b32_e32 v102, v44
	s_nop 0
	v_permlane16_swap_b32_e32 v103, v45
	v_permlane16_swap_b32_e32 v102, v44
	s_waitcnt lgkmcnt(0)
	v_pk_add_f32 v[44:45], v[44:45], v[102:103]
	s_nop 1
	v_mov_b32_dpp v103, v45 row_ror:8 row_mask:0xf bank_mask:0xf
	v_mov_b32_dpp v102, v44 row_ror:8 row_mask:0xf bank_mask:0xf
	s_waitcnt lgkmcnt(0)
	v_pk_add_f32 v[44:45], v[44:45], v[102:103]
	s_nop 1
	v_mov_b32_dpp v103, v45 row_shl:4 row_mask:0xf bank_mask:0x5
	v_mov_b32_dpp v103, v45 row_shr:4 row_mask:0xf bank_mask:0xa
	v_mov_b32_dpp v102, v44 row_shl:4 row_mask:0xf bank_mask:0x5
	v_mov_b32_dpp v102, v44 row_shr:4 row_mask:0xf bank_mask:0xa
	s_waitcnt lgkmcnt(0)
	v_pk_add_f32 v[44:45], v[44:45], v[102:103]
	s_nop 1
	v_mov_b32_dpp v103, v45 quad_perm:[2,3,0,1] row_mask:0xf bank_mask:0xf
	v_mov_b32_dpp v102, v44 quad_perm:[2,3,0,1] row_mask:0xf bank_mask:0xf
	s_waitcnt lgkmcnt(0)
	v_pk_add_f32 v[44:45], v[44:45], v[102:103]
	s_nop 1
	v_mov_b32_dpp v103, v45 quad_perm:[1,0,3,2] row_mask:0xf bank_mask:0xf
	v_mov_b32_dpp v102, v44 quad_perm:[1,0,3,2] row_mask:0xf bank_mask:0xf
	s_waitcnt lgkmcnt(0)
	v_pk_add_f32 v[102:103], v[44:45], v[102:103]
	v_mov_b64_e32 v[44:45], s[72:73]
	v_pk_fma_f32 v[102:103], v[102:103], s[96:97], v[44:45] op_sel_hi:[1,0,0]
	s_nop 0
	v_mul_f32_e32 v99, 0x4b800000, v103
	v_cmp_gt_f32_e64 s[0:1], s77, v103
	v_cmp_gt_f32_e32 vcc, s77, v102
	s_nop 0
	v_cndmask_b32_e64 v99, v103, v99, s[0:1]
	v_rsq_f32_e32 v99, v99
	s_nop 0
	v_mul_f32_e32 v103, 0x45800000, v99
	v_cndmask_b32_e64 v110, v99, v103, s[0:1]
	v_pk_mul_f32 v[100:101], v[110:111], v[100:101] op_sel_hi:[0,1]
	v_pk_mul_f32 v[100:101], v[2:3], v[100:101]
	s_waitcnt vmcnt(24)
	v_and_b32_e32 v103, 0xffff0000, v96
	v_pk_mul_f32 v[100:101], v[104:105], v[100:101]
	s_nop 0
	v_cvt_pk_bf16_f32 v99, v100, v101
	global_store_dword v[70:71], v99, off
	v_mul_f32_e32 v70, 0x4b800000, v102
	v_cndmask_b32_e32 v70, v102, v70, vcc
	v_rsq_f32_e32 v70, v70
	v_mul_f32_e32 v99, 0xbfb8aa3b, v109
	v_exp_f32_e32 v99, v99
	v_lshlrev_b32_e32 v102, 16, v96
	v_mul_f32_e32 v71, 0x45800000, v70
	v_cndmask_b32_e32 v70, v70, v71, vcc
	v_mul_f32_e32 v71, 0xbfb8aa3b, v108
	v_exp_f32_e32 v71, v71
	v_add_f32_e32 v99, 1.0, v99
	v_rcp_f32_e32 v101, v99
	v_add_f32_e32 v71, 1.0, v71
	v_rcp_f32_e32 v100, v71
	v_pk_mul_f32 v[70:71], v[70:71], v[106:107] op_sel_hi:[0,1]
	v_pk_mul_f32 v[70:71], v[2:3], v[70:71]
	v_pk_mul_f32 v[100:101], v[100:101], v[108:109]
	s_nop 0
	v_pk_mul_f32 v[70:71], v[100:101], v[70:71]
	s_nop 0
	v_cvt_pk_bf16_f32 v70, v70, v71
	global_store_dword v[68:69], v70, off
	v_lshlrev_b32_e32 v70, 16, v98
	v_lshlrev_b32_e32 v68, 16, v97
	v_and_b32_e32 v69, 0xffff0000, v97
	v_mul_f32_e32 v97, 0xbfb8aa3b, v70
	v_exp_f32_e32 v97, v97
	v_and_b32_e32 v71, 0xffff0000, v98
	v_pk_mul_f32 v[98:99], v[68:69], v[68:69]
	v_add_f32_e32 v97, 1.0, v97
	v_rcp_f32_e32 v100, v97
	v_mul_f32_e32 v97, 0xbfb8aa3b, v71
	v_exp_f32_e32 v97, v97
	v_mov_b32_e32 v105, v98
	v_add_f32_e32 v97, 1.0, v97
	v_rcp_f32_e32 v101, v97
	s_nop 0
	v_pk_mul_f32 v[70:71], v[100:101], v[70:71]
	v_lshlrev_b32_e32 v100, 16, v95
	v_and_b32_e32 v101, 0xffff0000, v95
	v_pk_mul_f32 v[96:97], v[100:101], v[100:101]
	s_nop 0
	v_mov_b32_e32 v104, v96
	v_mov_b32_e32 v98, v97
	v_pk_add_f32 v[96:97], v[104:105], v[98:99]
	v_mov_b32_e32 v99, v97
	v_mov_b32_e32 v98, v96
	s_nop 0
	v_permlane32_swap_b32_e32 v99, v97
	v_permlane32_swap_b32_e32 v98, v96
	s_waitcnt lgkmcnt(0)
	v_pk_add_f32 v[96:97], v[96:97], v[98:99]
	v_mov_b32_e32 v99, v97
	v_mov_b32_e32 v98, v96
	s_nop 0
	v_permlane16_swap_b32_e32 v99, v97
	v_permlane16_swap_b32_e32 v98, v96
	s_waitcnt lgkmcnt(0)
	v_pk_add_f32 v[96:97], v[96:97], v[98:99]
	s_nop 1
	v_mov_b32_dpp v99, v97 row_ror:8 row_mask:0xf bank_mask:0xf
	v_mov_b32_dpp v98, v96 row_ror:8 row_mask:0xf bank_mask:0xf
	s_waitcnt lgkmcnt(0)
	v_pk_add_f32 v[96:97], v[96:97], v[98:99]
	s_nop 1
	v_mov_b32_dpp v99, v97 row_shl:4 row_mask:0xf bank_mask:0x5
	v_mov_b32_dpp v99, v97 row_shr:4 row_mask:0xf bank_mask:0xa
	v_mov_b32_dpp v98, v96 row_shl:4 row_mask:0xf bank_mask:0x5
	v_mov_b32_dpp v98, v96 row_shr:4 row_mask:0xf bank_mask:0xa
	s_waitcnt lgkmcnt(0)
	v_pk_add_f32 v[96:97], v[96:97], v[98:99]
	s_nop 1
	v_mov_b32_dpp v99, v97 quad_perm:[2,3,0,1] row_mask:0xf bank_mask:0xf
	v_mov_b32_dpp v98, v96 quad_perm:[2,3,0,1] row_mask:0xf bank_mask:0xf
	s_waitcnt lgkmcnt(0)
	v_pk_add_f32 v[96:97], v[96:97], v[98:99]
	s_nop 1
	v_mov_b32_dpp v99, v97 quad_perm:[1,0,3,2] row_mask:0xf bank_mask:0xf
	v_mov_b32_dpp v98, v96 quad_perm:[1,0,3,2] row_mask:0xf bank_mask:0xf
	s_waitcnt lgkmcnt(0)
	v_pk_add_f32 v[96:97], v[96:97], v[98:99]
	s_nop 0
	v_pk_fma_f32 v[96:97], v[96:97], s[96:97], v[44:45] op_sel_hi:[1,0,0]
	s_nop 0
	v_mul_f32_e32 v95, 0x4b800000, v97
	v_cmp_gt_f32_e64 s[0:1], s77, v97
	v_cmp_gt_f32_e32 vcc, s77, v96
	s_nop 0
	v_cndmask_b32_e64 v95, v97, v95, s[0:1]
	v_rsq_f32_e32 v95, v95
	s_nop 0
	v_mul_f32_e32 v97, 0x45800000, v95
	v_cndmask_b32_e64 v98, v95, v97, s[0:1]
	v_pk_mul_f32 v[68:69], v[98:99], v[68:69] op_sel_hi:[0,1]
	v_pk_mul_f32 v[68:69], v[2:3], v[68:69]
	s_waitcnt vmcnt(23)
	v_and_b32_e32 v95, 0xffff0000, v92
	v_pk_mul_f32 v[68:69], v[70:71], v[68:69]
	s_nop 0
	v_cvt_pk_bf16_f32 v68, v68, v69
	global_store_dword v[66:67], v68, off
	v_mul_f32_e32 v66, 0x4b800000, v96
	v_cndmask_b32_e32 v66, v96, v66, vcc
	v_rsq_f32_e32 v66, v66
	v_mul_f32_e32 v69, 0xbfb8aa3b, v103
	v_exp_f32_e32 v69, v69
	v_mul_f32_e32 v67, 0x45800000, v66
	v_cndmask_b32_e32 v66, v66, v67, vcc
	v_mul_f32_e32 v67, 0xbfb8aa3b, v102
	v_exp_f32_e32 v67, v67
	v_add_f32_e32 v69, 1.0, v69
	v_rcp_f32_e32 v69, v69
	v_add_f32_e32 v67, 1.0, v67
	v_rcp_f32_e32 v68, v67
	v_pk_mul_f32 v[66:67], v[66:67], v[100:101] op_sel_hi:[0,1]
	v_pk_mul_f32 v[66:67], v[2:3], v[66:67]
	v_pk_mul_f32 v[68:69], v[68:69], v[102:103]
	s_nop 0
	v_pk_mul_f32 v[66:67], v[68:69], v[66:67]
	s_nop 0
	v_cvt_pk_bf16_f32 v66, v66, v67
	global_store_dword v[64:65], v66, off
	v_lshlrev_b32_e32 v66, 16, v94
	v_and_b32_e32 v67, 0xffff0000, v94
	v_mul_f32_e32 v70, 0xbfb8aa3b, v66
	v_mul_f32_e32 v71, 0xbfb8aa3b, v67
	v_exp_f32_e32 v70, v70
	v_exp_f32_e32 v71, v71
	v_lshlrev_b32_e32 v64, 16, v93
	v_and_b32_e32 v65, 0xffff0000, v93
	v_add_f32_e32 v70, 1.0, v70
	v_add_f32_e32 v71, 1.0, v71
	v_rcp_f32_e32 v70, v70
	v_rcp_f32_e32 v71, v71
	v_pk_mul_f32 v[68:69], v[64:65], v[64:65]
	v_lshlrev_b32_e32 v94, 16, v92
	v_mov_b32_e32 v97, v68
	v_pk_mul_f32 v[66:67], v[70:71], v[66:67]
	s_waitcnt vmcnt(14)
	v_lshlrev_b32_e32 v70, 16, v91
	v_and_b32_e32 v71, 0xffff0000, v91
	v_pk_mul_f32 v[92:93], v[70:71], v[70:71]
	s_nop 0
	v_mov_b32_e32 v96, v92
	v_mov_b32_e32 v68, v93
	v_pk_add_f32 v[68:69], v[96:97], v[68:69]
	v_mov_b32_e32 v93, v69
	v_mov_b32_e32 v92, v68
	s_nop 0
	v_permlane32_swap_b32_e32 v93, v69
	v_permlane32_swap_b32_e32 v92, v68
	s_waitcnt lgkmcnt(0)
	v_pk_add_f32 v[68:69], v[68:69], v[92:93]
	v_mov_b32_e32 v93, v69
	v_mov_b32_e32 v92, v68
	s_nop 0
	v_permlane16_swap_b32_e32 v93, v69
	v_permlane16_swap_b32_e32 v92, v68
	s_waitcnt lgkmcnt(0)
	v_pk_add_f32 v[68:69], v[68:69], v[92:93]
	s_nop 1
	v_mov_b32_dpp v93, v69 row_ror:8 row_mask:0xf bank_mask:0xf
	v_mov_b32_dpp v92, v68 row_ror:8 row_mask:0xf bank_mask:0xf
	s_waitcnt lgkmcnt(0)
	v_pk_add_f32 v[68:69], v[68:69], v[92:93]
	s_nop 1
	v_mov_b32_dpp v93, v69 row_shl:4 row_mask:0xf bank_mask:0x5
	v_mov_b32_dpp v93, v69 row_shr:4 row_mask:0xf bank_mask:0xa
	v_mov_b32_dpp v92, v68 row_shl:4 row_mask:0xf bank_mask:0x5
	v_mov_b32_dpp v92, v68 row_shr:4 row_mask:0xf bank_mask:0xa
	s_waitcnt lgkmcnt(0)
	v_pk_add_f32 v[68:69], v[68:69], v[92:93]
	s_nop 1
	v_mov_b32_dpp v93, v69 quad_perm:[2,3,0,1] row_mask:0xf bank_mask:0xf
	v_mov_b32_dpp v92, v68 quad_perm:[2,3,0,1] row_mask:0xf bank_mask:0xf
	s_waitcnt lgkmcnt(0)
	v_pk_add_f32 v[68:69], v[68:69], v[92:93]
	s_nop 1
	v_mov_b32_dpp v93, v69 quad_perm:[1,0,3,2] row_mask:0xf bank_mask:0xf
	v_mov_b32_dpp v92, v68 quad_perm:[1,0,3,2] row_mask:0xf bank_mask:0xf
	s_waitcnt lgkmcnt(0)
	v_pk_add_f32 v[68:69], v[68:69], v[92:93]
	s_nop 0
	v_pk_fma_f32 v[68:69], v[68:69], s[96:97], v[44:45] op_sel_hi:[1,0,0]
	s_nop 0
	v_mul_f32_e32 v91, 0x4b800000, v69
	v_cmp_gt_f32_e64 s[0:1], s77, v69
	v_cmp_gt_f32_e32 vcc, s77, v68
	s_nop 0
	v_cndmask_b32_e64 v69, v69, v91, s[0:1]
	v_rsq_f32_e32 v69, v69
	s_nop 0
	v_mul_f32_e32 v91, 0x45800000, v69
	v_cndmask_b32_e64 v92, v69, v91, s[0:1]
	v_pk_mul_f32 v[64:65], v[92:93], v[64:65] op_sel_hi:[0,1]
	v_pk_mul_f32 v[64:65], v[2:3], v[64:65]
	v_and_b32_e32 v69, 0xffff0000, v88
	v_pk_mul_f32 v[64:65], v[66:67], v[64:65]
	s_nop 0
	v_cvt_pk_bf16_f32 v64, v64, v65
	global_store_dword v[62:63], v64, off
	v_mul_f32_e32 v62, 0x4b800000, v68
	v_cndmask_b32_e32 v62, v68, v62, vcc
	v_rsq_f32_e32 v62, v62
	v_mul_f32_e32 v65, 0xbfb8aa3b, v95
	v_exp_f32_e32 v65, v65
	v_lshlrev_b32_e32 v68, 16, v88
	v_mul_f32_e32 v63, 0x45800000, v62
	v_cndmask_b32_e32 v62, v62, v63, vcc
	v_mul_f32_e32 v63, 0xbfb8aa3b, v94
	v_exp_f32_e32 v63, v63
	v_add_f32_e32 v65, 1.0, v65
	v_rcp_f32_e32 v65, v65
	v_add_f32_e32 v63, 1.0, v63
	v_rcp_f32_e32 v64, v63
	v_pk_mul_f32 v[62:63], v[62:63], v[70:71] op_sel_hi:[0,1]
	v_pk_mul_f32 v[62:63], v[2:3], v[62:63]
	v_pk_mul_f32 v[64:65], v[64:65], v[94:95]
	s_nop 0
	v_pk_mul_f32 v[62:63], v[64:65], v[62:63]
	s_nop 0
	v_cvt_pk_bf16_f32 v62, v62, v63
	global_store_dword v[60:61], v62, off
	v_lshlrev_b32_e32 v62, 16, v90
	v_and_b32_e32 v63, 0xffff0000, v90
	v_mul_f32_e32 v66, 0xbfb8aa3b, v62
	v_mul_f32_e32 v67, 0xbfb8aa3b, v63
	v_exp_f32_e32 v66, v66
	v_exp_f32_e32 v67, v67
	s_waitcnt vmcnt(15)
	v_lshlrev_b32_e32 v60, 16, v89
	v_and_b32_e32 v61, 0xffff0000, v89
	v_add_f32_e32 v66, 1.0, v66
	v_add_f32_e32 v67, 1.0, v67
	v_rcp_f32_e32 v66, v66
	v_rcp_f32_e32 v67, v67
	v_pk_mul_f32 v[64:65], v[60:61], v[60:61]
	v_pk_mul_f32 v[62:63], v[66:67], v[62:63]
	s_waitcnt vmcnt(14)
	v_lshlrev_b32_e32 v66, 16, v87
	v_and_b32_e32 v67, 0xffff0000, v87
	v_pk_mul_f32 v[70:71], v[66:67], v[66:67]
	v_mov_b32_e32 v89, v64
	v_mov_b32_e32 v88, v70
	v_mov_b32_e32 v64, v71
	v_pk_add_f32 v[64:65], v[88:89], v[64:65]
	v_mov_b32_e32 v71, v65
	v_mov_b32_e32 v70, v64
	s_nop 0
	v_permlane32_swap_b32_e32 v71, v65
	v_permlane32_swap_b32_e32 v70, v64
	s_waitcnt lgkmcnt(0)
	v_pk_add_f32 v[64:65], v[64:65], v[70:71]
	v_mov_b32_e32 v71, v65
	v_mov_b32_e32 v70, v64
	s_nop 0
	v_permlane16_swap_b32_e32 v71, v65
	v_permlane16_swap_b32_e32 v70, v64
	s_waitcnt lgkmcnt(0)
	v_pk_add_f32 v[64:65], v[64:65], v[70:71]
	s_nop 1
	v_mov_b32_dpp v71, v65 row_ror:8 row_mask:0xf bank_mask:0xf
	v_mov_b32_dpp v70, v64 row_ror:8 row_mask:0xf bank_mask:0xf
	s_waitcnt lgkmcnt(0)
	v_pk_add_f32 v[64:65], v[64:65], v[70:71]
	s_nop 1
	v_mov_b32_dpp v71, v65 row_shl:4 row_mask:0xf bank_mask:0x5
	v_mov_b32_dpp v71, v65 row_shr:4 row_mask:0xf bank_mask:0xa
	v_mov_b32_dpp v70, v64 row_shl:4 row_mask:0xf bank_mask:0x5
	v_mov_b32_dpp v70, v64 row_shr:4 row_mask:0xf bank_mask:0xa
	s_waitcnt lgkmcnt(0)
	v_pk_add_f32 v[64:65], v[64:65], v[70:71]
	s_nop 1
	v_mov_b32_dpp v71, v65 quad_perm:[2,3,0,1] row_mask:0xf bank_mask:0xf
	v_mov_b32_dpp v70, v64 quad_perm:[2,3,0,1] row_mask:0xf bank_mask:0xf
	s_waitcnt lgkmcnt(0)
	v_pk_add_f32 v[64:65], v[64:65], v[70:71]
	s_nop 1
	v_mov_b32_dpp v71, v65 quad_perm:[1,0,3,2] row_mask:0xf bank_mask:0xf
	v_mov_b32_dpp v70, v64 quad_perm:[1,0,3,2] row_mask:0xf bank_mask:0xf
	s_waitcnt lgkmcnt(0)
	v_pk_add_f32 v[64:65], v[64:65], v[70:71]
	s_nop 0
	v_pk_fma_f32 v[64:65], v[64:65], s[96:97], v[44:45] op_sel_hi:[1,0,0]
	s_nop 0
	v_mul_f32_e32 v70, 0x4b800000, v65
	v_cmp_gt_f32_e64 s[0:1], s77, v65
	v_cmp_gt_f32_e32 vcc, s77, v64
	s_nop 0
	v_cndmask_b32_e64 v65, v65, v70, s[0:1]
	v_rsq_f32_e32 v65, v65
	s_nop 0
	v_mul_f32_e32 v70, 0x45800000, v65
	v_cndmask_b32_e64 v70, v65, v70, s[0:1]
	v_pk_mul_f32 v[60:61], v[70:71], v[60:61] op_sel_hi:[0,1]
	v_pk_mul_f32 v[60:61], v[2:3], v[60:61]
	v_and_b32_e32 v65, 0xffff0000, v84
	v_pk_mul_f32 v[60:61], v[62:63], v[60:61]
	s_nop 0
	v_cvt_pk_bf16_f32 v60, v60, v61
	global_store_dword v[58:59], v60, off
	v_mul_f32_e32 v58, 0x4b800000, v64
	v_cndmask_b32_e32 v58, v64, v58, vcc
	v_rsq_f32_e32 v58, v58
	v_mul_f32_e32 v61, 0xbfb8aa3b, v69
	v_exp_f32_e32 v61, v61
	v_lshlrev_b32_e32 v64, 16, v84
	v_mul_f32_e32 v59, 0x45800000, v58
	v_cndmask_b32_e32 v58, v58, v59, vcc
	v_mul_f32_e32 v59, 0xbfb8aa3b, v68
	v_exp_f32_e32 v59, v59
	v_add_f32_e32 v61, 1.0, v61
	v_rcp_f32_e32 v61, v61
	v_add_f32_e32 v59, 1.0, v59
	v_rcp_f32_e32 v60, v59
	v_pk_mul_f32 v[58:59], v[58:59], v[66:67] op_sel_hi:[0,1]
	v_pk_mul_f32 v[58:59], v[2:3], v[58:59]
	v_pk_mul_f32 v[60:61], v[60:61], v[68:69]
	s_nop 0
	v_pk_mul_f32 v[58:59], v[60:61], v[58:59]
	s_nop 0
	v_cvt_pk_bf16_f32 v58, v58, v59
	global_store_dword v[56:57], v58, off
	v_lshlrev_b32_e32 v58, 16, v86
	v_and_b32_e32 v59, 0xffff0000, v86
	v_mul_f32_e32 v62, 0xbfb8aa3b, v58
	v_mul_f32_e32 v63, 0xbfb8aa3b, v59
	v_exp_f32_e32 v62, v62
	v_exp_f32_e32 v63, v63
	s_waitcnt vmcnt(15)
	v_lshlrev_b32_e32 v56, 16, v85
	v_and_b32_e32 v57, 0xffff0000, v85
	v_add_f32_e32 v62, 1.0, v62
	v_add_f32_e32 v63, 1.0, v63
	v_rcp_f32_e32 v62, v62
	v_rcp_f32_e32 v63, v63
	v_pk_mul_f32 v[60:61], v[56:57], v[56:57]
	v_pk_mul_f32 v[58:59], v[62:63], v[58:59]
	s_waitcnt vmcnt(14)
	v_lshlrev_b32_e32 v62, 16, v83
	v_and_b32_e32 v63, 0xffff0000, v83
	v_pk_mul_f32 v[66:67], v[62:63], v[62:63]
	v_mov_b32_e32 v69, v60
	v_mov_b32_e32 v68, v66
	v_mov_b32_e32 v60, v67
	v_pk_add_f32 v[60:61], v[68:69], v[60:61]
	v_mov_b32_e32 v67, v61
	v_mov_b32_e32 v66, v60
	s_nop 0
	v_permlane32_swap_b32_e32 v67, v61
	v_permlane32_swap_b32_e32 v66, v60
	s_waitcnt lgkmcnt(0)
	v_pk_add_f32 v[60:61], v[60:61], v[66:67]
	v_mov_b32_e32 v67, v61
	v_mov_b32_e32 v66, v60
	s_nop 0
	v_permlane16_swap_b32_e32 v67, v61
	v_permlane16_swap_b32_e32 v66, v60
	s_waitcnt lgkmcnt(0)
	v_pk_add_f32 v[60:61], v[60:61], v[66:67]
	s_nop 1
	v_mov_b32_dpp v67, v61 row_ror:8 row_mask:0xf bank_mask:0xf
	v_mov_b32_dpp v66, v60 row_ror:8 row_mask:0xf bank_mask:0xf
	s_waitcnt lgkmcnt(0)
	v_pk_add_f32 v[60:61], v[60:61], v[66:67]
	s_nop 1
	v_mov_b32_dpp v67, v61 row_shl:4 row_mask:0xf bank_mask:0x5
	v_mov_b32_dpp v67, v61 row_shr:4 row_mask:0xf bank_mask:0xa
	v_mov_b32_dpp v66, v60 row_shl:4 row_mask:0xf bank_mask:0x5
	v_mov_b32_dpp v66, v60 row_shr:4 row_mask:0xf bank_mask:0xa
	s_waitcnt lgkmcnt(0)
	v_pk_add_f32 v[60:61], v[60:61], v[66:67]
	s_nop 1
	v_mov_b32_dpp v67, v61 quad_perm:[2,3,0,1] row_mask:0xf bank_mask:0xf
	v_mov_b32_dpp v66, v60 quad_perm:[2,3,0,1] row_mask:0xf bank_mask:0xf
	s_waitcnt lgkmcnt(0)
	v_pk_add_f32 v[60:61], v[60:61], v[66:67]
	s_nop 1
	v_mov_b32_dpp v67, v61 quad_perm:[1,0,3,2] row_mask:0xf bank_mask:0xf
	v_mov_b32_dpp v66, v60 quad_perm:[1,0,3,2] row_mask:0xf bank_mask:0xf
	s_waitcnt lgkmcnt(0)
	v_pk_add_f32 v[60:61], v[60:61], v[66:67]
	s_nop 0
	v_pk_fma_f32 v[60:61], v[60:61], s[96:97], v[44:45] op_sel_hi:[1,0,0]
	s_nop 0
	v_mul_f32_e32 v66, 0x4b800000, v61
	v_cmp_gt_f32_e64 s[0:1], s77, v61
	v_cmp_gt_f32_e32 vcc, s77, v60
	s_nop 0
	v_cndmask_b32_e64 v61, v61, v66, s[0:1]
	v_rsq_f32_e32 v61, v61
	s_nop 0
	v_mul_f32_e32 v66, 0x45800000, v61
	v_cndmask_b32_e64 v66, v61, v66, s[0:1]
	v_pk_mul_f32 v[56:57], v[66:67], v[56:57] op_sel_hi:[0,1]
	v_pk_mul_f32 v[56:57], v[2:3], v[56:57]
	v_and_b32_e32 v61, 0xffff0000, v80
	v_pk_mul_f32 v[56:57], v[58:59], v[56:57]
	s_nop 0
	v_cvt_pk_bf16_f32 v56, v56, v57
	global_store_dword v[54:55], v56, off
	v_mul_f32_e32 v54, 0x4b800000, v60
	v_cndmask_b32_e32 v54, v60, v54, vcc
	v_rsq_f32_e32 v54, v54
	v_mul_f32_e32 v57, 0xbfb8aa3b, v65
	v_exp_f32_e32 v57, v57
	v_lshlrev_b32_e32 v60, 16, v80
	v_mul_f32_e32 v55, 0x45800000, v54
	v_cndmask_b32_e32 v54, v54, v55, vcc
	v_mul_f32_e32 v55, 0xbfb8aa3b, v64
	v_exp_f32_e32 v55, v55
	v_add_f32_e32 v57, 1.0, v57
	v_rcp_f32_e32 v57, v57
	v_add_f32_e32 v55, 1.0, v55
	v_rcp_f32_e32 v56, v55
	v_pk_mul_f32 v[54:55], v[54:55], v[62:63] op_sel_hi:[0,1]
	v_pk_mul_f32 v[54:55], v[2:3], v[54:55]
	v_pk_mul_f32 v[56:57], v[56:57], v[64:65]
	s_nop 0
	v_pk_mul_f32 v[54:55], v[56:57], v[54:55]
	s_nop 0
	v_cvt_pk_bf16_f32 v54, v54, v55
	global_store_dword v[52:53], v54, off
	v_lshlrev_b32_e32 v54, 16, v82
	v_and_b32_e32 v55, 0xffff0000, v82
	v_mul_f32_e32 v58, 0xbfb8aa3b, v54
	v_mul_f32_e32 v59, 0xbfb8aa3b, v55
	v_exp_f32_e32 v58, v58
	v_exp_f32_e32 v59, v59
	s_waitcnt vmcnt(15)
	v_lshlrev_b32_e32 v52, 16, v81
	v_and_b32_e32 v53, 0xffff0000, v81
	v_add_f32_e32 v58, 1.0, v58
	v_add_f32_e32 v59, 1.0, v59
	v_rcp_f32_e32 v58, v58
	v_rcp_f32_e32 v59, v59
	v_pk_mul_f32 v[56:57], v[52:53], v[52:53]
	v_pk_mul_f32 v[54:55], v[58:59], v[54:55]
	s_waitcnt vmcnt(14)
	v_lshlrev_b32_e32 v58, 16, v79
	v_and_b32_e32 v59, 0xffff0000, v79
	v_pk_mul_f32 v[62:63], v[58:59], v[58:59]
	v_mov_b32_e32 v65, v56
	v_mov_b32_e32 v64, v62
	v_mov_b32_e32 v56, v63
	v_pk_add_f32 v[56:57], v[64:65], v[56:57]
	v_mov_b32_e32 v63, v57
	v_mov_b32_e32 v62, v56
	s_nop 0
	v_permlane32_swap_b32_e32 v63, v57
	v_permlane32_swap_b32_e32 v62, v56
	s_waitcnt lgkmcnt(0)
	v_pk_add_f32 v[56:57], v[56:57], v[62:63]
	v_mov_b32_e32 v63, v57
	v_mov_b32_e32 v62, v56
	s_nop 0
	v_permlane16_swap_b32_e32 v63, v57
	v_permlane16_swap_b32_e32 v62, v56
	s_waitcnt lgkmcnt(0)
	v_pk_add_f32 v[56:57], v[56:57], v[62:63]
	s_nop 1
	v_mov_b32_dpp v63, v57 row_ror:8 row_mask:0xf bank_mask:0xf
	v_mov_b32_dpp v62, v56 row_ror:8 row_mask:0xf bank_mask:0xf
	s_waitcnt lgkmcnt(0)
	v_pk_add_f32 v[56:57], v[56:57], v[62:63]
	s_nop 1
	v_mov_b32_dpp v63, v57 row_shl:4 row_mask:0xf bank_mask:0x5
	v_mov_b32_dpp v63, v57 row_shr:4 row_mask:0xf bank_mask:0xa
	v_mov_b32_dpp v62, v56 row_shl:4 row_mask:0xf bank_mask:0x5
	v_mov_b32_dpp v62, v56 row_shr:4 row_mask:0xf bank_mask:0xa
	s_waitcnt lgkmcnt(0)
	v_pk_add_f32 v[56:57], v[56:57], v[62:63]
	s_nop 1
	v_mov_b32_dpp v63, v57 quad_perm:[2,3,0,1] row_mask:0xf bank_mask:0xf
	v_mov_b32_dpp v62, v56 quad_perm:[2,3,0,1] row_mask:0xf bank_mask:0xf
	s_waitcnt lgkmcnt(0)
	v_pk_add_f32 v[56:57], v[56:57], v[62:63]
	s_nop 1
	v_mov_b32_dpp v63, v57 quad_perm:[1,0,3,2] row_mask:0xf bank_mask:0xf
	v_mov_b32_dpp v62, v56 quad_perm:[1,0,3,2] row_mask:0xf bank_mask:0xf
	s_waitcnt lgkmcnt(0)
	v_pk_add_f32 v[56:57], v[56:57], v[62:63]
	s_nop 0
	v_pk_fma_f32 v[56:57], v[56:57], s[96:97], v[44:45] op_sel_hi:[1,0,0]
	s_nop 0
	v_mul_f32_e32 v62, 0x4b800000, v57
	v_cmp_gt_f32_e64 s[0:1], s77, v57
	v_cmp_gt_f32_e32 vcc, s77, v56
	s_nop 0
	v_cndmask_b32_e64 v57, v57, v62, s[0:1]
	v_rsq_f32_e32 v57, v57
	s_nop 0
	v_mul_f32_e32 v62, 0x45800000, v57
	v_cndmask_b32_e64 v62, v57, v62, s[0:1]
	v_pk_mul_f32 v[52:53], v[62:63], v[52:53] op_sel_hi:[0,1]
	v_pk_mul_f32 v[52:53], v[2:3], v[52:53]
	v_and_b32_e32 v57, 0xffff0000, v76
	v_pk_mul_f32 v[52:53], v[54:55], v[52:53]
	s_nop 0
	v_cvt_pk_bf16_f32 v52, v52, v53
	global_store_dword v[50:51], v52, off
	v_mul_f32_e32 v50, 0x4b800000, v56
	v_cndmask_b32_e32 v50, v56, v50, vcc
	v_rsq_f32_e32 v50, v50
	v_mul_f32_e32 v53, 0xbfb8aa3b, v61
	v_exp_f32_e32 v53, v53
	v_lshlrev_b32_e32 v56, 16, v76
	v_mul_f32_e32 v51, 0x45800000, v50
	v_cndmask_b32_e32 v50, v50, v51, vcc
	v_mul_f32_e32 v51, 0xbfb8aa3b, v60
	v_exp_f32_e32 v51, v51
	v_add_f32_e32 v53, 1.0, v53
	v_rcp_f32_e32 v53, v53
	v_add_f32_e32 v51, 1.0, v51
	v_rcp_f32_e32 v52, v51
	v_pk_mul_f32 v[50:51], v[50:51], v[58:59] op_sel_hi:[0,1]
	v_pk_mul_f32 v[50:51], v[2:3], v[50:51]
	v_pk_mul_f32 v[52:53], v[52:53], v[60:61]
	s_nop 0
	v_pk_mul_f32 v[50:51], v[52:53], v[50:51]
	s_nop 0
	v_cvt_pk_bf16_f32 v50, v50, v51
	global_store_dword v[48:49], v50, off
	v_lshlrev_b32_e32 v50, 16, v78
	v_and_b32_e32 v51, 0xffff0000, v78
	v_mul_f32_e32 v54, 0xbfb8aa3b, v50
	v_mul_f32_e32 v55, 0xbfb8aa3b, v51
	v_exp_f32_e32 v54, v54
	v_exp_f32_e32 v55, v55
	s_waitcnt vmcnt(15)
	v_lshlrev_b32_e32 v48, 16, v77
	v_and_b32_e32 v49, 0xffff0000, v77
	v_add_f32_e32 v54, 1.0, v54
	v_add_f32_e32 v55, 1.0, v55
	v_rcp_f32_e32 v54, v54
	v_rcp_f32_e32 v55, v55
	v_pk_mul_f32 v[52:53], v[48:49], v[48:49]
	v_pk_mul_f32 v[50:51], v[54:55], v[50:51]
	s_waitcnt vmcnt(14)
	v_lshlrev_b32_e32 v54, 16, v75
	v_and_b32_e32 v55, 0xffff0000, v75
	v_pk_mul_f32 v[58:59], v[54:55], v[54:55]
	v_mov_b32_e32 v61, v52
	v_mov_b32_e32 v60, v58
	v_mov_b32_e32 v52, v59
	v_pk_add_f32 v[52:53], v[60:61], v[52:53]
	v_mov_b32_e32 v59, v53
	v_mov_b32_e32 v58, v52
	s_nop 0
	v_permlane32_swap_b32_e32 v59, v53
	v_permlane32_swap_b32_e32 v58, v52
	s_waitcnt lgkmcnt(0)
	v_pk_add_f32 v[52:53], v[52:53], v[58:59]
	v_mov_b32_e32 v59, v53
	v_mov_b32_e32 v58, v52
	s_nop 0
	v_permlane16_swap_b32_e32 v59, v53
	v_permlane16_swap_b32_e32 v58, v52
	s_waitcnt lgkmcnt(0)
	v_pk_add_f32 v[52:53], v[52:53], v[58:59]
	s_nop 1
	v_mov_b32_dpp v59, v53 row_ror:8 row_mask:0xf bank_mask:0xf
	v_mov_b32_dpp v58, v52 row_ror:8 row_mask:0xf bank_mask:0xf
	s_waitcnt lgkmcnt(0)
	v_pk_add_f32 v[52:53], v[52:53], v[58:59]
	s_nop 1
	v_mov_b32_dpp v59, v53 row_shl:4 row_mask:0xf bank_mask:0x5
	v_mov_b32_dpp v59, v53 row_shr:4 row_mask:0xf bank_mask:0xa
	v_mov_b32_dpp v58, v52 row_shl:4 row_mask:0xf bank_mask:0x5
	v_mov_b32_dpp v58, v52 row_shr:4 row_mask:0xf bank_mask:0xa
	s_waitcnt lgkmcnt(0)
	v_pk_add_f32 v[52:53], v[52:53], v[58:59]
	s_nop 1
	v_mov_b32_dpp v59, v53 quad_perm:[2,3,0,1] row_mask:0xf bank_mask:0xf
	v_mov_b32_dpp v58, v52 quad_perm:[2,3,0,1] row_mask:0xf bank_mask:0xf
	s_waitcnt lgkmcnt(0)
	v_pk_add_f32 v[52:53], v[52:53], v[58:59]
	s_nop 1
	v_mov_b32_dpp v59, v53 quad_perm:[1,0,3,2] row_mask:0xf bank_mask:0xf
	v_mov_b32_dpp v58, v52 quad_perm:[1,0,3,2] row_mask:0xf bank_mask:0xf
	s_waitcnt lgkmcnt(0)
	v_pk_add_f32 v[52:53], v[52:53], v[58:59]
	s_nop 0
	v_pk_fma_f32 v[52:53], v[52:53], s[96:97], v[44:45] op_sel_hi:[1,0,0]
	s_nop 0
	v_mul_f32_e32 v58, 0x4b800000, v53
	v_cmp_gt_f32_e64 s[0:1], s77, v53
	v_cmp_gt_f32_e32 vcc, s77, v52
	s_nop 0
	v_cndmask_b32_e64 v53, v53, v58, s[0:1]
	v_rsq_f32_e32 v53, v53
	s_nop 0
	v_mul_f32_e32 v58, 0x45800000, v53
	v_cndmask_b32_e64 v58, v53, v58, s[0:1]
	v_pk_mul_f32 v[48:49], v[58:59], v[48:49] op_sel_hi:[0,1]
	v_pk_mul_f32 v[48:49], v[2:3], v[48:49]
	v_and_b32_e32 v53, 0xffff0000, v72
	v_pk_mul_f32 v[48:49], v[50:51], v[48:49]
	s_nop 0
	v_cvt_pk_bf16_f32 v48, v48, v49
	global_store_dword v[46:47], v48, off
	v_mul_f32_e32 v46, 0x4b800000, v52
	v_cndmask_b32_e32 v46, v52, v46, vcc
	v_rsq_f32_e32 v46, v46
	v_mul_f32_e32 v49, 0xbfb8aa3b, v57
	v_exp_f32_e32 v49, v49
	v_lshlrev_b32_e32 v52, 16, v72
	v_mul_f32_e32 v47, 0x45800000, v46
	v_cndmask_b32_e32 v46, v46, v47, vcc
	v_mul_f32_e32 v47, 0xbfb8aa3b, v56
	v_exp_f32_e32 v47, v47
	v_add_f32_e32 v49, 1.0, v49
	v_rcp_f32_e32 v49, v49
	v_add_f32_e32 v47, 1.0, v47
	v_rcp_f32_e32 v48, v47
	v_pk_mul_f32 v[46:47], v[46:47], v[54:55] op_sel_hi:[0,1]
	v_pk_mul_f32 v[46:47], v[2:3], v[46:47]
	v_pk_mul_f32 v[48:49], v[48:49], v[56:57]
	s_nop 0
	v_pk_mul_f32 v[46:47], v[48:49], v[46:47]
	s_nop 0
	v_cvt_pk_bf16_f32 v46, v46, v47
	global_store_dword v[42:43], v46, off
	v_lshlrev_b32_e32 v46, 16, v74
	v_and_b32_e32 v47, 0xffff0000, v74
	v_mul_f32_e32 v50, 0xbfb8aa3b, v46
	v_mul_f32_e32 v51, 0xbfb8aa3b, v47
	v_exp_f32_e32 v50, v50
	v_exp_f32_e32 v51, v51
	s_waitcnt vmcnt(15)
	v_lshlrev_b32_e32 v42, 16, v73
	v_and_b32_e32 v43, 0xffff0000, v73
	v_add_f32_e32 v50, 1.0, v50
	v_add_f32_e32 v51, 1.0, v51
	v_rcp_f32_e32 v50, v50
	v_rcp_f32_e32 v51, v51
	v_pk_mul_f32 v[48:49], v[42:43], v[42:43]
	v_pk_mul_f32 v[46:47], v[50:51], v[46:47]
	s_waitcnt vmcnt(14)
	v_lshlrev_b32_e32 v50, 16, v0
	v_and_b32_e32 v51, 0xffff0000, v0
	v_pk_mul_f32 v[54:55], v[50:51], v[50:51]
	v_mov_b32_e32 v57, v48
	v_mov_b32_e32 v56, v54
	v_mov_b32_e32 v48, v55
	v_pk_add_f32 v[48:49], v[56:57], v[48:49]
	v_mov_b32_e32 v55, v49
	v_mov_b32_e32 v54, v48
	s_nop 0
	v_permlane32_swap_b32_e32 v55, v49
	v_permlane32_swap_b32_e32 v54, v48
	s_waitcnt lgkmcnt(0)
	v_pk_add_f32 v[48:49], v[48:49], v[54:55]
	v_mov_b32_e32 v55, v49
	v_mov_b32_e32 v54, v48
	s_nop 0
	v_permlane16_swap_b32_e32 v55, v49
	v_permlane16_swap_b32_e32 v54, v48
	s_waitcnt lgkmcnt(0)
	v_pk_add_f32 v[48:49], v[48:49], v[54:55]
	s_nop 1
	v_mov_b32_dpp v55, v49 row_ror:8 row_mask:0xf bank_mask:0xf
	v_mov_b32_dpp v54, v48 row_ror:8 row_mask:0xf bank_mask:0xf
	s_waitcnt lgkmcnt(0)
	v_pk_add_f32 v[48:49], v[48:49], v[54:55]
	s_nop 1
	v_mov_b32_dpp v55, v49 row_shl:4 row_mask:0xf bank_mask:0x5
	v_mov_b32_dpp v55, v49 row_shr:4 row_mask:0xf bank_mask:0xa
	v_mov_b32_dpp v54, v48 row_shl:4 row_mask:0xf bank_mask:0x5
	v_mov_b32_dpp v54, v48 row_shr:4 row_mask:0xf bank_mask:0xa
	s_waitcnt lgkmcnt(0)
	v_pk_add_f32 v[48:49], v[48:49], v[54:55]
	s_nop 1
	v_mov_b32_dpp v55, v49 quad_perm:[2,3,0,1] row_mask:0xf bank_mask:0xf
	v_mov_b32_dpp v54, v48 quad_perm:[2,3,0,1] row_mask:0xf bank_mask:0xf
	s_waitcnt lgkmcnt(0)
	v_pk_add_f32 v[48:49], v[48:49], v[54:55]
	s_nop 1
	v_mov_b32_dpp v55, v49 quad_perm:[1,0,3,2] row_mask:0xf bank_mask:0xf
	v_mov_b32_dpp v54, v48 quad_perm:[1,0,3,2] row_mask:0xf bank_mask:0xf
	s_waitcnt lgkmcnt(0)
	v_pk_add_f32 v[48:49], v[48:49], v[54:55]
	s_nop 0
	v_pk_fma_f32 v[44:45], v[48:49], s[96:97], v[44:45] op_sel_hi:[1,0,0]
	s_nop 0
	v_mul_f32_e32 v0, 0x4b800000, v45
	v_cmp_gt_f32_e64 s[0:1], s77, v45
	v_cmp_gt_f32_e32 vcc, s77, v44
	s_nop 0
	v_cndmask_b32_e64 v0, v45, v0, s[0:1]
	v_rsq_f32_e32 v0, v0
	s_nop 0
	v_mul_f32_e32 v45, 0x45800000, v0
	v_cndmask_b32_e64 v0, v0, v45, s[0:1]
	v_pk_mul_f32 v[42:43], v[0:1], v[42:43] op_sel_hi:[0,1]
	v_pk_mul_f32 v[42:43], v[2:3], v[42:43]
	s_nop 0
	v_pk_mul_f32 v[42:43], v[46:47], v[42:43]
	s_nop 0
	v_cvt_pk_bf16_f32 v0, v42, v43
	global_store_dword v[40:41], v0, off
	v_mul_f32_e32 v0, 0x4b800000, v44
	v_cndmask_b32_e32 v0, v44, v0, vcc
	v_rsq_f32_e32 v0, v0
	s_nop 0
	v_mul_f32_e32 v40, 0x45800000, v0
	v_cndmask_b32_e32 v0, v0, v40, vcc
	v_mul_f32_e32 v40, 0xbfb8aa3b, v52
	v_pk_mul_f32 v[42:43], v[0:1], v[50:51] op_sel_hi:[0,1]
	v_mul_f32_e32 v0, 0xbfb8aa3b, v53
	v_exp_f32_e32 v40, v40
	v_exp_f32_e32 v0, v0
	v_pk_mul_f32 v[42:43], v[2:3], v[42:43]
	v_add_f32_e32 v40, 1.0, v40
	v_add_f32_e32 v0, 1.0, v0
	v_rcp_f32_e32 v40, v40
	v_rcp_f32_e32 v41, v0
	s_nop 0
	v_pk_mul_f32 v[40:41], v[40:41], v[52:53]
	s_nop 0
	v_pk_mul_f32 v[40:41], v[40:41], v[42:43]
	s_nop 0
	v_cvt_pk_bf16_f32 v0, v40, v41
	global_store_dword v[38:39], v0, off
	s_branch .LBB0_313

; DI bf16_t f2bf(float f) { unsigned u = __float_as_uint(f); u += 0x7fffu + ((u >> 16) & 1u); return (bf16_t)(u >> 16); }
; DI float wave_sum(float v) { for (int o = 32; o; o >>= 1) v += __shfl_xor(v, o); return v; }
; DI void run_phase(const Params& p, int ph, unsigned char* smem, const int tid, const int rep) {
;     ...
; #pragma unroll
;             for (int u = 0; u < 2; ++u) { const int t = t0 + u;
;                 const float ang = (float)ps[u] * invf; float sn, cs; sincosf(ang, &sn, &cs);
;                 const float kr = krv[u];
; #pragma unroll
;                 for (int h = 0; h < 4; ++h) {
;                     { const float a0 = qa[u][h][0], a1 = qa[u][h][1], a2 = qa[u][h][2];
;                       const float rs = rsqrtf(wave_sum(a0 * a0 + a1 * a1 + a2 * a2) * (1.f / 192.f) + NEPS) * (0.07216878364870322f * LOG2E);
;                       const float y2 = a2 * rs * gq2; const float oth = __shfl_xor(y2, 32);
;                       const float rot = (lane < 32) ? (y2 * cs - oth * sn) : (y2 * cs + oth * sn);
;                       bf16_t* qo = mlaq + (size_t)t * 768 + h * 192; qo[lane] = f2bf(a0 * rs * gq0); qo[lane + 64] = f2bf(a1 * rs * gq1); qo[lane + 128] = f2bf(rot); }
;                     { const float a0 = ka[u][h][0], a1 = ka[u][h][1];
;                       const float rs = rsqrtf(wave_sum(a0 * a0 + a1 * a1 + kr * kr) * (1.f / 192.f) + NEPS);
;                       const float y2 = kr * rs * gk2; const float oth = __shfl_xor(y2, 32);
;                       const float rot = (lane < 32) ? (y2 * cs - oth * sn) : (y2 * cs + oth * sn);
;                       bf16_t* ko = mlak + (size_t)t * 768 + h * 192; ko[lane] = f2bf(a0 * rs * gk0); ko[lane + 64] = f2bf(a1 * rs * gk1); ko[lane + 128] = f2bf(rot); }
;                 }
.LBB0_331:
	s_or_b64 exec, exec, s[0:1]
	v_mul_f32_e32 v26, v24, v24
	v_fmamk_f32 v27, v26, 0xb94c1982, v249
	v_fmaak_f32 v27, v26, v27, 0xbe2aaa9d
	v_mul_f32_e32 v27, v26, v27
	v_fmac_f32_e32 v24, v24, v27
	v_fmamk_f32 v27, v26, 0x37d75334, v223
	v_fmaak_f32 v27, v26, v27, 0x3d2aabf7
	v_fmaak_f32 v27, v26, v27, 0xbf000004
	v_fma_f32 v26, v26, v27, 1.0
	v_lshlrev_b32_e32 v27, 30, v25
	v_and_b32_e32 v25, 1, v25
	v_cmp_eq_u32_e32 vcc, 0, v25
	s_brev_b32 s0, 1
	s_waitcnt vmcnt(41)
	v_lshlrev_b32_e32 v19, 16, v58
	v_cndmask_b32_e32 v25, v26, v24, vcc
	v_xor_b32_e32 v24, 0x80000000, v24
	v_cndmask_b32_e32 v24, v24, v26, vcc
	v_lshlrev_b32_e32 v18, 16, v51
	s_waitcnt vmcnt(39)
	v_lshlrev_b32_e32 v33, 16, v53
	v_lshlrev_b32_e32 v32, 16, v50
	v_xor_b32_e32 v17, v17, v16
	v_bitop3_b32 v24, v24, v27, s0 bitop3:0x78
	s_movk_i32 s0, 0x1f8
	v_lshlrev_b32_e32 v70, 16, v57
	s_waitcnt vmcnt(38)
	v_lshlrev_b32_e32 v30, 16, v55
	s_waitcnt vmcnt(35)
	v_lshlrev_b32_e32 v28, 16, v54
	s_waitcnt vmcnt(25)
	v_lshlrev_b32_e32 v13, 16, v61
	v_lshlrev_b32_e32 v12, 16, v49
	v_and_b32_e32 v34, 0x80000000, v27
	v_xor_b32_e32 v17, v17, v25
	v_cmp_class_f32_e64 vcc, v16, s0
	v_pk_mul_f32 v[26:27], v[18:19], v[18:19]
	v_pk_mul_f32 v[54:55], v[32:33], v[32:33]
	v_lshlrev_b32_e32 v11, 16, v52
	s_waitcnt vmcnt(24)
	v_lshlrev_b32_e32 v10, 16, v56
	v_xor_b32_e32 v17, v17, v34
	v_cndmask_b32_e32 v34, v224, v24, vcc
	v_pk_mul_f32 v[24:25], v[12:13], v[12:13]
	v_mul_f32_e32 v53, v70, v70
	v_mov_b32_e32 v56, v54
	v_mov_b32_e32 v57, v26
	v_mov_b32_e32 v52, v55
	v_pk_add_f32 v[52:53], v[56:57], v[52:53]
	v_mov_b32_e32 v26, v24
	v_pk_add_f32 v[26:27], v[26:27], v[52:53]
	v_mov_b32_e32 v53, v27
	v_mov_b32_e32 v52, v26
	s_nop 0
	v_permlane32_swap_b32_e32 v53, v27
	v_permlane32_swap_b32_e32 v52, v26
	s_mov_b32 s4, 0x3baaaaab
	v_cndmask_b32_e32 v35, v224, v17, vcc
	v_mad_i64_i32 v[16:17], s[0:1], v3, s7, v[6:7]
	s_waitcnt lgkmcnt(0)
	v_pk_add_f32 v[26:27], v[26:27], v[52:53]
	v_mov_b32_e32 v53, v27
	v_mov_b32_e32 v52, v26
	s_nop 0
	v_permlane16_swap_b32_e32 v53, v27
	v_permlane16_swap_b32_e32 v52, v26
	v_lshlrev_b32_e32 v31, 16, v63
	v_lshlrev_b32_e32 v29, 16, v59
	v_lshlrev_b32_e32 v51, 16, v62
	v_pk_mul_f32 v[54:55], v[28:29], v[28:29]
	s_waitcnt lgkmcnt(0)
	v_pk_add_f32 v[26:27], v[26:27], v[52:53]
	s_nop 1
	v_mov_b32_dpp v53, v27 row_ror:8 row_mask:0xf bank_mask:0xf
	v_mov_b32_dpp v52, v26 row_ror:8 row_mask:0xf bank_mask:0xf
	v_mov_b32_e32 v56, v54
	v_lshlrev_b32_e32 v23, 16, v66
	v_lshlrev_b32_e32 v22, 16, v60
	v_lshlrev_b32_e32 v21, 16, v67
	s_waitcnt lgkmcnt(0)
	v_pk_add_f32 v[26:27], v[26:27], v[52:53]
	s_nop 1
	v_mov_b32_dpp v53, v27 row_shl:4 row_mask:0xf bank_mask:0x5
	v_mov_b32_dpp v53, v27 row_shr:4 row_mask:0xf bank_mask:0xa
	v_mov_b32_dpp v52, v26 row_shl:4 row_mask:0xf bank_mask:0x5
	v_mov_b32_dpp v52, v26 row_shr:4 row_mask:0xf bank_mask:0xa
	v_lshlrev_b32_e32 v20, 16, v64
	v_lshlrev_b32_e32 v50, 16, v65
	v_lshlrev_b32_e32 v15, 16, v69
	v_lshlrev_b32_e32 v14, 16, v68
	s_waitcnt lgkmcnt(0)
	v_pk_add_f32 v[26:27], v[26:27], v[52:53]
	s_nop 1
	v_mov_b32_dpp v53, v27 quad_perm:[2,3,0,1] row_mask:0xf bank_mask:0xf
	v_mov_b32_dpp v52, v26 quad_perm:[2,3,0,1] row_mask:0xf bank_mask:0xf
	v_add_u32_e32 v2, s17, v2
	s_waitcnt lgkmcnt(0)
	v_pk_add_f32 v[26:27], v[26:27], v[52:53]
	s_nop 1
	v_mov_b32_dpp v53, v27 quad_perm:[1,0,3,2] row_mask:0xf bank_mask:0xf
	v_mov_b32_dpp v52, v26 quad_perm:[1,0,3,2] row_mask:0xf bank_mask:0xf
	s_waitcnt lgkmcnt(0)
	v_pk_add_f32 v[52:53], v[26:27], v[52:53]
	v_mov_b64_e32 v[26:27], s[72:73]
	v_pk_fma_f32 v[52:53], v[52:53], s[4:5], v[26:27] op_sel_hi:[1,0,0]
	s_nop 0
	v_mul_f32_e32 v49, 0x4b800000, v53
	v_cmp_gt_f32_e64 s[0:1], s77, v53
	v_cmp_gt_f32_e32 vcc, s77, v52
	s_nop 0
	v_cndmask_b32_e64 v49, v53, v49, s[0:1]
	v_rsq_f32_e32 v49, v49
	s_nop 0
	v_mul_f32_e32 v53, 0x45800000, v49
	v_cndmask_b32_e64 v49, v49, v53, s[0:1]
	v_mul_f32_e32 v49, 0x3dd53b94, v49
	v_mul_f32_e32 v19, v49, v19
	v_mul_f32_e32 v19, v41, v19
	ds_bpermute_b32 v53, v43, v19
	v_mul_f32_e32 v18, v49, v18
	v_mul_f32_e32 v18, v36, v18
	s_waitcnt lgkmcnt(0)
	v_mul_f32_e32 v53, v35, v53
	v_cndmask_b32_e64 v53, v53, -v53, s[38:39]
	v_fmac_f32_e32 v53, v34, v19
	v_bfe_u32 v19, v18, 16, 1
	v_add3_u32 v18, v18, v19, s11
	global_store_short_d16_hi v[16:17], v18, off
	v_mul_f32_e32 v18, v49, v70
	v_mul_f32_e32 v18, v37, v18
	v_bfe_u32 v19, v18, 16, 1
	v_add3_u32 v18, v18, v19, s11
	global_store_short_d16_hi v[16:17], v18, off offset:128
	v_bfe_u32 v18, v53, 16, 1
	v_add3_u32 v18, v53, v18, s11
	global_store_short_d16_hi v[16:17], v18, off offset:256
	v_mul_f32_e32 v18, 0x4b800000, v52
	v_cndmask_b32_e32 v18, v52, v18, vcc
	v_rsq_f32_e32 v18, v18
	v_mul_f32_e32 v53, v51, v51
	v_mul_f32_e32 v19, 0x45800000, v18
	v_cndmask_b32_e32 v49, v18, v19, vcc
	v_mul_f32_e32 v18, v49, v12
	v_mul_f32_e32 v18, v40, v18
	ds_bpermute_b32 v19, v43, v18
	s_waitcnt lgkmcnt(0)
	v_mul_f32_e32 v19, v35, v19
	v_cndmask_b32_e64 v52, v19, -v19, s[38:39]
	v_fmac_f32_e32 v52, v34, v18
	v_mul_f32_e32 v18, v49, v32
	v_mul_f32_e32 v18, v38, v18
	v_bfe_u32 v19, v18, 16, 1
	v_add3_u32 v32, v18, v19, s11
	v_mad_i64_i32 v[18:19], s[0:1], v3, s7, v[8:9]
	v_mul_f32_e32 v3, v49, v33
	v_mul_f32_e32 v3, v39, v3
	global_store_short_d16_hi v[18:19], v32, off
	v_bfe_u32 v32, v3, 16, 1
	v_add3_u32 v3, v3, v32, s11
	global_store_short_d16_hi v[18:19], v3, off offset:128
	v_bfe_u32 v3, v52, 16, 1
	v_pk_mul_f32 v[32:33], v[30:31], v[30:31]
	v_add3_u32 v3, v52, v3, s11
	v_mov_b32_e32 v57, v32
	v_mov_b32_e32 v52, v55
	v_pk_add_f32 v[52:53], v[56:57], v[52:53]
	v_mov_b32_e32 v32, v24
	v_pk_add_f32 v[32:33], v[32:33], v[52:53]
	v_mov_b32_e32 v53, v33
	v_mov_b32_e32 v52, v32
	s_nop 0
	v_permlane32_swap_b32_e32 v53, v33
	v_permlane32_swap_b32_e32 v52, v32
	global_store_short_d16_hi v[18:19], v3, off offset:256
	s_waitcnt lgkmcnt(0)
; DI bf16_t f2bf(float f) { unsigned u = __float_as_uint(f); u += 0x7fffu + ((u >> 16) & 1u); return (bf16_t)(u >> 16); }
; DI float wave_sum(float v) { for (int o = 32; o; o >>= 1) v += __shfl_xor(v, o); return v; }
; DI void run_phase(const Params& p, int ph, unsigned char* smem, const int tid, const int rep) {
;     ...
;                 for (int h = 0; h < 4; ++h) {
;                     { const float a0 = qa[u][h][0], a1 = qa[u][h][1], a2 = qa[u][h][2];
;                       const float rs = rsqrtf(wave_sum(a0 * a0 + a1 * a1 + a2 * a2) * (1.f / 192.f) + NEPS) * (0.07216878364870322f * LOG2E);
;                       const float y2 = a2 * rs * gq2; const float oth = __shfl_xor(y2, 32);
;                       const float rot = (lane < 32) ? (y2 * cs - oth * sn) : (y2 * cs + oth * sn);
;                       bf16_t* qo = mlaq + (size_t)t * 768 + h * 192; qo[lane] = f2bf(a0 * rs * gq0); qo[lane + 64] = f2bf(a1 * rs * gq1); qo[lane + 128] = f2bf(rot); }
;                     { const float a0 = ka[u][h][0], a1 = ka[u][h][1];
;                       const float rs = rsqrtf(wave_sum(a0 * a0 + a1 * a1 + kr * kr) * (1.f / 192.f) + NEPS);
;                       const float y2 = kr * rs * gk2; const float oth = __shfl_xor(y2, 32);
;                       const float rot = (lane < 32) ? (y2 * cs - oth * sn) : (y2 * cs + oth * sn);
;                       bf16_t* ko = mlak + (size_t)t * 768 + h * 192; ko[lane] = f2bf(a0 * rs * gk0); ko[lane + 64] = f2bf(a1 * rs * gk1); ko[lane + 128] = f2bf(rot); }
	v_pk_add_f32 v[32:33], v[32:33], v[52:53]
	v_mov_b32_e32 v53, v33
	v_mov_b32_e32 v52, v32
	s_nop 0
	v_permlane16_swap_b32_e32 v53, v33
	v_permlane16_swap_b32_e32 v52, v32
	s_waitcnt lgkmcnt(0)
	v_pk_add_f32 v[32:33], v[32:33], v[52:53]
	s_nop 1
	v_mov_b32_dpp v53, v33 row_ror:8 row_mask:0xf bank_mask:0xf
	v_mov_b32_dpp v52, v32 row_ror:8 row_mask:0xf bank_mask:0xf
	s_waitcnt lgkmcnt(0)
	v_pk_add_f32 v[32:33], v[32:33], v[52:53]
	s_nop 1
	v_mov_b32_dpp v53, v33 row_shl:4 row_mask:0xf bank_mask:0x5
	v_mov_b32_dpp v53, v33 row_shr:4 row_mask:0xf bank_mask:0xa
	v_mov_b32_dpp v52, v32 row_shl:4 row_mask:0xf bank_mask:0x5
	v_mov_b32_dpp v52, v32 row_shr:4 row_mask:0xf bank_mask:0xa
	s_waitcnt lgkmcnt(0)
	v_pk_add_f32 v[32:33], v[32:33], v[52:53]
	s_nop 1
	v_mov_b32_dpp v53, v33 quad_perm:[2,3,0,1] row_mask:0xf bank_mask:0xf
	v_mov_b32_dpp v52, v32 quad_perm:[2,3,0,1] row_mask:0xf bank_mask:0xf
	s_waitcnt lgkmcnt(0)
	v_pk_add_f32 v[32:33], v[32:33], v[52:53]
	s_nop 1
	v_mov_b32_dpp v53, v33 quad_perm:[1,0,3,2] row_mask:0xf bank_mask:0xf
	v_mov_b32_dpp v52, v32 quad_perm:[1,0,3,2] row_mask:0xf bank_mask:0xf
	s_waitcnt lgkmcnt(0)
	v_pk_add_f32 v[32:33], v[32:33], v[52:53]
	s_nop 0
	v_pk_fma_f32 v[32:33], v[32:33], s[4:5], v[26:27] op_sel_hi:[1,0,0]
	s_nop 0
	v_mul_f32_e32 v3, 0x4b800000, v33
	v_cmp_gt_f32_e64 s[0:1], s77, v33
	v_cmp_gt_f32_e32 vcc, s77, v32
	s_nop 0
	v_cndmask_b32_e64 v3, v33, v3, s[0:1]
	v_rsq_f32_e32 v3, v3
	s_nop 0
	v_mul_f32_e32 v33, 0x45800000, v3
	v_cndmask_b32_e64 v3, v3, v33, s[0:1]
	v_mul_f32_e32 v3, 0x3dd53b94, v3
	v_mul_f32_e32 v31, v3, v31
	v_mul_f32_e32 v31, v41, v31
	ds_bpermute_b32 v33, v43, v31
	v_mul_f32_e32 v30, v3, v30
	v_mul_f32_e32 v30, v36, v30
	v_mul_f32_e32 v3, v3, v51
	v_mul_f32_e32 v3, v37, v3
	s_waitcnt lgkmcnt(0)
	v_mul_f32_e32 v33, v35, v33
	v_cndmask_b32_e64 v33, v33, -v33, s[38:39]
	v_fmac_f32_e32 v33, v34, v31
	v_bfe_u32 v31, v30, 16, 1
	v_add3_u32 v30, v30, v31, s11
	global_store_short_d16_hi v[16:17], v30, off offset:384
	v_bfe_u32 v30, v3, 16, 1
	v_add3_u32 v3, v3, v30, s11
	global_store_short_d16_hi v[16:17], v3, off offset:512
	v_bfe_u32 v3, v33, 16, 1
	v_add3_u32 v3, v33, v3, s11
	global_store_short_d16_hi v[16:17], v3, off offset:640
	v_mul_f32_e32 v3, 0x4b800000, v32
	v_cndmask_b32_e32 v3, v32, v3, vcc
	v_rsq_f32_e32 v3, v3
	v_pk_mul_f32 v[32:33], v[20:21], v[20:21]
	v_mul_f32_e32 v30, 0x45800000, v3
	v_cndmask_b32_e32 v3, v3, v30, vcc
	v_mul_f32_e32 v30, v3, v12
	v_mul_f32_e32 v30, v40, v30
	ds_bpermute_b32 v31, v43, v30
	v_mul_f32_e32 v28, v3, v28
	v_mul_f32_e32 v28, v38, v28
	v_mul_f32_e32 v3, v3, v29
	v_mul_f32_e32 v3, v39, v3
	s_waitcnt lgkmcnt(0)
	v_mul_f32_e32 v31, v35, v31
	v_cndmask_b32_e64 v31, v31, -v31, s[38:39]
	v_fmac_f32_e32 v31, v34, v30
	v_bfe_u32 v30, v28, 16, 1
	v_add3_u32 v28, v28, v30, s11
	global_store_short_d16_hi v[18:19], v28, off offset:384
	v_bfe_u32 v28, v3, 16, 1
	v_add3_u32 v3, v3, v28, s11
	global_store_short_d16_hi v[18:19], v3, off offset:512
	v_bfe_u32 v3, v31, 16, 1
	v_pk_mul_f32 v[28:29], v[22:23], v[22:23]
	v_add3_u32 v3, v31, v3, s11
	v_mul_f32_e32 v31, v50, v50
	v_mov_b32_e32 v52, v32
	v_mov_b32_e32 v53, v28
	v_mov_b32_e32 v30, v33
	v_pk_add_f32 v[30:31], v[52:53], v[30:31]
	v_mov_b32_e32 v28, v24
	v_pk_add_f32 v[28:29], v[28:29], v[30:31]
	v_mov_b32_e32 v31, v29
	v_mov_b32_e32 v30, v28
	s_nop 0
	v_permlane32_swap_b32_e32 v31, v29
	v_permlane32_swap_b32_e32 v30, v28
	global_store_short_d16_hi v[18:19], v3, off offset:640
	s_waitcnt lgkmcnt(0)
	v_pk_add_f32 v[28:29], v[28:29], v[30:31]
	v_mov_b32_e32 v31, v29
	v_mov_b32_e32 v30, v28
	s_nop 0
	v_permlane16_swap_b32_e32 v31, v29
	v_permlane16_swap_b32_e32 v30, v28
	s_waitcnt lgkmcnt(0)
	v_pk_add_f32 v[28:29], v[28:29], v[30:31]
	s_nop 1
	v_mov_b32_dpp v31, v29 row_ror:8 row_mask:0xf bank_mask:0xf
	v_mov_b32_dpp v30, v28 row_ror:8 row_mask:0xf bank_mask:0xf
	s_waitcnt lgkmcnt(0)
	v_pk_add_f32 v[28:29], v[28:29], v[30:31]
	s_nop 1
	v_mov_b32_dpp v31, v29 row_shl:4 row_mask:0xf bank_mask:0x5
	v_mov_b32_dpp v31, v29 row_shr:4 row_mask:0xf bank_mask:0xa
	v_mov_b32_dpp v30, v28 row_shl:4 row_mask:0xf bank_mask:0x5
	v_mov_b32_dpp v30, v28 row_shr:4 row_mask:0xf bank_mask:0xa
	s_waitcnt lgkmcnt(0)
	v_pk_add_f32 v[28:29], v[28:29], v[30:31]
	s_nop 1
	v_mov_b32_dpp v31, v29 quad_perm:[2,3,0,1] row_mask:0xf bank_mask:0xf
	v_mov_b32_dpp v30, v28 quad_perm:[2,3,0,1] row_mask:0xf bank_mask:0xf
	s_waitcnt lgkmcnt(0)
	v_pk_add_f32 v[28:29], v[28:29], v[30:31]
	s_nop 1
	v_mov_b32_dpp v31, v29 quad_perm:[1,0,3,2] row_mask:0xf bank_mask:0xf
	v_mov_b32_dpp v30, v28 quad_perm:[1,0,3,2] row_mask:0xf bank_mask:0xf
	s_waitcnt lgkmcnt(0)
	v_pk_add_f32 v[28:29], v[28:29], v[30:31]
	s_nop 0
	v_pk_fma_f32 v[28:29], v[28:29], s[4:5], v[26:27] op_sel_hi:[1,0,0]
	s_nop 0
	v_mul_f32_e32 v3, 0x4b800000, v29
	v_cmp_gt_f32_e64 s[0:1], s77, v29
	v_cmp_gt_f32_e32 vcc, s77, v28
	s_nop 0
	v_cndmask_b32_e64 v3, v29, v3, s[0:1]
	v_rsq_f32_e32 v3, v3
	s_nop 0
	v_mul_f32_e32 v29, 0x45800000, v3
	v_cndmask_b32_e64 v3, v3, v29, s[0:1]
	v_mul_f32_e32 v3, 0x3dd53b94, v3
	v_mul_f32_e32 v23, v3, v23
	v_mul_f32_e32 v23, v41, v23
	ds_bpermute_b32 v29, v43, v23
	v_mul_f32_e32 v22, v3, v22
	v_mul_f32_e32 v22, v36, v22
	v_mul_f32_e32 v3, v3, v50
	v_mul_f32_e32 v3, v37, v3
	s_waitcnt lgkmcnt(0)
; DI bf16_t f2bf(float f) { unsigned u = __float_as_uint(f); u += 0x7fffu + ((u >> 16) & 1u); return (bf16_t)(u >> 16); }
; DI float wave_sum(float v) { for (int o = 32; o; o >>= 1) v += __shfl_xor(v, o); return v; }
; DI void run_phase(const Params& p, int ph, unsigned char* smem, const int tid, const int rep) {
;     ...
;                 for (int h = 0; h < 4; ++h) {
;                     { const float a0 = qa[u][h][0], a1 = qa[u][h][1], a2 = qa[u][h][2];
;                       const float rs = rsqrtf(wave_sum(a0 * a0 + a1 * a1 + a2 * a2) * (1.f / 192.f) + NEPS) * (0.07216878364870322f * LOG2E);
;                       const float y2 = a2 * rs * gq2; const float oth = __shfl_xor(y2, 32);
;                       const float rot = (lane < 32) ? (y2 * cs - oth * sn) : (y2 * cs + oth * sn);
;                       bf16_t* qo = mlaq + (size_t)t * 768 + h * 192; qo[lane] = f2bf(a0 * rs * gq0); qo[lane + 64] = f2bf(a1 * rs * gq1); qo[lane + 128] = f2bf(rot); }
;                     { const float a0 = ka[u][h][0], a1 = ka[u][h][1];
;                       const float rs = rsqrtf(wave_sum(a0 * a0 + a1 * a1 + kr * kr) * (1.f / 192.f) + NEPS);
;                       const float y2 = kr * rs * gk2; const float oth = __shfl_xor(y2, 32);
;                       const float rot = (lane < 32) ? (y2 * cs - oth * sn) : (y2 * cs + oth * sn);
;                       bf16_t* ko = mlak + (size_t)t * 768 + h * 192; ko[lane] = f2bf(a0 * rs * gk0); ko[lane + 64] = f2bf(a1 * rs * gk1); ko[lane + 128] = f2bf(rot); }
;                 }
	v_mul_f32_e32 v29, v35, v29
	v_cndmask_b32_e64 v29, v29, -v29, s[38:39]
	v_fmac_f32_e32 v29, v34, v23
	v_bfe_u32 v23, v22, 16, 1
	v_add3_u32 v22, v22, v23, s11
	global_store_short_d16_hi v[16:17], v22, off offset:768
	v_bfe_u32 v22, v3, 16, 1
	v_add3_u32 v3, v3, v22, s11
	global_store_short_d16_hi v[16:17], v3, off offset:896
	v_bfe_u32 v3, v29, 16, 1
	v_add3_u32 v3, v29, v3, s11
	global_store_short_d16_hi v[16:17], v3, off offset:1024
	v_mul_f32_e32 v3, 0x4b800000, v28
	v_cndmask_b32_e32 v3, v28, v3, vcc
	v_rsq_f32_e32 v3, v3
	s_nop 0
	v_mul_f32_e32 v22, 0x45800000, v3
	v_cndmask_b32_e32 v3, v3, v22, vcc
	v_mul_f32_e32 v22, v3, v12
	v_mul_f32_e32 v22, v40, v22
	ds_bpermute_b32 v23, v43, v22
	v_mul_f32_e32 v20, v3, v20
	v_mul_f32_e32 v20, v38, v20
	v_mul_f32_e32 v3, v3, v21
	v_mul_f32_e32 v3, v39, v3
	s_waitcnt lgkmcnt(0)
	v_mul_f32_e32 v23, v35, v23
	v_cndmask_b32_e64 v23, v23, -v23, s[38:39]
	v_fmac_f32_e32 v23, v34, v22
	v_bfe_u32 v22, v20, 16, 1
	v_add3_u32 v20, v20, v22, s11
	global_store_short_d16_hi v[18:19], v20, off offset:768
	v_bfe_u32 v20, v3, 16, 1
	v_add3_u32 v3, v3, v20, s11
	global_store_short_d16_hi v[18:19], v3, off offset:896
	v_bfe_u32 v3, v23, 16, 1
	v_pk_mul_f32 v[20:21], v[14:15], v[14:15]
	v_add3_u32 v3, v23, v3, s11
	v_pk_mov_b32 v[22:23], v[24:25], v[20:21] op_sel:[1,0]
	v_mov_b32_e32 v25, v21
	v_pk_fma_f32 v[22:23], v[10:11], v[10:11], v[22:23]
	global_store_short_d16_hi v[18:19], v3, off offset:1024
	v_pk_add_f32 v[20:21], v[24:25], v[22:23]
	v_mov_b32_e32 v23, v21
	v_mov_b32_e32 v22, v20
	s_nop 0
	v_permlane32_swap_b32_e32 v23, v21
	v_permlane32_swap_b32_e32 v22, v20
	s_waitcnt lgkmcnt(0)
	v_pk_add_f32 v[20:21], v[20:21], v[22:23]
	v_mov_b32_e32 v23, v21
	v_mov_b32_e32 v22, v20
	s_nop 0
	v_permlane16_swap_b32_e32 v23, v21
	v_permlane16_swap_b32_e32 v22, v20
	s_waitcnt lgkmcnt(0)
	v_pk_add_f32 v[20:21], v[20:21], v[22:23]
	s_nop 1
	v_mov_b32_dpp v23, v21 row_ror:8 row_mask:0xf bank_mask:0xf
	v_mov_b32_dpp v22, v20 row_ror:8 row_mask:0xf bank_mask:0xf
	s_waitcnt lgkmcnt(0)
	v_pk_add_f32 v[20:21], v[20:21], v[22:23]
	s_nop 1
	v_mov_b32_dpp v23, v21 row_shl:4 row_mask:0xf bank_mask:0x5
	v_mov_b32_dpp v23, v21 row_shr:4 row_mask:0xf bank_mask:0xa
	v_mov_b32_dpp v22, v20 row_shl:4 row_mask:0xf bank_mask:0x5
	v_mov_b32_dpp v22, v20 row_shr:4 row_mask:0xf bank_mask:0xa
	s_waitcnt lgkmcnt(0)
	v_pk_add_f32 v[20:21], v[20:21], v[22:23]
	s_nop 1
	v_mov_b32_dpp v23, v21 quad_perm:[2,3,0,1] row_mask:0xf bank_mask:0xf
	v_mov_b32_dpp v22, v20 quad_perm:[2,3,0,1] row_mask:0xf bank_mask:0xf
	s_waitcnt lgkmcnt(0)
	v_pk_add_f32 v[20:21], v[20:21], v[22:23]
	s_nop 1
	v_mov_b32_dpp v23, v21 quad_perm:[1,0,3,2] row_mask:0xf bank_mask:0xf
	v_mov_b32_dpp v22, v20 quad_perm:[1,0,3,2] row_mask:0xf bank_mask:0xf
	s_waitcnt lgkmcnt(0)
	v_pk_add_f32 v[20:21], v[20:21], v[22:23]
	s_nop 0
	v_pk_fma_f32 v[20:21], v[20:21], s[4:5], v[26:27] op_sel_hi:[1,0,0]
	s_nop 0
	v_mul_f32_e32 v3, 0x4b800000, v21
	v_cmp_gt_f32_e64 s[0:1], s77, v21
	v_cmp_gt_f32_e32 vcc, s77, v20
	s_nop 0
	v_cndmask_b32_e64 v3, v21, v3, s[0:1]
	v_rsq_f32_e32 v3, v3
	s_nop 0
	v_mul_f32_e32 v21, 0x45800000, v3
	v_cndmask_b32_e64 v3, v3, v21, s[0:1]
	v_mul_f32_e32 v3, 0x3dd53b94, v3
	v_mul_f32_e32 v15, v3, v15
	v_mul_f32_e32 v15, v41, v15
	ds_bpermute_b32 v21, v43, v15
	v_mul_f32_e32 v14, v3, v14
	v_mul_f32_e32 v3, v3, v11
	v_mul_f32_e32 v3, v37, v3
	v_bfe_u32 v11, v3, 16, 1
	s_waitcnt lgkmcnt(0)
	v_mul_f32_e32 v21, v35, v21
	v_cndmask_b32_e64 v21, v21, -v21, s[38:39]
	v_fmac_f32_e32 v21, v34, v15
	v_add3_u32 v3, v3, v11, s11
	global_store_short_d16_hi v[16:17], v3, off offset:1280
	v_bfe_u32 v3, v21, 16, 1
	v_add3_u32 v3, v21, v3, s11
	global_store_short_d16_hi v[16:17], v3, off offset:1408
	v_mul_f32_e32 v3, 0x4b800000, v20
	v_cndmask_b32_e32 v3, v20, v3, vcc
	v_rsq_f32_e32 v3, v3
	v_mul_f32_e32 v14, v36, v14
	v_bfe_u32 v15, v14, 16, 1
	v_add3_u32 v14, v14, v15, s11
	v_mul_f32_e32 v11, 0x45800000, v3
	v_cndmask_b32_e32 v3, v3, v11, vcc
	v_mul_f32_e32 v11, v3, v12
	v_mul_f32_e32 v11, v40, v11
	ds_bpermute_b32 v12, v43, v11
	v_cmp_lt_i32_e32 vcc, s11, v2
	s_or_b64 s[34:35], vcc, s[34:35]
	global_store_short_d16_hi v[16:17], v14, off offset:1152
	s_waitcnt lgkmcnt(0)
	v_mul_f32_e32 v12, v35, v12
	v_cndmask_b32_e64 v12, v12, -v12, s[38:39]
	v_fmac_f32_e32 v12, v34, v11
	v_mul_f32_e32 v11, v3, v13
	v_mul_f32_e32 v3, v3, v10
	v_mul_f32_e32 v3, v39, v3
	v_bfe_u32 v10, v3, 16, 1
	v_mul_f32_e32 v11, v38, v11
	v_add3_u32 v3, v3, v10, s11
	v_bfe_u32 v13, v11, 16, 1
	global_store_short_d16_hi v[18:19], v3, off offset:1280
	v_bfe_u32 v3, v12, 16, 1
	v_add3_u32 v11, v11, v13, s11
	v_add3_u32 v3, v12, v3, s11
	global_store_short_d16_hi v[18:19], v11, off offset:1152
	global_store_short_d16_hi v[18:19], v3, off offset:1408
	s_andn2_b64 exec, exec, s[34:35]
	s_cbranch_execz .LBB0_340

; DI bf16_t f2bf(float f) { unsigned u = __float_as_uint(f); u += 0x7fffu + ((u >> 16) & 1u); return (bf16_t)(u >> 16); }
; DI float wave_sum(float v) { for (int o = 32; o; o >>= 1) v += __shfl_xor(v, o); return v; }
; DI void run_phase(const Params& p, int ph, unsigned char* smem, const int tid, const int rep) {
;     ...
; #pragma unroll
;             for (int u = 0; u < 2; ++u) { const int t = t0 + u;
;                 const float ang = (float)ps[u] * invf; float sn, cs; sincosf(ang, &sn, &cs);
;                 const float kr = krv[u];
; #pragma unroll
;                 for (int h = 0; h < 4; ++h) {
;                     { const float a0 = qa[u][h][0], a1 = qa[u][h][1], a2 = qa[u][h][2];
;                       const float rs = rsqrtf(wave_sum(a0 * a0 + a1 * a1 + a2 * a2) * (1.f / 192.f) + NEPS) * (0.07216878364870322f * LOG2E);
;                       const float y2 = a2 * rs * gq2; const float oth = __shfl_xor(y2, 32);
;                       const float rot = (lane < 32) ? (y2 * cs - oth * sn) : (y2 * cs + oth * sn);
;                       bf16_t* qo = mlaq + (size_t)t * 768 + h * 192; qo[lane] = f2bf(a0 * rs * gq0); qo[lane + 64] = f2bf(a1 * rs * gq1); qo[lane + 128] = f2bf(rot); }
;                     { const float a0 = ka[u][h][0], a1 = ka[u][h][1];
;                       const float rs = rsqrtf(wave_sum(a0 * a0 + a1 * a1 + kr * kr) * (1.f / 192.f) + NEPS);
;                       const float y2 = kr * rs * gk2; const float oth = __shfl_xor(y2, 32);
;                       const float rot = (lane < 32) ? (y2 * cs - oth * sn) : (y2 * cs + oth * sn);
;                       bf16_t* ko = mlak + (size_t)t * 768 + h * 192; ko[lane] = f2bf(a0 * rs * gk0); ko[lane + 64] = f2bf(a1 * rs * gk1); ko[lane + 128] = f2bf(rot); }
;                 }
.LBB0_336:
	s_or_b64 exec, exec, s[0:1]
	s_waitcnt vmcnt(40)
	v_lshlrev_b32_e32 v20, 16, v15
	s_waitcnt vmcnt(22)
	v_lshlrev_b32_e32 v15, 16, v14
	v_lshlrev_b32_e32 v14, 16, v12
	s_waitcnt vmcnt(21)
	v_lshlrev_b32_e32 v12, 16, v18
	v_mul_f32_e32 v18, v78, v78
	v_lshlrev_b32_e32 v32, 16, v19
	v_fmamk_f32 v19, v18, 0xb94c1982, v249
	v_fmaak_f32 v19, v18, v19, 0xbe2aaa9d
	v_mul_f32_e32 v19, v18, v19
	v_fmac_f32_e32 v78, v78, v19
	v_fmamk_f32 v19, v18, 0x37d75334, v223
	v_fmaak_f32 v19, v18, v19, 0x3d2aabf7
	v_lshlrev_b32_e32 v30, 16, v27
	v_fmaak_f32 v19, v18, v19, 0xbf000004
	v_and_b32_e32 v27, 1, v79
	v_fma_f32 v18, v18, v19, 1.0
	v_cmp_eq_u32_e32 vcc, 0, v27
	v_lshlrev_b32_e32 v31, 16, v28
	v_lshlrev_b32_e32 v19, 30, v79
	v_cndmask_b32_e32 v27, v18, v78, vcc
	v_xor_b32_e32 v28, v77, v10
	v_lshlrev_b32_e32 v33, 16, v24
	v_lshlrev_b32_e32 v24, 16, v26
	v_and_b32_e32 v26, 0x80000000, v19
	v_xor_b32_e32 v27, v28, v27
	v_xor_b32_e32 v26, v27, v26
	v_xor_b32_e32 v27, 0x80000000, v78
	v_cndmask_b32_e32 v18, v27, v18, vcc
	s_brev_b32 s0, 1
	v_lshlrev_b32_e32 v21, 16, v17
	v_lshlrev_b32_e32 v35, 16, v25
	v_lshlrev_b32_e32 v34, 16, v22
	v_bitop3_b32 v18, v18, v19, s0 bitop3:0x78
	s_movk_i32 s0, 0x1f8
	v_lshlrev_b32_e32 v80, 16, v16
	v_lshlrev_b32_e32 v22, 16, v29
	v_lshlrev_b32_e32 v17, 16, v76
	v_cmp_class_f32_e64 vcc, v10, s0
	v_pk_mul_f32 v[28:29], v[20:21], v[20:21]
	v_pk_mul_f32 v[76:77], v[34:35], v[34:35]
	v_lshlrev_b32_e32 v72, 16, v23
	v_lshlrev_b32_e32 v71, 16, v70
	v_lshlrev_b32_e32 v23, 16, v74
	v_lshlrev_b32_e32 v16, 16, v75
	v_cndmask_b32_e32 v70, v224, v26, vcc
	v_pk_mul_f32 v[26:27], v[14:15], v[14:15]
	v_mul_f32_e32 v75, v80, v80
	v_mov_b32_e32 v78, v76
	v_mov_b32_e32 v79, v28
	v_mov_b32_e32 v74, v77
	v_pk_add_f32 v[74:75], v[78:79], v[74:75]
	v_mov_b32_e32 v28, v26
	v_pk_add_f32 v[28:29], v[28:29], v[74:75]
	v_mov_b32_e32 v75, v29
	v_mov_b32_e32 v74, v28
	s_nop 0
	v_permlane32_swap_b32_e32 v75, v29
	v_permlane32_swap_b32_e32 v74, v28
	s_mov_b32 s4, 0x3baaaaab
	v_cndmask_b32_e32 v10, v224, v18, vcc
	v_mad_i64_i32 v[18:19], s[0:1], v2, s7, v[6:7]
	s_waitcnt lgkmcnt(0)
	v_pk_add_f32 v[28:29], v[28:29], v[74:75]
	v_mov_b32_e32 v75, v29
	v_mov_b32_e32 v74, v28
	s_nop 0
	v_permlane16_swap_b32_e32 v75, v29
	v_permlane16_swap_b32_e32 v74, v28
	v_lshlrev_b32_e32 v25, 16, v73
	v_pk_mul_f32 v[76:77], v[30:31], v[30:31]
	v_lshlrev_b32_e32 v13, 16, v13
	v_mov_b32_e32 v78, v76
	s_waitcnt lgkmcnt(0)
	v_pk_add_f32 v[28:29], v[28:29], v[74:75]
	s_nop 1
	v_mov_b32_dpp v75, v29 row_ror:8 row_mask:0xf bank_mask:0xf
	v_mov_b32_dpp v74, v28 row_ror:8 row_mask:0xf bank_mask:0xf
	s_waitcnt lgkmcnt(0)
	v_pk_add_f32 v[28:29], v[28:29], v[74:75]
	s_nop 1
	v_mov_b32_dpp v75, v29 row_shl:4 row_mask:0xf bank_mask:0x5
	v_mov_b32_dpp v75, v29 row_shr:4 row_mask:0xf bank_mask:0xa
	v_mov_b32_dpp v74, v28 row_shl:4 row_mask:0xf bank_mask:0x5
	v_mov_b32_dpp v74, v28 row_shr:4 row_mask:0xf bank_mask:0xa
	s_waitcnt lgkmcnt(0)
	v_pk_add_f32 v[28:29], v[28:29], v[74:75]
	s_nop 1
	v_mov_b32_dpp v75, v29 quad_perm:[2,3,0,1] row_mask:0xf bank_mask:0xf
	v_mov_b32_dpp v74, v28 quad_perm:[2,3,0,1] row_mask:0xf bank_mask:0xf
	s_waitcnt lgkmcnt(0)
	v_pk_add_f32 v[28:29], v[28:29], v[74:75]
	s_nop 1
	v_mov_b32_dpp v75, v29 quad_perm:[1,0,3,2] row_mask:0xf bank_mask:0xf
	v_mov_b32_dpp v74, v28 quad_perm:[1,0,3,2] row_mask:0xf bank_mask:0xf
	s_waitcnt lgkmcnt(0)
	v_pk_add_f32 v[74:75], v[28:29], v[74:75]
	v_mov_b64_e32 v[28:29], s[72:73]
	v_pk_fma_f32 v[74:75], v[74:75], s[4:5], v[28:29] op_sel_hi:[1,0,0]
	s_nop 0
	v_mul_f32_e32 v73, 0x4b800000, v75
	v_cmp_gt_f32_e64 s[0:1], s77, v75
	v_cmp_gt_f32_e32 vcc, s77, v74
	s_nop 0
	v_cndmask_b32_e64 v73, v75, v73, s[0:1]
	v_rsq_f32_e32 v73, v73
	s_nop 0
	v_mul_f32_e32 v75, 0x45800000, v73
	v_cndmask_b32_e64 v73, v73, v75, s[0:1]
	v_mul_f32_e32 v73, 0x3dd53b94, v73
	v_mul_f32_e32 v21, v73, v21
	v_mul_f32_e32 v21, v41, v21
	ds_bpermute_b32 v75, v43, v21
	v_mul_f32_e32 v20, v73, v20
	v_mul_f32_e32 v20, v36, v20
	s_waitcnt lgkmcnt(0)
	v_mul_f32_e32 v75, v70, v75
	v_cndmask_b32_e64 v75, v75, -v75, s[38:39]
	v_fmac_f32_e32 v75, v10, v21
	v_bfe_u32 v21, v20, 16, 1
	v_add3_u32 v20, v20, v21, s11
	global_store_short_d16_hi v[18:19], v20, off
	v_mul_f32_e32 v20, v73, v80
	v_mul_f32_e32 v20, v37, v20
	v_bfe_u32 v21, v20, 16, 1
	v_add3_u32 v20, v20, v21, s11
	global_store_short_d16_hi v[18:19], v20, off offset:128
	v_bfe_u32 v20, v75, 16, 1
	v_add3_u32 v20, v75, v20, s11
	global_store_short_d16_hi v[18:19], v20, off offset:256
	v_mul_f32_e32 v20, 0x4b800000, v74
	v_cndmask_b32_e32 v20, v74, v20, vcc
	v_rsq_f32_e32 v20, v20
	v_mul_f32_e32 v75, v72, v72
	v_mul_f32_e32 v21, 0x45800000, v20
	v_cndmask_b32_e32 v73, v20, v21, vcc
	v_mul_f32_e32 v20, v73, v14
	v_mul_f32_e32 v20, v40, v20
	ds_bpermute_b32 v21, v43, v20
	s_waitcnt lgkmcnt(0)
	v_mul_f32_e32 v21, v70, v21
	v_cndmask_b32_e64 v74, v21, -v21, s[38:39]
	v_fmac_f32_e32 v74, v10, v20
	v_mul_f32_e32 v20, v73, v34
	v_mul_f32_e32 v20, v38, v20
	v_bfe_u32 v21, v20, 16, 1
	v_add3_u32 v34, v20, v21, s11
	v_mad_i64_i32 v[20:21], s[0:1], v2, s7, v[8:9]
	global_store_short_d16_hi v[20:21], v34, off
	v_mul_f32_e32 v34, v73, v35
	v_mul_f32_e32 v34, v39, v34
	v_bfe_u32 v35, v34, 16, 1
	v_add3_u32 v34, v34, v35, s11
	global_store_short_d16_hi v[20:21], v34, off offset:128
	v_bfe_u32 v34, v74, 16, 1
	v_add3_u32 v34, v74, v34, s11
	global_store_short_d16_hi v[20:21], v34, off offset:256
	v_pk_mul_f32 v[34:35], v[32:33], v[32:33]
	v_mov_b32_e32 v74, v77
	v_mov_b32_e32 v79, v34
	v_pk_add_f32 v[74:75], v[78:79], v[74:75]
	v_mov_b32_e32 v34, v26
	v_pk_add_f32 v[34:35], v[34:35], v[74:75]
	v_mov_b32_e32 v75, v35
	v_mov_b32_e32 v74, v34
	s_nop 0
	v_permlane32_swap_b32_e32 v75, v35
	v_permlane32_swap_b32_e32 v74, v34
	s_waitcnt lgkmcnt(0)
; DI bf16_t f2bf(float f) { unsigned u = __float_as_uint(f); u += 0x7fffu + ((u >> 16) & 1u); return (bf16_t)(u >> 16); }
; DI float wave_sum(float v) { for (int o = 32; o; o >>= 1) v += __shfl_xor(v, o); return v; }
; DI void run_phase(const Params& p, int ph, unsigned char* smem, const int tid, const int rep) {
;     ...
;                 for (int h = 0; h < 4; ++h) {
;                     { const float a0 = qa[u][h][0], a1 = qa[u][h][1], a2 = qa[u][h][2];
;                       const float rs = rsqrtf(wave_sum(a0 * a0 + a1 * a1 + a2 * a2) * (1.f / 192.f) + NEPS) * (0.07216878364870322f * LOG2E);
;                       const float y2 = a2 * rs * gq2; const float oth = __shfl_xor(y2, 32);
;                       const float rot = (lane < 32) ? (y2 * cs - oth * sn) : (y2 * cs + oth * sn);
;                       bf16_t* qo = mlaq + (size_t)t * 768 + h * 192; qo[lane] = f2bf(a0 * rs * gq0); qo[lane + 64] = f2bf(a1 * rs * gq1); qo[lane + 128] = f2bf(rot); }
;                     { const float a0 = ka[u][h][0], a1 = ka[u][h][1];
;                       const float rs = rsqrtf(wave_sum(a0 * a0 + a1 * a1 + kr * kr) * (1.f / 192.f) + NEPS);
;                       const float y2 = kr * rs * gk2; const float oth = __shfl_xor(y2, 32);
;                       const float rot = (lane < 32) ? (y2 * cs - oth * sn) : (y2 * cs + oth * sn);
;                       bf16_t* ko = mlak + (size_t)t * 768 + h * 192; ko[lane] = f2bf(a0 * rs * gk0); ko[lane + 64] = f2bf(a1 * rs * gk1); ko[lane + 128] = f2bf(rot); }
	v_pk_add_f32 v[34:35], v[34:35], v[74:75]
	v_mov_b32_e32 v75, v35
	v_mov_b32_e32 v74, v34
	s_nop 0
	v_permlane16_swap_b32_e32 v75, v35
	v_permlane16_swap_b32_e32 v74, v34
	s_waitcnt lgkmcnt(0)
	v_pk_add_f32 v[34:35], v[34:35], v[74:75]
	s_nop 1
	v_mov_b32_dpp v75, v35 row_ror:8 row_mask:0xf bank_mask:0xf
	v_mov_b32_dpp v74, v34 row_ror:8 row_mask:0xf bank_mask:0xf
	s_waitcnt lgkmcnt(0)
	v_pk_add_f32 v[34:35], v[34:35], v[74:75]
	s_nop 1
	v_mov_b32_dpp v75, v35 row_shl:4 row_mask:0xf bank_mask:0x5
	v_mov_b32_dpp v75, v35 row_shr:4 row_mask:0xf bank_mask:0xa
	v_mov_b32_dpp v74, v34 row_shl:4 row_mask:0xf bank_mask:0x5
	v_mov_b32_dpp v74, v34 row_shr:4 row_mask:0xf bank_mask:0xa
	s_waitcnt lgkmcnt(0)
	v_pk_add_f32 v[34:35], v[34:35], v[74:75]
	s_nop 1
	v_mov_b32_dpp v75, v35 quad_perm:[2,3,0,1] row_mask:0xf bank_mask:0xf
	v_mov_b32_dpp v74, v34 quad_perm:[2,3,0,1] row_mask:0xf bank_mask:0xf
	s_waitcnt lgkmcnt(0)
	v_pk_add_f32 v[34:35], v[34:35], v[74:75]
	s_nop 1
	v_mov_b32_dpp v75, v35 quad_perm:[1,0,3,2] row_mask:0xf bank_mask:0xf
	v_mov_b32_dpp v74, v34 quad_perm:[1,0,3,2] row_mask:0xf bank_mask:0xf
	s_waitcnt lgkmcnt(0)
	v_pk_add_f32 v[34:35], v[34:35], v[74:75]
	s_nop 0
	v_pk_fma_f32 v[34:35], v[34:35], s[4:5], v[28:29] op_sel_hi:[1,0,0]
	s_nop 0
	v_mul_f32_e32 v73, 0x4b800000, v35
	v_cmp_gt_f32_e64 s[0:1], s77, v35
	v_cmp_gt_f32_e32 vcc, s77, v34
	s_nop 0
	v_cndmask_b32_e64 v35, v35, v73, s[0:1]
	v_rsq_f32_e32 v35, v35
	s_nop 0
	v_mul_f32_e32 v73, 0x45800000, v35
	v_cndmask_b32_e64 v35, v35, v73, s[0:1]
	v_mul_f32_e32 v35, 0x3dd53b94, v35
	v_mul_f32_e32 v33, v35, v33
	v_mul_f32_e32 v33, v41, v33
	ds_bpermute_b32 v73, v43, v33
	v_mul_f32_e32 v32, v35, v32
	v_mul_f32_e32 v32, v36, v32
	s_waitcnt lgkmcnt(0)
	v_mul_f32_e32 v73, v70, v73
	v_cndmask_b32_e64 v73, v73, -v73, s[38:39]
	v_fmac_f32_e32 v73, v10, v33
	v_bfe_u32 v33, v32, 16, 1
	v_add3_u32 v32, v32, v33, s11
	global_store_short_d16_hi v[18:19], v32, off offset:384
	v_mul_f32_e32 v32, v35, v72
	v_mul_f32_e32 v32, v37, v32
	v_bfe_u32 v33, v32, 16, 1
	v_add3_u32 v32, v32, v33, s11
	global_store_short_d16_hi v[18:19], v32, off offset:512
	v_bfe_u32 v32, v73, 16, 1
	v_add3_u32 v32, v73, v32, s11
	global_store_short_d16_hi v[18:19], v32, off offset:640
	v_mul_f32_e32 v32, 0x4b800000, v34
	v_cndmask_b32_e32 v32, v34, v32, vcc
	v_rsq_f32_e32 v32, v32
	s_nop 0
	v_mul_f32_e32 v33, 0x45800000, v32
	v_cndmask_b32_e32 v32, v32, v33, vcc
	v_mul_f32_e32 v33, v32, v14
	v_mul_f32_e32 v33, v40, v33
	ds_bpermute_b32 v34, v43, v33
	v_mul_f32_e32 v30, v32, v30
	v_mul_f32_e32 v30, v38, v30
	s_waitcnt lgkmcnt(0)
	v_mul_f32_e32 v34, v70, v34
	v_cndmask_b32_e64 v34, v34, -v34, s[38:39]
	v_fmac_f32_e32 v34, v10, v33
	v_bfe_u32 v33, v30, 16, 1
	v_add3_u32 v30, v30, v33, s11
	global_store_short_d16_hi v[20:21], v30, off offset:384
	v_mul_f32_e32 v30, v32, v31
	v_mul_f32_e32 v30, v39, v30
	v_bfe_u32 v31, v30, 16, 1
	v_add3_u32 v30, v30, v31, s11
	global_store_short_d16_hi v[20:21], v30, off offset:512
	v_bfe_u32 v30, v34, 16, 1
	v_add3_u32 v30, v34, v30, s11
	global_store_short_d16_hi v[20:21], v30, off offset:640
	v_pk_mul_f32 v[30:31], v[24:25], v[24:25]
	v_pk_mul_f32 v[34:35], v[22:23], v[22:23]
	v_mul_f32_e32 v33, v71, v71
	v_mov_b32_e32 v72, v34
	v_mov_b32_e32 v73, v30
	v_mov_b32_e32 v32, v35
	v_pk_add_f32 v[32:33], v[72:73], v[32:33]
	v_mov_b32_e32 v30, v26
	v_pk_add_f32 v[30:31], v[30:31], v[32:33]
	v_mov_b32_e32 v33, v31
	v_mov_b32_e32 v32, v30
	s_nop 0
	v_permlane32_swap_b32_e32 v33, v31
	v_permlane32_swap_b32_e32 v32, v30
	s_waitcnt lgkmcnt(0)
	v_pk_add_f32 v[30:31], v[30:31], v[32:33]
	v_mov_b32_e32 v33, v31
	v_mov_b32_e32 v32, v30
	s_nop 0
	v_permlane16_swap_b32_e32 v33, v31
	v_permlane16_swap_b32_e32 v32, v30
	s_waitcnt lgkmcnt(0)
	v_pk_add_f32 v[30:31], v[30:31], v[32:33]
	s_nop 1
	v_mov_b32_dpp v33, v31 row_ror:8 row_mask:0xf bank_mask:0xf
	v_mov_b32_dpp v32, v30 row_ror:8 row_mask:0xf bank_mask:0xf
	s_waitcnt lgkmcnt(0)
	v_pk_add_f32 v[30:31], v[30:31], v[32:33]
	s_nop 1
	v_mov_b32_dpp v33, v31 row_shl:4 row_mask:0xf bank_mask:0x5
	v_mov_b32_dpp v33, v31 row_shr:4 row_mask:0xf bank_mask:0xa
	v_mov_b32_dpp v32, v30 row_shl:4 row_mask:0xf bank_mask:0x5
	v_mov_b32_dpp v32, v30 row_shr:4 row_mask:0xf bank_mask:0xa
	s_waitcnt lgkmcnt(0)
	v_pk_add_f32 v[30:31], v[30:31], v[32:33]
	s_nop 1
	v_mov_b32_dpp v33, v31 quad_perm:[2,3,0,1] row_mask:0xf bank_mask:0xf
	v_mov_b32_dpp v32, v30 quad_perm:[2,3,0,1] row_mask:0xf bank_mask:0xf
	s_waitcnt lgkmcnt(0)
	v_pk_add_f32 v[30:31], v[30:31], v[32:33]
	s_nop 1
	v_mov_b32_dpp v33, v31 quad_perm:[1,0,3,2] row_mask:0xf bank_mask:0xf
	v_mov_b32_dpp v32, v30 quad_perm:[1,0,3,2] row_mask:0xf bank_mask:0xf
	s_waitcnt lgkmcnt(0)
	v_pk_add_f32 v[30:31], v[30:31], v[32:33]
	s_nop 0
	v_pk_fma_f32 v[30:31], v[30:31], s[4:5], v[28:29] op_sel_hi:[1,0,0]
	s_nop 0
	v_mul_f32_e32 v32, 0x4b800000, v31
	v_cmp_gt_f32_e64 s[0:1], s77, v31
	v_cmp_gt_f32_e32 vcc, s77, v30
	s_nop 0
	v_cndmask_b32_e64 v31, v31, v32, s[0:1]
	v_rsq_f32_e32 v31, v31
	s_nop 0
	v_mul_f32_e32 v32, 0x45800000, v31
	v_cndmask_b32_e64 v31, v31, v32, s[0:1]
	v_mul_f32_e32 v31, 0x3dd53b94, v31
	v_mul_f32_e32 v25, v31, v25
	v_mul_f32_e32 v25, v41, v25
	ds_bpermute_b32 v32, v43, v25
	v_mul_f32_e32 v24, v31, v24
	v_mul_f32_e32 v24, v36, v24
	s_waitcnt lgkmcnt(0)
; DI bf16_t f2bf(float f) { unsigned u = __float_as_uint(f); u += 0x7fffu + ((u >> 16) & 1u); return (bf16_t)(u >> 16); }
; DI float wave_sum(float v) { for (int o = 32; o; o >>= 1) v += __shfl_xor(v, o); return v; }
; DI void run_phase(const Params& p, int ph, unsigned char* smem, const int tid, const int rep) {
;     ...
;                 const float ang = (float)ps[u] * invf; float sn, cs; sincosf(ang, &sn, &cs);
;     ...
;                 for (int h = 0; h < 4; ++h) {
;                     { const float a0 = qa[u][h][0], a1 = qa[u][h][1], a2 = qa[u][h][2];
;                       const float rs = rsqrtf(wave_sum(a0 * a0 + a1 * a1 + a2 * a2) * (1.f / 192.f) + NEPS) * (0.07216878364870322f * LOG2E);
;                       const float y2 = a2 * rs * gq2; const float oth = __shfl_xor(y2, 32);
;                       const float rot = (lane < 32) ? (y2 * cs - oth * sn) : (y2 * cs + oth * sn);
;                       bf16_t* qo = mlaq + (size_t)t * 768 + h * 192; qo[lane] = f2bf(a0 * rs * gq0); qo[lane + 64] = f2bf(a1 * rs * gq1); qo[lane + 128] = f2bf(rot); }
;                     { const float a0 = ka[u][h][0], a1 = ka[u][h][1];
;                       const float rs = rsqrtf(wave_sum(a0 * a0 + a1 * a1 + kr * kr) * (1.f / 192.f) + NEPS);
;                       const float y2 = kr * rs * gk2; const float oth = __shfl_xor(y2, 32);
;                       const float rot = (lane < 32) ? (y2 * cs - oth * sn) : (y2 * cs + oth * sn);
;                       bf16_t* ko = mlak + (size_t)t * 768 + h * 192; ko[lane] = f2bf(a0 * rs * gk0); ko[lane + 64] = f2bf(a1 * rs * gk1); ko[lane + 128] = f2bf(rot); }
;                 }
	v_mul_f32_e32 v32, v70, v32
	v_cndmask_b32_e64 v32, v32, -v32, s[38:39]
	v_fmac_f32_e32 v32, v10, v25
	v_bfe_u32 v25, v24, 16, 1
	v_add3_u32 v24, v24, v25, s11
	global_store_short_d16_hi v[18:19], v24, off offset:768
	v_mul_f32_e32 v24, v31, v71
	v_mul_f32_e32 v24, v37, v24
	v_bfe_u32 v25, v24, 16, 1
	v_add3_u32 v24, v24, v25, s11
	global_store_short_d16_hi v[18:19], v24, off offset:896
	v_bfe_u32 v24, v32, 16, 1
	v_add3_u32 v24, v32, v24, s11
	global_store_short_d16_hi v[18:19], v24, off offset:1024
	v_mul_f32_e32 v24, 0x4b800000, v30
	v_cndmask_b32_e32 v24, v30, v24, vcc
	v_rsq_f32_e32 v24, v24
	s_nop 0
	v_mul_f32_e32 v25, 0x45800000, v24
	v_cndmask_b32_e32 v24, v24, v25, vcc
	v_mul_f32_e32 v25, v24, v14
	v_mul_f32_e32 v25, v40, v25
	ds_bpermute_b32 v30, v43, v25
	v_mul_f32_e32 v22, v24, v22
	v_mul_f32_e32 v22, v38, v22
	s_waitcnt lgkmcnt(0)
	v_mul_f32_e32 v30, v70, v30
	v_cndmask_b32_e64 v30, v30, -v30, s[38:39]
	v_fmac_f32_e32 v30, v10, v25
	v_bfe_u32 v25, v22, 16, 1
	v_add3_u32 v22, v22, v25, s11
	global_store_short_d16_hi v[20:21], v22, off offset:768
	v_mul_f32_e32 v22, v24, v23
	v_mul_f32_e32 v22, v39, v22
	v_bfe_u32 v23, v22, 16, 1
	v_add3_u32 v22, v22, v23, s11
	global_store_short_d16_hi v[20:21], v22, off offset:896
	v_bfe_u32 v22, v30, 16, 1
	v_add3_u32 v22, v30, v22, s11
	global_store_short_d16_hi v[20:21], v22, off offset:1024
	v_pk_mul_f32 v[22:23], v[16:17], v[16:17]
	s_nop 0
	v_pk_mov_b32 v[24:25], v[26:27], v[22:23] op_sel:[1,0]
	v_mov_b32_e32 v27, v23
	v_pk_fma_f32 v[24:25], v[12:13], v[12:13], v[24:25]
	s_nop 0
	v_pk_add_f32 v[22:23], v[26:27], v[24:25]
	v_mov_b32_e32 v25, v23
	v_mov_b32_e32 v24, v22
	s_nop 0
	v_permlane32_swap_b32_e32 v25, v23
	v_permlane32_swap_b32_e32 v24, v22
	s_waitcnt lgkmcnt(0)
	v_pk_add_f32 v[22:23], v[22:23], v[24:25]
	v_mov_b32_e32 v25, v23
	v_mov_b32_e32 v24, v22
	s_nop 0
	v_permlane16_swap_b32_e32 v25, v23
	v_permlane16_swap_b32_e32 v24, v22
	s_waitcnt lgkmcnt(0)
	v_pk_add_f32 v[22:23], v[22:23], v[24:25]
	s_nop 1
	v_mov_b32_dpp v25, v23 row_ror:8 row_mask:0xf bank_mask:0xf
	v_mov_b32_dpp v24, v22 row_ror:8 row_mask:0xf bank_mask:0xf
	s_waitcnt lgkmcnt(0)
	v_pk_add_f32 v[22:23], v[22:23], v[24:25]
	s_nop 1
	v_mov_b32_dpp v25, v23 row_shl:4 row_mask:0xf bank_mask:0x5
	v_mov_b32_dpp v25, v23 row_shr:4 row_mask:0xf bank_mask:0xa
	v_mov_b32_dpp v24, v22 row_shl:4 row_mask:0xf bank_mask:0x5
	v_mov_b32_dpp v24, v22 row_shr:4 row_mask:0xf bank_mask:0xa
	s_waitcnt lgkmcnt(0)
	v_pk_add_f32 v[22:23], v[22:23], v[24:25]
	s_nop 1
	v_mov_b32_dpp v25, v23 quad_perm:[2,3,0,1] row_mask:0xf bank_mask:0xf
	v_mov_b32_dpp v24, v22 quad_perm:[2,3,0,1] row_mask:0xf bank_mask:0xf
	s_waitcnt lgkmcnt(0)
	v_pk_add_f32 v[22:23], v[22:23], v[24:25]
	s_nop 1
	v_mov_b32_dpp v25, v23 quad_perm:[1,0,3,2] row_mask:0xf bank_mask:0xf
	v_mov_b32_dpp v24, v22 quad_perm:[1,0,3,2] row_mask:0xf bank_mask:0xf
	s_waitcnt lgkmcnt(0)
	v_pk_add_f32 v[22:23], v[22:23], v[24:25]
	s_nop 0
	v_pk_fma_f32 v[22:23], v[22:23], s[4:5], v[28:29] op_sel_hi:[1,0,0]
	s_nop 0
	v_mul_f32_e32 v24, 0x4b800000, v23
	v_cmp_gt_f32_e64 s[0:1], s77, v23
	v_cmp_gt_f32_e32 vcc, s77, v22
	s_nop 0
	v_cndmask_b32_e64 v23, v23, v24, s[0:1]
	v_rsq_f32_e32 v23, v23
	s_nop 0
	v_mul_f32_e32 v24, 0x45800000, v23
	v_cndmask_b32_e64 v23, v23, v24, s[0:1]
	v_mul_f32_e32 v23, 0x3dd53b94, v23
	v_mul_f32_e32 v17, v23, v17
	v_mul_f32_e32 v17, v41, v17
	ds_bpermute_b32 v24, v43, v17
	v_mul_f32_e32 v16, v23, v16
	v_mul_f32_e32 v16, v36, v16
	v_mul_f32_e32 v13, v23, v13
	v_mul_f32_e32 v13, v37, v13
	s_waitcnt lgkmcnt(0)
	v_mul_f32_e32 v24, v70, v24
	v_cndmask_b32_e64 v24, v24, -v24, s[38:39]
	v_fmac_f32_e32 v24, v10, v17
	v_bfe_u32 v17, v16, 16, 1
	v_add3_u32 v16, v16, v17, s11
	global_store_short_d16_hi v[18:19], v16, off offset:1152
	v_bfe_u32 v16, v13, 16, 1
	v_add3_u32 v13, v13, v16, s11
	global_store_short_d16_hi v[18:19], v13, off offset:1280
	v_bfe_u32 v13, v24, 16, 1
	v_add3_u32 v13, v24, v13, s11
	global_store_short_d16_hi v[18:19], v13, off offset:1408
	v_mul_f32_e32 v13, 0x4b800000, v22
	v_cndmask_b32_e32 v13, v22, v13, vcc
	v_rsq_f32_e32 v13, v13
	s_brev_b32 s0, 18
	v_mul_f32_e32 v16, 0x45800000, v13
	v_cndmask_b32_e32 v13, v13, v16, vcc
	v_mul_f32_e32 v14, v13, v14
	v_mul_f32_e32 v14, v40, v14
	ds_bpermute_b32 v16, v43, v14
	s_waitcnt lgkmcnt(0)
	v_mul_f32_e32 v16, v70, v16
	v_cndmask_b32_e64 v16, v16, -v16, s[38:39]
	v_fmac_f32_e32 v16, v10, v14
	v_mul_f32_e32 v10, v13, v15
	v_mul_f32_e32 v10, v38, v10
	v_bfe_u32 v14, v10, 16, 1
	v_add3_u32 v10, v10, v14, s11
	global_store_short_d16_hi v[20:21], v10, off offset:1152
	v_mul_f32_e32 v10, v13, v12
	v_mul_f32_e32 v10, v39, v10
	v_bfe_u32 v12, v10, 16, 1
	v_add3_u32 v10, v10, v12, s11
	global_store_short_d16_hi v[20:21], v10, off offset:1280
	v_bfe_u32 v10, v16, 16, 1
	v_add3_u32 v10, v16, v10, s11
	global_store_short_d16_hi v[20:21], v10, off offset:1408
	v_cvt_f32_i32_e32 v10, v11
	v_mul_f32_e32 v16, v42, v10
	v_and_b32_e32 v17, 0x7fffffff, v16
	v_cmp_nlt_f32_e64 s[0:1], |v16|, s0
	s_and_saveexec_b64 s[40:41], s[0:1]
	s_xor_b64 s[44:45], exec, s[40:41]
	s_cbranch_execz .LBB0_338
; DI void run_phase(const Params& p, int ph, unsigned char* smem, const int tid, const int rep) {
;     ...
;                 const float ang = (float)ps[u] * invf; float sn, cs; sincosf(ang, &sn, &cs);
	v_lshrrev_b32_e32 v10, 23, v17
	v_add_u32_e32 v10, 0xffffff88, v10
	v_cmp_lt_u32_e32 vcc, 63, v10
	s_mov_b32 s4, 0xfe5163ab
	v_mov_b32_e32 v13, v1
	v_cndmask_b32_e32 v11, 0, v195, vcc
	v_add_u32_e32 v10, v11, v10
	v_cmp_lt_u32_e64 s[0:1], 31, v10
	v_mov_b32_e32 v15, v1
	v_mov_b32_e32 v19, v1
	v_cndmask_b32_e64 v11, 0, v184, s[0:1]
	v_add_u32_e32 v10, v11, v10
	v_cmp_lt_u32_e64 s[40:41], 31, v10
	v_mov_b32_e32 v21, v1
	v_mov_b32_e32 v23, v1
	v_cndmask_b32_e64 v11, 0, v184, s[40:41]
	v_add_u32_e32 v26, v11, v10
	v_and_b32_e32 v10, 0x7fffff, v17
	v_or_b32_e32 v27, 0x800000, v10
	v_mad_u64_u32 v[10:11], s[42:43], v27, s4, 0
	v_mov_b32_e32 v12, v11
	s_mov_b32 s4, 0x3c439041
	v_mad_u64_u32 v[12:13], s[42:43], v27, s4, v[12:13]
	v_mov_b32_e32 v14, v13
	s_mov_b32 s4, 0xdb629599
	v_mad_u64_u32 v[14:15], s[42:43], v27, s4, v[14:15]
	v_mov_b32_e32 v18, v15
	s_mov_b32 s4, 0xf534ddc0
	v_mad_u64_u32 v[18:19], s[42:43], v27, s4, v[18:19]
	v_mov_b32_e32 v20, v19
	s_mov_b32 s4, 0xfc2757d1
	v_mad_u64_u32 v[20:21], s[42:43], v27, s4, v[20:21]
	v_mov_b32_e32 v22, v21
	s_mov_b32 s4, 0x4e441529
	v_mad_u64_u32 v[22:23], s[42:43], v27, s4, v[22:23]
	v_mov_b32_e32 v24, v23
	v_mov_b32_e32 v25, v1
	s_mov_b32 s4, 0xa2f9836e
	v_mad_u64_u32 v[24:25], s[42:43], v27, s4, v[24:25]
	v_cndmask_b32_e32 v11, v22, v18, vcc
	v_cndmask_b32_e32 v13, v24, v20, vcc
	v_cndmask_b32_e32 v19, v25, v22, vcc
	v_cndmask_b32_e64 v15, v13, v11, s[0:1]
	v_cndmask_b32_e64 v13, v19, v13, s[0:1]
	v_cndmask_b32_e32 v19, v20, v14, vcc
	v_cndmask_b32_e64 v11, v11, v19, s[0:1]
	v_cndmask_b32_e32 v12, v18, v12, vcc
	v_cndmask_b32_e64 v13, v13, v15, s[40:41]
	v_cndmask_b32_e64 v15, v15, v11, s[40:41]
	v_sub_u32_e32 v20, 32, v26
	v_cndmask_b32_e64 v18, v19, v12, s[0:1]
	v_alignbit_b32 v21, v13, v15, v20
	v_cmp_eq_u32_e64 s[42:43], 0, v26
	v_cndmask_b32_e64 v11, v11, v18, s[40:41]
	v_alignbit_b32 v19, v15, v11, v20
	v_cndmask_b32_e64 v13, v21, v13, s[42:43]
	v_cndmask_b32_e32 v10, v14, v10, vcc
	v_cndmask_b32_e64 v15, v19, v15, s[42:43]
	v_bfe_u32 v22, v13, 29, 1
	v_cndmask_b32_e64 v10, v12, v10, s[0:1]
	v_alignbit_b32 v19, v13, v15, 30
	v_sub_u32_e32 v23, 0, v22
	v_cndmask_b32_e64 v10, v18, v10, s[40:41]
	v_xor_b32_e32 v19, v19, v23
	v_alignbit_b32 v12, v11, v10, v20
	v_cndmask_b32_e64 v11, v12, v11, s[42:43]
	v_ffbh_u32_e32 v14, v19
	v_alignbit_b32 v12, v15, v11, 30
	v_min_u32_e32 v14, 32, v14
	v_alignbit_b32 v10, v11, v10, 30
	v_xor_b32_e32 v12, v12, v23
	v_sub_u32_e32 v15, 31, v14
	v_xor_b32_e32 v10, v10, v23
	v_alignbit_b32 v18, v19, v12, v15
	v_alignbit_b32 v10, v12, v10, v15
	v_alignbit_b32 v11, v18, v10, 9
	v_ffbh_u32_e32 v12, v11
	v_min_u32_e32 v12, 32, v12
	v_lshrrev_b32_e32 v21, 29, v13
	v_not_b32_e32 v15, v12
	v_alignbit_b32 v10, v11, v10, v15
	v_lshlrev_b32_e32 v11, 31, v21
	v_or_b32_e32 v15, 0x33000000, v11
	v_add_lshl_u32 v12, v12, v14, 23
	v_lshrrev_b32_e32 v10, 9, v10
	v_sub_u32_e32 v12, v15, v12
	v_or_b32_e32 v11, 0.5, v11
	v_lshlrev_b32_e32 v14, 23, v14
	v_or_b32_e32 v10, v12, v10
	v_lshrrev_b32_e32 v12, 9, v18
	v_sub_u32_e32 v11, v11, v14
	v_or_b32_e32 v11, v12, v11
	v_mul_f32_e32 v12, 0x3fc90fda, v11
	s_mov_b32 s0, 0x3fc90fda
	v_fma_f32 v14, v11, s0, -v12
	v_fmac_f32_e32 v14, 0x33a22168, v11
	v_fmac_f32_e32 v14, 0x3fc90fda, v10
	v_lshrrev_b32_e32 v10, 30, v13
	v_add_f32_e32 v24, v12, v14
	v_add_u32_e32 v25, v22, v10

; DI unsigned pk2(float lo, float hi) { const f32x2 v = {lo, hi}; return __builtin_bit_cast(unsigned, __builtin_convertvector(v, bf16v2_t)); }
; DI float wave_sum(float v) { for (int o = 32; o; o >>= 1) v += __shfl_xor(v, o); return v; }
; DI void run_phase(const Params& p, int ph, unsigned char* smem, const int tid, const int rep) {
;     ...
; #pragma unroll
;               for (int u = 0; u < 4; ++u) { const bf16_t* pr = proj + (size_t)(t0 + u) * PLD; vq[u] = *(const u32x2*)(pr + 2048 + 4 * lane); vkv[u] = *(const unsigned*)(pr + 2304 + 2 * lane);
; #pragma unroll
;                   for (int hq = 0; hq < 8; ++hq) vf[u][hq] = *(const unsigned*)(pr + 3520 + hq * 128 + 2 * lane); }
; #pragma unroll
;               for (int u = 0; u < 4; ++u) { const int t = t0 + u; bf16_t* pr = proj + (size_t)t * PLD;
;                   { const u32x2 v = vq[u]; const float a0 = __uint_as_float(v[0] << 16), a1 = __uint_as_float(v[0] & 0xffff0000u), a2 = __uint_as_float(v[1] << 16), a3 = __uint_as_float(v[1] & 0xffff0000u);
;                     const float rs = rsqrtf(wave_sum(a0 * a0 + a1 * a1 + a2 * a2 + a3 * a3) * (1.f / 256.f) + NEPS);
;                     u32x2 o; o[0] = pk2(a0 * rs * ggq[0], a1 * rs * ggq[1]); o[1] = pk2(a2 * rs * ggq[2], a3 * rs * ggq[3]); *(u32x2*)(mlaa + (size_t)t * 384 + 4 * lane) = o; }
;                   { const unsigned v = vkv[u]; const float a0 = __uint_as_float(v << 16), a1 = __uint_as_float(v & 0xffff0000u);
;                     const float rs = rsqrtf(wave_sum(a0 * a0 + a1 * a1) * (1.f / 128.f) + NEPS);
;                     *(unsigned*)(mlaa + (size_t)t * 384 + 256 + 2 * lane) = pk2(a0 * rs * gkv0, a1 * rs * gkv1); }
; #pragma unroll
;                   for (int hq = 0; hq < 8; ++hq) { const unsigned v = vf[u][hq]; const float a0 = __uint_as_float(v << 16), a1 = __uint_as_float(v & 0xffff0000u);
;                     const float rs = rsqrtf(wave_sum(a0 * a0 + a1 * a1) * (1.f / 128.f) + NEPS) * ((hq < 4) ? 0.08838834764831845f * LOG2E : 1.f);
;                     *(unsigned*)(pr + 3520 + hq * 128 + 2 * lane) = pk2(a0 * rs * ((hq < 4) ? fq0 : fk0), a1 * rs * ((hq < 4) ? fq1 : fk1)); } } } }
.LBB0_372:
	v_mov_b64_e32 v[14:15], s[30:31]
	v_mad_i64_i32 v[16:17], s[0:1], v44, s3, v[14:15]
	v_lshl_add_u64 v[18:19], v[16:17], 0, v[0:1]
	v_add_co_u32_e32 v18, vcc, 0x1000, v18
	v_mov_b32_e32 v13, v1
	s_nop 0
	v_addc_co_u32_e32 v19, vcc, 0, v19, vcc
	v_lshl_add_u64 v[16:17], v[16:17], 0, v[12:13]
	global_load_dwordx2 v[18:19], v[18:19], off
	v_add_co_u32_e32 v36, vcc, 0x1000, v16
	v_add_u32_e32 v79, 1, v44
	s_nop 0
	v_addc_co_u32_e32 v37, vcc, 0, v17, vcc
	global_load_dword v89, v[36:37], off offset:512
	v_lshl_add_u64 v[34:35], v[16:17], 0, s[34:35]
	global_load_dword v88, v[36:37], off offset:2944
	global_load_dword v87, v[34:35], off offset:256
	global_load_dword v86, v[34:35], off offset:512
	global_load_dword v85, v[34:35], off offset:768
	global_load_dword v84, v[34:35], off offset:1024
	global_load_dword v83, v[34:35], off offset:1280
	global_load_dword v82, v[34:35], off offset:1536
	global_load_dword v81, v[34:35], off offset:1792
	v_mad_i64_i32 v[16:17], s[0:1], v79, s3, v[14:15]
	v_lshl_add_u64 v[20:21], v[16:17], 0, v[0:1]
	v_add_co_u32_e32 v20, vcc, s87, v20
	v_lshl_add_u64 v[16:17], v[16:17], 0, v[12:13]
	s_nop 0
	v_addc_co_u32_e32 v21, vcc, 0, v21, vcc
	v_add_co_u32_e32 v32, vcc, s87, v16
	v_add_u32_e32 v69, 2, v44
	s_nop 0
	v_addc_co_u32_e32 v33, vcc, 0, v17, vcc
	v_lshl_add_u64 v[28:29], v[16:17], 0, s[34:35]
	v_mad_i64_i32 v[16:17], s[0:1], v69, s3, v[14:15]
	global_load_dwordx2 v[40:41], v[20:21], off
	global_load_dword v80, v[32:33], off offset:512
	v_lshl_add_u64 v[20:21], v[16:17], 0, v[0:1]
	v_add_co_u32_e32 v20, vcc, s87, v20
	v_lshl_add_u64 v[16:17], v[16:17], 0, v[12:13]
	s_nop 0
	v_addc_co_u32_e32 v21, vcc, 0, v21, vcc
	v_add_co_u32_e32 v26, vcc, s87, v16
	v_add_u32_e32 v59, 3, v44
	s_nop 0
	v_addc_co_u32_e32 v27, vcc, 0, v17, vcc
	v_mad_i64_i32 v[14:15], s[0:1], v59, s3, v[14:15]
	global_load_dword v78, v[32:33], off offset:2944
	global_load_dword v77, v[28:29], off offset:256
	global_load_dword v76, v[28:29], off offset:512
	global_load_dword v75, v[28:29], off offset:768
	global_load_dword v74, v[28:29], off offset:1024
	global_load_dword v73, v[28:29], off offset:1280
	global_load_dword v72, v[28:29], off offset:1536
	global_load_dword v71, v[28:29], off offset:1792
	global_load_dwordx2 v[30:31], v[20:21], off
	global_load_dword v70, v[26:27], off offset:512
	v_lshl_add_u64 v[22:23], v[16:17], 0, s[34:35]
	v_lshl_add_u64 v[16:17], v[14:15], 0, v[0:1]
	v_add_co_u32_e32 v16, vcc, s87, v16
	v_lshl_add_u64 v[14:15], v[14:15], 0, v[12:13]
	s_nop 0
	v_addc_co_u32_e32 v17, vcc, 0, v17, vcc
	global_load_dword v68, v[26:27], off offset:2944
	global_load_dword v67, v[22:23], off offset:256
	global_load_dword v66, v[22:23], off offset:512
	global_load_dword v65, v[22:23], off offset:768
	global_load_dword v64, v[22:23], off offset:1024
	global_load_dword v63, v[22:23], off offset:1280
	global_load_dword v62, v[22:23], off offset:1536
	global_load_dword v61, v[22:23], off offset:1792
	global_load_dwordx2 v[24:25], v[16:17], off
	v_add_co_u32_e32 v16, vcc, s87, v14
	s_waitcnt vmcnt(0)
	v_and_b32_e32 v43, 0xffff0000, v18
	v_and_b32_e32 v21, 0xffff0000, v19
	v_and_b32_e32 v20, s0, v18
	v_lshlrev_b32_e32 v42, 16, v18
	v_mul_f32_e32 v18, v43, v43
	v_lshlrev_b32_e32 v38, 16, v19
	v_mov_b32_e32 v39, v21
	v_pk_fma_f32 v[18:19], v[42:43], v[42:43], v[18:19] op_sel_hi:[1,1,0]
	v_lshlrev_b32_e32 v96, 16, v89
	v_and_b32_e32 v97, 0xffff0000, v89
	v_pk_mul_f32 v[90:91], v[20:21], v[20:21]
	v_pk_fma_f32 v[18:19], v[38:39], v[38:39], v[18:19]
	v_pk_mul_f32 v[98:99], v[96:97], v[96:97]
	v_mov_b64_e32 v[20:21], s[12:13]
	v_mov_b32_e32 v90, v98
	v_pk_mov_b32 v[18:19], v[98:99], v[18:19] op_sel:[1,0]
	v_mad_i64_i32 v[92:93], s[0:1], v44, s22, v[20:21]
	v_pk_add_f32 v[18:19], v[90:91], v[18:19]
	v_mov_b32_e32 v91, v19
	v_mov_b32_e32 v90, v18
	s_nop 0
	v_permlane32_swap_b32_e32 v91, v19
	v_permlane32_swap_b32_e32 v90, v18
	v_addc_co_u32_e32 v17, vcc, 0, v15, vcc
	v_lshl_add_u64 v[94:95], v[92:93], 0, v[0:1]
	global_load_dword v60, v[16:17], off offset:512
	s_waitcnt lgkmcnt(0)
	v_pk_add_f32 v[18:19], v[18:19], v[90:91]
	v_mov_b32_e32 v91, v19
	v_mov_b32_e32 v90, v18
	s_nop 0
	v_permlane16_swap_b32_e32 v91, v19
	v_permlane16_swap_b32_e32 v90, v18
	v_lshl_add_u64 v[14:15], v[14:15], 0, s[34:35]
	global_load_dword v58, v[16:17], off offset:2944
	global_load_dword v57, v[14:15], off offset:256
	global_load_dword v56, v[14:15], off offset:512
	global_load_dword v55, v[14:15], off offset:768
	global_load_dword v54, v[14:15], off offset:1024
	global_load_dword v53, v[14:15], off offset:1280
	global_load_dword v52, v[14:15], off offset:1536
	global_load_dword v51, v[14:15], off offset:1792
	v_add_u32_e32 v44, s4, v44
	s_waitcnt lgkmcnt(0)
	v_pk_add_f32 v[18:19], v[18:19], v[90:91]
	s_nop 1
	v_mov_b32_dpp v91, v19 row_ror:8 row_mask:0xf bank_mask:0xf
	v_mov_b32_dpp v90, v18 row_ror:8 row_mask:0xf bank_mask:0xf
	s_waitcnt lgkmcnt(0)
	v_pk_add_f32 v[18:19], v[18:19], v[90:91]
	s_nop 1
	v_mov_b32_dpp v91, v19 row_shl:4 row_mask:0xf bank_mask:0x5
	v_mov_b32_dpp v91, v19 row_shr:4 row_mask:0xf bank_mask:0xa
	v_mov_b32_dpp v90, v18 row_shl:4 row_mask:0xf bank_mask:0x5
	v_mov_b32_dpp v90, v18 row_shr:4 row_mask:0xf bank_mask:0xa
	s_waitcnt lgkmcnt(0)
	v_pk_add_f32 v[18:19], v[18:19], v[90:91]
	s_nop 1
	v_mov_b32_dpp v91, v19 quad_perm:[2,3,0,1] row_mask:0xf bank_mask:0xf
	v_mov_b32_dpp v90, v18 quad_perm:[2,3,0,1] row_mask:0xf bank_mask:0xf
	s_waitcnt lgkmcnt(0)
	v_pk_add_f32 v[18:19], v[18:19], v[90:91]
	s_nop 1
	v_mov_b32_dpp v91, v19 quad_perm:[1,0,3,2] row_mask:0xf bank_mask:0xf
	v_mov_b32_dpp v90, v18 quad_perm:[1,0,3,2] row_mask:0xf bank_mask:0xf
	s_waitcnt lgkmcnt(0)
; DI unsigned pk2(float lo, float hi) { const f32x2 v = {lo, hi}; return __builtin_bit_cast(unsigned, __builtin_convertvector(v, bf16v2_t)); }
; DI float wave_sum(float v) { for (int o = 32; o; o >>= 1) v += __shfl_xor(v, o); return v; }
; DI void run_phase(const Params& p, int ph, unsigned char* smem, const int tid, const int rep) {
;     ...
;               for (int u = 0; u < 4; ++u) { const int t = t0 + u; bf16_t* pr = proj + (size_t)t * PLD;
;                   { const u32x2 v = vq[u]; const float a0 = __uint_as_float(v[0] << 16), a1 = __uint_as_float(v[0] & 0xffff0000u), a2 = __uint_as_float(v[1] << 16), a3 = __uint_as_float(v[1] & 0xffff0000u);
;                     const float rs = rsqrtf(wave_sum(a0 * a0 + a1 * a1 + a2 * a2 + a3 * a3) * (1.f / 256.f) + NEPS);
;                     u32x2 o; o[0] = pk2(a0 * rs * ggq[0], a1 * rs * ggq[1]); o[1] = pk2(a2 * rs * ggq[2], a3 * rs * ggq[3]); *(u32x2*)(mlaa + (size_t)t * 384 + 4 * lane) = o; }
;                   { const unsigned v = vkv[u]; const float a0 = __uint_as_float(v << 16), a1 = __uint_as_float(v & 0xffff0000u);
;                     const float rs = rsqrtf(wave_sum(a0 * a0 + a1 * a1) * (1.f / 128.f) + NEPS);
;                     *(unsigned*)(mlaa + (size_t)t * 384 + 256 + 2 * lane) = pk2(a0 * rs * gkv0, a1 * rs * gkv1); }
; #pragma unroll
;                   for (int hq = 0; hq < 8; ++hq) { const unsigned v = vf[u][hq]; const float a0 = __uint_as_float(v << 16), a1 = __uint_as_float(v & 0xffff0000u);
;                     const float rs = rsqrtf(wave_sum(a0 * a0 + a1 * a1) * (1.f / 128.f) + NEPS) * ((hq < 4) ? 0.08838834764831845f * LOG2E : 1.f);
;                     *(unsigned*)(pr + 3520 + hq * 128 + 2 * lane) = pk2(a0 * rs * ((hq < 4) ? fq0 : fk0), a1 * rs * ((hq < 4) ? fq1 : fk1)); } } } }
	v_pk_add_f32 v[90:91], v[18:19], v[90:91]
	v_mov_b64_e32 v[18:19], s[72:73]
	v_pk_fma_f32 v[90:91], v[90:91], s[96:97], v[18:19] op_sel_hi:[1,1,0]
	s_nop 0
	v_mul_f32_e32 v89, 0x4b800000, v91
	v_cmp_gt_f32_e64 s[0:1], s77, v91
	v_cmp_gt_f32_e32 vcc, s77, v90
	s_nop 0
	v_cndmask_b32_e64 v89, v91, v89, s[0:1]
	v_rsq_f32_e32 v89, v89
	s_nop 0
	v_mul_f32_e32 v91, 0x45800000, v89
	v_cndmask_b32_e64 v98, v89, v91, s[0:1]
	v_pk_mul_f32 v[42:43], v[98:99], v[42:43] op_sel_hi:[0,1]
	v_pk_mul_f32 v[38:39], v[98:99], v[38:39] op_sel_hi:[0,1]
	v_pk_mul_f32 v[42:43], v[2:3], v[42:43]
	v_pk_mul_f32 v[38:39], v[4:5], v[38:39]
	v_cvt_pk_bf16_f32 v42, v42, v43
	v_cvt_pk_bf16_f32 v43, v38, v39
	v_mul_f32_e32 v38, 0x4b800000, v90
	v_cndmask_b32_e32 v38, v90, v38, vcc
	v_rsq_f32_e32 v38, v38
	global_store_dwordx2 v[94:95], v[42:43], off
	v_and_b32_e32 v89, 0xffff0000, v87
	v_mul_f32_e32 v39, 0x45800000, v38
	v_cndmask_b32_e32 v38, v38, v39, vcc
	v_pk_mul_f32 v[38:39], v[38:39], v[96:97] op_sel_hi:[0,1]
	v_pk_mul_f32 v[38:39], v[6:7], v[38:39]
	s_nop 0
	v_cvt_pk_bf16_f32 v42, v38, v39
	v_lshl_add_u64 v[38:39], v[92:93], 0, v[12:13]
	global_store_dword v[38:39], v42, off offset:512
	v_lshlrev_b32_e32 v38, 16, v88
	v_and_b32_e32 v39, 0xffff0000, v88
	v_lshlrev_b32_e32 v88, 16, v87
	v_pk_mul_f32 v[42:43], v[38:39], v[38:39]
	v_pk_mul_f32 v[90:91], v[88:89], v[88:89]
	v_mov_b32_e32 v93, v42
	v_mov_b32_e32 v92, v90
	v_mov_b32_e32 v42, v91
	v_pk_add_f32 v[42:43], v[92:93], v[42:43]
	v_mov_b32_e32 v91, v43
	v_mov_b32_e32 v90, v42
	s_nop 0
	v_permlane32_swap_b32_e32 v91, v43
	v_permlane32_swap_b32_e32 v90, v42
	s_waitcnt lgkmcnt(0)
	v_pk_add_f32 v[42:43], v[42:43], v[90:91]
	v_mov_b32_e32 v91, v43
	v_mov_b32_e32 v90, v42
	s_nop 0
	v_permlane16_swap_b32_e32 v91, v43
	v_permlane16_swap_b32_e32 v90, v42
	s_waitcnt lgkmcnt(0)
	v_pk_add_f32 v[42:43], v[42:43], v[90:91]
	s_nop 1
	v_mov_b32_dpp v91, v43 row_ror:8 row_mask:0xf bank_mask:0xf
	v_mov_b32_dpp v90, v42 row_ror:8 row_mask:0xf bank_mask:0xf
	s_waitcnt lgkmcnt(0)
	v_pk_add_f32 v[42:43], v[42:43], v[90:91]
	s_nop 1
	v_mov_b32_dpp v91, v43 row_shl:4 row_mask:0xf bank_mask:0x5
	v_mov_b32_dpp v91, v43 row_shr:4 row_mask:0xf bank_mask:0xa
	v_mov_b32_dpp v90, v42 row_shl:4 row_mask:0xf bank_mask:0x5
	v_mov_b32_dpp v90, v42 row_shr:4 row_mask:0xf bank_mask:0xa
	s_waitcnt lgkmcnt(0)
	v_pk_add_f32 v[42:43], v[42:43], v[90:91]
	s_nop 1
	v_mov_b32_dpp v91, v43 quad_perm:[2,3,0,1] row_mask:0xf bank_mask:0xf
	v_mov_b32_dpp v90, v42 quad_perm:[2,3,0,1] row_mask:0xf bank_mask:0xf
	s_waitcnt lgkmcnt(0)
	v_pk_add_f32 v[42:43], v[42:43], v[90:91]
	s_nop 1
	v_mov_b32_dpp v91, v43 quad_perm:[1,0,3,2] row_mask:0xf bank_mask:0xf
	v_mov_b32_dpp v90, v42 quad_perm:[1,0,3,2] row_mask:0xf bank_mask:0xf
	s_waitcnt lgkmcnt(0)
	v_pk_add_f32 v[42:43], v[42:43], v[90:91]
	s_nop 0
	v_pk_fma_f32 v[42:43], v[42:43], s[96:97], v[18:19] op_sel_hi:[1,0,0]
	s_nop 0
	v_mul_f32_e32 v87, 0x4b800000, v43
	v_cmp_gt_f32_e64 s[0:1], s77, v43
	v_cmp_gt_f32_e32 vcc, s77, v42
	s_nop 0
	v_cndmask_b32_e64 v43, v43, v87, s[0:1]
	v_rsq_f32_e32 v43, v43
	s_nop 0
	v_mul_f32_e32 v87, 0x45800000, v43
	v_cndmask_b32_e64 v43, v43, v87, s[0:1]
	v_mul_f32_e32 v90, 0x3e0293ee, v43
	v_pk_mul_f32 v[38:39], v[90:91], v[38:39] op_sel_hi:[0,1]
	v_pk_mul_f32 v[38:39], v[8:9], v[38:39]
	v_and_b32_e32 v43, 0xffff0000, v85
	v_cvt_pk_bf16_f32 v38, v38, v39
	global_store_dword v[36:37], v38, off offset:2944
	v_mul_f32_e32 v36, 0x4b800000, v42
	v_cndmask_b32_e32 v36, v42, v36, vcc
	v_rsq_f32_e32 v36, v36
	v_lshlrev_b32_e32 v42, 16, v85
	v_mul_f32_e32 v37, 0x45800000, v36
	v_cndmask_b32_e32 v36, v36, v37, vcc
	v_mul_f32_e32 v36, 0x3e0293ee, v36
	v_pk_mul_f32 v[36:37], v[36:37], v[88:89] op_sel_hi:[0,1]
	v_pk_mul_f32 v[36:37], v[8:9], v[36:37]
	s_nop 0
	v_cvt_pk_bf16_f32 v36, v36, v37
	global_store_dword v[34:35], v36, off offset:256
	v_lshlrev_b32_e32 v36, 16, v86
	v_and_b32_e32 v37, 0xffff0000, v86
	v_pk_mul_f32 v[38:39], v[36:37], v[36:37]
	v_pk_mul_f32 v[86:87], v[42:43], v[42:43]
	v_mov_b32_e32 v89, v38
	v_mov_b32_e32 v88, v86
	v_mov_b32_e32 v38, v87
	v_pk_add_f32 v[38:39], v[88:89], v[38:39]
	v_mov_b32_e32 v87, v39
	v_mov_b32_e32 v86, v38
	s_nop 0
	v_permlane32_swap_b32_e32 v87, v39
	v_permlane32_swap_b32_e32 v86, v38
	s_waitcnt lgkmcnt(0)
	v_pk_add_f32 v[38:39], v[38:39], v[86:87]
	v_mov_b32_e32 v87, v39
	v_mov_b32_e32 v86, v38
	s_nop 0
	v_permlane16_swap_b32_e32 v87, v39
	v_permlane16_swap_b32_e32 v86, v38
	s_waitcnt lgkmcnt(0)
	v_pk_add_f32 v[38:39], v[38:39], v[86:87]
	s_nop 1
	v_mov_b32_dpp v87, v39 row_ror:8 row_mask:0xf bank_mask:0xf
	v_mov_b32_dpp v86, v38 row_ror:8 row_mask:0xf bank_mask:0xf
	s_waitcnt lgkmcnt(0)
	v_pk_add_f32 v[38:39], v[38:39], v[86:87]
	s_nop 1
	v_mov_b32_dpp v87, v39 row_shl:4 row_mask:0xf bank_mask:0x5
	v_mov_b32_dpp v87, v39 row_shr:4 row_mask:0xf bank_mask:0xa
	v_mov_b32_dpp v86, v38 row_shl:4 row_mask:0xf bank_mask:0x5
	v_mov_b32_dpp v86, v38 row_shr:4 row_mask:0xf bank_mask:0xa
	s_waitcnt lgkmcnt(0)
	v_pk_add_f32 v[38:39], v[38:39], v[86:87]
	s_nop 1
	v_mov_b32_dpp v87, v39 quad_perm:[2,3,0,1] row_mask:0xf bank_mask:0xf
	v_mov_b32_dpp v86, v38 quad_perm:[2,3,0,1] row_mask:0xf bank_mask:0xf
	s_waitcnt lgkmcnt(0)
	v_pk_add_f32 v[38:39], v[38:39], v[86:87]
	s_nop 1
	v_mov_b32_dpp v87, v39 quad_perm:[1,0,3,2] row_mask:0xf bank_mask:0xf
	v_mov_b32_dpp v86, v38 quad_perm:[1,0,3,2] row_mask:0xf bank_mask:0xf
	s_waitcnt lgkmcnt(0)
; DI unsigned pk2(float lo, float hi) { const f32x2 v = {lo, hi}; return __builtin_bit_cast(unsigned, __builtin_convertvector(v, bf16v2_t)); }
; DI float wave_sum(float v) { for (int o = 32; o; o >>= 1) v += __shfl_xor(v, o); return v; }
; DI void run_phase(const Params& p, int ph, unsigned char* smem, const int tid, const int rep) {
;     ...
; #pragma unroll
;                   for (int hq = 0; hq < 8; ++hq) { const unsigned v = vf[u][hq]; const float a0 = __uint_as_float(v << 16), a1 = __uint_as_float(v & 0xffff0000u);
;                     const float rs = rsqrtf(wave_sum(a0 * a0 + a1 * a1) * (1.f / 128.f) + NEPS) * ((hq < 4) ? 0.08838834764831845f * LOG2E : 1.f);
;                     *(unsigned*)(pr + 3520 + hq * 128 + 2 * lane) = pk2(a0 * rs * ((hq < 4) ? fq0 : fk0), a1 * rs * ((hq < 4) ? fq1 : fk1)); } } } }
	v_pk_add_f32 v[38:39], v[38:39], v[86:87]
	s_nop 0
	v_pk_fma_f32 v[38:39], v[38:39], s[96:97], v[18:19] op_sel_hi:[1,0,0]
	s_nop 0
	v_mul_f32_e32 v85, 0x4b800000, v39
	v_cmp_gt_f32_e64 s[0:1], s77, v39
	v_cmp_gt_f32_e32 vcc, s77, v38
	s_nop 0
	v_cndmask_b32_e64 v39, v39, v85, s[0:1]
	v_rsq_f32_e32 v39, v39
	s_nop 0
	v_mul_f32_e32 v85, 0x45800000, v39
	v_cndmask_b32_e64 v39, v39, v85, s[0:1]
	v_mul_f32_e32 v86, 0x3e0293ee, v39
	v_pk_mul_f32 v[36:37], v[86:87], v[36:37] op_sel_hi:[0,1]
	v_pk_mul_f32 v[36:37], v[8:9], v[36:37]
	s_nop 0
	v_cvt_pk_bf16_f32 v36, v36, v37
	global_store_dword v[34:35], v36, off offset:512
	v_mul_f32_e32 v36, 0x4b800000, v38
	v_cndmask_b32_e32 v36, v38, v36, vcc
	v_rsq_f32_e32 v36, v36
	s_nop 0
	v_mul_f32_e32 v37, 0x45800000, v36
	v_cndmask_b32_e32 v36, v36, v37, vcc
	v_mul_f32_e32 v36, 0x3e0293ee, v36
	v_pk_mul_f32 v[36:37], v[36:37], v[42:43] op_sel_hi:[0,1]
	v_pk_mul_f32 v[36:37], v[8:9], v[36:37]
	v_lshlrev_b32_e32 v42, 16, v83
	v_cvt_pk_bf16_f32 v36, v36, v37
	global_store_dword v[34:35], v36, off offset:768
	v_lshlrev_b32_e32 v36, 16, v84
	v_and_b32_e32 v37, 0xffff0000, v84
	v_and_b32_e32 v43, 0xffff0000, v83
	v_pk_mul_f32 v[38:39], v[36:37], v[36:37]
	v_pk_mul_f32 v[84:85], v[42:43], v[42:43]
	v_mov_b32_e32 v87, v38
	v_mov_b32_e32 v86, v84
	v_mov_b32_e32 v38, v85
	v_pk_add_f32 v[38:39], v[86:87], v[38:39]
	v_mov_b32_e32 v85, v39
	v_mov_b32_e32 v84, v38
	s_nop 0
	v_permlane32_swap_b32_e32 v85, v39
	v_permlane32_swap_b32_e32 v84, v38
	s_waitcnt lgkmcnt(0)
	v_pk_add_f32 v[38:39], v[38:39], v[84:85]
	v_mov_b32_e32 v85, v39
	v_mov_b32_e32 v84, v38
	s_nop 0
	v_permlane16_swap_b32_e32 v85, v39
	v_permlane16_swap_b32_e32 v84, v38
	s_waitcnt lgkmcnt(0)
	v_pk_add_f32 v[38:39], v[38:39], v[84:85]
	s_nop 1
	v_mov_b32_dpp v85, v39 row_ror:8 row_mask:0xf bank_mask:0xf
	v_mov_b32_dpp v84, v38 row_ror:8 row_mask:0xf bank_mask:0xf
	s_waitcnt lgkmcnt(0)
	v_pk_add_f32 v[38:39], v[38:39], v[84:85]
	s_nop 1
	v_mov_b32_dpp v85, v39 row_shl:4 row_mask:0xf bank_mask:0x5
	v_mov_b32_dpp v85, v39 row_shr:4 row_mask:0xf bank_mask:0xa
	v_mov_b32_dpp v84, v38 row_shl:4 row_mask:0xf bank_mask:0x5
	v_mov_b32_dpp v84, v38 row_shr:4 row_mask:0xf bank_mask:0xa
	s_waitcnt lgkmcnt(0)
	v_pk_add_f32 v[38:39], v[38:39], v[84:85]
	s_nop 1
	v_mov_b32_dpp v85, v39 quad_perm:[2,3,0,1] row_mask:0xf bank_mask:0xf
	v_mov_b32_dpp v84, v38 quad_perm:[2,3,0,1] row_mask:0xf bank_mask:0xf
	s_waitcnt lgkmcnt(0)
	v_pk_add_f32 v[38:39], v[38:39], v[84:85]
	s_nop 1
	v_mov_b32_dpp v85, v39 quad_perm:[1,0,3,2] row_mask:0xf bank_mask:0xf
	v_mov_b32_dpp v84, v38 quad_perm:[1,0,3,2] row_mask:0xf bank_mask:0xf
	s_waitcnt lgkmcnt(0)
	v_pk_add_f32 v[38:39], v[38:39], v[84:85]
	s_nop 0
	v_pk_fma_f32 v[38:39], v[38:39], s[96:97], v[18:19] op_sel_hi:[1,0,0]
	s_nop 0
	v_mul_f32_e32 v83, 0x4b800000, v39
	v_cmp_gt_f32_e64 s[0:1], s77, v39
	v_cmp_gt_f32_e32 vcc, s77, v38
	s_nop 0
	v_cndmask_b32_e64 v39, v39, v83, s[0:1]
	v_rsq_f32_e32 v39, v39
	s_nop 0
	v_mul_f32_e32 v83, 0x45800000, v39
	v_cndmask_b32_e64 v84, v39, v83, s[0:1]
	v_pk_mul_f32 v[36:37], v[84:85], v[36:37] op_sel_hi:[0,1]
	v_pk_mul_f32 v[36:37], v[10:11], v[36:37]
	s_nop 0
	v_cvt_pk_bf16_f32 v36, v36, v37
	global_store_dword v[34:35], v36, off offset:1024
	v_mul_f32_e32 v36, 0x4b800000, v38
	v_cndmask_b32_e32 v36, v38, v36, vcc
	v_rsq_f32_e32 v36, v36
	s_nop 0
	v_mul_f32_e32 v37, 0x45800000, v36
	v_cndmask_b32_e32 v36, v36, v37, vcc
	v_pk_mul_f32 v[36:37], v[36:37], v[42:43] op_sel_hi:[0,1]
	v_pk_mul_f32 v[36:37], v[10:11], v[36:37]
	v_lshlrev_b32_e32 v42, 16, v81
	v_cvt_pk_bf16_f32 v36, v36, v37
	global_store_dword v[34:35], v36, off offset:1280
	v_lshlrev_b32_e32 v36, 16, v82
	v_and_b32_e32 v37, 0xffff0000, v82
	v_and_b32_e32 v43, 0xffff0000, v81
	v_pk_mul_f32 v[38:39], v[36:37], v[36:37]
	v_pk_mul_f32 v[82:83], v[42:43], v[42:43]
	v_mov_b32_e32 v85, v38
	v_mov_b32_e32 v84, v82
	v_mov_b32_e32 v38, v83
	v_pk_add_f32 v[38:39], v[84:85], v[38:39]
	v_mov_b32_e32 v83, v39
	v_mov_b32_e32 v82, v38
	s_nop 0
	v_permlane32_swap_b32_e32 v83, v39
	v_permlane32_swap_b32_e32 v82, v38
	v_lshlrev_b32_e32 v84, 16, v80
	v_and_b32_e32 v85, 0xffff0000, v80
	s_waitcnt lgkmcnt(0)
	v_pk_add_f32 v[38:39], v[38:39], v[82:83]
	v_mov_b32_e32 v83, v39
	v_mov_b32_e32 v82, v38
	s_nop 0
	v_permlane16_swap_b32_e32 v83, v39
	v_permlane16_swap_b32_e32 v82, v38
	s_waitcnt lgkmcnt(0)
	v_pk_add_f32 v[38:39], v[38:39], v[82:83]
	s_nop 1
	v_mov_b32_dpp v83, v39 row_ror:8 row_mask:0xf bank_mask:0xf
	v_mov_b32_dpp v82, v38 row_ror:8 row_mask:0xf bank_mask:0xf
	s_waitcnt lgkmcnt(0)
	v_pk_add_f32 v[38:39], v[38:39], v[82:83]
	s_nop 1
	v_mov_b32_dpp v83, v39 row_shl:4 row_mask:0xf bank_mask:0x5
	v_mov_b32_dpp v83, v39 row_shr:4 row_mask:0xf bank_mask:0xa
	v_mov_b32_dpp v82, v38 row_shl:4 row_mask:0xf bank_mask:0x5
	v_mov_b32_dpp v82, v38 row_shr:4 row_mask:0xf bank_mask:0xa
	s_waitcnt lgkmcnt(0)
	v_pk_add_f32 v[38:39], v[38:39], v[82:83]
	s_nop 1
	v_mov_b32_dpp v83, v39 quad_perm:[2,3,0,1] row_mask:0xf bank_mask:0xf
	v_mov_b32_dpp v82, v38 quad_perm:[2,3,0,1] row_mask:0xf bank_mask:0xf
	s_waitcnt lgkmcnt(0)
	v_pk_add_f32 v[38:39], v[38:39], v[82:83]
	s_nop 1
	v_mov_b32_dpp v83, v39 quad_perm:[1,0,3,2] row_mask:0xf bank_mask:0xf
	v_mov_b32_dpp v82, v38 quad_perm:[1,0,3,2] row_mask:0xf bank_mask:0xf
	s_waitcnt lgkmcnt(0)
; DI unsigned pk2(float lo, float hi) { const f32x2 v = {lo, hi}; return __builtin_bit_cast(unsigned, __builtin_convertvector(v, bf16v2_t)); }
; DI float wave_sum(float v) { for (int o = 32; o; o >>= 1) v += __shfl_xor(v, o); return v; }
; DI void run_phase(const Params& p, int ph, unsigned char* smem, const int tid, const int rep) {
;     ...
;               for (int u = 0; u < 4; ++u) { const int t = t0 + u; bf16_t* pr = proj + (size_t)t * PLD;
;                   { const u32x2 v = vq[u]; const float a0 = __uint_as_float(v[0] << 16), a1 = __uint_as_float(v[0] & 0xffff0000u), a2 = __uint_as_float(v[1] << 16), a3 = __uint_as_float(v[1] & 0xffff0000u);
;                     const float rs = rsqrtf(wave_sum(a0 * a0 + a1 * a1 + a2 * a2 + a3 * a3) * (1.f / 256.f) + NEPS);
;                     u32x2 o; o[0] = pk2(a0 * rs * ggq[0], a1 * rs * ggq[1]); o[1] = pk2(a2 * rs * ggq[2], a3 * rs * ggq[3]); *(u32x2*)(mlaa + (size_t)t * 384 + 4 * lane) = o; }
;                   { const unsigned v = vkv[u]; const float a0 = __uint_as_float(v << 16), a1 = __uint_as_float(v & 0xffff0000u);
;                     const float rs = rsqrtf(wave_sum(a0 * a0 + a1 * a1) * (1.f / 128.f) + NEPS);
;                     *(unsigned*)(mlaa + (size_t)t * 384 + 256 + 2 * lane) = pk2(a0 * rs * gkv0, a1 * rs * gkv1); }
; #pragma unroll
;                   for (int hq = 0; hq < 8; ++hq) { const unsigned v = vf[u][hq]; const float a0 = __uint_as_float(v << 16), a1 = __uint_as_float(v & 0xffff0000u);
;                     const float rs = rsqrtf(wave_sum(a0 * a0 + a1 * a1) * (1.f / 128.f) + NEPS) * ((hq < 4) ? 0.08838834764831845f * LOG2E : 1.f);
;                     *(unsigned*)(pr + 3520 + hq * 128 + 2 * lane) = pk2(a0 * rs * ((hq < 4) ? fq0 : fk0), a1 * rs * ((hq < 4) ? fq1 : fk1)); } } } }
	v_pk_add_f32 v[38:39], v[38:39], v[82:83]
	s_nop 0
	v_pk_fma_f32 v[38:39], v[38:39], s[96:97], v[18:19] op_sel_hi:[1,0,0]
	s_nop 0
	v_mul_f32_e32 v81, 0x4b800000, v39
	v_cmp_gt_f32_e64 s[0:1], s77, v39
	v_cmp_gt_f32_e32 vcc, s77, v38
	s_nop 0
	v_cndmask_b32_e64 v39, v39, v81, s[0:1]
	v_rsq_f32_e32 v39, v39
	s_nop 0
	v_mul_f32_e32 v81, 0x45800000, v39
	v_cndmask_b32_e64 v82, v39, v81, s[0:1]
	v_pk_mul_f32 v[36:37], v[82:83], v[36:37] op_sel_hi:[0,1]
	v_pk_mul_f32 v[36:37], v[10:11], v[36:37]
	v_pk_mul_f32 v[80:81], v[84:85], v[84:85]
	v_cvt_pk_bf16_f32 v36, v36, v37
	global_store_dword v[34:35], v36, off offset:1536
	v_mul_f32_e32 v36, 0x4b800000, v38
	v_cndmask_b32_e32 v36, v38, v36, vcc
	v_rsq_f32_e32 v36, v36
	s_nop 0
	v_mul_f32_e32 v37, 0x45800000, v36
	v_cndmask_b32_e32 v36, v36, v37, vcc
	v_pk_mul_f32 v[36:37], v[36:37], v[42:43] op_sel_hi:[0,1]
	v_pk_mul_f32 v[36:37], v[10:11], v[36:37]
	s_nop 0
	v_cvt_pk_bf16_f32 v36, v36, v37
	global_store_dword v[34:35], v36, off offset:1792
	v_and_b32_e32 v37, 0xffff0000, v41
	v_and_b32_e32 v36, s0, v40
	v_mov_b32_e32 v35, v37
	v_pk_mul_f32 v[38:39], v[36:37], v[36:37]
	v_and_b32_e32 v37, 0xffff0000, v40
	v_lshlrev_b32_e32 v36, 16, v40
	v_mul_f32_e32 v38, v37, v37
	v_lshlrev_b32_e32 v34, 16, v41
	v_pk_fma_f32 v[40:41], v[36:37], v[36:37], v[38:39] op_sel_hi:[1,1,0]
	v_mov_b32_e32 v38, v80
	v_pk_fma_f32 v[40:41], v[34:35], v[34:35], v[40:41]
	v_mad_i64_i32 v[42:43], s[0:1], v79, s22, v[20:21]
	v_pk_mov_b32 v[40:41], v[80:81], v[40:41] op_sel:[1,0]
	v_lshl_add_u64 v[82:83], v[42:43], 0, v[0:1]
	v_pk_add_f32 v[38:39], v[38:39], v[40:41]
	v_mov_b32_e32 v41, v39
	v_mov_b32_e32 v40, v38
	s_nop 0
	v_permlane32_swap_b32_e32 v41, v39
	v_permlane32_swap_b32_e32 v40, v38
	s_waitcnt lgkmcnt(0)
	v_pk_add_f32 v[38:39], v[38:39], v[40:41]
	v_mov_b32_e32 v41, v39
	v_mov_b32_e32 v40, v38
	s_nop 0
	v_permlane16_swap_b32_e32 v41, v39
	v_permlane16_swap_b32_e32 v40, v38
	s_waitcnt lgkmcnt(0)
	v_pk_add_f32 v[38:39], v[38:39], v[40:41]
	s_nop 1
	v_mov_b32_dpp v41, v39 row_ror:8 row_mask:0xf bank_mask:0xf
	v_mov_b32_dpp v40, v38 row_ror:8 row_mask:0xf bank_mask:0xf
	s_waitcnt lgkmcnt(0)
	v_pk_add_f32 v[38:39], v[38:39], v[40:41]
	s_nop 1
	v_mov_b32_dpp v41, v39 row_shl:4 row_mask:0xf bank_mask:0x5
	v_mov_b32_dpp v41, v39 row_shr:4 row_mask:0xf bank_mask:0xa
	v_mov_b32_dpp v40, v38 row_shl:4 row_mask:0xf bank_mask:0x5
	v_mov_b32_dpp v40, v38 row_shr:4 row_mask:0xf bank_mask:0xa
	s_waitcnt lgkmcnt(0)
	v_pk_add_f32 v[38:39], v[38:39], v[40:41]
	s_nop 1
	v_mov_b32_dpp v41, v39 quad_perm:[2,3,0,1] row_mask:0xf bank_mask:0xf
	v_mov_b32_dpp v40, v38 quad_perm:[2,3,0,1] row_mask:0xf bank_mask:0xf
	s_waitcnt lgkmcnt(0)
	v_pk_add_f32 v[38:39], v[38:39], v[40:41]
	s_nop 1
	v_mov_b32_dpp v41, v39 quad_perm:[1,0,3,2] row_mask:0xf bank_mask:0xf
	v_mov_b32_dpp v40, v38 quad_perm:[1,0,3,2] row_mask:0xf bank_mask:0xf
	s_waitcnt lgkmcnt(0)
	v_pk_add_f32 v[38:39], v[38:39], v[40:41]
	s_nop 0
	v_pk_fma_f32 v[38:39], v[38:39], s[96:97], v[18:19] op_sel_hi:[1,1,0]
	s_nop 0
	v_mul_f32_e32 v40, 0x4b800000, v39
	v_cmp_gt_f32_e64 s[0:1], s77, v39
	v_cmp_gt_f32_e32 vcc, s77, v38
	s_nop 0
	v_cndmask_b32_e64 v39, v39, v40, s[0:1]
	v_rsq_f32_e32 v39, v39
	s_nop 0
	v_mul_f32_e32 v40, 0x45800000, v39
	v_cndmask_b32_e64 v40, v39, v40, s[0:1]
	v_pk_mul_f32 v[36:37], v[40:41], v[36:37] op_sel_hi:[0,1]
	v_pk_mul_f32 v[34:35], v[40:41], v[34:35] op_sel_hi:[0,1]
	v_pk_mul_f32 v[36:37], v[2:3], v[36:37]
	v_pk_mul_f32 v[34:35], v[4:5], v[34:35]
	v_cvt_pk_bf16_f32 v36, v36, v37
	v_cvt_pk_bf16_f32 v37, v34, v35
	v_mul_f32_e32 v34, 0x4b800000, v38
	v_cndmask_b32_e32 v34, v38, v34, vcc
	v_rsq_f32_e32 v34, v34
	global_store_dwordx2 v[82:83], v[36:37], off
	v_lshlrev_b32_e32 v38, 16, v77
	v_and_b32_e32 v39, 0xffff0000, v77
	v_mul_f32_e32 v35, 0x45800000, v34
	v_cndmask_b32_e32 v34, v34, v35, vcc
	v_pk_mul_f32 v[34:35], v[34:35], v[84:85] op_sel_hi:[0,1]
	v_pk_mul_f32 v[34:35], v[6:7], v[34:35]
	v_pk_mul_f32 v[40:41], v[38:39], v[38:39]
	v_cvt_pk_bf16_f32 v36, v34, v35
	v_lshl_add_u64 v[34:35], v[42:43], 0, v[12:13]
	global_store_dword v[34:35], v36, off offset:512
	v_lshlrev_b32_e32 v34, 16, v78
	v_and_b32_e32 v35, 0xffff0000, v78
	v_pk_mul_f32 v[36:37], v[34:35], v[34:35]
	v_mov_b32_e32 v42, v40
	v_mov_b32_e32 v43, v36
	v_mov_b32_e32 v36, v41
	v_pk_add_f32 v[36:37], v[42:43], v[36:37]
	v_mov_b32_e32 v41, v37
	v_mov_b32_e32 v40, v36
	s_nop 0
	v_permlane32_swap_b32_e32 v41, v37
	v_permlane32_swap_b32_e32 v40, v36
	s_waitcnt lgkmcnt(0)
	v_pk_add_f32 v[36:37], v[36:37], v[40:41]
	v_mov_b32_e32 v41, v37
	v_mov_b32_e32 v40, v36
	s_nop 0
	v_permlane16_swap_b32_e32 v41, v37
	v_permlane16_swap_b32_e32 v40, v36
	s_waitcnt lgkmcnt(0)
	v_pk_add_f32 v[36:37], v[36:37], v[40:41]
	s_nop 1
	v_mov_b32_dpp v41, v37 row_ror:8 row_mask:0xf bank_mask:0xf
	v_mov_b32_dpp v40, v36 row_ror:8 row_mask:0xf bank_mask:0xf
	s_waitcnt lgkmcnt(0)
	v_pk_add_f32 v[36:37], v[36:37], v[40:41]
	s_nop 1
	v_mov_b32_dpp v41, v37 row_shl:4 row_mask:0xf bank_mask:0x5
	v_mov_b32_dpp v41, v37 row_shr:4 row_mask:0xf bank_mask:0xa
	v_mov_b32_dpp v40, v36 row_shl:4 row_mask:0xf bank_mask:0x5
	v_mov_b32_dpp v40, v36 row_shr:4 row_mask:0xf bank_mask:0xa
	s_waitcnt lgkmcnt(0)
	v_pk_add_f32 v[36:37], v[36:37], v[40:41]
	s_nop 1
	v_mov_b32_dpp v41, v37 quad_perm:[2,3,0,1] row_mask:0xf bank_mask:0xf
	v_mov_b32_dpp v40, v36 quad_perm:[2,3,0,1] row_mask:0xf bank_mask:0xf
	s_waitcnt lgkmcnt(0)
	v_pk_add_f32 v[36:37], v[36:37], v[40:41]
	s_nop 1
	v_mov_b32_dpp v41, v37 quad_perm:[1,0,3,2] row_mask:0xf bank_mask:0xf
	v_mov_b32_dpp v40, v36 quad_perm:[1,0,3,2] row_mask:0xf bank_mask:0xf
	s_waitcnt lgkmcnt(0)
; DI unsigned pk2(float lo, float hi) { const f32x2 v = {lo, hi}; return __builtin_bit_cast(unsigned, __builtin_convertvector(v, bf16v2_t)); }
; DI float wave_sum(float v) { for (int o = 32; o; o >>= 1) v += __shfl_xor(v, o); return v; }
; DI void run_phase(const Params& p, int ph, unsigned char* smem, const int tid, const int rep) {
;     ...
;               for (int u = 0; u < 4; ++u) { const int t = t0 + u; bf16_t* pr = proj + (size_t)t * PLD;
;                   { const u32x2 v = vq[u]; const float a0 = __uint_as_float(v[0] << 16), a1 = __uint_as_float(v[0] & 0xffff0000u), a2 = __uint_as_float(v[1] << 16), a3 = __uint_as_float(v[1] & 0xffff0000u);
;                     const float rs = rsqrtf(wave_sum(a0 * a0 + a1 * a1 + a2 * a2 + a3 * a3) * (1.f / 256.f) + NEPS);
;                     u32x2 o; o[0] = pk2(a0 * rs * ggq[0], a1 * rs * ggq[1]); o[1] = pk2(a2 * rs * ggq[2], a3 * rs * ggq[3]); *(u32x2*)(mlaa + (size_t)t * 384 + 4 * lane) = o; }
;                   { const unsigned v = vkv[u]; const float a0 = __uint_as_float(v << 16), a1 = __uint_as_float(v & 0xffff0000u);
;                     const float rs = rsqrtf(wave_sum(a0 * a0 + a1 * a1) * (1.f / 128.f) + NEPS);
;                     *(unsigned*)(mlaa + (size_t)t * 384 + 256 + 2 * lane) = pk2(a0 * rs * gkv0, a1 * rs * gkv1); }
; #pragma unroll
;                   for (int hq = 0; hq < 8; ++hq) { const unsigned v = vf[u][hq]; const float a0 = __uint_as_float(v << 16), a1 = __uint_as_float(v & 0xffff0000u);
;                     const float rs = rsqrtf(wave_sum(a0 * a0 + a1 * a1) * (1.f / 128.f) + NEPS) * ((hq < 4) ? 0.08838834764831845f * LOG2E : 1.f);
;                     *(unsigned*)(pr + 3520 + hq * 128 + 2 * lane) = pk2(a0 * rs * ((hq < 4) ? fq0 : fk0), a1 * rs * ((hq < 4) ? fq1 : fk1)); } } } }
	v_pk_add_f32 v[36:37], v[36:37], v[40:41]
	s_nop 0
	v_pk_fma_f32 v[36:37], v[36:37], s[96:97], v[18:19] op_sel_hi:[1,0,0]
	s_nop 0
	v_mul_f32_e32 v40, 0x4b800000, v37
	v_cmp_gt_f32_e64 s[0:1], s77, v37
	v_cmp_gt_f32_e32 vcc, s77, v36
	s_nop 0
	v_cndmask_b32_e64 v37, v37, v40, s[0:1]
	v_rsq_f32_e32 v37, v37
	s_nop 0
	v_mul_f32_e32 v40, 0x45800000, v37
	v_cndmask_b32_e64 v37, v37, v40, s[0:1]
	v_mul_f32_e32 v40, 0x3e0293ee, v37
	v_pk_mul_f32 v[34:35], v[40:41], v[34:35] op_sel_hi:[0,1]
	v_pk_mul_f32 v[34:35], v[8:9], v[34:35]
	v_and_b32_e32 v37, 0xffff0000, v75
	v_cvt_pk_bf16_f32 v34, v34, v35
	global_store_dword v[32:33], v34, off offset:2944
	v_mul_f32_e32 v32, 0x4b800000, v36
	v_cndmask_b32_e32 v32, v36, v32, vcc
	v_rsq_f32_e32 v32, v32
	v_lshlrev_b32_e32 v36, 16, v75
	v_mul_f32_e32 v33, 0x45800000, v32
	v_cndmask_b32_e32 v32, v32, v33, vcc
	v_mul_f32_e32 v32, 0x3e0293ee, v32
	v_pk_mul_f32 v[32:33], v[32:33], v[38:39] op_sel_hi:[0,1]
	v_pk_mul_f32 v[32:33], v[8:9], v[32:33]
	v_pk_mul_f32 v[38:39], v[36:37], v[36:37]
	v_cvt_pk_bf16_f32 v32, v32, v33
	global_store_dword v[28:29], v32, off offset:256
	v_lshlrev_b32_e32 v32, 16, v76
	v_and_b32_e32 v33, 0xffff0000, v76
	v_pk_mul_f32 v[34:35], v[32:33], v[32:33]
	v_mov_b32_e32 v40, v38
	v_mov_b32_e32 v41, v34
	v_mov_b32_e32 v34, v39
	v_pk_add_f32 v[34:35], v[40:41], v[34:35]
	v_mov_b32_e32 v39, v35
	v_mov_b32_e32 v38, v34
	s_nop 0
	v_permlane32_swap_b32_e32 v39, v35
	v_permlane32_swap_b32_e32 v38, v34
	s_waitcnt lgkmcnt(0)
	v_pk_add_f32 v[34:35], v[34:35], v[38:39]
	v_mov_b32_e32 v39, v35
	v_mov_b32_e32 v38, v34
	s_nop 0
	v_permlane16_swap_b32_e32 v39, v35
	v_permlane16_swap_b32_e32 v38, v34
	s_waitcnt lgkmcnt(0)
	v_pk_add_f32 v[34:35], v[34:35], v[38:39]
	s_nop 1
	v_mov_b32_dpp v39, v35 row_ror:8 row_mask:0xf bank_mask:0xf
	v_mov_b32_dpp v38, v34 row_ror:8 row_mask:0xf bank_mask:0xf
	s_waitcnt lgkmcnt(0)
	v_pk_add_f32 v[34:35], v[34:35], v[38:39]
	s_nop 1
	v_mov_b32_dpp v39, v35 row_shl:4 row_mask:0xf bank_mask:0x5
	v_mov_b32_dpp v39, v35 row_shr:4 row_mask:0xf bank_mask:0xa
	v_mov_b32_dpp v38, v34 row_shl:4 row_mask:0xf bank_mask:0x5
	v_mov_b32_dpp v38, v34 row_shr:4 row_mask:0xf bank_mask:0xa
	s_waitcnt lgkmcnt(0)
	v_pk_add_f32 v[34:35], v[34:35], v[38:39]
	s_nop 1
	v_mov_b32_dpp v39, v35 quad_perm:[2,3,0,1] row_mask:0xf bank_mask:0xf
	v_mov_b32_dpp v38, v34 quad_perm:[2,3,0,1] row_mask:0xf bank_mask:0xf
	s_waitcnt lgkmcnt(0)
	v_pk_add_f32 v[34:35], v[34:35], v[38:39]
	s_nop 1
	v_mov_b32_dpp v39, v35 quad_perm:[1,0,3,2] row_mask:0xf bank_mask:0xf
	v_mov_b32_dpp v38, v34 quad_perm:[1,0,3,2] row_mask:0xf bank_mask:0xf
	s_waitcnt lgkmcnt(0)
	v_pk_add_f32 v[34:35], v[34:35], v[38:39]
	s_nop 0
	v_pk_fma_f32 v[34:35], v[34:35], s[96:97], v[18:19] op_sel_hi:[1,0,0]
	s_nop 0
	v_mul_f32_e32 v38, 0x4b800000, v35
	v_cmp_gt_f32_e64 s[0:1], s77, v35
	v_cmp_gt_f32_e32 vcc, s77, v34
	s_nop 0
	v_cndmask_b32_e64 v35, v35, v38, s[0:1]
	v_rsq_f32_e32 v35, v35
	s_nop 0
	v_mul_f32_e32 v38, 0x45800000, v35
	v_cndmask_b32_e64 v35, v35, v38, s[0:1]
	v_mul_f32_e32 v38, 0x3e0293ee, v35
	v_pk_mul_f32 v[32:33], v[38:39], v[32:33] op_sel_hi:[0,1]
	v_pk_mul_f32 v[32:33], v[8:9], v[32:33]
	s_nop 0
	v_cvt_pk_bf16_f32 v32, v32, v33
	global_store_dword v[28:29], v32, off offset:512
	v_mul_f32_e32 v32, 0x4b800000, v34
	v_cndmask_b32_e32 v32, v34, v32, vcc
	v_rsq_f32_e32 v32, v32
	s_nop 0
	v_mul_f32_e32 v33, 0x45800000, v32
	v_cndmask_b32_e32 v32, v32, v33, vcc
	v_mul_f32_e32 v32, 0x3e0293ee, v32
	v_pk_mul_f32 v[32:33], v[32:33], v[36:37] op_sel_hi:[0,1]
	v_pk_mul_f32 v[32:33], v[8:9], v[32:33]
	v_lshlrev_b32_e32 v36, 16, v73
	v_cvt_pk_bf16_f32 v32, v32, v33
	global_store_dword v[28:29], v32, off offset:768
	v_lshlrev_b32_e32 v32, 16, v74
	v_and_b32_e32 v33, 0xffff0000, v74
	v_and_b32_e32 v37, 0xffff0000, v73
	v_pk_mul_f32 v[34:35], v[32:33], v[32:33]
	v_pk_mul_f32 v[38:39], v[36:37], v[36:37]
	v_mov_b32_e32 v41, v34
	v_mov_b32_e32 v40, v38
	v_mov_b32_e32 v34, v39
	v_pk_add_f32 v[34:35], v[40:41], v[34:35]
	v_mov_b32_e32 v39, v35
	v_mov_b32_e32 v38, v34
	s_nop 0
	v_permlane32_swap_b32_e32 v39, v35
	v_permlane32_swap_b32_e32 v38, v34
	s_waitcnt lgkmcnt(0)
	v_pk_add_f32 v[34:35], v[34:35], v[38:39]
	v_mov_b32_e32 v39, v35
	v_mov_b32_e32 v38, v34
	s_nop 0
	v_permlane16_swap_b32_e32 v39, v35
	v_permlane16_swap_b32_e32 v38, v34
	s_waitcnt lgkmcnt(0)
	v_pk_add_f32 v[34:35], v[34:35], v[38:39]
	s_nop 1
	v_mov_b32_dpp v39, v35 row_ror:8 row_mask:0xf bank_mask:0xf
	v_mov_b32_dpp v38, v34 row_ror:8 row_mask:0xf bank_mask:0xf
	s_waitcnt lgkmcnt(0)
	v_pk_add_f32 v[34:35], v[34:35], v[38:39]
	s_nop 1
	v_mov_b32_dpp v39, v35 row_shl:4 row_mask:0xf bank_mask:0x5
	v_mov_b32_dpp v39, v35 row_shr:4 row_mask:0xf bank_mask:0xa
	v_mov_b32_dpp v38, v34 row_shl:4 row_mask:0xf bank_mask:0x5
	v_mov_b32_dpp v38, v34 row_shr:4 row_mask:0xf bank_mask:0xa
	s_waitcnt lgkmcnt(0)
	v_pk_add_f32 v[34:35], v[34:35], v[38:39]
	s_nop 1
	v_mov_b32_dpp v39, v35 quad_perm:[2,3,0,1] row_mask:0xf bank_mask:0xf
	v_mov_b32_dpp v38, v34 quad_perm:[2,3,0,1] row_mask:0xf bank_mask:0xf
	s_waitcnt lgkmcnt(0)
	v_pk_add_f32 v[34:35], v[34:35], v[38:39]
	s_nop 1
	v_mov_b32_dpp v39, v35 quad_perm:[1,0,3,2] row_mask:0xf bank_mask:0xf
	v_mov_b32_dpp v38, v34 quad_perm:[1,0,3,2] row_mask:0xf bank_mask:0xf
	s_waitcnt lgkmcnt(0)
; DI unsigned pk2(float lo, float hi) { const f32x2 v = {lo, hi}; return __builtin_bit_cast(unsigned, __builtin_convertvector(v, bf16v2_t)); }
; DI float wave_sum(float v) { for (int o = 32; o; o >>= 1) v += __shfl_xor(v, o); return v; }
; DI void run_phase(const Params& p, int ph, unsigned char* smem, const int tid, const int rep) {
;     ...
;               for (int u = 0; u < 4; ++u) { const int t = t0 + u; bf16_t* pr = proj + (size_t)t * PLD;
;                   { const u32x2 v = vq[u]; const float a0 = __uint_as_float(v[0] << 16), a1 = __uint_as_float(v[0] & 0xffff0000u), a2 = __uint_as_float(v[1] << 16), a3 = __uint_as_float(v[1] & 0xffff0000u);
;                     const float rs = rsqrtf(wave_sum(a0 * a0 + a1 * a1 + a2 * a2 + a3 * a3) * (1.f / 256.f) + NEPS);
;                     u32x2 o; o[0] = pk2(a0 * rs * ggq[0], a1 * rs * ggq[1]); o[1] = pk2(a2 * rs * ggq[2], a3 * rs * ggq[3]); *(u32x2*)(mlaa + (size_t)t * 384 + 4 * lane) = o; }
;                   { const unsigned v = vkv[u]; const float a0 = __uint_as_float(v << 16), a1 = __uint_as_float(v & 0xffff0000u);
;                     const float rs = rsqrtf(wave_sum(a0 * a0 + a1 * a1) * (1.f / 128.f) + NEPS);
;                     *(unsigned*)(mlaa + (size_t)t * 384 + 256 + 2 * lane) = pk2(a0 * rs * gkv0, a1 * rs * gkv1); }
; #pragma unroll
;                   for (int hq = 0; hq < 8; ++hq) { const unsigned v = vf[u][hq]; const float a0 = __uint_as_float(v << 16), a1 = __uint_as_float(v & 0xffff0000u);
;                     const float rs = rsqrtf(wave_sum(a0 * a0 + a1 * a1) * (1.f / 128.f) + NEPS) * ((hq < 4) ? 0.08838834764831845f * LOG2E : 1.f);
;                     *(unsigned*)(pr + 3520 + hq * 128 + 2 * lane) = pk2(a0 * rs * ((hq < 4) ? fq0 : fk0), a1 * rs * ((hq < 4) ? fq1 : fk1)); } } } }
	v_pk_add_f32 v[34:35], v[34:35], v[38:39]
	s_nop 0
	v_pk_fma_f32 v[34:35], v[34:35], s[96:97], v[18:19] op_sel_hi:[1,0,0]
	s_nop 0
	v_mul_f32_e32 v38, 0x4b800000, v35
	v_cmp_gt_f32_e64 s[0:1], s77, v35
	v_cmp_gt_f32_e32 vcc, s77, v34
	s_nop 0
	v_cndmask_b32_e64 v35, v35, v38, s[0:1]
	v_rsq_f32_e32 v35, v35
	s_nop 0
	v_mul_f32_e32 v38, 0x45800000, v35
	v_cndmask_b32_e64 v38, v35, v38, s[0:1]
	v_pk_mul_f32 v[32:33], v[38:39], v[32:33] op_sel_hi:[0,1]
	v_pk_mul_f32 v[32:33], v[10:11], v[32:33]
	s_nop 0
	v_cvt_pk_bf16_f32 v32, v32, v33
	global_store_dword v[28:29], v32, off offset:1024
	v_mul_f32_e32 v32, 0x4b800000, v34
	v_cndmask_b32_e32 v32, v34, v32, vcc
	v_rsq_f32_e32 v32, v32
	s_nop 0
	v_mul_f32_e32 v33, 0x45800000, v32
	v_cndmask_b32_e32 v32, v32, v33, vcc
	v_pk_mul_f32 v[32:33], v[32:33], v[36:37] op_sel_hi:[0,1]
	v_pk_mul_f32 v[32:33], v[10:11], v[32:33]
	v_lshlrev_b32_e32 v36, 16, v71
	v_cvt_pk_bf16_f32 v32, v32, v33
	global_store_dword v[28:29], v32, off offset:1280
	v_lshlrev_b32_e32 v32, 16, v72
	v_and_b32_e32 v33, 0xffff0000, v72
	v_and_b32_e32 v37, 0xffff0000, v71
	v_pk_mul_f32 v[34:35], v[32:33], v[32:33]
	v_pk_mul_f32 v[38:39], v[36:37], v[36:37]
	v_mov_b32_e32 v41, v34
	v_mov_b32_e32 v40, v38
	v_mov_b32_e32 v34, v39
	v_pk_add_f32 v[34:35], v[40:41], v[34:35]
	v_mov_b32_e32 v39, v35
	v_mov_b32_e32 v38, v34
	s_nop 0
	v_permlane32_swap_b32_e32 v39, v35
	v_permlane32_swap_b32_e32 v38, v34
	v_lshlrev_b32_e32 v40, 16, v70
	v_and_b32_e32 v41, 0xffff0000, v70
	v_pk_mul_f32 v[42:43], v[40:41], v[40:41]
	s_waitcnt lgkmcnt(0)
	v_pk_add_f32 v[34:35], v[34:35], v[38:39]
	v_mov_b32_e32 v39, v35
	v_mov_b32_e32 v38, v34
	s_nop 0
	v_permlane16_swap_b32_e32 v39, v35
	v_permlane16_swap_b32_e32 v38, v34
	s_waitcnt lgkmcnt(0)
	v_pk_add_f32 v[34:35], v[34:35], v[38:39]
	s_nop 1
	v_mov_b32_dpp v39, v35 row_ror:8 row_mask:0xf bank_mask:0xf
	v_mov_b32_dpp v38, v34 row_ror:8 row_mask:0xf bank_mask:0xf
	s_waitcnt lgkmcnt(0)
	v_pk_add_f32 v[34:35], v[34:35], v[38:39]
	s_nop 1
	v_mov_b32_dpp v39, v35 row_shl:4 row_mask:0xf bank_mask:0x5
	v_mov_b32_dpp v39, v35 row_shr:4 row_mask:0xf bank_mask:0xa
	v_mov_b32_dpp v38, v34 row_shl:4 row_mask:0xf bank_mask:0x5
	v_mov_b32_dpp v38, v34 row_shr:4 row_mask:0xf bank_mask:0xa
	s_waitcnt lgkmcnt(0)
	v_pk_add_f32 v[34:35], v[34:35], v[38:39]
	s_nop 1
	v_mov_b32_dpp v39, v35 quad_perm:[2,3,0,1] row_mask:0xf bank_mask:0xf
	v_mov_b32_dpp v38, v34 quad_perm:[2,3,0,1] row_mask:0xf bank_mask:0xf
	s_waitcnt lgkmcnt(0)
	v_pk_add_f32 v[34:35], v[34:35], v[38:39]
	s_nop 1
	v_mov_b32_dpp v39, v35 quad_perm:[1,0,3,2] row_mask:0xf bank_mask:0xf
	v_mov_b32_dpp v38, v34 quad_perm:[1,0,3,2] row_mask:0xf bank_mask:0xf
	s_waitcnt lgkmcnt(0)
	v_pk_add_f32 v[34:35], v[34:35], v[38:39]
	s_nop 0
	v_pk_fma_f32 v[34:35], v[34:35], s[96:97], v[18:19] op_sel_hi:[1,0,0]
	s_nop 0
	v_mul_f32_e32 v38, 0x4b800000, v35
	v_cmp_gt_f32_e64 s[0:1], s77, v35
	v_cmp_gt_f32_e32 vcc, s77, v34
	s_nop 0
	v_cndmask_b32_e64 v35, v35, v38, s[0:1]
	v_rsq_f32_e32 v35, v35
	s_nop 0
	v_mul_f32_e32 v38, 0x45800000, v35
	v_cndmask_b32_e64 v38, v35, v38, s[0:1]
	v_pk_mul_f32 v[32:33], v[38:39], v[32:33] op_sel_hi:[0,1]
	v_pk_mul_f32 v[32:33], v[10:11], v[32:33]
	s_nop 0
	v_cvt_pk_bf16_f32 v32, v32, v33
	global_store_dword v[28:29], v32, off offset:1536
	v_mul_f32_e32 v32, 0x4b800000, v34
	v_cndmask_b32_e32 v32, v34, v32, vcc
	v_rsq_f32_e32 v32, v32
	s_nop 0
	v_mul_f32_e32 v33, 0x45800000, v32
	v_cndmask_b32_e32 v32, v32, v33, vcc
	v_pk_mul_f32 v[32:33], v[32:33], v[36:37] op_sel_hi:[0,1]
	v_pk_mul_f32 v[32:33], v[10:11], v[32:33]
	s_nop 0
	v_cvt_pk_bf16_f32 v32, v32, v33
	global_store_dword v[28:29], v32, off offset:1792
	v_and_b32_e32 v33, 0xffff0000, v31
	v_and_b32_e32 v32, s0, v30
	v_mov_b32_e32 v29, v33
	v_pk_mul_f32 v[34:35], v[32:33], v[32:33]
	v_and_b32_e32 v33, 0xffff0000, v30
	v_lshlrev_b32_e32 v32, 16, v30
	v_mul_f32_e32 v30, v33, v33
	v_lshlrev_b32_e32 v28, 16, v31
	v_pk_fma_f32 v[30:31], v[32:33], v[32:33], v[30:31] op_sel_hi:[1,1,0]
	v_mov_b32_e32 v34, v42
	v_pk_fma_f32 v[30:31], v[28:29], v[28:29], v[30:31]
	v_mad_i64_i32 v[36:37], s[0:1], v69, s22, v[20:21]
	v_pk_mov_b32 v[30:31], v[42:43], v[30:31] op_sel:[1,0]
	v_lshl_add_u64 v[38:39], v[36:37], 0, v[0:1]
	v_pk_add_f32 v[30:31], v[34:35], v[30:31]
	v_mov_b32_e32 v35, v31
	v_mov_b32_e32 v34, v30
	s_nop 0
	v_permlane32_swap_b32_e32 v35, v31
	v_permlane32_swap_b32_e32 v34, v30
	s_waitcnt lgkmcnt(0)
	v_pk_add_f32 v[30:31], v[30:31], v[34:35]
	v_mov_b32_e32 v35, v31
	v_mov_b32_e32 v34, v30
	s_nop 0
	v_permlane16_swap_b32_e32 v35, v31
	v_permlane16_swap_b32_e32 v34, v30
	s_waitcnt lgkmcnt(0)
	v_pk_add_f32 v[30:31], v[30:31], v[34:35]
	s_nop 1
	v_mov_b32_dpp v35, v31 row_ror:8 row_mask:0xf bank_mask:0xf
	v_mov_b32_dpp v34, v30 row_ror:8 row_mask:0xf bank_mask:0xf
	s_waitcnt lgkmcnt(0)
	v_pk_add_f32 v[30:31], v[30:31], v[34:35]
	s_nop 1
	v_mov_b32_dpp v35, v31 row_shl:4 row_mask:0xf bank_mask:0x5
	v_mov_b32_dpp v35, v31 row_shr:4 row_mask:0xf bank_mask:0xa
	v_mov_b32_dpp v34, v30 row_shl:4 row_mask:0xf bank_mask:0x5
	v_mov_b32_dpp v34, v30 row_shr:4 row_mask:0xf bank_mask:0xa
	s_waitcnt lgkmcnt(0)
	v_pk_add_f32 v[30:31], v[30:31], v[34:35]
	s_nop 1
	v_mov_b32_dpp v35, v31 quad_perm:[2,3,0,1] row_mask:0xf bank_mask:0xf
	v_mov_b32_dpp v34, v30 quad_perm:[2,3,0,1] row_mask:0xf bank_mask:0xf
	s_waitcnt lgkmcnt(0)
	v_pk_add_f32 v[30:31], v[30:31], v[34:35]
	s_nop 1
	v_mov_b32_dpp v35, v31 quad_perm:[1,0,3,2] row_mask:0xf bank_mask:0xf
	v_mov_b32_dpp v34, v30 quad_perm:[1,0,3,2] row_mask:0xf bank_mask:0xf
	s_waitcnt lgkmcnt(0)
; DI unsigned pk2(float lo, float hi) { const f32x2 v = {lo, hi}; return __builtin_bit_cast(unsigned, __builtin_convertvector(v, bf16v2_t)); }
; DI float wave_sum(float v) { for (int o = 32; o; o >>= 1) v += __shfl_xor(v, o); return v; }
; DI void run_phase(const Params& p, int ph, unsigned char* smem, const int tid, const int rep) {
;     ...
;               for (int u = 0; u < 4; ++u) { const int t = t0 + u; bf16_t* pr = proj + (size_t)t * PLD;
;                   { const u32x2 v = vq[u]; const float a0 = __uint_as_float(v[0] << 16), a1 = __uint_as_float(v[0] & 0xffff0000u), a2 = __uint_as_float(v[1] << 16), a3 = __uint_as_float(v[1] & 0xffff0000u);
;                     const float rs = rsqrtf(wave_sum(a0 * a0 + a1 * a1 + a2 * a2 + a3 * a3) * (1.f / 256.f) + NEPS);
;                     u32x2 o; o[0] = pk2(a0 * rs * ggq[0], a1 * rs * ggq[1]); o[1] = pk2(a2 * rs * ggq[2], a3 * rs * ggq[3]); *(u32x2*)(mlaa + (size_t)t * 384 + 4 * lane) = o; }
;                   { const unsigned v = vkv[u]; const float a0 = __uint_as_float(v << 16), a1 = __uint_as_float(v & 0xffff0000u);
;                     const float rs = rsqrtf(wave_sum(a0 * a0 + a1 * a1) * (1.f / 128.f) + NEPS);
;                     *(unsigned*)(mlaa + (size_t)t * 384 + 256 + 2 * lane) = pk2(a0 * rs * gkv0, a1 * rs * gkv1); }
; #pragma unroll
;                   for (int hq = 0; hq < 8; ++hq) { const unsigned v = vf[u][hq]; const float a0 = __uint_as_float(v << 16), a1 = __uint_as_float(v & 0xffff0000u);
;                     const float rs = rsqrtf(wave_sum(a0 * a0 + a1 * a1) * (1.f / 128.f) + NEPS) * ((hq < 4) ? 0.08838834764831845f * LOG2E : 1.f);
;                     *(unsigned*)(pr + 3520 + hq * 128 + 2 * lane) = pk2(a0 * rs * ((hq < 4) ? fq0 : fk0), a1 * rs * ((hq < 4) ? fq1 : fk1)); } } } }
	v_pk_add_f32 v[30:31], v[30:31], v[34:35]
	s_nop 0
	v_pk_fma_f32 v[30:31], v[30:31], s[96:97], v[18:19] op_sel_hi:[1,1,0]
	s_nop 0
	v_mul_f32_e32 v34, 0x4b800000, v31
	v_cmp_gt_f32_e64 s[0:1], s77, v31
	v_cmp_gt_f32_e32 vcc, s77, v30
	s_nop 0
	v_cndmask_b32_e64 v31, v31, v34, s[0:1]
	v_rsq_f32_e32 v31, v31
	s_nop 0
	v_mul_f32_e32 v34, 0x45800000, v31
	v_cndmask_b32_e64 v34, v31, v34, s[0:1]
	v_pk_mul_f32 v[32:33], v[34:35], v[32:33] op_sel_hi:[0,1]
	v_pk_mul_f32 v[28:29], v[34:35], v[28:29] op_sel_hi:[0,1]
	v_pk_mul_f32 v[32:33], v[2:3], v[32:33]
	v_pk_mul_f32 v[28:29], v[4:5], v[28:29]
	v_cvt_pk_bf16_f32 v32, v32, v33
	v_cvt_pk_bf16_f32 v33, v28, v29
	v_mul_f32_e32 v28, 0x4b800000, v30
	v_cndmask_b32_e32 v28, v30, v28, vcc
	v_rsq_f32_e32 v28, v28
	global_store_dwordx2 v[38:39], v[32:33], off
	v_lshlrev_b32_e32 v32, 16, v67
	v_and_b32_e32 v33, 0xffff0000, v67
	v_mul_f32_e32 v29, 0x45800000, v28
	v_cndmask_b32_e32 v28, v28, v29, vcc
	v_pk_mul_f32 v[28:29], v[28:29], v[40:41] op_sel_hi:[0,1]
	v_pk_mul_f32 v[28:29], v[6:7], v[28:29]
	v_pk_mul_f32 v[34:35], v[32:33], v[32:33]
	v_cvt_pk_bf16_f32 v30, v28, v29
	v_lshl_add_u64 v[28:29], v[36:37], 0, v[12:13]
	global_store_dword v[28:29], v30, off offset:512
	v_lshlrev_b32_e32 v28, 16, v68
	v_and_b32_e32 v29, 0xffff0000, v68
	v_pk_mul_f32 v[30:31], v[28:29], v[28:29]
	v_mov_b32_e32 v36, v34
	v_mov_b32_e32 v37, v30
	v_mov_b32_e32 v30, v35
	v_pk_add_f32 v[30:31], v[36:37], v[30:31]
	v_mov_b32_e32 v35, v31
	v_mov_b32_e32 v34, v30
	s_nop 0
	v_permlane32_swap_b32_e32 v35, v31
	v_permlane32_swap_b32_e32 v34, v30
	s_waitcnt lgkmcnt(0)
	v_pk_add_f32 v[30:31], v[30:31], v[34:35]
	v_mov_b32_e32 v35, v31
	v_mov_b32_e32 v34, v30
	s_nop 0
	v_permlane16_swap_b32_e32 v35, v31
	v_permlane16_swap_b32_e32 v34, v30
	s_waitcnt lgkmcnt(0)
	v_pk_add_f32 v[30:31], v[30:31], v[34:35]
	s_nop 1
	v_mov_b32_dpp v35, v31 row_ror:8 row_mask:0xf bank_mask:0xf
	v_mov_b32_dpp v34, v30 row_ror:8 row_mask:0xf bank_mask:0xf
	s_waitcnt lgkmcnt(0)
	v_pk_add_f32 v[30:31], v[30:31], v[34:35]
	s_nop 1
	v_mov_b32_dpp v35, v31 row_shl:4 row_mask:0xf bank_mask:0x5
	v_mov_b32_dpp v35, v31 row_shr:4 row_mask:0xf bank_mask:0xa
	v_mov_b32_dpp v34, v30 row_shl:4 row_mask:0xf bank_mask:0x5
	v_mov_b32_dpp v34, v30 row_shr:4 row_mask:0xf bank_mask:0xa
	s_waitcnt lgkmcnt(0)
	v_pk_add_f32 v[30:31], v[30:31], v[34:35]
	s_nop 1
	v_mov_b32_dpp v35, v31 quad_perm:[2,3,0,1] row_mask:0xf bank_mask:0xf
	v_mov_b32_dpp v34, v30 quad_perm:[2,3,0,1] row_mask:0xf bank_mask:0xf
	s_waitcnt lgkmcnt(0)
	v_pk_add_f32 v[30:31], v[30:31], v[34:35]
	s_nop 1
	v_mov_b32_dpp v35, v31 quad_perm:[1,0,3,2] row_mask:0xf bank_mask:0xf
	v_mov_b32_dpp v34, v30 quad_perm:[1,0,3,2] row_mask:0xf bank_mask:0xf
	s_waitcnt lgkmcnt(0)
	v_pk_add_f32 v[30:31], v[30:31], v[34:35]
	s_nop 0
	v_pk_fma_f32 v[30:31], v[30:31], s[96:97], v[18:19] op_sel_hi:[1,0,0]
	s_nop 0
	v_mul_f32_e32 v34, 0x4b800000, v31
	v_cmp_gt_f32_e64 s[0:1], s77, v31
	v_cmp_gt_f32_e32 vcc, s77, v30
	s_nop 0
	v_cndmask_b32_e64 v31, v31, v34, s[0:1]
	v_rsq_f32_e32 v31, v31
	s_nop 0
	v_mul_f32_e32 v34, 0x45800000, v31
	v_cndmask_b32_e64 v31, v31, v34, s[0:1]
	v_mul_f32_e32 v34, 0x3e0293ee, v31
	v_pk_mul_f32 v[28:29], v[34:35], v[28:29] op_sel_hi:[0,1]
	v_pk_mul_f32 v[28:29], v[8:9], v[28:29]
	v_and_b32_e32 v31, 0xffff0000, v65
	v_cvt_pk_bf16_f32 v28, v28, v29
	global_store_dword v[26:27], v28, off offset:2944
	v_mul_f32_e32 v26, 0x4b800000, v30
	v_cndmask_b32_e32 v26, v30, v26, vcc
	v_rsq_f32_e32 v26, v26
	v_lshlrev_b32_e32 v30, 16, v65
	v_mul_f32_e32 v27, 0x45800000, v26
	v_cndmask_b32_e32 v26, v26, v27, vcc
	v_mul_f32_e32 v26, 0x3e0293ee, v26
	v_pk_mul_f32 v[26:27], v[26:27], v[32:33] op_sel_hi:[0,1]
	v_pk_mul_f32 v[26:27], v[8:9], v[26:27]
	v_pk_mul_f32 v[32:33], v[30:31], v[30:31]
	v_cvt_pk_bf16_f32 v26, v26, v27
	global_store_dword v[22:23], v26, off offset:256
	v_lshlrev_b32_e32 v26, 16, v66
	v_and_b32_e32 v27, 0xffff0000, v66
	v_pk_mul_f32 v[28:29], v[26:27], v[26:27]
	v_mov_b32_e32 v34, v32
	v_mov_b32_e32 v35, v28
	v_mov_b32_e32 v28, v33
	v_pk_add_f32 v[28:29], v[34:35], v[28:29]
	v_mov_b32_e32 v33, v29
	v_mov_b32_e32 v32, v28
	s_nop 0
	v_permlane32_swap_b32_e32 v33, v29
	v_permlane32_swap_b32_e32 v32, v28
	s_waitcnt lgkmcnt(0)
	v_pk_add_f32 v[28:29], v[28:29], v[32:33]
	v_mov_b32_e32 v33, v29
	v_mov_b32_e32 v32, v28
	s_nop 0
	v_permlane16_swap_b32_e32 v33, v29
	v_permlane16_swap_b32_e32 v32, v28
	s_waitcnt lgkmcnt(0)
	v_pk_add_f32 v[28:29], v[28:29], v[32:33]
	s_nop 1
	v_mov_b32_dpp v33, v29 row_ror:8 row_mask:0xf bank_mask:0xf
	v_mov_b32_dpp v32, v28 row_ror:8 row_mask:0xf bank_mask:0xf
	s_waitcnt lgkmcnt(0)
	v_pk_add_f32 v[28:29], v[28:29], v[32:33]
	s_nop 1
	v_mov_b32_dpp v33, v29 row_shl:4 row_mask:0xf bank_mask:0x5
	v_mov_b32_dpp v33, v29 row_shr:4 row_mask:0xf bank_mask:0xa
	v_mov_b32_dpp v32, v28 row_shl:4 row_mask:0xf bank_mask:0x5
	v_mov_b32_dpp v32, v28 row_shr:4 row_mask:0xf bank_mask:0xa
	s_waitcnt lgkmcnt(0)
	v_pk_add_f32 v[28:29], v[28:29], v[32:33]
	s_nop 1
	v_mov_b32_dpp v33, v29 quad_perm:[2,3,0,1] row_mask:0xf bank_mask:0xf
	v_mov_b32_dpp v32, v28 quad_perm:[2,3,0,1] row_mask:0xf bank_mask:0xf
	s_waitcnt lgkmcnt(0)
	v_pk_add_f32 v[28:29], v[28:29], v[32:33]
	s_nop 1
	v_mov_b32_dpp v33, v29 quad_perm:[1,0,3,2] row_mask:0xf bank_mask:0xf
	v_mov_b32_dpp v32, v28 quad_perm:[1,0,3,2] row_mask:0xf bank_mask:0xf
	s_waitcnt lgkmcnt(0)
; DI unsigned pk2(float lo, float hi) { const f32x2 v = {lo, hi}; return __builtin_bit_cast(unsigned, __builtin_convertvector(v, bf16v2_t)); }
; DI float wave_sum(float v) { for (int o = 32; o; o >>= 1) v += __shfl_xor(v, o); return v; }
; DI void run_phase(const Params& p, int ph, unsigned char* smem, const int tid, const int rep) {
;     ...
;               for (int u = 0; u < 4; ++u) { const int t = t0 + u; bf16_t* pr = proj + (size_t)t * PLD;
;                   { const u32x2 v = vq[u]; const float a0 = __uint_as_float(v[0] << 16), a1 = __uint_as_float(v[0] & 0xffff0000u), a2 = __uint_as_float(v[1] << 16), a3 = __uint_as_float(v[1] & 0xffff0000u);
;                     const float rs = rsqrtf(wave_sum(a0 * a0 + a1 * a1 + a2 * a2 + a3 * a3) * (1.f / 256.f) + NEPS);
;                     u32x2 o; o[0] = pk2(a0 * rs * ggq[0], a1 * rs * ggq[1]); o[1] = pk2(a2 * rs * ggq[2], a3 * rs * ggq[3]); *(u32x2*)(mlaa + (size_t)t * 384 + 4 * lane) = o; }
;                   { const unsigned v = vkv[u]; const float a0 = __uint_as_float(v << 16), a1 = __uint_as_float(v & 0xffff0000u);
;                     const float rs = rsqrtf(wave_sum(a0 * a0 + a1 * a1) * (1.f / 128.f) + NEPS);
;                     *(unsigned*)(mlaa + (size_t)t * 384 + 256 + 2 * lane) = pk2(a0 * rs * gkv0, a1 * rs * gkv1); }
; #pragma unroll
;                   for (int hq = 0; hq < 8; ++hq) { const unsigned v = vf[u][hq]; const float a0 = __uint_as_float(v << 16), a1 = __uint_as_float(v & 0xffff0000u);
;                     const float rs = rsqrtf(wave_sum(a0 * a0 + a1 * a1) * (1.f / 128.f) + NEPS) * ((hq < 4) ? 0.08838834764831845f * LOG2E : 1.f);
;                     *(unsigned*)(pr + 3520 + hq * 128 + 2 * lane) = pk2(a0 * rs * ((hq < 4) ? fq0 : fk0), a1 * rs * ((hq < 4) ? fq1 : fk1)); } } } }
	v_pk_add_f32 v[28:29], v[28:29], v[32:33]
	s_nop 0
	v_pk_fma_f32 v[28:29], v[28:29], s[96:97], v[18:19] op_sel_hi:[1,0,0]
	s_nop 0
	v_mul_f32_e32 v32, 0x4b800000, v29
	v_cmp_gt_f32_e64 s[0:1], s77, v29
	v_cmp_gt_f32_e32 vcc, s77, v28
	s_nop 0
	v_cndmask_b32_e64 v29, v29, v32, s[0:1]
	v_rsq_f32_e32 v29, v29
	s_nop 0
	v_mul_f32_e32 v32, 0x45800000, v29
	v_cndmask_b32_e64 v29, v29, v32, s[0:1]
	v_mul_f32_e32 v32, 0x3e0293ee, v29
	v_pk_mul_f32 v[26:27], v[32:33], v[26:27] op_sel_hi:[0,1]
	v_pk_mul_f32 v[26:27], v[8:9], v[26:27]
	s_nop 0
	v_cvt_pk_bf16_f32 v26, v26, v27
	global_store_dword v[22:23], v26, off offset:512
	v_mul_f32_e32 v26, 0x4b800000, v28
	v_cndmask_b32_e32 v26, v28, v26, vcc
	v_rsq_f32_e32 v26, v26
	s_nop 0
	v_mul_f32_e32 v27, 0x45800000, v26
	v_cndmask_b32_e32 v26, v26, v27, vcc
	v_mul_f32_e32 v26, 0x3e0293ee, v26
	v_pk_mul_f32 v[26:27], v[26:27], v[30:31] op_sel_hi:[0,1]
	v_pk_mul_f32 v[26:27], v[8:9], v[26:27]
	v_lshlrev_b32_e32 v30, 16, v63
	v_cvt_pk_bf16_f32 v26, v26, v27
	global_store_dword v[22:23], v26, off offset:768
	v_lshlrev_b32_e32 v26, 16, v64
	v_and_b32_e32 v27, 0xffff0000, v64
	v_and_b32_e32 v31, 0xffff0000, v63
	v_pk_mul_f32 v[28:29], v[26:27], v[26:27]
	v_pk_mul_f32 v[32:33], v[30:31], v[30:31]
	v_mov_b32_e32 v35, v28
	v_mov_b32_e32 v34, v32
	v_mov_b32_e32 v28, v33
	v_pk_add_f32 v[28:29], v[34:35], v[28:29]
	v_mov_b32_e32 v33, v29
	v_mov_b32_e32 v32, v28
	s_nop 0
	v_permlane32_swap_b32_e32 v33, v29
	v_permlane32_swap_b32_e32 v32, v28
	s_waitcnt lgkmcnt(0)
	v_pk_add_f32 v[28:29], v[28:29], v[32:33]
	v_mov_b32_e32 v33, v29
	v_mov_b32_e32 v32, v28
	s_nop 0
	v_permlane16_swap_b32_e32 v33, v29
	v_permlane16_swap_b32_e32 v32, v28
	s_waitcnt lgkmcnt(0)
	v_pk_add_f32 v[28:29], v[28:29], v[32:33]
	s_nop 1
	v_mov_b32_dpp v33, v29 row_ror:8 row_mask:0xf bank_mask:0xf
	v_mov_b32_dpp v32, v28 row_ror:8 row_mask:0xf bank_mask:0xf
	s_waitcnt lgkmcnt(0)
	v_pk_add_f32 v[28:29], v[28:29], v[32:33]
	s_nop 1
	v_mov_b32_dpp v33, v29 row_shl:4 row_mask:0xf bank_mask:0x5
	v_mov_b32_dpp v33, v29 row_shr:4 row_mask:0xf bank_mask:0xa
	v_mov_b32_dpp v32, v28 row_shl:4 row_mask:0xf bank_mask:0x5
	v_mov_b32_dpp v32, v28 row_shr:4 row_mask:0xf bank_mask:0xa
	s_waitcnt lgkmcnt(0)
	v_pk_add_f32 v[28:29], v[28:29], v[32:33]
	s_nop 1
	v_mov_b32_dpp v33, v29 quad_perm:[2,3,0,1] row_mask:0xf bank_mask:0xf
	v_mov_b32_dpp v32, v28 quad_perm:[2,3,0,1] row_mask:0xf bank_mask:0xf
	s_waitcnt lgkmcnt(0)
	v_pk_add_f32 v[28:29], v[28:29], v[32:33]
	s_nop 1
	v_mov_b32_dpp v33, v29 quad_perm:[1,0,3,2] row_mask:0xf bank_mask:0xf
	v_mov_b32_dpp v32, v28 quad_perm:[1,0,3,2] row_mask:0xf bank_mask:0xf
	s_waitcnt lgkmcnt(0)
	v_pk_add_f32 v[28:29], v[28:29], v[32:33]
	s_nop 0
	v_pk_fma_f32 v[28:29], v[28:29], s[96:97], v[18:19] op_sel_hi:[1,0,0]
	s_nop 0
	v_mul_f32_e32 v32, 0x4b800000, v29
	v_cmp_gt_f32_e64 s[0:1], s77, v29
	v_cmp_gt_f32_e32 vcc, s77, v28
	s_nop 0
	v_cndmask_b32_e64 v29, v29, v32, s[0:1]
	v_rsq_f32_e32 v29, v29
	s_nop 0
	v_mul_f32_e32 v32, 0x45800000, v29
	v_cndmask_b32_e64 v32, v29, v32, s[0:1]
	v_pk_mul_f32 v[26:27], v[32:33], v[26:27] op_sel_hi:[0,1]
	v_pk_mul_f32 v[26:27], v[10:11], v[26:27]
	s_nop 0
	v_cvt_pk_bf16_f32 v26, v26, v27
	global_store_dword v[22:23], v26, off offset:1024
	v_mul_f32_e32 v26, 0x4b800000, v28
	v_cndmask_b32_e32 v26, v28, v26, vcc
	v_rsq_f32_e32 v26, v26
	s_nop 0
	v_mul_f32_e32 v27, 0x45800000, v26
	v_cndmask_b32_e32 v26, v26, v27, vcc
	v_pk_mul_f32 v[26:27], v[26:27], v[30:31] op_sel_hi:[0,1]
	v_pk_mul_f32 v[26:27], v[10:11], v[26:27]
	v_lshlrev_b32_e32 v30, 16, v61
	v_cvt_pk_bf16_f32 v26, v26, v27
	global_store_dword v[22:23], v26, off offset:1280
	v_lshlrev_b32_e32 v26, 16, v62
	v_and_b32_e32 v27, 0xffff0000, v62
	v_and_b32_e32 v31, 0xffff0000, v61
	v_pk_mul_f32 v[28:29], v[26:27], v[26:27]
	v_pk_mul_f32 v[32:33], v[30:31], v[30:31]
	v_mov_b32_e32 v35, v28
	v_mov_b32_e32 v34, v32
	v_mov_b32_e32 v28, v33
	v_pk_add_f32 v[28:29], v[34:35], v[28:29]
	v_mov_b32_e32 v33, v29
	v_mov_b32_e32 v32, v28
	s_nop 0
	v_permlane32_swap_b32_e32 v33, v29
	v_permlane32_swap_b32_e32 v32, v28
	s_waitcnt lgkmcnt(0)
	v_pk_add_f32 v[28:29], v[28:29], v[32:33]
	v_mov_b32_e32 v33, v29
	v_mov_b32_e32 v32, v28
	s_nop 0
	v_permlane16_swap_b32_e32 v33, v29
	v_permlane16_swap_b32_e32 v32, v28
	s_waitcnt lgkmcnt(0)
	v_pk_add_f32 v[28:29], v[28:29], v[32:33]
	s_nop 1
	v_mov_b32_dpp v33, v29 row_ror:8 row_mask:0xf bank_mask:0xf
	v_mov_b32_dpp v32, v28 row_ror:8 row_mask:0xf bank_mask:0xf
	s_waitcnt lgkmcnt(0)
	v_pk_add_f32 v[28:29], v[28:29], v[32:33]
	s_nop 1
	v_mov_b32_dpp v33, v29 row_shl:4 row_mask:0xf bank_mask:0x5
	v_mov_b32_dpp v33, v29 row_shr:4 row_mask:0xf bank_mask:0xa
	v_mov_b32_dpp v32, v28 row_shl:4 row_mask:0xf bank_mask:0x5
	v_mov_b32_dpp v32, v28 row_shr:4 row_mask:0xf bank_mask:0xa
	s_waitcnt lgkmcnt(0)
	v_pk_add_f32 v[28:29], v[28:29], v[32:33]
	s_nop 1
	v_mov_b32_dpp v33, v29 quad_perm:[2,3,0,1] row_mask:0xf bank_mask:0xf
	v_mov_b32_dpp v32, v28 quad_perm:[2,3,0,1] row_mask:0xf bank_mask:0xf
	s_waitcnt lgkmcnt(0)
	v_pk_add_f32 v[28:29], v[28:29], v[32:33]
	s_nop 1
	v_mov_b32_dpp v33, v29 quad_perm:[1,0,3,2] row_mask:0xf bank_mask:0xf
	v_mov_b32_dpp v32, v28 quad_perm:[1,0,3,2] row_mask:0xf bank_mask:0xf
	s_waitcnt lgkmcnt(0)
	v_pk_add_f32 v[28:29], v[28:29], v[32:33]
	s_nop 0
	v_pk_fma_f32 v[28:29], v[28:29], s[96:97], v[18:19] op_sel_hi:[1,0,0]
	s_nop 0
	v_mul_f32_e32 v32, 0x4b800000, v29
	v_cmp_gt_f32_e64 s[0:1], s77, v29
	v_cmp_gt_f32_e32 vcc, s77, v28
	s_nop 0
	v_cndmask_b32_e64 v29, v29, v32, s[0:1]
	v_rsq_f32_e32 v29, v29
	s_nop 0
	v_mul_f32_e32 v32, 0x45800000, v29
	v_cndmask_b32_e64 v32, v29, v32, s[0:1]
	v_pk_mul_f32 v[26:27], v[32:33], v[26:27] op_sel_hi:[0,1]
	v_pk_mul_f32 v[26:27], v[10:11], v[26:27]
	s_waitcnt vmcnt(36)
; DI unsigned pk2(float lo, float hi) { const f32x2 v = {lo, hi}; return __builtin_bit_cast(unsigned, __builtin_convertvector(v, bf16v2_t)); }
; DI float wave_sum(float v) { for (int o = 32; o; o >>= 1) v += __shfl_xor(v, o); return v; }
; DI void run_phase(const Params& p, int ph, unsigned char* smem, const int tid, const int rep) {
;     ...
;               for (int u = 0; u < 4; ++u) { const int t = t0 + u; bf16_t* pr = proj + (size_t)t * PLD;
;                   { const u32x2 v = vq[u]; const float a0 = __uint_as_float(v[0] << 16), a1 = __uint_as_float(v[0] & 0xffff0000u), a2 = __uint_as_float(v[1] << 16), a3 = __uint_as_float(v[1] & 0xffff0000u);
;                     const float rs = rsqrtf(wave_sum(a0 * a0 + a1 * a1 + a2 * a2 + a3 * a3) * (1.f / 256.f) + NEPS);
;                     u32x2 o; o[0] = pk2(a0 * rs * ggq[0], a1 * rs * ggq[1]); o[1] = pk2(a2 * rs * ggq[2], a3 * rs * ggq[3]); *(u32x2*)(mlaa + (size_t)t * 384 + 4 * lane) = o; }
;                   { const unsigned v = vkv[u]; const float a0 = __uint_as_float(v << 16), a1 = __uint_as_float(v & 0xffff0000u);
;                     const float rs = rsqrtf(wave_sum(a0 * a0 + a1 * a1) * (1.f / 128.f) + NEPS);
;                     *(unsigned*)(mlaa + (size_t)t * 384 + 256 + 2 * lane) = pk2(a0 * rs * gkv0, a1 * rs * gkv1); }
; #pragma unroll
;                   for (int hq = 0; hq < 8; ++hq) { const unsigned v = vf[u][hq]; const float a0 = __uint_as_float(v << 16), a1 = __uint_as_float(v & 0xffff0000u);
;                     const float rs = rsqrtf(wave_sum(a0 * a0 + a1 * a1) * (1.f / 128.f) + NEPS) * ((hq < 4) ? 0.08838834764831845f * LOG2E : 1.f);
;                     *(unsigned*)(pr + 3520 + hq * 128 + 2 * lane) = pk2(a0 * rs * ((hq < 4) ? fq0 : fk0), a1 * rs * ((hq < 4) ? fq1 : fk1)); } } } }
	v_lshlrev_b32_e32 v32, 16, v60
	v_cvt_pk_bf16_f32 v26, v26, v27
	global_store_dword v[22:23], v26, off offset:1536
	v_mul_f32_e32 v26, 0x4b800000, v28
	v_cndmask_b32_e32 v26, v28, v26, vcc
	v_rsq_f32_e32 v26, v26
	v_and_b32_e32 v33, 0xffff0000, v60
	v_pk_mul_f32 v[34:35], v[32:33], v[32:33]
	v_mul_f32_e32 v27, 0x45800000, v26
	v_cndmask_b32_e32 v26, v26, v27, vcc
	v_pk_mul_f32 v[26:27], v[26:27], v[30:31] op_sel_hi:[0,1]
	v_pk_mul_f32 v[26:27], v[10:11], v[26:27]
	s_nop 0
	v_cvt_pk_bf16_f32 v26, v26, v27
	global_store_dword v[22:23], v26, off offset:1792
	v_and_b32_e32 v27, 0xffff0000, v25
	v_and_b32_e32 v26, s0, v24
	v_mov_b32_e32 v23, v27
	v_pk_mul_f32 v[28:29], v[26:27], v[26:27]
	v_and_b32_e32 v27, 0xffff0000, v24
	v_lshlrev_b32_e32 v26, 16, v24
	v_mul_f32_e32 v24, v27, v27
	v_lshlrev_b32_e32 v22, 16, v25
	v_pk_fma_f32 v[24:25], v[26:27], v[26:27], v[24:25] op_sel_hi:[1,1,0]
	v_mov_b32_e32 v28, v34
	v_pk_fma_f32 v[24:25], v[22:23], v[22:23], v[24:25]
	v_mad_i64_i32 v[20:21], s[0:1], v59, s22, v[20:21]
	v_pk_mov_b32 v[24:25], v[34:35], v[24:25] op_sel:[1,0]
	v_lshl_add_u64 v[30:31], v[20:21], 0, v[0:1]
	v_pk_add_f32 v[24:25], v[28:29], v[24:25]
	v_mov_b32_e32 v29, v25
	v_mov_b32_e32 v28, v24
	s_nop 0
	v_permlane32_swap_b32_e32 v29, v25
	v_permlane32_swap_b32_e32 v28, v24
	v_lshl_add_u64 v[20:21], v[20:21], 0, v[12:13]
	s_waitcnt lgkmcnt(0)
	v_pk_add_f32 v[24:25], v[24:25], v[28:29]
	v_mov_b32_e32 v29, v25
	v_mov_b32_e32 v28, v24
	s_nop 0
	v_permlane16_swap_b32_e32 v29, v25
	v_permlane16_swap_b32_e32 v28, v24
	s_waitcnt lgkmcnt(0)
	v_pk_add_f32 v[24:25], v[24:25], v[28:29]
	s_nop 1
	v_mov_b32_dpp v29, v25 row_ror:8 row_mask:0xf bank_mask:0xf
	v_mov_b32_dpp v28, v24 row_ror:8 row_mask:0xf bank_mask:0xf
	s_waitcnt lgkmcnt(0)
	v_pk_add_f32 v[24:25], v[24:25], v[28:29]
	s_nop 1
	v_mov_b32_dpp v29, v25 row_shl:4 row_mask:0xf bank_mask:0x5
	v_mov_b32_dpp v29, v25 row_shr:4 row_mask:0xf bank_mask:0xa
	v_mov_b32_dpp v28, v24 row_shl:4 row_mask:0xf bank_mask:0x5
	v_mov_b32_dpp v28, v24 row_shr:4 row_mask:0xf bank_mask:0xa
	s_waitcnt lgkmcnt(0)
	v_pk_add_f32 v[24:25], v[24:25], v[28:29]
	s_nop 1
	v_mov_b32_dpp v29, v25 quad_perm:[2,3,0,1] row_mask:0xf bank_mask:0xf
	v_mov_b32_dpp v28, v24 quad_perm:[2,3,0,1] row_mask:0xf bank_mask:0xf
	s_waitcnt lgkmcnt(0)
	v_pk_add_f32 v[24:25], v[24:25], v[28:29]
	s_nop 1
	v_mov_b32_dpp v29, v25 quad_perm:[1,0,3,2] row_mask:0xf bank_mask:0xf
	v_mov_b32_dpp v28, v24 quad_perm:[1,0,3,2] row_mask:0xf bank_mask:0xf
	s_waitcnt lgkmcnt(0)
	v_pk_add_f32 v[24:25], v[24:25], v[28:29]
	s_nop 0
	v_pk_fma_f32 v[24:25], v[24:25], s[96:97], v[18:19] op_sel_hi:[1,1,0]
	s_nop 0
	v_mul_f32_e32 v28, 0x4b800000, v25
	v_cmp_gt_f32_e64 s[0:1], s77, v25
	v_cmp_gt_f32_e32 vcc, s77, v24
	s_nop 0
	v_cndmask_b32_e64 v25, v25, v28, s[0:1]
	v_rsq_f32_e32 v25, v25
	s_nop 0
	v_mul_f32_e32 v28, 0x45800000, v25
	v_cndmask_b32_e64 v28, v25, v28, s[0:1]
	v_pk_mul_f32 v[26:27], v[28:29], v[26:27] op_sel_hi:[0,1]
	v_pk_mul_f32 v[22:23], v[28:29], v[22:23] op_sel_hi:[0,1]
	v_pk_mul_f32 v[26:27], v[2:3], v[26:27]
	v_pk_mul_f32 v[22:23], v[4:5], v[22:23]
	v_cvt_pk_bf16_f32 v26, v26, v27
	v_cvt_pk_bf16_f32 v27, v22, v23
	v_mul_f32_e32 v22, 0x4b800000, v24
	v_cndmask_b32_e32 v22, v24, v22, vcc
	v_rsq_f32_e32 v22, v22
	s_waitcnt vmcnt(36)
	v_lshlrev_b32_e32 v24, 16, v57
	v_and_b32_e32 v25, 0xffff0000, v57
	global_store_dwordx2 v[30:31], v[26:27], off
	v_mul_f32_e32 v23, 0x45800000, v22
	v_cndmask_b32_e32 v22, v22, v23, vcc
	v_pk_mul_f32 v[22:23], v[22:23], v[32:33] op_sel_hi:[0,1]
	v_pk_mul_f32 v[22:23], v[6:7], v[22:23]
	v_pk_mul_f32 v[26:27], v[24:25], v[24:25]
	v_cvt_pk_bf16_f32 v22, v22, v23
	global_store_dword v[20:21], v22, off offset:512
	v_lshlrev_b32_e32 v20, 16, v58
	v_and_b32_e32 v21, 0xffff0000, v58
	v_pk_mul_f32 v[22:23], v[20:21], v[20:21]
	v_mov_b32_e32 v28, v26
	v_mov_b32_e32 v29, v22
	v_mov_b32_e32 v22, v27
	v_pk_add_f32 v[22:23], v[28:29], v[22:23]
	v_mov_b32_e32 v27, v23
	v_mov_b32_e32 v26, v22
	s_nop 0
	v_permlane32_swap_b32_e32 v27, v23
	v_permlane32_swap_b32_e32 v26, v22
	s_waitcnt lgkmcnt(0)
	v_pk_add_f32 v[22:23], v[22:23], v[26:27]
	v_mov_b32_e32 v27, v23
	v_mov_b32_e32 v26, v22
	s_nop 0
	v_permlane16_swap_b32_e32 v27, v23
	v_permlane16_swap_b32_e32 v26, v22
	s_waitcnt lgkmcnt(0)
	v_pk_add_f32 v[22:23], v[22:23], v[26:27]
	s_nop 1
	v_mov_b32_dpp v27, v23 row_ror:8 row_mask:0xf bank_mask:0xf
	v_mov_b32_dpp v26, v22 row_ror:8 row_mask:0xf bank_mask:0xf
	s_waitcnt lgkmcnt(0)
	v_pk_add_f32 v[22:23], v[22:23], v[26:27]
	s_nop 1
	v_mov_b32_dpp v27, v23 row_shl:4 row_mask:0xf bank_mask:0x5
	v_mov_b32_dpp v27, v23 row_shr:4 row_mask:0xf bank_mask:0xa
	v_mov_b32_dpp v26, v22 row_shl:4 row_mask:0xf bank_mask:0x5
	v_mov_b32_dpp v26, v22 row_shr:4 row_mask:0xf bank_mask:0xa
	s_waitcnt lgkmcnt(0)
	v_pk_add_f32 v[22:23], v[22:23], v[26:27]
	s_nop 1
	v_mov_b32_dpp v27, v23 quad_perm:[2,3,0,1] row_mask:0xf bank_mask:0xf
	v_mov_b32_dpp v26, v22 quad_perm:[2,3,0,1] row_mask:0xf bank_mask:0xf
	s_waitcnt lgkmcnt(0)
	v_pk_add_f32 v[22:23], v[22:23], v[26:27]
	s_nop 1
	v_mov_b32_dpp v27, v23 quad_perm:[1,0,3,2] row_mask:0xf bank_mask:0xf
	v_mov_b32_dpp v26, v22 quad_perm:[1,0,3,2] row_mask:0xf bank_mask:0xf
	s_waitcnt lgkmcnt(0)
	v_pk_add_f32 v[22:23], v[22:23], v[26:27]
	s_nop 0
	v_pk_fma_f32 v[22:23], v[22:23], s[96:97], v[18:19] op_sel_hi:[1,0,0]
	s_nop 0
	v_mul_f32_e32 v13, 0x4b800000, v23
	v_cmp_gt_f32_e64 s[0:1], s77, v23
	v_cmp_gt_f32_e32 vcc, s77, v22
	s_nop 0
	v_cndmask_b32_e64 v13, v23, v13, s[0:1]
	v_rsq_f32_e32 v13, v13
	s_nop 0
	v_mul_f32_e32 v23, 0x45800000, v13
	v_cndmask_b32_e64 v13, v13, v23, s[0:1]
	v_mul_f32_e32 v26, 0x3e0293ee, v13
	v_pk_mul_f32 v[20:21], v[26:27], v[20:21] op_sel_hi:[0,1]
	v_pk_mul_f32 v[20:21], v[8:9], v[20:21]
	s_waitcnt vmcnt(36)
; DI unsigned pk2(float lo, float hi) { const f32x2 v = {lo, hi}; return __builtin_bit_cast(unsigned, __builtin_convertvector(v, bf16v2_t)); }
; DI float wave_sum(float v) { for (int o = 32; o; o >>= 1) v += __shfl_xor(v, o); return v; }
; DI void run_phase(const Params& p, int ph, unsigned char* smem, const int tid, const int rep) {
;     ...
;               for (int u = 0; u < 4; ++u) { const int t = t0 + u; bf16_t* pr = proj + (size_t)t * PLD;
;                   { const u32x2 v = vq[u]; const float a0 = __uint_as_float(v[0] << 16), a1 = __uint_as_float(v[0] & 0xffff0000u), a2 = __uint_as_float(v[1] << 16), a3 = __uint_as_float(v[1] & 0xffff0000u);
;                     const float rs = rsqrtf(wave_sum(a0 * a0 + a1 * a1 + a2 * a2 + a3 * a3) * (1.f / 256.f) + NEPS);
;                     u32x2 o; o[0] = pk2(a0 * rs * ggq[0], a1 * rs * ggq[1]); o[1] = pk2(a2 * rs * ggq[2], a3 * rs * ggq[3]); *(u32x2*)(mlaa + (size_t)t * 384 + 4 * lane) = o; }
;                   { const unsigned v = vkv[u]; const float a0 = __uint_as_float(v << 16), a1 = __uint_as_float(v & 0xffff0000u);
;                     const float rs = rsqrtf(wave_sum(a0 * a0 + a1 * a1) * (1.f / 128.f) + NEPS);
;                     *(unsigned*)(mlaa + (size_t)t * 384 + 256 + 2 * lane) = pk2(a0 * rs * gkv0, a1 * rs * gkv1); }
; #pragma unroll
;                   for (int hq = 0; hq < 8; ++hq) { const unsigned v = vf[u][hq]; const float a0 = __uint_as_float(v << 16), a1 = __uint_as_float(v & 0xffff0000u);
;                     const float rs = rsqrtf(wave_sum(a0 * a0 + a1 * a1) * (1.f / 128.f) + NEPS) * ((hq < 4) ? 0.08838834764831845f * LOG2E : 1.f);
;                     *(unsigned*)(pr + 3520 + hq * 128 + 2 * lane) = pk2(a0 * rs * ((hq < 4) ? fq0 : fk0), a1 * rs * ((hq < 4) ? fq1 : fk1)); } } } }
	v_and_b32_e32 v23, 0xffff0000, v55
	v_cvt_pk_bf16_f32 v13, v20, v21
	global_store_dword v[16:17], v13, off offset:2944
	v_mul_f32_e32 v13, 0x4b800000, v22
	v_cndmask_b32_e32 v13, v22, v13, vcc
	v_rsq_f32_e32 v13, v13
	v_lshlrev_b32_e32 v22, 16, v55
	v_mul_f32_e32 v16, 0x45800000, v13
	v_cndmask_b32_e32 v13, v13, v16, vcc
	v_mul_f32_e32 v16, 0x3e0293ee, v13
	v_pk_mul_f32 v[16:17], v[16:17], v[24:25] op_sel_hi:[0,1]
	v_pk_mul_f32 v[16:17], v[8:9], v[16:17]
	v_pk_mul_f32 v[24:25], v[22:23], v[22:23]
	v_cvt_pk_bf16_f32 v13, v16, v17
	v_lshlrev_b32_e32 v16, 16, v56
	v_and_b32_e32 v17, 0xffff0000, v56
	v_pk_mul_f32 v[20:21], v[16:17], v[16:17]
	v_mov_b32_e32 v26, v24
	v_mov_b32_e32 v27, v20
	v_mov_b32_e32 v20, v25
	v_pk_add_f32 v[20:21], v[26:27], v[20:21]
	v_mov_b32_e32 v25, v21
	v_mov_b32_e32 v24, v20
	s_nop 0
	v_permlane32_swap_b32_e32 v25, v21
	v_permlane32_swap_b32_e32 v24, v20
	global_store_dword v[14:15], v13, off offset:256
	s_waitcnt lgkmcnt(0)
	v_pk_add_f32 v[20:21], v[20:21], v[24:25]
	v_mov_b32_e32 v25, v21
	v_mov_b32_e32 v24, v20
	s_nop 0
	v_permlane16_swap_b32_e32 v25, v21
	v_permlane16_swap_b32_e32 v24, v20
	s_waitcnt lgkmcnt(0)
	v_pk_add_f32 v[20:21], v[20:21], v[24:25]
	s_nop 1
	v_mov_b32_dpp v25, v21 row_ror:8 row_mask:0xf bank_mask:0xf
	v_mov_b32_dpp v24, v20 row_ror:8 row_mask:0xf bank_mask:0xf
	s_waitcnt lgkmcnt(0)
	v_pk_add_f32 v[20:21], v[20:21], v[24:25]
	s_nop 1
	v_mov_b32_dpp v25, v21 row_shl:4 row_mask:0xf bank_mask:0x5
	v_mov_b32_dpp v25, v21 row_shr:4 row_mask:0xf bank_mask:0xa
	v_mov_b32_dpp v24, v20 row_shl:4 row_mask:0xf bank_mask:0x5
	v_mov_b32_dpp v24, v20 row_shr:4 row_mask:0xf bank_mask:0xa
	s_waitcnt lgkmcnt(0)
	v_pk_add_f32 v[20:21], v[20:21], v[24:25]
	s_nop 1
	v_mov_b32_dpp v25, v21 quad_perm:[2,3,0,1] row_mask:0xf bank_mask:0xf
	v_mov_b32_dpp v24, v20 quad_perm:[2,3,0,1] row_mask:0xf bank_mask:0xf
	s_waitcnt lgkmcnt(0)
	v_pk_add_f32 v[20:21], v[20:21], v[24:25]
	s_nop 1
	v_mov_b32_dpp v25, v21 quad_perm:[1,0,3,2] row_mask:0xf bank_mask:0xf
	v_mov_b32_dpp v24, v20 quad_perm:[1,0,3,2] row_mask:0xf bank_mask:0xf
	s_waitcnt lgkmcnt(0)
	v_pk_add_f32 v[20:21], v[20:21], v[24:25]
	s_nop 0
	v_pk_fma_f32 v[20:21], v[20:21], s[96:97], v[18:19] op_sel_hi:[1,0,0]
	s_nop 0
	v_mul_f32_e32 v13, 0x4b800000, v21
	v_cmp_gt_f32_e64 s[0:1], s77, v21
	v_cmp_gt_f32_e32 vcc, s77, v20
	s_nop 0
	v_cndmask_b32_e64 v13, v21, v13, s[0:1]
	v_rsq_f32_e32 v13, v13
	s_nop 0
	v_mul_f32_e32 v21, 0x45800000, v13
	v_cndmask_b32_e64 v13, v13, v21, s[0:1]
	v_mul_f32_e32 v24, 0x3e0293ee, v13
	v_pk_mul_f32 v[16:17], v[24:25], v[16:17] op_sel_hi:[0,1]
	v_pk_mul_f32 v[16:17], v[8:9], v[16:17]
	s_nop 0
	v_cvt_pk_bf16_f32 v13, v16, v17
	global_store_dword v[14:15], v13, off offset:512
	v_mul_f32_e32 v13, 0x4b800000, v20
	v_cndmask_b32_e32 v13, v20, v13, vcc
	v_rsq_f32_e32 v13, v13
	s_nop 0
	v_mul_f32_e32 v16, 0x45800000, v13
	v_cndmask_b32_e32 v13, v13, v16, vcc
	v_mul_f32_e32 v16, 0x3e0293ee, v13
	v_pk_mul_f32 v[16:17], v[16:17], v[22:23] op_sel_hi:[0,1]
	v_pk_mul_f32 v[16:17], v[8:9], v[16:17]
	s_waitcnt vmcnt(37)
	v_lshlrev_b32_e32 v22, 16, v53
	v_cvt_pk_bf16_f32 v13, v16, v17
	v_lshlrev_b32_e32 v16, 16, v54
	v_and_b32_e32 v17, 0xffff0000, v54
	v_and_b32_e32 v23, 0xffff0000, v53
	v_pk_mul_f32 v[20:21], v[16:17], v[16:17]
	v_pk_mul_f32 v[24:25], v[22:23], v[22:23]
	v_mov_b32_e32 v27, v20
	v_mov_b32_e32 v26, v24
	v_mov_b32_e32 v20, v25
	v_pk_add_f32 v[20:21], v[26:27], v[20:21]
	v_mov_b32_e32 v25, v21
	v_mov_b32_e32 v24, v20
	s_nop 0
	v_permlane32_swap_b32_e32 v25, v21
	v_permlane32_swap_b32_e32 v24, v20
	global_store_dword v[14:15], v13, off offset:768
	s_waitcnt lgkmcnt(0)
	v_pk_add_f32 v[20:21], v[20:21], v[24:25]
	v_mov_b32_e32 v25, v21
	v_mov_b32_e32 v24, v20
	s_nop 0
	v_permlane16_swap_b32_e32 v25, v21
	v_permlane16_swap_b32_e32 v24, v20
	s_waitcnt lgkmcnt(0)
	v_pk_add_f32 v[20:21], v[20:21], v[24:25]
	s_nop 1
	v_mov_b32_dpp v25, v21 row_ror:8 row_mask:0xf bank_mask:0xf
	v_mov_b32_dpp v24, v20 row_ror:8 row_mask:0xf bank_mask:0xf
	s_waitcnt lgkmcnt(0)
	v_pk_add_f32 v[20:21], v[20:21], v[24:25]
	s_nop 1
	v_mov_b32_dpp v25, v21 row_shl:4 row_mask:0xf bank_mask:0x5
	v_mov_b32_dpp v25, v21 row_shr:4 row_mask:0xf bank_mask:0xa
	v_mov_b32_dpp v24, v20 row_shl:4 row_mask:0xf bank_mask:0x5
	v_mov_b32_dpp v24, v20 row_shr:4 row_mask:0xf bank_mask:0xa
	s_waitcnt lgkmcnt(0)
; DI unsigned pk2(float lo, float hi) { const f32x2 v = {lo, hi}; return __builtin_bit_cast(unsigned, __builtin_convertvector(v, bf16v2_t)); }
; DI float wave_sum(float v) { for (int o = 32; o; o >>= 1) v += __shfl_xor(v, o); return v; }
; DI void run_phase(const Params& p, int ph, unsigned char* smem, const int tid, const int rep) {
;     ...
;               for (int u = 0; u < 4; ++u) { const int t = t0 + u; bf16_t* pr = proj + (size_t)t * PLD;
;                   { const u32x2 v = vq[u]; const float a0 = __uint_as_float(v[0] << 16), a1 = __uint_as_float(v[0] & 0xffff0000u), a2 = __uint_as_float(v[1] << 16), a3 = __uint_as_float(v[1] & 0xffff0000u);
;                     const float rs = rsqrtf(wave_sum(a0 * a0 + a1 * a1 + a2 * a2 + a3 * a3) * (1.f / 256.f) + NEPS);
;                     u32x2 o; o[0] = pk2(a0 * rs * ggq[0], a1 * rs * ggq[1]); o[1] = pk2(a2 * rs * ggq[2], a3 * rs * ggq[3]); *(u32x2*)(mlaa + (size_t)t * 384 + 4 * lane) = o; }
;                   { const unsigned v = vkv[u]; const float a0 = __uint_as_float(v << 16), a1 = __uint_as_float(v & 0xffff0000u);
;                     const float rs = rsqrtf(wave_sum(a0 * a0 + a1 * a1) * (1.f / 128.f) + NEPS);
;                     *(unsigned*)(mlaa + (size_t)t * 384 + 256 + 2 * lane) = pk2(a0 * rs * gkv0, a1 * rs * gkv1); }
; #pragma unroll
;                   for (int hq = 0; hq < 8; ++hq) { const unsigned v = vf[u][hq]; const float a0 = __uint_as_float(v << 16), a1 = __uint_as_float(v & 0xffff0000u);
;                     const float rs = rsqrtf(wave_sum(a0 * a0 + a1 * a1) * (1.f / 128.f) + NEPS) * ((hq < 4) ? 0.08838834764831845f * LOG2E : 1.f);
;                     *(unsigned*)(pr + 3520 + hq * 128 + 2 * lane) = pk2(a0 * rs * ((hq < 4) ? fq0 : fk0), a1 * rs * ((hq < 4) ? fq1 : fk1)); } } } }
	v_pk_add_f32 v[20:21], v[20:21], v[24:25]
	s_nop 1
	v_mov_b32_dpp v25, v21 quad_perm:[2,3,0,1] row_mask:0xf bank_mask:0xf
	v_mov_b32_dpp v24, v20 quad_perm:[2,3,0,1] row_mask:0xf bank_mask:0xf
	s_waitcnt lgkmcnt(0)
	v_pk_add_f32 v[20:21], v[20:21], v[24:25]
	s_nop 1
	v_mov_b32_dpp v25, v21 quad_perm:[1,0,3,2] row_mask:0xf bank_mask:0xf
	v_mov_b32_dpp v24, v20 quad_perm:[1,0,3,2] row_mask:0xf bank_mask:0xf
	s_waitcnt lgkmcnt(0)
	v_pk_add_f32 v[20:21], v[20:21], v[24:25]
	s_nop 0
	v_pk_fma_f32 v[20:21], v[20:21], s[96:97], v[18:19] op_sel_hi:[1,0,0]
	s_nop 0
	v_mul_f32_e32 v13, 0x4b800000, v21
	v_cmp_gt_f32_e64 s[0:1], s77, v21
	v_cmp_gt_f32_e32 vcc, s77, v20
	s_nop 0
	v_cndmask_b32_e64 v13, v21, v13, s[0:1]
	v_rsq_f32_e32 v13, v13
	s_nop 0
	v_mul_f32_e32 v21, 0x45800000, v13
	v_cndmask_b32_e64 v24, v13, v21, s[0:1]
	v_pk_mul_f32 v[16:17], v[24:25], v[16:17] op_sel_hi:[0,1]
	v_pk_mul_f32 v[16:17], v[10:11], v[16:17]
	s_nop 0
	v_cvt_pk_bf16_f32 v13, v16, v17
	global_store_dword v[14:15], v13, off offset:1024
	v_mul_f32_e32 v13, 0x4b800000, v20
	v_cndmask_b32_e32 v13, v20, v13, vcc
	v_rsq_f32_e32 v13, v13
	s_nop 0
	v_mul_f32_e32 v16, 0x45800000, v13
	v_cndmask_b32_e32 v16, v13, v16, vcc
	v_pk_mul_f32 v[16:17], v[16:17], v[22:23] op_sel_hi:[0,1]
	v_pk_mul_f32 v[16:17], v[10:11], v[16:17]
	s_waitcnt vmcnt(37)
	v_lshlrev_b32_e32 v22, 16, v51
	v_cvt_pk_bf16_f32 v13, v16, v17
	v_lshlrev_b32_e32 v16, 16, v52
	v_and_b32_e32 v17, 0xffff0000, v52
	v_and_b32_e32 v23, 0xffff0000, v51
	v_pk_mul_f32 v[20:21], v[16:17], v[16:17]
	v_pk_mul_f32 v[24:25], v[22:23], v[22:23]
	v_mov_b32_e32 v27, v20
	v_mov_b32_e32 v26, v24
	v_mov_b32_e32 v20, v25
	v_pk_add_f32 v[20:21], v[26:27], v[20:21]
	v_mov_b32_e32 v25, v21
	v_mov_b32_e32 v24, v20
	s_nop 0
	v_permlane32_swap_b32_e32 v25, v21
	v_permlane32_swap_b32_e32 v24, v20
	global_store_dword v[14:15], v13, off offset:1280
	s_waitcnt lgkmcnt(0)
	v_pk_add_f32 v[20:21], v[20:21], v[24:25]
	v_mov_b32_e32 v25, v21
	v_mov_b32_e32 v24, v20
	s_nop 0
	v_permlane16_swap_b32_e32 v25, v21
	v_permlane16_swap_b32_e32 v24, v20
	s_waitcnt lgkmcnt(0)
	v_pk_add_f32 v[20:21], v[20:21], v[24:25]
	s_nop 1
	v_mov_b32_dpp v25, v21 row_ror:8 row_mask:0xf bank_mask:0xf
	v_mov_b32_dpp v24, v20 row_ror:8 row_mask:0xf bank_mask:0xf
	s_waitcnt lgkmcnt(0)
	v_pk_add_f32 v[20:21], v[20:21], v[24:25]
	s_nop 1
	v_mov_b32_dpp v25, v21 row_shl:4 row_mask:0xf bank_mask:0x5
	v_mov_b32_dpp v25, v21 row_shr:4 row_mask:0xf bank_mask:0xa
	v_mov_b32_dpp v24, v20 row_shl:4 row_mask:0xf bank_mask:0x5
	v_mov_b32_dpp v24, v20 row_shr:4 row_mask:0xf bank_mask:0xa
	s_waitcnt lgkmcnt(0)
	v_pk_add_f32 v[20:21], v[20:21], v[24:25]
	s_nop 1
	v_mov_b32_dpp v25, v21 quad_perm:[2,3,0,1] row_mask:0xf bank_mask:0xf
	v_mov_b32_dpp v24, v20 quad_perm:[2,3,0,1] row_mask:0xf bank_mask:0xf
	s_waitcnt lgkmcnt(0)
	v_pk_add_f32 v[20:21], v[20:21], v[24:25]
	s_nop 1
	v_mov_b32_dpp v25, v21 quad_perm:[1,0,3,2] row_mask:0xf bank_mask:0xf
	v_mov_b32_dpp v24, v20 quad_perm:[1,0,3,2] row_mask:0xf bank_mask:0xf
	s_waitcnt lgkmcnt(0)
	v_pk_add_f32 v[20:21], v[20:21], v[24:25]
	s_nop 0
	v_pk_fma_f32 v[18:19], v[20:21], s[96:97], v[18:19] op_sel_hi:[1,0,0]
	s_nop 0
	v_mul_f32_e32 v13, 0x4b800000, v19
	v_cmp_gt_f32_e64 s[0:1], s77, v19
	v_cmp_gt_f32_e32 vcc, s77, v18
	s_nop 0
	v_cndmask_b32_e64 v13, v19, v13, s[0:1]
	v_rsq_f32_e32 v13, v13
	s_nop 0
	v_mul_f32_e32 v19, 0x45800000, v13
	v_cndmask_b32_e64 v20, v13, v19, s[0:1]
	v_pk_mul_f32 v[16:17], v[20:21], v[16:17] op_sel_hi:[0,1]
	v_pk_mul_f32 v[16:17], v[10:11], v[16:17]
	s_nop 0
	v_cvt_pk_bf16_f32 v13, v16, v17
	global_store_dword v[14:15], v13, off offset:1536
	v_mul_f32_e32 v13, 0x4b800000, v18
	v_cndmask_b32_e32 v13, v18, v13, vcc
	v_rsq_f32_e32 v13, v13
	s_nop 0
	v_mul_f32_e32 v16, 0x45800000, v13
	v_cndmask_b32_e32 v16, v13, v16, vcc
	v_pk_mul_f32 v[16:17], v[16:17], v[22:23] op_sel_hi:[0,1]
	v_pk_mul_f32 v[16:17], v[10:11], v[16:17]
	v_cmp_lt_i32_e32 vcc, s11, v44
	v_cvt_pk_bf16_f32 v13, v16, v17
	s_or_b64 s[40:41], vcc, s[40:41]
	global_store_dword v[14:15], v13, off offset:1792
	s_andn2_b64 exec, exec, s[40:41]
	s_cbranch_execnz .LBB0_372

; DI float wave_sum(float v) { for (int o = 32; o; o >>= 1) v += __shfl_xor(v, o); return v; }
; DI void rmsnorm_phase(const float* x, const float* g, bf16_t* h, int ntok, const int tid) {
;     ...
;     for (int t0 = (blockIdx.x * 8 + wv) * 2; t0 < ntok; t0 += gridDim.x * 16) {
;         f32x4 v[2][4];
; #pragma unroll
;         for (int u = 0; u < 2; ++u)
; #pragma unroll
;             for (int c = 0; c < 4; ++c) v[u][c] = ((const f32x4*)(x + (size_t)(t0 + u) * 1024))[lane + 64 * c];
; #pragma unroll
;         for (int u = 0; u < 2; ++u) { float ss = 0.f;
; #pragma unroll
;             for (int c = 0; c < 4; ++c) ss += v[u][c][0] * v[u][c][0] + v[u][c][1] * v[u][c][1] + v[u][c][2] * v[u][c][2] + v[u][c][3] * v[u][c][3];
;             ss = wave_sum(ss);
;             const float rs = rsqrtf(ss * (1.f / 1024.f) + NEPS);
.LBB0_702:
	v_ashrrev_i32_e32 v51, 31, v50
	v_lshlrev_b64 v[18:19], 12, v[50:51]
	v_add_u32_e32 v56, 1, v50
	v_lshl_add_u64 v[18:19], v[52:53], 0, v[18:19]
	v_ashrrev_i32_e32 v57, 31, v56
	global_load_dwordx4 v[46:49], v[18:19], off
	global_load_dwordx4 v[42:45], v[18:19], off offset:1024
	global_load_dwordx4 v[38:41], v[18:19], off offset:2048
	global_load_dwordx4 v[34:37], v[18:19], off offset:3072
	v_lshlrev_b64 v[18:19], 12, v[56:57]
	v_lshl_add_u64 v[18:19], v[52:53], 0, v[18:19]
	global_load_dwordx4 v[30:33], v[18:19], off
	global_load_dwordx4 v[26:29], v[18:19], off offset:1024
	global_load_dwordx4 v[22:25], v[18:19], off offset:2048
	s_nop 0
	global_load_dwordx4 v[18:21], v[18:19], off offset:3072
	s_waitcnt vmcnt(7)
	v_mov_b32_e32 v66, v47
	s_waitcnt vmcnt(6)
	v_mov_b32_e32 v67, v43
	v_mov_b32_e32 v58, v46
	s_waitcnt vmcnt(3)
	v_mov_b32_e32 v72, v31
	s_waitcnt vmcnt(2)
	v_mov_b32_e32 v73, v27
	v_mov_b32_e32 v59, v42
	v_pk_mul_f32 v[66:67], v[66:67], v[66:67]
	v_mov_b32_e32 v70, v30
	v_mov_b32_e32 v71, v26
	v_pk_mul_f32 v[72:73], v[72:73], v[72:73]
	v_pk_fma_f32 v[58:59], v[58:59], v[58:59], v[66:67]
	v_mov_b32_e32 v66, v48
	v_mov_b32_e32 v67, v44
	v_pk_fma_f32 v[70:71], v[70:71], v[70:71], v[72:73]
	v_mov_b32_e32 v72, v32
	v_mov_b32_e32 v73, v28
	v_pk_fma_f32 v[58:59], v[66:67], v[66:67], v[58:59]
	v_mov_b32_e32 v66, v49
	v_mov_b32_e32 v67, v45
	v_mov_b32_e32 v68, v39
	v_mov_b32_e32 v69, v35
	v_pk_fma_f32 v[70:71], v[72:73], v[72:73], v[70:71]
	v_mov_b32_e32 v72, v33
	v_mov_b32_e32 v73, v29
	s_waitcnt vmcnt(1)
	v_mov_b32_e32 v74, v23
	s_waitcnt vmcnt(0)
	v_mov_b32_e32 v75, v19
	v_pk_fma_f32 v[66:67], v[66:67], v[66:67], v[58:59]
	v_mov_b32_e32 v58, v38
	v_mov_b32_e32 v59, v34
	v_pk_mul_f32 v[68:69], v[68:69], v[68:69]
	v_pk_fma_f32 v[70:71], v[72:73], v[72:73], v[70:71]
	v_mov_b32_e32 v72, v22
	v_mov_b32_e32 v73, v18
	v_pk_mul_f32 v[74:75], v[74:75], v[74:75]
	v_pk_fma_f32 v[58:59], v[58:59], v[58:59], v[68:69]
	v_mov_b32_e32 v68, v40
	v_mov_b32_e32 v69, v36
	v_pk_fma_f32 v[72:73], v[72:73], v[72:73], v[74:75]
	v_mov_b32_e32 v74, v24
	v_mov_b32_e32 v75, v20
	v_pk_fma_f32 v[58:59], v[68:69], v[68:69], v[58:59]
	v_mov_b32_e32 v68, v41
	v_mov_b32_e32 v69, v37
	v_pk_fma_f32 v[72:73], v[74:75], v[74:75], v[72:73]
	v_mov_b32_e32 v74, v25
	v_mov_b32_e32 v75, v21
	v_pk_fma_f32 v[68:69], v[68:69], v[68:69], v[58:59]
	v_pk_fma_f32 v[72:73], v[74:75], v[74:75], v[72:73]
	v_mov_b32_e32 v74, v70
	v_mov_b32_e32 v75, v66
	v_mov_b32_e32 v66, v71
	v_pk_add_f32 v[66:67], v[74:75], v[66:67]
	v_mov_b32_e32 v70, v72
	v_mov_b32_e32 v71, v68
	v_pk_add_f32 v[66:67], v[66:67], v[70:71]
	v_mov_b32_e32 v68, v73
	v_pk_add_f32 v[66:67], v[66:67], v[68:69]
	v_mov_b32_e32 v69, v67
	v_mov_b32_e32 v68, v66
	s_nop 0
	v_permlane32_swap_b32_e32 v69, v67
	v_permlane32_swap_b32_e32 v68, v66
	v_lshlrev_b64 v[58:59], 11, v[50:51]
	v_lshl_add_u64 v[58:59], v[54:55], 0, v[58:59]
	v_add_u32_e32 v50, s17, v50
	s_waitcnt lgkmcnt(0)
	v_pk_add_f32 v[66:67], v[66:67], v[68:69]
	v_mov_b32_e32 v69, v67
	v_mov_b32_e32 v68, v66
	s_nop 0
	v_permlane16_swap_b32_e32 v69, v67
	v_permlane16_swap_b32_e32 v68, v66
	s_waitcnt lgkmcnt(0)
	v_pk_add_f32 v[66:67], v[66:67], v[68:69]
	s_nop 1
	v_mov_b32_dpp v69, v67 row_ror:8 row_mask:0xf bank_mask:0xf
	v_mov_b32_dpp v68, v66 row_ror:8 row_mask:0xf bank_mask:0xf
	s_waitcnt lgkmcnt(0)
	v_pk_add_f32 v[66:67], v[66:67], v[68:69]
	s_nop 1
	v_mov_b32_dpp v69, v67 row_shl:4 row_mask:0xf bank_mask:0x5
	v_mov_b32_dpp v69, v67 row_shr:4 row_mask:0xf bank_mask:0xa
	v_mov_b32_dpp v68, v66 row_shl:4 row_mask:0xf bank_mask:0x5
	v_mov_b32_dpp v68, v66 row_shr:4 row_mask:0xf bank_mask:0xa
	s_waitcnt lgkmcnt(0)
; DI unsigned pk2(float lo, float hi) { const f32x2 v = {lo, hi}; return __builtin_bit_cast(unsigned, __builtin_convertvector(v, bf16v2_t)); }
; DI float wave_sum(float v) { for (int o = 32; o; o >>= 1) v += __shfl_xor(v, o); return v; }
; DI void rmsnorm_phase(const float* x, const float* g, bf16_t* h, int ntok, const int tid) {
;     ...
;             ss = wave_sum(ss);
;             const float rs = rsqrtf(ss * (1.f / 1024.f) + NEPS);
; #pragma unroll
;             for (int c = 0; c < 4; ++c) { u32x2 o; o[0] = pk2(v[u][c][0] * rs * gg[c][0], v[u][c][1] * rs * gg[c][1]); o[1] = pk2(v[u][c][2] * rs * gg[c][2], v[u][c][3] * rs * gg[c][3]);
;                 *(u32x2*)(h + (size_t)(t0 + u) * 1024 + (lane + 64 * c) * 4) = o; } }
	v_pk_add_f32 v[66:67], v[66:67], v[68:69]
	s_nop 1
	v_mov_b32_dpp v69, v67 quad_perm:[2,3,0,1] row_mask:0xf bank_mask:0xf
	v_mov_b32_dpp v68, v66 quad_perm:[2,3,0,1] row_mask:0xf bank_mask:0xf
	s_waitcnt lgkmcnt(0)
	v_pk_add_f32 v[66:67], v[66:67], v[68:69]
	s_nop 1
	v_mov_b32_dpp v69, v67 quad_perm:[1,0,3,2] row_mask:0xf bank_mask:0xf
	v_mov_b32_dpp v68, v66 quad_perm:[1,0,3,2] row_mask:0xf bank_mask:0xf
	s_waitcnt lgkmcnt(0)
	v_pk_add_f32 v[66:67], v[66:67], v[68:69]
	s_nop 0
	v_pk_fma_f32 v[66:67], v[66:67], s[4:5], v[190:191] op_sel_hi:[1,0,0]
	s_nop 0
	v_mul_f32_e32 v0, 0x4b800000, v67
	v_cmp_gt_f32_e64 s[0:1], s77, v67
	v_cmp_gt_f32_e32 vcc, s77, v66
	s_nop 0
	v_cndmask_b32_e64 v0, v67, v0, s[0:1]
	v_rsq_f32_e32 v0, v0
	s_nop 0
	v_mul_f32_e32 v51, 0x45800000, v0
	v_cndmask_b32_e64 v0, v0, v51, s[0:1]
	v_pk_mul_f32 v[46:47], v[46:47], v[0:1] op_sel_hi:[1,0]
	v_pk_mul_f32 v[48:49], v[48:49], v[0:1] op_sel_hi:[1,0]
	v_pk_mul_f32 v[42:43], v[42:43], v[0:1] op_sel_hi:[1,0]
	v_pk_mul_f32 v[44:45], v[44:45], v[0:1] op_sel_hi:[1,0]
	v_pk_mul_f32 v[38:39], v[38:39], v[0:1] op_sel_hi:[1,0]
	v_pk_mul_f32 v[40:41], v[40:41], v[0:1] op_sel_hi:[1,0]
	v_pk_mul_f32 v[34:35], v[34:35], v[0:1] op_sel_hi:[1,0]
	v_pk_mul_f32 v[36:37], v[36:37], v[0:1] op_sel_hi:[1,0]
	v_mul_f32_e32 v0, 0x4b800000, v66
	v_cndmask_b32_e32 v0, v66, v0, vcc
	v_rsq_f32_e32 v0, v0
	v_pk_mul_f32 v[34:35], v[2:3], v[34:35]
	v_pk_mul_f32 v[36:37], v[4:5], v[36:37]
	v_cvt_pk_bf16_f32 v34, v34, v35
	v_cvt_pk_bf16_f32 v35, v36, v37
	global_store_dwordx2 v[58:59], v[34:35], off offset:1536
	v_mul_f32_e32 v34, 0x45800000, v0
	v_cndmask_b32_e32 v0, v0, v34, vcc
	v_pk_mul_f32 v[30:31], v[30:31], v[0:1] op_sel_hi:[1,0]
	v_pk_mul_f32 v[32:33], v[32:33], v[0:1] op_sel_hi:[1,0]
	v_pk_mul_f32 v[26:27], v[26:27], v[0:1] op_sel_hi:[1,0]
	v_pk_mul_f32 v[28:29], v[28:29], v[0:1] op_sel_hi:[1,0]
	v_pk_mul_f32 v[22:23], v[22:23], v[0:1] op_sel_hi:[1,0]
	v_pk_mul_f32 v[24:25], v[24:25], v[0:1] op_sel_hi:[1,0]
	v_pk_mul_f32 v[18:19], v[18:19], v[0:1] op_sel_hi:[1,0]
	v_pk_mul_f32 v[20:21], v[20:21], v[0:1] op_sel_hi:[1,0]
	v_pk_mul_f32 v[46:47], v[14:15], v[46:47]
	v_pk_mul_f32 v[48:49], v[16:17], v[48:49]
	v_pk_mul_f32 v[42:43], v[10:11], v[42:43]
	v_pk_mul_f32 v[44:45], v[12:13], v[44:45]
	v_pk_mul_f32 v[38:39], v[6:7], v[38:39]
	v_pk_mul_f32 v[40:41], v[8:9], v[40:41]
	v_lshlrev_b64 v[34:35], 11, v[56:57]
	v_pk_mul_f32 v[30:31], v[14:15], v[30:31]
	v_pk_mul_f32 v[32:33], v[16:17], v[32:33]
	v_pk_mul_f32 v[26:27], v[10:11], v[26:27]
	v_pk_mul_f32 v[28:29], v[12:13], v[28:29]
	v_pk_mul_f32 v[22:23], v[6:7], v[22:23]
	v_pk_mul_f32 v[24:25], v[8:9], v[24:25]
	v_pk_mul_f32 v[18:19], v[2:3], v[18:19]
	v_pk_mul_f32 v[20:21], v[4:5], v[20:21]
	v_cmp_lt_i32_e32 vcc, s16, v50
	v_cvt_pk_bf16_f32 v46, v46, v47
	v_cvt_pk_bf16_f32 v47, v48, v49
	v_cvt_pk_bf16_f32 v42, v42, v43
	v_cvt_pk_bf16_f32 v43, v44, v45
	v_cvt_pk_bf16_f32 v38, v38, v39
	v_cvt_pk_bf16_f32 v39, v40, v41
	v_cvt_pk_bf16_f32 v30, v30, v31
	v_cvt_pk_bf16_f32 v31, v32, v33
	v_lshl_add_u64 v[32:33], v[54:55], 0, v[34:35]
	v_cvt_pk_bf16_f32 v26, v26, v27
	v_cvt_pk_bf16_f32 v27, v28, v29
	v_cvt_pk_bf16_f32 v22, v22, v23
	v_cvt_pk_bf16_f32 v23, v24, v25
	v_cvt_pk_bf16_f32 v18, v18, v19
	v_cvt_pk_bf16_f32 v19, v20, v21
	s_or_b64 s[12:13], vcc, s[12:13]
	global_store_dwordx2 v[58:59], v[46:47], off
	global_store_dwordx2 v[58:59], v[42:43], off offset:512
	global_store_dwordx2 v[58:59], v[38:39], off offset:1024
	global_store_dwordx2 v[32:33], v[30:31], off
	global_store_dwordx2 v[32:33], v[26:27], off offset:512
	global_store_dwordx2 v[32:33], v[22:23], off offset:1024
	global_store_dwordx2 v[32:33], v[18:19], off offset:1536
	s_andn2_b64 exec, exec, s[12:13]
	s_cbranch_execnz .LBB0_702
	s_getpc_b64 s[98:99]
